# speedup vs baseline: 1.0472x; 1.0007x over previous
;     ...
;   for (int kt = 0; kt < nk; ++kt) {
;     const int kn = (kt + 1 < nk) ? kt + 1 : kt;
;     GW_LOAD2(kn * 64, kn * bkstep)
;     __builtin_amdgcn_sched_barrier(0);
;     __builtin_amdgcn_s_setprio(1);
; #pragma unroll
;     for (int st = 0; st < 4; ++st) {
;       bf16x8 a0 = *(const bf16x8*)(Ab + st * 32);
;       bf16x8 a1 = *(const bf16x8*)(Ab + 32 * LSTR + st * 32);
;       bf16x8 b0 = *(const bf16x8*)(Bb + st * 32);
;       bf16x8 b1 = *(const bf16x8*)(Bb + 32 * LSTR + st * 32);
;       bf16x8 b2 = *(const bf16x8*)(Bb + 64 * LSTR + st * 32);
;       bf16x8 b3 = *(const bf16x8*)(Bb + 96 * LSTR + st * 32);
;       acc[0][0] = mfma32(a0, b0, acc[0][0]);
;       acc[0][1] = mfma32(a0, b1, acc[0][1]);
;       acc[0][2] = mfma32(a0, b2, acc[0][2]);
;       acc[0][3] = mfma32(a0, b3, acc[0][3]);
;       acc[1][0] = mfma32(a1, b0, acc[1][0]);
;       acc[1][1] = mfma32(a1, b1, acc[1][1]);
;       acc[1][2] = mfma32(a1, b2, acc[1][2]);
;       acc[1][3] = mfma32(a1, b3, acc[1][3]);
;     }
;     __builtin_amdgcn_s_setprio(0);
;     __builtin_amdgcn_sched_barrier(0);
;     __syncthreads();
;     GW_STORE()
;     __syncthreads();
;   }
.LBB0_238:
	s_barrier
	s_setprio 1
	ds_read_b128 v[202:205], v131 offset:0
	ds_read_b128 v[214:217], v136 offset:18432
	ds_read_b128 v[218:221], v136 offset:23040
	ds_read_b128 v[224:227], v136 offset:27648
	ds_read_b128 v[228:231], v136 offset:32256
	ds_read_b128 v[210:213], v131 offset:4608
	s_waitcnt lgkmcnt(4)
	v_mfma_f32_32x32x16_bf16 v[114:129], v[202:205], v[214:217], v[114:129]
	ds_read_b128 v[206:209], v131 offset:32
	ds_read_b128 v[232:235], v136 offset:18464
	s_waitcnt lgkmcnt(5)
	v_mfma_f32_32x32x16_bf16 v[98:113], v[202:205], v[218:221], v[98:113]
	ds_read_b128 v[236:239], v136 offset:23072
	s_waitcnt lgkmcnt(5)
	v_mfma_f32_32x32x16_bf16 v[82:97], v[202:205], v[224:227], v[82:97]
	ds_read_b128 v[240:243], v136 offset:27680
	s_waitcnt lgkmcnt(5)
	v_mfma_f32_32x32x16_bf16 v[66:81], v[202:205], v[228:231], v[66:81]
	ds_read_b128 v[244:247], v136 offset:32288
	s_waitcnt lgkmcnt(5)
	v_mfma_f32_32x32x16_bf16 v[50:65], v[210:213], v[214:217], v[50:65]
	v_lshl_add_u64 v[150:151], v[148:149], 0, s[10:11]
	v_add_co_u32_e32 v150, vcc, 0x12c31000, v150
	s_nop 1
	v_addc_co_u32_e32 v151, vcc, 0, v151, vcc
	global_load_dwordx4 v[150:153], v[150:151], off offset:384
	v_mfma_f32_32x32x16_bf16 v[34:49], v[210:213], v[218:221], v[34:49]
	v_lshl_add_u64 v[154:155], v[148:149], 0, s[10:11]
	v_add_co_u32_e32 v154, vcc, 0x12c41000, v154
	s_nop 1
	v_addc_co_u32_e32 v155, vcc, 0, v155, vcc
	global_load_dwordx4 v[154:157], v[154:155], off offset:384
	v_mfma_f32_32x32x16_bf16 v[18:33], v[210:213], v[224:227], v[18:33]
	v_lshl_add_u64 v[158:159], v[148:149], 0, s[10:11]
	v_add_co_u32_e32 v158, vcc, 0x12c51000, v158
	s_nop 1
	v_addc_co_u32_e32 v159, vcc, 0, v159, vcc
	global_load_dwordx4 v[158:161], v[158:159], off offset:384
	v_mfma_f32_32x32x16_bf16 v[2:17], v[210:213], v[228:231], v[2:17]
	v_lshl_add_u64 v[162:163], v[148:149], 0, s[10:11]
	v_add_co_u32_e32 v162, vcc, 0x12c61000, v162
	s_nop 1
	v_addc_co_u32_e32 v163, vcc, 0, v163, vcc
	global_load_dwordx4 v[162:165], v[162:163], off offset:384
	ds_read_b128 v[210:213], v131 offset:4640
	s_waitcnt lgkmcnt(4)
	v_mfma_f32_32x32x16_bf16 v[114:129], v[206:209], v[232:235], v[114:129]
	ds_read_b128 v[202:205], v131 offset:64
	ds_read_b128 v[214:217], v136 offset:18496
	s_waitcnt lgkmcnt(5)
	v_mfma_f32_32x32x16_bf16 v[98:113], v[206:209], v[236:239], v[98:113]
	ds_read_b128 v[218:221], v136 offset:23104
	s_waitcnt lgkmcnt(5)
	v_mfma_f32_32x32x16_bf16 v[82:97], v[206:209], v[240:243], v[82:97]
	ds_read_b128 v[224:227], v136 offset:27712
	s_waitcnt lgkmcnt(5)
	v_mfma_f32_32x32x16_bf16 v[66:81], v[206:209], v[244:247], v[66:81]
	ds_read_b128 v[228:231], v136 offset:32320
	s_waitcnt lgkmcnt(5)
	v_mfma_f32_32x32x16_bf16 v[50:65], v[210:213], v[232:235], v[50:65]
	v_lshl_add_u64 v[166:167], v[132:133], 0, s[10:11]
	global_load_dwordx4 v[166:169], v[166:167], off offset:128
	v_mfma_f32_32x32x16_bf16 v[34:49], v[210:213], v[236:239], v[34:49]
	v_lshl_add_u64 v[170:171], v[132:133], 0, s[10:11]
	v_add_co_u32_e32 v170, vcc, s37, v170
	s_nop 1
	v_addc_co_u32_e32 v171, vcc, 0, v171, vcc
	global_load_dwordx4 v[170:173], v[170:171], off offset:128
	v_mfma_f32_32x32x16_bf16 v[18:33], v[210:213], v[240:243], v[18:33]
	v_lshl_add_u64 v[174:175], v[132:133], 0, s[10:11]
	v_add_co_u32_e32 v174, vcc, s38, v174
	s_nop 1
	v_addc_co_u32_e32 v175, vcc, 0, v175, vcc
	global_load_dwordx4 v[174:177], v[174:175], off offset:128
	v_mfma_f32_32x32x16_bf16 v[2:17], v[210:213], v[244:247], v[2:17]
	v_lshl_add_u64 v[178:179], v[132:133], 0, s[10:11]
	v_add_co_u32_e32 v178, vcc, s39, v178
	s_nop 1
	v_addc_co_u32_e32 v179, vcc, 0, v179, vcc
	global_load_dwordx4 v[178:181], v[178:179], off offset:128
	ds_read_b128 v[210:213], v131 offset:4672
	s_waitcnt lgkmcnt(4)
	v_mfma_f32_32x32x16_bf16 v[114:129], v[202:205], v[214:217], v[114:129]
	ds_read_b128 v[206:209], v131 offset:96
	ds_read_b128 v[232:235], v136 offset:18528
	s_waitcnt lgkmcnt(5)
	v_mfma_f32_32x32x16_bf16 v[98:113], v[202:205], v[218:221], v[98:113]
	ds_read_b128 v[236:239], v136 offset:23136
	s_waitcnt lgkmcnt(5)
	v_mfma_f32_32x32x16_bf16 v[82:97], v[202:205], v[224:227], v[82:97]
	ds_read_b128 v[240:243], v136 offset:27744
	s_waitcnt lgkmcnt(5)
	v_mfma_f32_32x32x16_bf16 v[66:81], v[202:205], v[228:231], v[66:81]
	ds_read_b128 v[244:247], v136 offset:32352
	s_waitcnt lgkmcnt(5)
	v_mfma_f32_32x32x16_bf16 v[50:65], v[210:213], v[214:217], v[50:65]
	v_lshl_add_u64 v[186:187], v[132:133], 0, s[10:11]
	v_add_co_u32_e32 v186, vcc, s40, v186
	s_nop 1
	v_addc_co_u32_e32 v187, vcc, 0, v187, vcc
	global_load_dwordx4 v[186:189], v[186:187], off offset:128
	v_mfma_f32_32x32x16_bf16 v[34:49], v[210:213], v[218:221], v[34:49]
	v_lshl_add_u64 v[190:191], v[132:133], 0, s[10:11]
	v_add_co_u32_e32 v190, vcc, s41, v190
	s_nop 1
	v_addc_co_u32_e32 v191, vcc, 0, v191, vcc
	global_load_dwordx4 v[190:193], v[190:191], off offset:128
	v_mfma_f32_32x32x16_bf16 v[18:33], v[210:213], v[224:227], v[18:33]
	v_lshl_add_u64 v[194:195], v[132:133], 0, s[10:11]
	v_add_co_u32_e32 v194, vcc, s42, v194
	s_nop 1
	v_addc_co_u32_e32 v195, vcc, 0, v195, vcc
	global_load_dwordx4 v[194:197], v[194:195], off offset:128
	v_mfma_f32_32x32x16_bf16 v[2:17], v[210:213], v[228:231], v[2:17]
	v_lshl_add_u64 v[198:199], v[132:133], 0, s[10:11]
	v_add_co_u32_e32 v198, vcc, s43, v198
	s_nop 1
	v_addc_co_u32_e32 v199, vcc, 0, v199, vcc
	global_load_dwordx4 v[198:201], v[198:199], off offset:128
	ds_read_b128 v[210:213], v131 offset:4704
	s_waitcnt lgkmcnt(4)
	v_mfma_f32_32x32x16_bf16 v[114:129], v[206:209], v[232:235], v[114:129]
	s_waitcnt lgkmcnt(3)
	v_mfma_f32_32x32x16_bf16 v[98:113], v[206:209], v[236:239], v[98:113]
	s_waitcnt lgkmcnt(2)
	v_mfma_f32_32x32x16_bf16 v[82:97], v[206:209], v[240:243], v[82:97]
	s_waitcnt lgkmcnt(1)
	v_mfma_f32_32x32x16_bf16 v[66:81], v[206:209], v[244:247], v[66:81]
	s_waitcnt lgkmcnt(0)
	v_mfma_f32_32x32x16_bf16 v[50:65], v[210:213], v[232:235], v[50:65]
	v_mfma_f32_32x32x16_bf16 v[34:49], v[210:213], v[236:239], v[34:49]
	v_mfma_f32_32x32x16_bf16 v[18:33], v[210:213], v[240:243], v[18:33]
	v_mfma_f32_32x32x16_bf16 v[2:17], v[210:213], v[244:247], v[2:17]
	s_setprio 0
	s_add_u32 s10, s10, 0x80
	s_addc_u32 s11, s11, 0
	s_cmpk_lg_i32 s10, 0x700
	s_barrier
; #define GW_LOAD(KOFF) GW_LOAD2(KOFF, 0)
;     ...
;   GW_LOAD(0)
;   GW_STORE()
;   __syncthreads();
;   const int nk = K >> 6;
;   const char* Ab = smem + (wm * 64 + (lane & 31)) * LSTR + (lane >> 5) * 16;
;   const char* Bb = smem + WTILE_A + (wn * 128 + (lane & 31)) * LSTR + (lane >> 5) * 16;
;   for (int kt = 0; kt < nk; ++kt) {
;     const int kn = (kt + 1 < nk) ? kt + 1 : kt;
;     GW_LOAD2(kn * 64, kn * bkstep)
;     __builtin_amdgcn_sched_barrier(0);
;     __builtin_amdgcn_s_setprio(1);
; #pragma unroll
;     for (int st = 0; st < 4; ++st) {
;       bf16x8 a0 = *(const bf16x8*)(Ab + st * 32);
;       bf16x8 a1 = *(const bf16x8*)(Ab + 32 * LSTR + st * 32);
;       bf16x8 b0 = *(const bf16x8*)(Bb + st * 32);
;       bf16x8 b1 = *(const bf16x8*)(Bb + 32 * LSTR + st * 32);
;       bf16x8 b2 = *(const bf16x8*)(Bb + 64 * LSTR + st * 32);
;       bf16x8 b3 = *(const bf16x8*)(Bb + 96 * LSTR + st * 32);
;       acc[0][0] = mfma32(a0, b0, acc[0][0]);
;       acc[0][1] = mfma32(a0, b1, acc[0][1]);
;       acc[0][2] = mfma32(a0, b2, acc[0][2]);
;       acc[0][3] = mfma32(a0, b3, acc[0][3]);
;       acc[1][0] = mfma32(a1, b0, acc[1][0]);
;       acc[1][1] = mfma32(a1, b1, acc[1][1]);
;       acc[1][2] = mfma32(a1, b2, acc[1][2]);
;       acc[1][3] = mfma32(a1, b3, acc[1][3]);
;     }
;     __builtin_amdgcn_s_setprio(0);
;     __builtin_amdgcn_sched_barrier(0);
;     __syncthreads();
;     GW_STORE()
;     __syncthreads();
	s_waitcnt vmcnt(11)
	ds_write_b128 v130, v[150:153]
	s_waitcnt vmcnt(10)
	ds_write_b128 v130, v[154:157] offset:4608
	s_waitcnt vmcnt(9)
	ds_write_b128 v130, v[158:161] offset:9216
	s_waitcnt vmcnt(8)
	ds_write_b128 v130, v[162:165] offset:13824
	s_waitcnt vmcnt(7)
	ds_write_b128 v130, v[166:169] offset:18432
	s_waitcnt vmcnt(6)
	ds_write_b128 v130, v[170:173] offset:23040
	s_waitcnt vmcnt(5)
	ds_write_b128 v130, v[174:177] offset:27648
	s_waitcnt vmcnt(4)
	ds_write_b128 v130, v[178:181] offset:32256
	s_waitcnt vmcnt(3)
	ds_write_b128 v130, v[186:189] offset:36864
	s_waitcnt vmcnt(2)
	ds_write_b128 v130, v[190:193] offset:41472
	s_waitcnt vmcnt(1)
	ds_write_b128 v130, v[194:197] offset:46080
	s_waitcnt vmcnt(0)
	ds_write_b128 v130, v[198:201] offset:50688
	s_waitcnt lgkmcnt(0)
	s_cbranch_scc1 .LBB0_238
	s_barrier
	s_setprio 1
	ds_read_b128 v[202:205], v131 offset:0
	ds_read_b128 v[214:217], v136 offset:18432
	ds_read_b128 v[218:221], v136 offset:23040
	ds_read_b128 v[224:227], v136 offset:27648
	ds_read_b128 v[228:231], v136 offset:32256
	ds_read_b128 v[210:213], v131 offset:4608
	s_waitcnt lgkmcnt(4)
	v_mfma_f32_32x32x16_bf16 v[114:129], v[202:205], v[214:217], v[114:129]
	ds_read_b128 v[206:209], v131 offset:32
	ds_read_b128 v[232:235], v136 offset:18464
	s_waitcnt lgkmcnt(5)
	v_mfma_f32_32x32x16_bf16 v[98:113], v[202:205], v[218:221], v[98:113]
	ds_read_b128 v[236:239], v136 offset:23072
	s_waitcnt lgkmcnt(5)
	v_mfma_f32_32x32x16_bf16 v[82:97], v[202:205], v[224:227], v[82:97]
	ds_read_b128 v[240:243], v136 offset:27680
	s_waitcnt lgkmcnt(5)
	v_mfma_f32_32x32x16_bf16 v[66:81], v[202:205], v[228:231], v[66:81]
	ds_read_b128 v[244:247], v136 offset:32288
	s_waitcnt lgkmcnt(5)
	v_mfma_f32_32x32x16_bf16 v[50:65], v[210:213], v[214:217], v[50:65]
	v_lshl_add_u64 v[150:151], v[148:149], 0, s[10:11]
	v_add_co_u32_e32 v150, vcc, 0x12c31000, v150
	s_nop 1
	v_addc_co_u32_e32 v151, vcc, 0, v151, vcc
	global_load_dwordx4 v[150:153], v[150:151], off offset:384
	v_mfma_f32_32x32x16_bf16 v[34:49], v[210:213], v[218:221], v[34:49]
	v_lshl_add_u64 v[154:155], v[148:149], 0, s[10:11]
	v_add_co_u32_e32 v154, vcc, 0x12c41000, v154
	s_nop 1
	v_addc_co_u32_e32 v155, vcc, 0, v155, vcc
	global_load_dwordx4 v[154:157], v[154:155], off offset:384
	v_mfma_f32_32x32x16_bf16 v[18:33], v[210:213], v[224:227], v[18:33]
	v_lshl_add_u64 v[158:159], v[148:149], 0, s[10:11]
	v_add_co_u32_e32 v158, vcc, 0x12c51000, v158
	s_nop 1
	v_addc_co_u32_e32 v159, vcc, 0, v159, vcc
	global_load_dwordx4 v[158:161], v[158:159], off offset:384
	v_mfma_f32_32x32x16_bf16 v[2:17], v[210:213], v[228:231], v[2:17]
	v_lshl_add_u64 v[162:163], v[148:149], 0, s[10:11]
	v_add_co_u32_e32 v162, vcc, 0x12c61000, v162
	s_nop 1
	v_addc_co_u32_e32 v163, vcc, 0, v163, vcc
	global_load_dwordx4 v[162:165], v[162:163], off offset:384
	ds_read_b128 v[210:213], v131 offset:4640
	s_waitcnt lgkmcnt(4)
	v_mfma_f32_32x32x16_bf16 v[114:129], v[206:209], v[232:235], v[114:129]
	ds_read_b128 v[202:205], v131 offset:64
	ds_read_b128 v[214:217], v136 offset:18496
	s_waitcnt lgkmcnt(5)
	v_mfma_f32_32x32x16_bf16 v[98:113], v[206:209], v[236:239], v[98:113]
	ds_read_b128 v[218:221], v136 offset:23104
	s_waitcnt lgkmcnt(5)
	v_mfma_f32_32x32x16_bf16 v[82:97], v[206:209], v[240:243], v[82:97]
	ds_read_b128 v[224:227], v136 offset:27712
	s_waitcnt lgkmcnt(5)
	v_mfma_f32_32x32x16_bf16 v[66:81], v[206:209], v[244:247], v[66:81]
	ds_read_b128 v[228:231], v136 offset:32320
	s_waitcnt lgkmcnt(5)
	v_mfma_f32_32x32x16_bf16 v[50:65], v[210:213], v[232:235], v[50:65]
	v_lshl_add_u64 v[166:167], v[132:133], 0, s[10:11]
	global_load_dwordx4 v[166:169], v[166:167], off offset:128
	v_mfma_f32_32x32x16_bf16 v[34:49], v[210:213], v[236:239], v[34:49]
	v_lshl_add_u64 v[170:171], v[132:133], 0, s[10:11]
	v_add_co_u32_e32 v170, vcc, s37, v170
	s_nop 1
	v_addc_co_u32_e32 v171, vcc, 0, v171, vcc
	global_load_dwordx4 v[170:173], v[170:171], off offset:128
	v_mfma_f32_32x32x16_bf16 v[18:33], v[210:213], v[240:243], v[18:33]
	v_lshl_add_u64 v[174:175], v[132:133], 0, s[10:11]
	v_add_co_u32_e32 v174, vcc, s38, v174
	s_nop 1
	v_addc_co_u32_e32 v175, vcc, 0, v175, vcc
	global_load_dwordx4 v[174:177], v[174:175], off offset:128
	v_mfma_f32_32x32x16_bf16 v[2:17], v[210:213], v[244:247], v[2:17]
	v_lshl_add_u64 v[178:179], v[132:133], 0, s[10:11]
	v_add_co_u32_e32 v178, vcc, s39, v178
	s_nop 1
	v_addc_co_u32_e32 v179, vcc, 0, v179, vcc
	global_load_dwordx4 v[178:181], v[178:179], off offset:128
	ds_read_b128 v[210:213], v131 offset:4672
	s_waitcnt lgkmcnt(4)
	v_mfma_f32_32x32x16_bf16 v[114:129], v[202:205], v[214:217], v[114:129]
	ds_read_b128 v[206:209], v131 offset:96
	ds_read_b128 v[232:235], v136 offset:18528
	s_waitcnt lgkmcnt(5)
	v_mfma_f32_32x32x16_bf16 v[98:113], v[202:205], v[218:221], v[98:113]
	ds_read_b128 v[236:239], v136 offset:23136
	s_waitcnt lgkmcnt(5)
	v_mfma_f32_32x32x16_bf16 v[82:97], v[202:205], v[224:227], v[82:97]
	ds_read_b128 v[240:243], v136 offset:27744
	s_waitcnt lgkmcnt(5)
	v_mfma_f32_32x32x16_bf16 v[66:81], v[202:205], v[228:231], v[66:81]
	ds_read_b128 v[244:247], v136 offset:32352
	s_waitcnt lgkmcnt(5)
	v_mfma_f32_32x32x16_bf16 v[50:65], v[210:213], v[214:217], v[50:65]
	v_lshl_add_u64 v[186:187], v[132:133], 0, s[10:11]
	v_add_co_u32_e32 v186, vcc, s40, v186
	s_nop 1
	v_addc_co_u32_e32 v187, vcc, 0, v187, vcc
	global_load_dwordx4 v[186:189], v[186:187], off offset:128
	v_mfma_f32_32x32x16_bf16 v[34:49], v[210:213], v[218:221], v[34:49]
	v_lshl_add_u64 v[190:191], v[132:133], 0, s[10:11]
	v_add_co_u32_e32 v190, vcc, s41, v190
	s_nop 1
	v_addc_co_u32_e32 v191, vcc, 0, v191, vcc
	global_load_dwordx4 v[190:193], v[190:191], off offset:128
	v_mfma_f32_32x32x16_bf16 v[18:33], v[210:213], v[224:227], v[18:33]
	v_lshl_add_u64 v[194:195], v[132:133], 0, s[10:11]
	v_add_co_u32_e32 v194, vcc, s42, v194
	s_nop 1
	v_addc_co_u32_e32 v195, vcc, 0, v195, vcc
	global_load_dwordx4 v[194:197], v[194:195], off offset:128
	v_mfma_f32_32x32x16_bf16 v[2:17], v[210:213], v[228:231], v[2:17]
	v_lshl_add_u64 v[198:199], v[132:133], 0, s[10:11]
	v_add_co_u32_e32 v198, vcc, s43, v198
	s_nop 1
	v_addc_co_u32_e32 v199, vcc, 0, v199, vcc
	global_load_dwordx4 v[198:201], v[198:199], off offset:128
	ds_read_b128 v[210:213], v131 offset:4704
	s_waitcnt lgkmcnt(4)
	v_mfma_f32_32x32x16_bf16 v[114:129], v[206:209], v[232:235], v[114:129]
	s_waitcnt lgkmcnt(3)
	v_mfma_f32_32x32x16_bf16 v[98:113], v[206:209], v[236:239], v[98:113]
	s_waitcnt lgkmcnt(2)
	v_mfma_f32_32x32x16_bf16 v[82:97], v[206:209], v[240:243], v[82:97]
	s_waitcnt lgkmcnt(1)
	v_mfma_f32_32x32x16_bf16 v[66:81], v[206:209], v[244:247], v[66:81]
	s_waitcnt lgkmcnt(0)
	v_mfma_f32_32x32x16_bf16 v[50:65], v[210:213], v[232:235], v[50:65]
	v_mfma_f32_32x32x16_bf16 v[34:49], v[210:213], v[236:239], v[34:49]
	v_mfma_f32_32x32x16_bf16 v[18:33], v[210:213], v[240:243], v[18:33]
	v_mfma_f32_32x32x16_bf16 v[2:17], v[210:213], v[244:247], v[2:17]
	s_setprio 0
	s_add_u32 s10, s10, 0x80
	s_addc_u32 s11, s11, 0
	s_barrier
; #define GW_LOAD(KOFF) GW_LOAD2(KOFF, 0)
;     ...
;   GW_LOAD(0)
;   GW_STORE()
;   __syncthreads();
;   const int nk = K >> 6;
;   const char* Ab = smem + (wm * 64 + (lane & 31)) * LSTR + (lane >> 5) * 16;
;   const char* Bb = smem + WTILE_A + (wn * 128 + (lane & 31)) * LSTR + (lane >> 5) * 16;
;   for (int kt = 0; kt < nk; ++kt) {
;     const int kn = (kt + 1 < nk) ? kt + 1 : kt;
;     GW_LOAD2(kn * 64, kn * bkstep)
;     __builtin_amdgcn_sched_barrier(0);
;     __builtin_amdgcn_s_setprio(1);
; #pragma unroll
;     for (int st = 0; st < 4; ++st) {
;       bf16x8 a0 = *(const bf16x8*)(Ab + st * 32);
;       bf16x8 a1 = *(const bf16x8*)(Ab + 32 * LSTR + st * 32);
;       bf16x8 b0 = *(const bf16x8*)(Bb + st * 32);
;       bf16x8 b1 = *(const bf16x8*)(Bb + 32 * LSTR + st * 32);
;       bf16x8 b2 = *(const bf16x8*)(Bb + 64 * LSTR + st * 32);
;       bf16x8 b3 = *(const bf16x8*)(Bb + 96 * LSTR + st * 32);
;       acc[0][0] = mfma32(a0, b0, acc[0][0]);
;       acc[0][1] = mfma32(a0, b1, acc[0][1]);
;       acc[0][2] = mfma32(a0, b2, acc[0][2]);
;       acc[0][3] = mfma32(a0, b3, acc[0][3]);
;       acc[1][0] = mfma32(a1, b0, acc[1][0]);
;       acc[1][1] = mfma32(a1, b1, acc[1][1]);
;       acc[1][2] = mfma32(a1, b2, acc[1][2]);
;       acc[1][3] = mfma32(a1, b3, acc[1][3]);
;     }
;     __builtin_amdgcn_s_setprio(0);
;     __builtin_amdgcn_sched_barrier(0);
;     __syncthreads();
;     GW_STORE()
;     __syncthreads();
; __device__ __forceinline__ void inproj_tile(const Params& P, int l, int mt, int ntw, char* smem) {
;     ...
;   float* cs = (float*)smem;
;   const int row0 = mt * 128;
;   const bool isctx = row0 >= NLAT;
;   const int b = isctx ? ((row0 - NLAT) >> 8) : (row0 >> 12);
;   const int pos0 = isctx ? ((row0 - NLAT) & 255) : (row0 & 4095);
;   const int tk0 = isctx ? (SEQ + pos0) : pos0;
	s_waitcnt vmcnt(11)
	ds_write_b128 v130, v[150:153]
	s_waitcnt vmcnt(10)
	ds_write_b128 v130, v[154:157] offset:4608
	s_waitcnt vmcnt(9)
	ds_write_b128 v130, v[158:161] offset:9216
	s_waitcnt vmcnt(8)
	ds_write_b128 v130, v[162:165] offset:13824
	s_waitcnt vmcnt(7)
	ds_write_b128 v130, v[166:169] offset:18432
	s_waitcnt vmcnt(6)
	ds_write_b128 v130, v[170:173] offset:23040
	s_waitcnt vmcnt(5)
	ds_write_b128 v130, v[174:177] offset:27648
	s_waitcnt vmcnt(4)
	ds_write_b128 v130, v[178:181] offset:32256
	s_waitcnt vmcnt(3)
	ds_write_b128 v130, v[186:189] offset:36864
	s_waitcnt vmcnt(2)
	ds_write_b128 v130, v[190:193] offset:41472
	s_waitcnt vmcnt(1)
	ds_write_b128 v130, v[194:197] offset:46080
	s_waitcnt vmcnt(0)
	ds_write_b128 v130, v[198:201] offset:50688
	s_waitcnt lgkmcnt(0)
	s_barrier
	v_add_co_u32_e32 v160, vcc, 0x10000, v132
	s_nop 0
	s_nop 0
	s_nop 0
	v_addc_co_u32_e32 v161, vcc, 0, v133, vcc
	v_add_co_u32_e32 v164, vcc, 0x20000, v132
	s_nop 0
	v_addc_co_u32_e32 v165, vcc, 0, v133, vcc
	v_add_co_u32_e32 v168, vcc, 0x30000, v132
	s_mov_b32 s52, 0
	s_nop 0
	v_addc_co_u32_e32 v169, vcc, 0, v133, vcc
	v_add_co_u32_e32 v172, vcc, 0x40000, v132
	s_nop 0
	v_addc_co_u32_e32 v173, vcc, 0, v133, vcc
	v_add_co_u32_e32 v176, vcc, 0x50000, v132
	s_nop 1
	v_addc_co_u32_e32 v177, vcc, 0, v133, vcc
	v_add_co_u32_e32 v180, vcc, 0x60000, v132
	s_nop 0
	v_addc_co_u32_e32 v181, vcc, 0, v133, vcc
	v_add_co_u32_e32 v132, vcc, 0x70000, v132
	s_nop 1
	v_addc_co_u32_e32 v133, vcc, 0, v133, vcc
	s_setprio 1
	ds_read_b128 v[194:197], v131 offset:0
	ds_read_b128 v[206:209], v136 offset:18432
	ds_read_b128 v[210:213], v136 offset:23040
	ds_read_b128 v[214:217], v136 offset:27648
	ds_read_b128 v[218:221], v136 offset:32256
	ds_read_b128 v[202:205], v131 offset:4608
	s_waitcnt lgkmcnt(4)
	v_mfma_f32_32x32x16_bf16 v[114:129], v[194:197], v[206:209], v[114:129]
	ds_read_b128 v[198:201], v131 offset:32
	ds_read_b128 v[224:227], v136 offset:18464
	s_waitcnt lgkmcnt(5)
	v_mfma_f32_32x32x16_bf16 v[98:113], v[194:197], v[210:213], v[98:113]
	ds_read_b128 v[228:231], v136 offset:23072
	s_waitcnt lgkmcnt(5)
	v_mfma_f32_32x32x16_bf16 v[82:97], v[194:197], v[214:217], v[82:97]
	ds_read_b128 v[232:235], v136 offset:27680
	s_waitcnt lgkmcnt(5)
	v_mfma_f32_32x32x16_bf16 v[66:81], v[194:197], v[218:221], v[66:81]
	ds_read_b128 v[236:239], v136 offset:32288
	s_waitcnt lgkmcnt(5)
	v_mfma_f32_32x32x16_bf16 v[50:65], v[202:205], v[206:209], v[50:65]
	v_mfma_f32_32x32x16_bf16 v[34:49], v[202:205], v[210:213], v[34:49]
	v_mfma_f32_32x32x16_bf16 v[18:33], v[202:205], v[214:217], v[18:33]
	v_mfma_f32_32x32x16_bf16 v[2:17], v[202:205], v[218:221], v[2:17]
	ds_read_b128 v[202:205], v131 offset:4640
	s_waitcnt lgkmcnt(4)
	v_mfma_f32_32x32x16_bf16 v[114:129], v[198:201], v[224:227], v[114:129]
	ds_read_b128 v[194:197], v131 offset:64
	ds_read_b128 v[206:209], v136 offset:18496
	s_waitcnt lgkmcnt(5)
	v_mfma_f32_32x32x16_bf16 v[98:113], v[198:201], v[228:231], v[98:113]
	ds_read_b128 v[210:213], v136 offset:23104
	s_waitcnt lgkmcnt(5)
	v_mfma_f32_32x32x16_bf16 v[82:97], v[198:201], v[232:235], v[82:97]
	ds_read_b128 v[214:217], v136 offset:27712
	s_waitcnt lgkmcnt(5)
	v_mfma_f32_32x32x16_bf16 v[66:81], v[198:201], v[236:239], v[66:81]
	ds_read_b128 v[218:221], v136 offset:32320
	s_waitcnt lgkmcnt(5)
	v_mfma_f32_32x32x16_bf16 v[50:65], v[202:205], v[224:227], v[50:65]
	v_mfma_f32_32x32x16_bf16 v[34:49], v[202:205], v[228:231], v[34:49]
	v_mfma_f32_32x32x16_bf16 v[18:33], v[202:205], v[232:235], v[18:33]
	v_mfma_f32_32x32x16_bf16 v[2:17], v[202:205], v[236:239], v[2:17]
	ds_read_b128 v[202:205], v131 offset:4672
	s_waitcnt lgkmcnt(4)
	v_mfma_f32_32x32x16_bf16 v[114:129], v[194:197], v[206:209], v[114:129]
	ds_read_b128 v[198:201], v131 offset:96
	ds_read_b128 v[224:227], v136 offset:18528
	s_waitcnt lgkmcnt(5)
	v_mfma_f32_32x32x16_bf16 v[98:113], v[194:197], v[210:213], v[98:113]
	ds_read_b128 v[228:231], v136 offset:23136
	s_waitcnt lgkmcnt(5)
	v_mfma_f32_32x32x16_bf16 v[82:97], v[194:197], v[214:217], v[82:97]
	ds_read_b128 v[232:235], v136 offset:27744
	s_waitcnt lgkmcnt(5)
	v_mfma_f32_32x32x16_bf16 v[66:81], v[194:197], v[218:221], v[66:81]
	ds_read_b128 v[236:239], v136 offset:32352
	s_waitcnt lgkmcnt(5)
	v_mfma_f32_32x32x16_bf16 v[50:65], v[202:205], v[206:209], v[50:65]
	v_mfma_f32_32x32x16_bf16 v[34:49], v[202:205], v[210:213], v[34:49]
	v_mfma_f32_32x32x16_bf16 v[18:33], v[202:205], v[214:217], v[18:33]
	v_mfma_f32_32x32x16_bf16 v[2:17], v[202:205], v[218:221], v[2:17]
	ds_read_b128 v[202:205], v131 offset:4704
	s_waitcnt lgkmcnt(4)
	v_mfma_f32_32x32x16_bf16 v[114:129], v[198:201], v[224:227], v[114:129]
	s_waitcnt lgkmcnt(3)
	v_mfma_f32_32x32x16_bf16 v[98:113], v[198:201], v[228:231], v[98:113]
	s_waitcnt lgkmcnt(2)
	v_mfma_f32_32x32x16_bf16 v[82:97], v[198:201], v[232:235], v[82:97]
	s_waitcnt lgkmcnt(1)
	v_mfma_f32_32x32x16_bf16 v[66:81], v[198:201], v[236:239], v[66:81]
	s_waitcnt lgkmcnt(0)
	v_mfma_f32_32x32x16_bf16 v[50:65], v[202:205], v[224:227], v[50:65]
	v_mfma_f32_32x32x16_bf16 v[34:49], v[202:205], v[228:231], v[34:49]
	v_mfma_f32_32x32x16_bf16 v[18:33], v[202:205], v[232:235], v[18:33]
	v_mfma_f32_32x32x16_bf16 v[2:17], v[202:205], v[236:239], v[2:17]
	s_setprio 0
	s_lshl_b32 s20, s12, 7
	s_cmpk_lt_i32 s12, 0x100
	s_cselect_b64 s[10:11], -1, 0
	s_add_i32 s8, s20, 0xffff8000
	s_and_b32 s51, s20, 0x80
	s_lshr_b32 s8, s8, 8
	s_ashr_i32 s22, s18, 2
	s_and_b32 s53, s20, 0xf80
	s_or_b32 s13, s51, 0x1000
	s_barrier
; __device__ __forceinline__ void inproj_tile(const Params& P, int l, int mt, int ntw, char* smem) {
;     ...
;   float* cs = (float*)smem;
;   const int row0 = mt * 128;
;   const bool isctx = row0 >= NLAT;
;   const int b = isctx ? ((row0 - NLAT) >> 8) : (row0 >> 12);
;   const int pos0 = isctx ? ((row0 - NLAT) & 255) : (row0 & 4095);
;   const int tk0 = isctx ? (SEQ + pos0) : pos0;
;   int tid_ = threadIdx.x;
;   asm volatile("" : "+v"(tid_));
;   const int lane = tid_ & 63, wave = tid_ >> 6;
;   const int r = 32 * wave + (lane & 31), half = lane >> 5;
;   const size_t grow = (size_t)row0 + r;
;   const float* crow = cs + r * CSTR + half * 64;
; #pragma unroll 1
;   for (int hsel = 0; hsel < 2; ++hsel) {
;     const int nt = ntw * 2 + hsel;
;     wide_acc_to_lds(acc, cs, hsel);
;     if (nt < 4) {
;       const int part = nt >> 1, cb = (nt & 1) * 128;
;       if (!isctx) {
;         u16* base = WSP(u16, OFF_FTT) + (size_t)b * 256 * 8192 + part * 4096 + pos0;
;         epi_transposed(cs, [&](int ch) { return base + (size_t)(cb + ch) * 8192; });
;       } else {
;         u16* base = WSP(u16, OFF_FTTC) + (size_t)b * 256 * 512 + part * 256 + pos0;
;         epi_transposed(cs, [&](int ch) { return base + (size_t)(cb + ch) * 512; });
;       }
;     } else if (nt < 7 || (nt >= 10 && nt < 13)) {
;       const bool isq = nt < 7;
;       const int head = (isq ? (nt - 4) : (nt - 10)) * 2 + half;
;       const float* g = (isq ? P.na_qn_g : P.na_kn_g) + l * 64;
;       float ss = 0.f;
; #pragma unroll
;       for (int q = 0; q < 16; ++q) {
;         float4 a = *(const float4*)(crow + q * 4);
;         ss += a.x * a.x + a.y * a.y + a.z * a.z + a.w * a.w;
;       }
;       const float rinv = rsqrtf(ss * (1.f / 64.f) + EPS) * (isq ? (0.125f * LOG2E) : 1.f);
;       u16* dst = WSP(u16, isq ? OFF_QN : OFF_KN) + grow * 384 + head * 64;
; #pragma unroll 1
;       for (int q = 0; q < 8; ++q) {
;         float4 a = *(const float4*)(crow + q * 8), c = *(const float4*)(crow + q * 8 + 4);
;         float4 ga = *(const float4*)(g + q * 8), gc = *(const float4*)(g + q * 8 + 4);
;         *(uint4*)(dst + q * 8) = pack8(a.x * rinv * ga.x, a.y * rinv * ga.y, a.z * rinv * ga.z, a.w * rinv * ga.w,
;                                        c.x * rinv * gc.x, c.y * rinv * gc.y, c.z * rinv * gc.z, c.w * rinv * gc.w);
;       }
;     } else if ((nt >= 7 && nt < 10) || (nt >= 16 && nt < 19)) {
	s_cmpk_gt_i32 s12, 0xff
	v_mov_b32_e32 v152, v134
	s_waitcnt lgkmcnt(0)
	s_cselect_b32 s54, s13, s53
	s_movk_i32 s13, 0xffe0
	v_ashrrev_i32_e32 v153, 1, v152
	v_bfi_b32 v130, s13, v153, v152
	s_cselect_b32 s12, s8, s22
	s_cselect_b32 s15, s51, s53
	s_ashr_i32 s21, s20, 31
	v_ashrrev_i32_e32 v131, 31, v130
	s_ashr_i32 s23, s22, 31
	v_lshl_add_u64 v[132:133], v[130:131], 0, s[20:21]
	s_lshl_b64 s[20:21], s[22:23], 22
	s_lshl_b32 s22, s14, 12
	s_movk_i32 s13, 0x210
	s_lshl_b32 s33, s14, 1
	s_ashr_i32 s23, s22, 31
	s_lshl_b64 s[24:25], s[8:9], 18
	v_mul_lo_u32 v136, v130, s13
	v_lshlrev_b32_e32 v139, 1, v152
	s_mul_i32 s13, s12, 6
	s_cmp_gt_u32 s33, 9
	v_and_b32_e32 v185, 64, v139
	s_mul_i32 s55, s12, 0x330000
	s_mul_hi_i32 s56, s13, 0x88000
	s_cselect_b64 s[12:13], -1, 0
	s_cmp_gt_u32 s33, 21
	v_lshl_add_u32 v186, v185, 2, v136
	v_add_u32_e32 v136, s15, v153
	s_cselect_b64 s[14:15], -1, 0
	s_cmp_lt_u32 s33, 16
	s_cselect_b64 s[26:27], -1, 0
	s_and_b64 s[26:27], s[26:27], exec
	s_mov_b32 s8, 0x1fffff3
	s_cselect_b32 s50, s8, 0x1ffffed
	s_mov_b32 s8, 0x32a31100
	s_cselect_b32 s8, s8, 0x343b1100
	v_mov_b64_e32 v[144:145], s[90:91]
	v_mad_u64_u32 v[144:145], s[26:27], v132, s44, v[144:145]
	s_add_u32 s8, s90, s8
	s_addc_u32 s26, s91, 0
	s_add_u32 s8, s8, s55
	s_addc_u32 s27, s26, s56
	s_lshl_b32 s26, s54, 1
	s_add_u32 s26, s8, s26
	s_addc_u32 s27, s27, 0
	v_mov_b32_e32 v139, v137
	s_add_u32 s8, s30, s20
	v_lshl_add_u64 v[146:147], s[26:27], 0, v[138:139]
	s_addc_u32 s26, s31, s21
	s_lshl_b64 s[20:21], s[22:23], 1
	s_add_u32 s8, s8, s20
	s_addc_u32 s21, s26, s21
	s_lshl_b32 s20, s53, 1
	s_add_u32 s20, s8, s20
	s_addc_u32 s21, s21, 0
	s_add_u32 s8, s34, s24
	v_lshl_add_u64 v[148:149], s[20:21], 0, v[138:139]
	s_addc_u32 s22, s35, s25
	s_lshl_b64 s[20:21], s[16:17], 1
	s_add_u32 s8, s8, s20
	s_addc_u32 s17, s22, s21
	s_lshl_b32 s20, s51, 1
	v_ashrrev_i32_e32 v136, 2, v136
	s_add_u32 s20, s8, s20
	v_and_b32_e32 v140, -16, v136
	v_lshlrev_b32_e32 v136, 4, v130
	s_addc_u32 s21, s17, 0
	s_lshl_b32 s8, s18, 10
	s_lshl_b32 s17, s19, 7
	v_and_b32_e32 v136, 0x3f0, v136
	s_or_b32 s18, s8, s17
	v_and_b32_e32 v154, 31, v152
	v_mov_b64_e32 v[142:143], v[136:137]
	v_lshrrev_b32_e32 v132, 5, v153
	v_bfe_u32 v136, v152, 5, 1
	s_ashr_i32 s19, s18, 31
	v_mad_i32_i24 v145, v133, s44, v145
	v_lshl_add_u64 v[150:151], s[20:21], 0, v[138:139]
	v_mul_lo_u32 v132, v132, s45
	v_mul_u32_u24_e32 v133, 0x210, v154
	v_lshlrev_b32_e32 v139, 8, v136
	v_lshl_add_u64 v[130:131], s[18:19], 0, v[130:131]
	v_add3_u32 v139, v132, v133, v139
	v_mad_u64_u32 v[132:133], s[18:19], v130, s46, 0
	v_mad_i32_i24 v133, v131, s46, v133
	v_lshl_or_b32 v132, v136, 7, v132
	v_lshl_add_u64 v[152:153], s[4:5], 0, v[132:133]
	v_mov_b64_e32 v[132:133], s[6:7]
	s_add_i32 s51, s16, 0xfffff500
	v_mad_u64_u32 v[154:155], s[16:17], v130, s44, v[132:133]
	v_ashrrev_i32_e32 v141, 31, v140
	v_mad_i32_i24 v155, v131, s44, v155
	s_mov_b64 s[16:17], -1
	s_branch .LBB0_241

; #define GM_LOAD(KOFF) GM_LOAD2(KOFF, 0)
;     ...
;   GM_LOAD(0)
;   GM_STORE(smem)
;   __syncthreads();
;   const int nk = K >> 6;
;   const int aoff = (wm * 64 + (lane & 31)) * LSTR + (lane >> 5) * 16;
;   const int boff = (wn * 64 + (lane & 31)) * LSTR + (lane >> 5) * 16;
;   for (int kt = 0; kt < nk; ++kt) {
;     const int kn = (kt + 1 < nk) ? kt + 1 : kt;
;     GM_LOAD2(kn * 64, kn * bkstep)
;     __builtin_amdgcn_sched_barrier(0);
;     const char* As = smem + (kt & 1) * 2 * TILE_B;
;     const char* Bs = As + TILE_B;
;     if constexpr (HOIST) {
;       bf16x8 fa0[4], fa1[4], fb0[4], fb1[4];
; #pragma unroll
;       for (int st = 0; st < 4; ++st) {
;         fa0[st] = *(const bf16x8*)(As + aoff + st * 32);
; __device__ __forceinline__ void fourier_half_tile(const Params& P, bool isctx, int b, int mt, int nt, char* smem) {
;     ...
;   for (int br = 0; br < 2; ++br) {
;     f32x16 acc[2][2];
;     zero_acc(acc);
;     const u16* A = Abase + br * N;
;     const u16* Bt = Bbase + br * N;
;     gemm_main<false>([&](int rr) { return A + (size_t)rr * ld; }, Bt, ld, N, smem, acc);
.LBB0_359:
	s_lshl_b32 s6, s6, s21
	s_xor_b64 s[12:13], s[12:13], -1
	s_lshl_b64 s[14:15], s[6:7], 1
	s_add_u32 s26, s22, s14
	s_addc_u32 s27, s23, s15
	v_lshl_add_u64 v[2:3], s[26:27], 0, v[132:133]
	v_lshl_add_u64 v[158:159], v[2:3], 0, v[142:143]
	v_lshl_add_u64 v[2:3], s[26:27], 0, v[152:153]
	v_lshl_add_u64 v[166:167], v[146:147], 0, s[14:15]
	v_lshl_add_u64 v[160:161], v[2:3], 0, v[142:143]
	v_lshl_add_u64 v[2:3], s[26:27], 0, v[154:155]
	v_lshl_add_u64 v[168:169], v[166:167], 0, s[10:11]
	v_lshl_add_u64 v[162:163], v[2:3], 0, v[142:143]
	v_lshl_add_u64 v[2:3], s[26:27], 0, v[156:157]
	v_lshl_add_u64 v[170:171], v[168:169], 0, s[10:11]
	v_lshl_add_u64 v[164:165], v[2:3], 0, v[142:143]
	global_load_dwordx4 v[34:37], v[166:167], off
	global_load_dwordx4 v[38:41], v[168:169], off
	v_lshl_add_u64 v[172:173], v[166:167], 0, s[8:9]
	global_load_dwordx4 v[42:45], v[170:171], off
	global_load_dwordx4 v[46:49], v[172:173], off
	global_load_dwordx4 v[174:177], v[158:159], off
	global_load_dwordx4 v[178:181], v[160:161], off
	global_load_dwordx4 v[182:185], v[162:163], off
	global_load_dwordx4 v[186:189], v[164:165], off
	v_mov_b32_e32 v2, 0
	s_mov_b32 s14, 0
	s_mov_b32 s15, s24
	s_add_i32 s15, s15, -1
	s_mov_b32 s6, 64
	v_mov_b32_e32 v3, v2
	v_mov_b32_e32 v4, v2
	v_mov_b32_e32 v5, v2
	v_mov_b32_e32 v6, v2
	v_mov_b32_e32 v7, v2
	v_mov_b32_e32 v8, v2
	v_mov_b32_e32 v9, v2
	v_mov_b32_e32 v10, v2
	v_mov_b32_e32 v11, v2
	v_mov_b32_e32 v12, v2
	v_mov_b32_e32 v13, v2
	v_mov_b32_e32 v14, v2
	v_mov_b32_e32 v15, v2
	v_mov_b32_e32 v16, v2
	v_mov_b32_e32 v17, v2
	v_mov_b32_e32 v18, v2
	v_mov_b32_e32 v19, v2
	v_mov_b32_e32 v20, v2
	v_mov_b32_e32 v21, v2
	v_mov_b32_e32 v22, v2
	v_mov_b32_e32 v23, v2
	v_mov_b32_e32 v24, v2
	v_mov_b32_e32 v25, v2
	v_mov_b32_e32 v26, v2
	v_mov_b32_e32 v27, v2
	v_mov_b32_e32 v28, v2
	v_mov_b32_e32 v29, v2
	v_mov_b32_e32 v30, v2
	v_mov_b32_e32 v31, v2
	v_mov_b32_e32 v32, v2
	v_mov_b32_e32 v33, v2
	v_mov_b32_e32 v50, v2
	v_mov_b32_e32 v51, v2
	v_mov_b32_e32 v52, v2
	v_mov_b32_e32 v53, v2
	v_mov_b32_e32 v54, v2
	v_mov_b32_e32 v55, v2
	v_mov_b32_e32 v56, v2
	v_mov_b32_e32 v57, v2
	v_mov_b32_e32 v58, v2
	v_mov_b32_e32 v59, v2
	v_mov_b32_e32 v60, v2
	v_mov_b32_e32 v61, v2
	v_mov_b32_e32 v62, v2
	v_mov_b32_e32 v63, v2
	v_mov_b32_e32 v64, v2
	v_mov_b32_e32 v65, v2
	s_waitcnt vmcnt(7)
	ds_write_b128 v190, v[34:37] offset:18432
	s_waitcnt vmcnt(6)
	ds_write_b128 v190, v[38:41] offset:23040
	s_waitcnt vmcnt(5)
	ds_write_b128 v190, v[42:45] offset:27648
	s_waitcnt vmcnt(4)
	ds_write_b128 v190, v[46:49] offset:32256
	s_waitcnt vmcnt(3)
	ds_write_b128 v190, v[174:177]
	s_waitcnt vmcnt(2)
	ds_write_b128 v190, v[178:181] offset:4608
	s_waitcnt vmcnt(1)
	ds_write_b128 v190, v[182:185] offset:9216
	s_waitcnt vmcnt(0)
	ds_write_b128 v190, v[186:189] offset:13824
	v_mov_b32_e32 v34, v2
	v_mov_b32_e32 v35, v2
	v_mov_b32_e32 v36, v2
	v_mov_b32_e32 v37, v2
	v_mov_b32_e32 v38, v2
	v_mov_b32_e32 v39, v2
	v_mov_b32_e32 v40, v2
	v_mov_b32_e32 v41, v2
	v_mov_b32_e32 v42, v2
	v_mov_b32_e32 v43, v2
	v_mov_b32_e32 v44, v2
	v_mov_b32_e32 v45, v2
	v_mov_b32_e32 v46, v2
	v_mov_b32_e32 v47, v2
	v_mov_b32_e32 v48, v2
	v_mov_b32_e32 v49, v2
	s_waitcnt lgkmcnt(0)
	s_lshl_b64 s[26:27], s[6:7], 1
	v_lshl_add_u64 v[174:175], v[158:159], 0, s[26:27]
	v_lshl_add_u64 v[178:179], v[162:163], 0, s[26:27]
	v_lshl_add_u64 v[182:183], v[166:167], 0, s[26:27]
	v_lshl_add_u64 v[186:187], v[170:171], 0, s[26:27]
	v_lshl_add_u64 v[176:177], v[160:161], 0, s[26:27]
	global_load_dwordx4 v[198:201], v[174:175], off
	global_load_dwordx4 v[202:205], v[176:177], off
	v_lshl_add_u64 v[180:181], v[164:165], 0, s[26:27]
	global_load_dwordx4 v[206:209], v[178:179], off
	global_load_dwordx4 v[210:213], v[180:181], off
	v_lshl_add_u64 v[184:185], v[168:169], 0, s[26:27]
	global_load_dwordx4 v[214:217], v[182:183], off
	global_load_dwordx4 v[218:221], v[184:185], off
	v_lshl_add_u64 v[188:189], v[172:173], 0, s[26:27]
	global_load_dwordx4 v[224:227], v[186:187], off
	global_load_dwordx4 v[228:231], v[188:189], off
.LBB0_360:
	s_barrier
	s_and_b32 s25, s14, 2
	s_mulk_i32 s25, 0x4800
	v_add3_u32 v197, s25, v191, v192
	v_add3_u32 v223, s25, v193, v192
	ds_read_b128 v[232:235], v197 offset:0
	ds_read_b128 v[236:239], v223 offset:18432
	ds_read_b128 v[244:247], v197 offset:4608
	ds_read_b128 v[240:243], v223 offset:23040
	s_waitcnt lgkmcnt(2)
	v_mfma_f32_32x32x16_bf16 v[50:65], v[232:235], v[236:239], v[50:65]
	ds_read_b128 v[248:251], v197 offset:32
	s_waitcnt lgkmcnt(2)
	v_mfma_f32_32x32x16_bf16 v[2:17], v[244:247], v[236:239], v[2:17]
	ds_read_b128 v[236:239], v223 offset:18464
	s_waitcnt lgkmcnt(2)
	v_mfma_f32_32x32x16_bf16 v[18:33], v[232:235], v[240:243], v[18:33]
	ds_read_b128 v[232:235], v197 offset:4640
	v_mfma_f32_32x32x16_bf16 v[34:49], v[244:247], v[240:243], v[34:49]
	ds_read_b128 v[240:243], v223 offset:23072
	s_waitcnt lgkmcnt(2)
	v_mfma_f32_32x32x16_bf16 v[50:65], v[248:251], v[236:239], v[50:65]
	ds_read_b128 v[244:247], v197 offset:64
	s_waitcnt lgkmcnt(2)
	v_mfma_f32_32x32x16_bf16 v[2:17], v[232:235], v[236:239], v[2:17]
	ds_read_b128 v[236:239], v223 offset:18496
	s_waitcnt lgkmcnt(2)
	v_mfma_f32_32x32x16_bf16 v[18:33], v[248:251], v[240:243], v[18:33]
	ds_read_b128 v[248:251], v197 offset:4672
	v_mfma_f32_32x32x16_bf16 v[34:49], v[232:235], v[240:243], v[34:49]
	ds_read_b128 v[240:243], v223 offset:23104
	s_waitcnt lgkmcnt(2)
	v_mfma_f32_32x32x16_bf16 v[50:65], v[244:247], v[236:239], v[50:65]
	ds_read_b128 v[232:235], v197 offset:96
	s_waitcnt lgkmcnt(2)
	v_mfma_f32_32x32x16_bf16 v[2:17], v[248:251], v[236:239], v[2:17]
	ds_read_b128 v[236:239], v223 offset:18528
	s_waitcnt lgkmcnt(2)
;     ...
;   for (int kt = 0; kt < nk; ++kt) {
;     const int kn = (kt + 1 < nk) ? kt + 1 : kt;
;     GM_LOAD2(kn * 64, kn * bkstep)
;     __builtin_amdgcn_sched_barrier(0);
;     const char* As = smem + (kt & 1) * 2 * TILE_B;
;     const char* Bs = As + TILE_B;
;     if constexpr (HOIST) {
;       bf16x8 fa0[4], fa1[4], fb0[4], fb1[4];
; #pragma unroll
;       for (int st = 0; st < 4; ++st) {
;         fa0[st] = *(const bf16x8*)(As + aoff + st * 32);
;         fb0[st] = *(const bf16x8*)(Bs + boff + st * 32);
;         fa1[st] = *(const bf16x8*)(As + aoff + 32 * LSTR + st * 32);
;         fb1[st] = *(const bf16x8*)(Bs + boff + 32 * LSTR + st * 32);
;       }
;       __builtin_amdgcn_sched_barrier(0);
; #pragma unroll
;       for (int st = 0; st < 4; ++st) {
;         acc[0][0] = mfma32(fa0[st], fb0[st], acc[0][0]);
;         acc[0][1] = mfma32(fa0[st], fb1[st], acc[0][1]);
;         acc[1][0] = mfma32(fa1[st], fb0[st], acc[1][0]);
;         acc[1][1] = mfma32(fa1[st], fb1[st], acc[1][1]);
;       }
;     } else {
; #pragma unroll
;       for (int st = 0; st < 4; ++st) {
;         bf16x8 a0 = *(const bf16x8*)(As + aoff + st * 32);
;         bf16x8 a1 = *(const bf16x8*)(As + aoff + 32 * LSTR + st * 32);
;         bf16x8 b0 = *(const bf16x8*)(Bs + boff + st * 32);
;         bf16x8 b1 = *(const bf16x8*)(Bs + boff + 32 * LSTR + st * 32);
;         acc[0][0] = mfma32(a0, b0, acc[0][0]);
;         acc[0][1] = mfma32(a0, b1, acc[0][1]);
;         acc[1][0] = mfma32(a1, b0, acc[1][0]);
;         acc[1][1] = mfma32(a1, b1, acc[1][1]);
;       }
;     }
;     __builtin_amdgcn_sched_barrier(0);
;     {
;       char* Ad = smem + ((kt + 1) & 1) * 2 * TILE_B;
;       GM_STORE(Ad)
;     }
;     __syncthreads();
	v_mfma_f32_32x32x16_bf16 v[18:33], v[244:247], v[240:243], v[18:33]
	ds_read_b128 v[244:247], v197 offset:4704
	v_mfma_f32_32x32x16_bf16 v[34:49], v[248:251], v[240:243], v[34:49]
	ds_read_b128 v[240:243], v223 offset:23136
	s_waitcnt lgkmcnt(2)
	v_mfma_f32_32x32x16_bf16 v[50:65], v[232:235], v[236:239], v[50:65]
	s_waitcnt lgkmcnt(1)
	v_mfma_f32_32x32x16_bf16 v[2:17], v[244:247], v[236:239], v[2:17]
	s_waitcnt lgkmcnt(0)
	v_mfma_f32_32x32x16_bf16 v[18:33], v[232:235], v[240:243], v[18:33]
	v_mfma_f32_32x32x16_bf16 v[34:49], v[244:247], v[240:243], v[34:49]
	s_add_i32 s14, s14, 2
	s_and_b32 s25, s14, 2
	s_mulk_i32 s25, 0x4800
	s_add_i32 s15, s15, -1
	s_add_i32 s6, s6, 64
	v_add_u32_e32 v197, s25, v190
	s_lshl_b64 s[26:27], s[6:7], 1
	s_cmp_lg_u32 s15, 0
	s_waitcnt vmcnt(7)
	ds_write_b128 v197, v[198:201]
	v_lshl_add_u64 v[198:199], v[158:159], 0, s[26:27]
	global_load_dwordx4 v[198:201], v[198:199], off
	s_waitcnt vmcnt(7)
	ds_write_b128 v197, v[202:205] offset:4608
	v_lshl_add_u64 v[202:203], v[160:161], 0, s[26:27]
	global_load_dwordx4 v[202:205], v[202:203], off
	s_waitcnt vmcnt(7)
	ds_write_b128 v197, v[206:209] offset:9216
	v_lshl_add_u64 v[206:207], v[162:163], 0, s[26:27]
	global_load_dwordx4 v[206:209], v[206:207], off
	s_waitcnt vmcnt(7)
	ds_write_b128 v197, v[210:213] offset:13824
	v_lshl_add_u64 v[210:211], v[164:165], 0, s[26:27]
	global_load_dwordx4 v[210:213], v[210:211], off
	s_waitcnt vmcnt(7)
	ds_write_b128 v197, v[214:217] offset:18432
	v_lshl_add_u64 v[214:215], v[166:167], 0, s[26:27]
	global_load_dwordx4 v[214:217], v[214:215], off
	s_waitcnt vmcnt(7)
	ds_write_b128 v197, v[218:221] offset:23040
	v_lshl_add_u64 v[218:219], v[168:169], 0, s[26:27]
	global_load_dwordx4 v[218:221], v[218:219], off
	s_waitcnt vmcnt(7)
	ds_write_b128 v197, v[224:227] offset:27648
	v_lshl_add_u64 v[224:225], v[170:171], 0, s[26:27]
	global_load_dwordx4 v[224:227], v[224:225], off
	s_waitcnt vmcnt(7)
	ds_write_b128 v197, v[228:231] offset:32256
	v_lshl_add_u64 v[228:229], v[172:173], 0, s[26:27]
	global_load_dwordx4 v[228:231], v[228:229], off
	s_waitcnt lgkmcnt(0)
	s_cbranch_scc1 .LBB0_360
	s_barrier
	s_and_b32 s25, s14, 2
	s_mulk_i32 s25, 0x4800
	v_add3_u32 v197, s25, v191, v192
	v_add3_u32 v223, s25, v193, v192
	ds_read_b128 v[232:235], v197 offset:0
	ds_read_b128 v[236:239], v223 offset:18432
	ds_read_b128 v[244:247], v197 offset:4608
	ds_read_b128 v[240:243], v223 offset:23040
	s_waitcnt lgkmcnt(2)
	v_mfma_f32_32x32x16_bf16 v[50:65], v[232:235], v[236:239], v[50:65]
	ds_read_b128 v[248:251], v197 offset:32
	s_waitcnt lgkmcnt(2)
	v_mfma_f32_32x32x16_bf16 v[2:17], v[244:247], v[236:239], v[2:17]
	ds_read_b128 v[236:239], v223 offset:18464
	s_waitcnt lgkmcnt(2)
	v_mfma_f32_32x32x16_bf16 v[18:33], v[232:235], v[240:243], v[18:33]
	ds_read_b128 v[232:235], v197 offset:4640
	v_mfma_f32_32x32x16_bf16 v[34:49], v[244:247], v[240:243], v[34:49]
	ds_read_b128 v[240:243], v223 offset:23072
	s_waitcnt lgkmcnt(2)
	v_mfma_f32_32x32x16_bf16 v[50:65], v[248:251], v[236:239], v[50:65]
	ds_read_b128 v[244:247], v197 offset:64
	s_waitcnt lgkmcnt(2)
	v_mfma_f32_32x32x16_bf16 v[2:17], v[232:235], v[236:239], v[2:17]
	ds_read_b128 v[236:239], v223 offset:18496
	s_waitcnt lgkmcnt(2)
	v_mfma_f32_32x32x16_bf16 v[18:33], v[248:251], v[240:243], v[18:33]
	ds_read_b128 v[248:251], v197 offset:4672
	v_mfma_f32_32x32x16_bf16 v[34:49], v[232:235], v[240:243], v[34:49]
	ds_read_b128 v[240:243], v223 offset:23104
	s_waitcnt lgkmcnt(2)
	v_mfma_f32_32x32x16_bf16 v[50:65], v[244:247], v[236:239], v[50:65]
	ds_read_b128 v[232:235], v197 offset:96
	s_waitcnt lgkmcnt(2)
	v_mfma_f32_32x32x16_bf16 v[2:17], v[248:251], v[236:239], v[2:17]
	ds_read_b128 v[236:239], v223 offset:18528
	s_waitcnt lgkmcnt(2)
	v_mfma_f32_32x32x16_bf16 v[18:33], v[244:247], v[240:243], v[18:33]
	ds_read_b128 v[244:247], v197 offset:4704
	v_mfma_f32_32x32x16_bf16 v[34:49], v[248:251], v[240:243], v[34:49]
	ds_read_b128 v[240:243], v223 offset:23136
	s_waitcnt lgkmcnt(2)
	v_mfma_f32_32x32x16_bf16 v[50:65], v[232:235], v[236:239], v[50:65]
	s_waitcnt lgkmcnt(1)
	v_mfma_f32_32x32x16_bf16 v[2:17], v[244:247], v[236:239], v[2:17]
	s_waitcnt lgkmcnt(0)
	v_mfma_f32_32x32x16_bf16 v[18:33], v[232:235], v[240:243], v[18:33]
	v_mfma_f32_32x32x16_bf16 v[34:49], v[244:247], v[240:243], v[34:49]
	s_add_i32 s14, s14, 2
	s_and_b32 s25, s14, 2
	s_mulk_i32 s25, 0x4800
	s_add_i32 s6, s6, 64
	v_add_u32_e32 v197, s25, v190
	s_waitcnt vmcnt(7)
	ds_write_b128 v197, v[198:201]
	s_waitcnt vmcnt(6)
	ds_write_b128 v197, v[202:205] offset:4608
	s_waitcnt vmcnt(5)
	ds_write_b128 v197, v[206:209] offset:9216
	s_waitcnt vmcnt(4)
	ds_write_b128 v197, v[210:213] offset:13824
	s_waitcnt vmcnt(3)
	ds_write_b128 v197, v[214:217] offset:18432
	s_waitcnt vmcnt(2)
	ds_write_b128 v197, v[218:221] offset:23040
	s_waitcnt vmcnt(1)
	ds_write_b128 v197, v[224:227] offset:27648
	s_waitcnt vmcnt(0)
	ds_write_b128 v197, v[228:231] offset:32256
	s_waitcnt lgkmcnt(0)
	s_barrier
; __device__ __forceinline__ void acc_to_lds(const f32x16 (&acc)[2][2], float* cs) {
;   const int tid = threadIdx.x, lane = tid & 63, wave = tid >> 6;
;   const int wm = wave >> 1, wn = wave & 1;
; #pragma unroll
;   for (int i = 0; i < 2; ++i)
; #pragma unroll
;     for (int j = 0; j < 2; ++j)
; #pragma unroll
;       for (int r = 0; r < 16; ++r) {
;         int row = wm * 64 + i * 32 + (r & 3) + 8 * (r >> 2) + 4 * (lane >> 5);
;         int col = wn * 64 + j * 32 + (lane & 31);
;         cs[row * CSTR + col] = acc[i][j][r];
;       }
;   __syncthreads();
; __device__ __forceinline__ void fourier_half_tile(const Params& P, bool isctx, int b, int mt, int nt, char* smem) {
;     ...
;       u16* d1 = WSP(u16, OFF_FTO) + (rowbase + k) * 256 + nt * 128 + half * 64;
;       u16* d2 = WSP(u16, OFF_FTO) + (rowbase + (k > 0 ? N - k : 0)) * 256 + nt * 128 + half * 64;
; #pragma unroll
;       for (int q = 0; q < 8; ++q) {
;         float4 a = *(const float4*)(cs + r * CSTR + half * 64 + q * 8);
;         float4 c = *(const float4*)(cs + r * CSTR + half * 64 + q * 8 + 4);
;         uint4 o1, o2;
;         o1.x = pack2(pacc[q * 8 + 0] + a.x, pacc[q * 8 + 1] + a.y); o1.y = pack2(pacc[q * 8 + 2] + a.z, pacc[q * 8 + 3] + a.w);
;         o1.z = pack2(pacc[q * 8 + 4] + c.x, pacc[q * 8 + 5] + c.y); o1.w = pack2(pacc[q * 8 + 6] + c.z, pacc[q * 8 + 7] + c.w);
;         o2.x = pack2(pacc[q * 8 + 0] - a.x, pacc[q * 8 + 1] - a.y); o2.y = pack2(pacc[q * 8 + 2] - a.z, pacc[q * 8 + 3] - a.w);
;         o2.z = pack2(pacc[q * 8 + 4] - c.x, pacc[q * 8 + 5] - c.y); o2.w = pack2(pacc[q * 8 + 6] - c.z, pacc[q * 8 + 7] - c.w);
;         *(uint4*)(d1 + q * 8) = o1;
;         if (k > 0) *(uint4*)(d2 + q * 8) = o2;
	s_nop 0
	s_nop 0
	s_nop 0
	v_add3_u32 v197, s25, v191, v192
	v_add3_u32 v223, s25, v193, v192
	ds_read_b128 v[198:201], v197 offset:0
	ds_read_b128 v[202:205], v223 offset:18432
	ds_read_b128 v[210:213], v197 offset:4608
	ds_read_b128 v[206:209], v223 offset:23040
	s_waitcnt lgkmcnt(2)
	v_mfma_f32_32x32x16_bf16 v[50:65], v[198:201], v[202:205], v[50:65]
	ds_read_b128 v[214:217], v197 offset:32
	s_waitcnt lgkmcnt(2)
	v_mfma_f32_32x32x16_bf16 v[2:17], v[210:213], v[202:205], v[2:17]
	ds_read_b128 v[202:205], v223 offset:18464
	s_waitcnt lgkmcnt(2)
	v_mfma_f32_32x32x16_bf16 v[18:33], v[198:201], v[206:209], v[18:33]
	ds_read_b128 v[198:201], v197 offset:4640
	v_mfma_f32_32x32x16_bf16 v[34:49], v[210:213], v[206:209], v[34:49]
	ds_read_b128 v[206:209], v223 offset:23072
	s_waitcnt lgkmcnt(2)
	v_mfma_f32_32x32x16_bf16 v[50:65], v[214:217], v[202:205], v[50:65]
	ds_read_b128 v[210:213], v197 offset:64
	s_waitcnt lgkmcnt(2)
	v_mfma_f32_32x32x16_bf16 v[2:17], v[198:201], v[202:205], v[2:17]
	ds_read_b128 v[202:205], v223 offset:18496
	s_waitcnt lgkmcnt(2)
	v_mfma_f32_32x32x16_bf16 v[18:33], v[214:217], v[206:209], v[18:33]
	ds_read_b128 v[214:217], v197 offset:4672
	v_mfma_f32_32x32x16_bf16 v[34:49], v[198:201], v[206:209], v[34:49]
	ds_read_b128 v[206:209], v223 offset:23104
	s_waitcnt lgkmcnt(2)
	v_mfma_f32_32x32x16_bf16 v[50:65], v[210:213], v[202:205], v[50:65]
	ds_read_b128 v[198:201], v197 offset:96
	s_waitcnt lgkmcnt(2)
	v_mfma_f32_32x32x16_bf16 v[2:17], v[214:217], v[202:205], v[2:17]
	ds_read_b128 v[202:205], v223 offset:18528
	s_waitcnt lgkmcnt(2)
	v_mfma_f32_32x32x16_bf16 v[18:33], v[210:213], v[206:209], v[18:33]
	ds_read_b128 v[210:213], v197 offset:4704
	v_mfma_f32_32x32x16_bf16 v[34:49], v[214:217], v[206:209], v[34:49]
	ds_read_b128 v[206:209], v223 offset:23136
	s_waitcnt lgkmcnt(2)
	v_mfma_f32_32x32x16_bf16 v[50:65], v[198:201], v[202:205], v[50:65]
	s_waitcnt lgkmcnt(1)
	v_mfma_f32_32x32x16_bf16 v[2:17], v[210:213], v[202:205], v[2:17]
	s_waitcnt lgkmcnt(0)
	v_mfma_f32_32x32x16_bf16 v[18:33], v[198:201], v[206:209], v[18:33]
	v_mfma_f32_32x32x16_bf16 v[34:49], v[210:213], v[206:209], v[34:49]
	s_waitcnt lgkmcnt(0)
	s_barrier
	ds_write2_b32 v194, v50, v18 offset1:32
	ds_write2_b32 v194, v51, v19 offset0:132 offset1:164
	v_add_u32_e32 v18, 0x400, v194
	ds_write2_b32 v18, v52, v20 offset0:8 offset1:40
	ds_write2_b32 v18, v53, v21 offset0:140 offset1:172
	v_add_u32_e32 v18, 0x1000, v194
	ds_write2_b32 v18, v54, v22 offset0:32 offset1:64
	ds_write2_b32 v18, v55, v23 offset0:164 offset1:196
	v_add_u32_e32 v18, 0x1400, v194
	ds_write2_b32 v18, v56, v24 offset0:40 offset1:72
	ds_write2_b32 v18, v57, v25 offset0:172 offset1:204
	v_add_u32_e32 v18, 0x2000, v194
	ds_write2_b32 v18, v58, v26 offset0:64 offset1:96
	ds_write2_b32 v18, v59, v27 offset0:196 offset1:228
	v_add_u32_e32 v18, 0x2400, v194
	ds_write2_b32 v18, v60, v28 offset0:72 offset1:104
	ds_write2_b32 v18, v61, v29 offset0:204 offset1:236
	v_add_u32_e32 v18, 0x3000, v194
	ds_write2_b32 v18, v62, v30 offset0:96 offset1:128
	v_add_u32_e32 v18, 0x3200, v194
	ds_write2_b32 v18, v63, v31 offset0:100 offset1:132
	v_add_u32_e32 v18, 0x3400, v194
	ds_write2_b32 v18, v64, v32 offset0:104 offset1:136
	v_add_u32_e32 v18, 0x3600, v194
	ds_write2_b32 v18, v65, v33 offset0:108 offset1:140
	v_add_u32_e32 v18, 0x4000, v194
	ds_write2_b32 v18, v2, v34 offset0:128 offset1:160
	v_add_u32_e32 v2, 0x4400, v194
	ds_write2_b32 v2, v3, v35 offset0:4 offset1:36
	ds_write2_b32 v2, v4, v36 offset0:136 offset1:168
	v_add_u32_e32 v2, 0x4800, v194
	ds_write2_b32 v2, v5, v37 offset0:12 offset1:44
	v_add_u32_e32 v2, 0x5000, v194
	ds_write2_b32 v2, v6, v38 offset0:160 offset1:192
	v_add_u32_e32 v2, 0x5400, v194
	ds_write2_b32 v2, v7, v39 offset0:36 offset1:68
	ds_write2_b32 v2, v8, v40 offset0:168 offset1:200
	v_add_u32_e32 v2, 0x5800, v194
	ds_write2_b32 v2, v9, v41 offset0:44 offset1:76
	v_add_u32_e32 v2, 0x6000, v194
	ds_write2_b32 v2, v10, v42 offset0:192 offset1:224
	v_add_u32_e32 v2, 0x6400, v194
	ds_write2_b32 v2, v11, v43 offset0:68 offset1:100
	ds_write2_b32 v2, v12, v44 offset0:200 offset1:232
	v_add_u32_e32 v2, 0x6800, v194
	ds_write2_b32 v2, v13, v45 offset0:76 offset1:108
	v_add_u32_e32 v2, 0x7200, v194
	ds_write2_b32 v2, v14, v46 offset0:96 offset1:128
	v_add_u32_e32 v2, 0x7400, v194
	ds_write2_b32 v2, v15, v47 offset0:100 offset1:132
	v_add_u32_e32 v2, 0x7600, v194
	ds_write2_b32 v2, v16, v48 offset0:104 offset1:136
	v_add_u32_e32 v2, 0x7800, v194
	s_mov_b64 s[14:15], -1
	s_and_b64 vcc, exec, s[12:13]
	ds_write2_b32 v2, v17, v49 offset0:108 offset1:140
	s_waitcnt lgkmcnt(0)
	s_barrier
	s_cbranch_vccz .LBB0_379
	ds_read_b128 v[2:5], v195
	ds_read_b128 v[6:9], v195 offset:16
	s_waitcnt lgkmcnt(1)
	v_add_f32_e32 v10, v78, v2
	v_add_f32_e32 v11, v79, v3
	v_sub_f32_e32 v2, v78, v2
	v_sub_f32_e32 v3, v79, v3
	v_add_f32_e32 v12, v80, v4
	v_add_f32_e32 v13, v81, v5
	v_cvt_pk_bf16_f32 v2, v2, v3
	v_sub_f32_e32 v3, v80, v4
	v_sub_f32_e32 v4, v81, v5
	v_cvt_pk_bf16_f32 v10, v10, v11
	v_cvt_pk_bf16_f32 v11, v12, v13
	s_waitcnt lgkmcnt(0)
	v_add_f32_e32 v12, v74, v6
	v_add_f32_e32 v13, v75, v7
	v_cvt_pk_bf16_f32 v3, v3, v4
	v_sub_f32_e32 v4, v74, v6
	v_sub_f32_e32 v5, v75, v7
	v_cvt_pk_bf16_f32 v12, v12, v13
	v_add_f32_e32 v13, v76, v8
	v_cvt_pk_bf16_f32 v4, v4, v5
	v_sub_f32_e32 v5, v76, v8
	v_add_f32_e32 v14, v77, v9
	v_cvt_pk_bf16_f32 v13, v13, v14
	v_sub_f32_e32 v6, v77, v9
	v_cvt_pk_bf16_f32 v5, v5, v6
	global_store_dwordx4 v[148:149], v[10:13], off
	s_and_saveexec_b64 s[14:15], s[2:3]
	s_cbranch_execz .LBB0_364
	global_store_dwordx4 v[150:151], v[2:5], off

; #define GM_LOAD(KOFF) GM_LOAD2(KOFF, 0)
;     ...
;   GM_LOAD(0)
;   GM_STORE(smem)
;   __syncthreads();
;   const int nk = K >> 6;
;   const int aoff = (wm * 64 + (lane & 31)) * LSTR + (lane >> 5) * 16;
;   const int boff = (wn * 64 + (lane & 31)) * LSTR + (lane >> 5) * 16;
;   for (int kt = 0; kt < nk; ++kt) {
;     const int kn = (kt + 1 < nk) ? kt + 1 : kt;
;     GM_LOAD2(kn * 64, kn * bkstep)
; __device__ __forceinline__ void merge_tile(const Params& P, int l, int mt, int nt, char* smem) {
;     ...
;   for (int br = 0; br < 3; ++br) {
;     f32x16 acc[2][2];
;     zero_acc(acc);
;     const int K = (br == 0) ? 256 : 384;
;     const u16* A = WSP(u16, br == 0 ? OFF_FTO : (br == 1 ? OFF_ONA : OFF_ODF)) + (size_t)mt * 128 * K;
;     const u16* Bt = WSP(u16, br == 0 ? OFF_WFT : (br == 1 ? OFF_WNA : OFF_WDF)) + ((size_t)l * DM + nt * 128) * K;
;     gemm_main<false>([&](int rr) { return A + (size_t)rr * K; }, Bt, K, K, smem, acc);
.LBB0_631:
	s_cmp_eq_u32 s36, 1
	s_cselect_b32 s6, s19, 0x1cdb1100
	s_cselect_b32 s37, s20, 0x1980000
	s_cmp_eq_u32 s36, 0
	s_cselect_b32 s42, s21, 0x180
	s_cselect_b32 s43, 0x1e731100, s6
	s_mul_hi_u32 s6, s10, s42
	s_mul_i32 s38, s11, s42
	s_cselect_b32 s37, 0x1700000, s37
	s_add_u32 s40, s90, s43
	s_addc_u32 s41, s91, 0
	s_add_i32 s39, s6, s38
	s_mul_i32 s38, s10, s42
	s_lshl_b64 s[38:39], s[38:39], 1
	s_add_u32 s38, s40, s38
	s_addc_u32 s39, s41, s39
	s_add_u32 s6, s90, s37
	s_mul_hi_i32 s41, s42, s12
	s_mul_i32 s40, s42, s12
	s_addc_u32 s44, s91, 0
	s_lshl_b64 s[40:41], s[40:41], 1
	v_mul_u32_u24_e32 v2, s42, v1
	s_add_u32 s40, s6, s40
	v_lshlrev_b32_e32 v68, 1, v2
	s_addc_u32 s41, s44, s41
	v_lshl_add_u64 v[2:3], s[38:39], 0, v[68:69]
	s_lshl_b32 s6, s42, 6
	v_lshl_add_u64 v[4:5], v[2:3], 0, v[72:73]
	v_lshl_add_u64 v[2:3], v[2:3], 0, s[6:7]
	v_lshl_add_u64 v[6:7], v[2:3], 0, v[72:73]
	v_lshl_add_u64 v[2:3], v[2:3], 0, s[6:7]
	v_lshl_add_u64 v[10:11], v[2:3], 0, v[72:73]
	v_lshl_add_u64 v[2:3], v[2:3], 0, s[6:7]
	v_lshl_add_u64 v[14:15], v[2:3], 0, v[72:73]
	v_lshl_add_u64 v[2:3], s[40:41], 0, v[68:69]
	v_lshl_add_u64 v[18:19], v[2:3], 0, v[72:73]
	v_lshl_add_u64 v[26:27], v[18:19], 0, s[6:7]
	global_load_dwordx4 v[2:5], v[4:5], off
	s_nop 0
	global_load_dwordx4 v[6:9], v[6:7], off
	s_nop 0
	global_load_dwordx4 v[10:13], v[10:11], off
	s_nop 0
	global_load_dwordx4 v[14:17], v[14:15], off
	s_nop 0
	global_load_dwordx4 v[18:21], v[18:19], off
	s_nop 0
	global_load_dwordx4 v[22:25], v[26:27], off
	v_lshl_add_u64 v[26:27], v[26:27], 0, s[6:7]
	v_lshl_add_u64 v[30:31], v[26:27], 0, s[6:7]
	global_load_dwordx4 v[26:29], v[26:27], off
	s_nop 0
	global_load_dwordx4 v[30:33], v[30:31], off
	s_mul_i32 s6, s17, s42
	s_mul_hi_u32 s38, s16, s42
	s_lshr_b32 s56, s42, 6
	s_mul_i32 s39, s16, s42
	s_add_i32 s57, s38, s6
	s_add_i32 s6, s56, -2
	s_mul_i32 s40, s24, s42
	s_mul_hi_u32 s41, s23, s42
	s_add_u32 s38, s43, s39
	s_mul_i32 s44, s23, s42
	s_addc_u32 s39, 0, s57
	s_add_i32 s41, s41, s40
	s_mul_i32 s45, s26, s42
	s_mul_hi_u32 s46, s25, s42
	v_lshl_add_u64 v[146:147], v[70:71], 0, s[38:39]
	s_add_u32 s38, s43, s44
	s_mul_i32 s47, s25, s42
	s_addc_u32 s39, 0, s41
	s_add_i32 s46, s46, s45
	s_mul_i32 s48, s28, s42
	s_mul_hi_u32 s49, s27, s42
	v_lshl_add_u64 v[148:149], v[70:71], 0, s[38:39]
	s_add_u32 s38, s43, s47
	s_mul_i32 s50, s27, s42
	s_addc_u32 s39, 0, s46
	s_add_i32 s49, s49, s48
	s_mul_i32 s51, s15, s42
	s_mul_hi_u32 s52, s14, s42
	v_lshl_add_u64 v[150:151], v[70:71], 0, s[38:39]
	s_add_u32 s38, s43, s50
	s_mul_i32 s53, s14, s42
	s_addc_u32 s39, 0, s49
	s_add_i32 s52, s52, s51
	v_lshl_add_u64 v[152:153], v[70:71], 0, s[38:39]
	s_add_u32 s38, s37, s53
	s_mul_i32 s54, s30, s42
	s_mul_hi_u32 s55, s29, s42
	s_addc_u32 s39, 0, s52
	s_add_i32 s55, s55, s54
	v_lshl_add_u64 v[154:155], v[70:71], 0, s[38:39]
	s_mul_i32 s38, s29, s42
	s_add_u32 s38, s37, s38
	s_addc_u32 s39, 0, s55
	v_lshl_add_u64 v[156:157], v[70:71], 0, s[38:39]
	s_mul_i32 s38, s33, s42
	s_mul_hi_u32 s39, s31, s42
	s_add_i32 s39, s39, s38
	s_mul_i32 s38, s31, s42
	s_add_u32 s38, s37, s38
	s_addc_u32 s39, 0, s39
	v_lshl_add_u64 v[158:159], v[70:71], 0, s[38:39]
	s_mul_i32 s38, s35, s42
	s_mul_hi_u32 s39, s34, s42
	s_add_i32 s39, s39, s38
	s_mul_i32 s38, s34, s42
	s_add_u32 s38, s37, s38
	s_addc_u32 s39, 0, s39
	v_lshl_add_u64 v[160:161], v[70:71], 0, s[38:39]
	s_waitcnt vmcnt(7)
	ds_write_b128 v135, v[2:5]
	s_waitcnt vmcnt(6)
	ds_write_b128 v135, v[6:9] offset:4608
	s_waitcnt vmcnt(3)
	ds_write_b128 v135, v[18:21] offset:18432
	ds_write_b128 v135, v[10:13] offset:9216
	s_waitcnt vmcnt(2)
	ds_write_b128 v135, v[22:25] offset:23040
	ds_write_b128 v135, v[14:17] offset:13824
	s_waitcnt vmcnt(1)
	ds_write_b128 v135, v[26:29] offset:27648
	s_waitcnt vmcnt(0)
	ds_write_b128 v135, v[30:33] offset:32256
	s_mov_b32 s37, 0
	v_mov_b32_e32 v2, 0
	v_mov_b32_e32 v3, v75
	v_mov_b32_e32 v4, v75
	v_mov_b32_e32 v5, v75
	v_mov_b32_e32 v6, v75
	v_mov_b32_e32 v7, v75
	v_mov_b32_e32 v8, v75
	v_mov_b32_e32 v9, v75
	v_mov_b32_e32 v10, v75
	v_mov_b32_e32 v11, v75
	v_mov_b32_e32 v12, v75
	v_mov_b32_e32 v13, v75
	v_mov_b32_e32 v14, v75
	v_mov_b32_e32 v15, v75
	v_mov_b32_e32 v16, v75
	v_mov_b32_e32 v17, v75
	v_mov_b32_e32 v34, 0
	v_mov_b32_e32 v35, v75
	v_mov_b32_e32 v36, v75
	v_mov_b32_e32 v37, v75
	v_mov_b32_e32 v38, v75
	v_mov_b32_e32 v39, v75
	v_mov_b32_e32 v40, v75
	v_mov_b32_e32 v41, v75
	v_mov_b32_e32 v42, v75
	v_mov_b32_e32 v43, v75
	v_mov_b32_e32 v44, v75
	v_mov_b32_e32 v45, v75
	v_mov_b32_e32 v46, v75
	v_mov_b32_e32 v47, v75
	v_mov_b32_e32 v48, v75
	v_mov_b32_e32 v49, v75
	v_mov_b32_e32 v18, 0
	v_mov_b32_e32 v19, v75
	v_mov_b32_e32 v20, v75
	v_mov_b32_e32 v21, v75
	v_mov_b32_e32 v22, v75
	v_mov_b32_e32 v23, v75
	v_mov_b32_e32 v24, v75
	v_mov_b32_e32 v25, v75
	v_mov_b32_e32 v26, v75
	v_mov_b32_e32 v27, v75
	v_mov_b32_e32 v28, v75
	v_mov_b32_e32 v29, v75
	v_mov_b32_e32 v30, v75
	v_mov_b32_e32 v31, v75
	v_mov_b32_e32 v32, v75
	v_mov_b32_e32 v33, v75
	v_mov_b32_e32 v50, 0
	v_mov_b32_e32 v51, v75
	v_mov_b32_e32 v52, v75
	v_mov_b32_e32 v53, v75
	v_mov_b32_e32 v54, v75
	v_mov_b32_e32 v55, v75
	v_mov_b32_e32 v56, v75
	v_mov_b32_e32 v57, v75
	v_mov_b32_e32 v58, v75
	v_mov_b32_e32 v59, v75
	v_mov_b32_e32 v60, v75
	v_mov_b32_e32 v61, v75
	v_mov_b32_e32 v62, v75
	v_mov_b32_e32 v63, v75
	v_mov_b32_e32 v64, v75
	v_mov_b32_e32 v65, v75
	s_waitcnt lgkmcnt(0)
	v_lshl_add_u64 v[168:169], v[146:147], 0, v[68:69]
	v_lshl_add_u64 v[172:173], v[148:149], 0, v[68:69]
	v_lshl_add_u64 v[176:177], v[150:151], 0, v[68:69]
	v_lshl_add_u64 v[180:181], v[152:153], 0, v[68:69]
	v_lshl_add_u64 v[184:185], v[154:155], 0, v[68:69]
	v_lshl_add_u64 v[188:189], v[156:157], 0, v[68:69]
	v_lshl_add_u64 v[192:193], v[158:159], 0, v[68:69]
	v_lshl_add_u64 v[196:197], v[160:161], 0, v[68:69]
	global_load_dwordx4 v[168:171], v[168:169], off offset:128
	s_nop 0
	global_load_dwordx4 v[172:175], v[172:173], off offset:128
	s_nop 0
	global_load_dwordx4 v[176:179], v[176:177], off offset:128
	s_nop 0
	global_load_dwordx4 v[180:183], v[180:181], off offset:128
	s_nop 0
	global_load_dwordx4 v[184:187], v[184:185], off offset:128
	s_nop 0
	global_load_dwordx4 v[188:191], v[188:189], off offset:128
	s_nop 0
	global_load_dwordx4 v[192:195], v[192:193], off offset:128
	s_nop 0
	global_load_dwordx4 v[196:199], v[196:197], off offset:128
;     ...
;   for (int kt = 0; kt < nk; ++kt) {
;     const int kn = (kt + 1 < nk) ? kt + 1 : kt;
;     GM_LOAD2(kn * 64, kn * bkstep)
;     __builtin_amdgcn_sched_barrier(0);
;     const char* As = smem + (kt & 1) * 2 * TILE_B;
;     const char* Bs = As + TILE_B;
;     if constexpr (HOIST) {
;       bf16x8 fa0[4], fa1[4], fb0[4], fb1[4];
; #pragma unroll
;       for (int st = 0; st < 4; ++st) {
;         fa0[st] = *(const bf16x8*)(As + aoff + st * 32);
;         fb0[st] = *(const bf16x8*)(Bs + boff + st * 32);
;         fa1[st] = *(const bf16x8*)(As + aoff + 32 * LSTR + st * 32);
;         fb1[st] = *(const bf16x8*)(Bs + boff + 32 * LSTR + st * 32);
;       }
;       __builtin_amdgcn_sched_barrier(0);
; #pragma unroll
;       for (int st = 0; st < 4; ++st) {
;         acc[0][0] = mfma32(fa0[st], fb0[st], acc[0][0]);
;         acc[0][1] = mfma32(fa0[st], fb1[st], acc[0][1]);
;         acc[1][0] = mfma32(fa1[st], fb0[st], acc[1][0]);
;         acc[1][1] = mfma32(fa1[st], fb1[st], acc[1][1]);
;       }
;     } else {
; #pragma unroll
;       for (int st = 0; st < 4; ++st) {
;         bf16x8 a0 = *(const bf16x8*)(As + aoff + st * 32);
;         bf16x8 a1 = *(const bf16x8*)(As + aoff + 32 * LSTR + st * 32);
;         bf16x8 b0 = *(const bf16x8*)(Bs + boff + st * 32);
;         bf16x8 b1 = *(const bf16x8*)(Bs + boff + 32 * LSTR + st * 32);
;         acc[0][0] = mfma32(a0, b0, acc[0][0]);
;         acc[0][1] = mfma32(a0, b1, acc[0][1]);
;         acc[1][0] = mfma32(a1, b0, acc[1][0]);
;         acc[1][1] = mfma32(a1, b1, acc[1][1]);
;       }
;     }
;     __builtin_amdgcn_sched_barrier(0);
;     {
;       char* Ad = smem + ((kt + 1) & 1) * 2 * TILE_B;
;       GM_STORE(Ad)
;     }
;     __syncthreads();
.LBB0_632:
	s_barrier
	s_and_b32 s38, s37, 2
	s_mulk_i32 s38, 0x4800
	v_add3_u32 v167, s38, v162, v163
	v_add3_u32 v220, s38, v164, v163
	ds_read_b128 v[200:203], v167 offset:0
	ds_read_b128 v[204:207], v220 offset:18432
	ds_read_b128 v[212:215], v167 offset:4608
	ds_read_b128 v[208:211], v220 offset:23040
	s_waitcnt lgkmcnt(2)
	v_mfma_f32_32x32x16_bf16 v[34:49], v[200:203], v[204:207], v[34:49]
	ds_read_b128 v[216:219], v167 offset:32
	s_waitcnt lgkmcnt(2)
	v_mfma_f32_32x32x16_bf16 v[18:33], v[212:215], v[204:207], v[18:33]
	ds_read_b128 v[204:207], v220 offset:18464
	s_waitcnt lgkmcnt(2)
	v_mfma_f32_32x32x16_bf16 v[2:17], v[200:203], v[208:211], v[2:17]
	ds_read_b128 v[200:203], v167 offset:4640
	v_mfma_f32_32x32x16_bf16 v[50:65], v[212:215], v[208:211], v[50:65]
	ds_read_b128 v[208:211], v220 offset:23072
	s_waitcnt lgkmcnt(2)
	v_mfma_f32_32x32x16_bf16 v[34:49], v[216:219], v[204:207], v[34:49]
	ds_read_b128 v[212:215], v167 offset:64
	s_waitcnt lgkmcnt(2)
	v_mfma_f32_32x32x16_bf16 v[18:33], v[200:203], v[204:207], v[18:33]
	ds_read_b128 v[204:207], v220 offset:18496
	s_waitcnt lgkmcnt(2)
	v_mfma_f32_32x32x16_bf16 v[2:17], v[216:219], v[208:211], v[2:17]
	ds_read_b128 v[216:219], v167 offset:4672
	v_mfma_f32_32x32x16_bf16 v[50:65], v[200:203], v[208:211], v[50:65]
	ds_read_b128 v[208:211], v220 offset:23104
	s_waitcnt lgkmcnt(2)
	v_mfma_f32_32x32x16_bf16 v[34:49], v[212:215], v[204:207], v[34:49]
	ds_read_b128 v[200:203], v167 offset:96
	s_waitcnt lgkmcnt(2)
	v_mfma_f32_32x32x16_bf16 v[18:33], v[216:219], v[204:207], v[18:33]
	ds_read_b128 v[204:207], v220 offset:18528
	s_waitcnt lgkmcnt(2)
	v_mfma_f32_32x32x16_bf16 v[2:17], v[212:215], v[208:211], v[2:17]
	ds_read_b128 v[212:215], v167 offset:4704
	v_mfma_f32_32x32x16_bf16 v[50:65], v[216:219], v[208:211], v[50:65]
	ds_read_b128 v[208:211], v220 offset:23136
	s_waitcnt lgkmcnt(2)
	v_mfma_f32_32x32x16_bf16 v[34:49], v[200:203], v[204:207], v[34:49]
	s_waitcnt lgkmcnt(1)
	v_mfma_f32_32x32x16_bf16 v[18:33], v[212:215], v[204:207], v[18:33]
	s_waitcnt lgkmcnt(0)
	v_mfma_f32_32x32x16_bf16 v[2:17], v[200:203], v[208:211], v[2:17]
	v_mfma_f32_32x32x16_bf16 v[50:65], v[212:215], v[208:211], v[50:65]
	s_add_i32 s37, s37, 2
	s_and_b32 s38, s37, 2
	s_mulk_i32 s38, 0x4800
	s_add_i32 s6, s6, -1
	v_add_u32_e32 v167, s38, v135
	v_lshl_add_u64 v[146:147], v[146:147], 0, s[8:9]
	v_lshl_add_u64 v[148:149], v[148:149], 0, s[8:9]
	v_lshl_add_u64 v[150:151], v[150:151], 0, s[8:9]
	v_lshl_add_u64 v[152:153], v[152:153], 0, s[8:9]
	v_lshl_add_u64 v[154:155], v[154:155], 0, s[8:9]
	v_lshl_add_u64 v[156:157], v[156:157], 0, s[8:9]
	v_lshl_add_u64 v[158:159], v[158:159], 0, s[8:9]
	v_lshl_add_u64 v[160:161], v[160:161], 0, s[8:9]
	s_cmp_lg_u32 s6, 0
	s_waitcnt vmcnt(7)
	ds_write_b128 v167, v[168:171]
	v_lshl_add_u64 v[168:169], v[146:147], 0, v[68:69]
	global_load_dwordx4 v[168:171], v[168:169], off offset:128
	s_waitcnt vmcnt(7)
	ds_write_b128 v167, v[172:175] offset:4608
	v_lshl_add_u64 v[172:173], v[148:149], 0, v[68:69]
	global_load_dwordx4 v[172:175], v[172:173], off offset:128
	s_waitcnt vmcnt(7)
	ds_write_b128 v167, v[176:179] offset:9216
	v_lshl_add_u64 v[176:177], v[150:151], 0, v[68:69]
	global_load_dwordx4 v[176:179], v[176:177], off offset:128
	s_waitcnt vmcnt(7)
	ds_write_b128 v167, v[180:183] offset:13824
	v_lshl_add_u64 v[180:181], v[152:153], 0, v[68:69]
	global_load_dwordx4 v[180:183], v[180:181], off offset:128
	s_waitcnt vmcnt(7)
	ds_write_b128 v167, v[184:187] offset:18432
	v_lshl_add_u64 v[184:185], v[154:155], 0, v[68:69]
	global_load_dwordx4 v[184:187], v[184:185], off offset:128
	s_waitcnt vmcnt(7)
	ds_write_b128 v167, v[188:191] offset:23040
	v_lshl_add_u64 v[188:189], v[156:157], 0, v[68:69]
	global_load_dwordx4 v[188:191], v[188:189], off offset:128
	s_waitcnt vmcnt(7)
	ds_write_b128 v167, v[192:195] offset:27648
	v_lshl_add_u64 v[192:193], v[158:159], 0, v[68:69]
	global_load_dwordx4 v[192:195], v[192:193], off offset:128
	s_waitcnt vmcnt(7)
	ds_write_b128 v167, v[196:199] offset:32256
	v_lshl_add_u64 v[196:197], v[160:161], 0, v[68:69]
	global_load_dwordx4 v[196:199], v[196:197], off offset:128
	s_waitcnt lgkmcnt(0)
	s_cbranch_scc1 .LBB0_632
	s_barrier
	s_and_b32 s38, s37, 2
	s_mulk_i32 s38, 0x4800
	v_add3_u32 v167, s38, v162, v163
	v_add3_u32 v220, s38, v164, v163
	ds_read_b128 v[200:203], v167 offset:0
	ds_read_b128 v[204:207], v220 offset:18432
	ds_read_b128 v[212:215], v167 offset:4608
	ds_read_b128 v[208:211], v220 offset:23040
	s_waitcnt lgkmcnt(2)
	v_mfma_f32_32x32x16_bf16 v[34:49], v[200:203], v[204:207], v[34:49]
	ds_read_b128 v[216:219], v167 offset:32
	s_waitcnt lgkmcnt(2)
	v_mfma_f32_32x32x16_bf16 v[18:33], v[212:215], v[204:207], v[18:33]
	ds_read_b128 v[204:207], v220 offset:18464
	s_waitcnt lgkmcnt(2)
	v_mfma_f32_32x32x16_bf16 v[2:17], v[200:203], v[208:211], v[2:17]
	ds_read_b128 v[200:203], v167 offset:4640
	v_mfma_f32_32x32x16_bf16 v[50:65], v[212:215], v[208:211], v[50:65]
	ds_read_b128 v[208:211], v220 offset:23072
	s_waitcnt lgkmcnt(2)
	v_mfma_f32_32x32x16_bf16 v[34:49], v[216:219], v[204:207], v[34:49]
	ds_read_b128 v[212:215], v167 offset:64
	s_waitcnt lgkmcnt(2)
	v_mfma_f32_32x32x16_bf16 v[18:33], v[200:203], v[204:207], v[18:33]
	ds_read_b128 v[204:207], v220 offset:18496
	s_waitcnt lgkmcnt(2)
	v_mfma_f32_32x32x16_bf16 v[2:17], v[216:219], v[208:211], v[2:17]
	ds_read_b128 v[216:219], v167 offset:4672
	v_mfma_f32_32x32x16_bf16 v[50:65], v[200:203], v[208:211], v[50:65]
	ds_read_b128 v[208:211], v220 offset:23104
	s_waitcnt lgkmcnt(2)
	v_mfma_f32_32x32x16_bf16 v[34:49], v[212:215], v[204:207], v[34:49]
	ds_read_b128 v[200:203], v167 offset:96
	s_waitcnt lgkmcnt(2)
;     ...
;   for (int kt = 0; kt < nk; ++kt) {
;     const int kn = (kt + 1 < nk) ? kt + 1 : kt;
;     GM_LOAD2(kn * 64, kn * bkstep)
;     __builtin_amdgcn_sched_barrier(0);
;     const char* As = smem + (kt & 1) * 2 * TILE_B;
;     const char* Bs = As + TILE_B;
;     if constexpr (HOIST) {
;       bf16x8 fa0[4], fa1[4], fb0[4], fb1[4];
; #pragma unroll
;       for (int st = 0; st < 4; ++st) {
;         fa0[st] = *(const bf16x8*)(As + aoff + st * 32);
;         fb0[st] = *(const bf16x8*)(Bs + boff + st * 32);
;         fa1[st] = *(const bf16x8*)(As + aoff + 32 * LSTR + st * 32);
;         fb1[st] = *(const bf16x8*)(Bs + boff + 32 * LSTR + st * 32);
;       }
;       __builtin_amdgcn_sched_barrier(0);
; #pragma unroll
;       for (int st = 0; st < 4; ++st) {
;         acc[0][0] = mfma32(fa0[st], fb0[st], acc[0][0]);
;         acc[0][1] = mfma32(fa0[st], fb1[st], acc[0][1]);
;         acc[1][0] = mfma32(fa1[st], fb0[st], acc[1][0]);
;         acc[1][1] = mfma32(fa1[st], fb1[st], acc[1][1]);
;       }
;     } else {
; #pragma unroll
;       for (int st = 0; st < 4; ++st) {
;         bf16x8 a0 = *(const bf16x8*)(As + aoff + st * 32);
;         bf16x8 a1 = *(const bf16x8*)(As + aoff + 32 * LSTR + st * 32);
;         bf16x8 b0 = *(const bf16x8*)(Bs + boff + st * 32);
;         bf16x8 b1 = *(const bf16x8*)(Bs + boff + 32 * LSTR + st * 32);
;         acc[0][0] = mfma32(a0, b0, acc[0][0]);
;         acc[0][1] = mfma32(a0, b1, acc[0][1]);
;         acc[1][0] = mfma32(a1, b0, acc[1][0]);
;         acc[1][1] = mfma32(a1, b1, acc[1][1]);
;       }
;     }
;     __builtin_amdgcn_sched_barrier(0);
;     {
;       char* Ad = smem + ((kt + 1) & 1) * 2 * TILE_B;
;       GM_STORE(Ad)
;     }
;     __syncthreads();
; __device__ __forceinline__ void acc_to_lds(const f32x16 (&acc)[2][2], float* cs) {
;   const int tid = threadIdx.x, lane = tid & 63, wave = tid >> 6;
;   const int wm = wave >> 1, wn = wave & 1;
; #pragma unroll
;   for (int i = 0; i < 2; ++i)
; #pragma unroll
;     for (int j = 0; j < 2; ++j)
; #pragma unroll
;       for (int r = 0; r < 16; ++r) {
;         int row = wm * 64 + i * 32 + (r & 3) + 8 * (r >> 2) + 4 * (lane >> 5);
;         int col = wn * 64 + j * 32 + (lane & 31);
;         cs[row * CSTR + col] = acc[i][j][r];
;       }
;   __syncthreads();
	v_mfma_f32_32x32x16_bf16 v[18:33], v[216:219], v[204:207], v[18:33]
	ds_read_b128 v[204:207], v220 offset:18528
	s_waitcnt lgkmcnt(2)
	v_mfma_f32_32x32x16_bf16 v[2:17], v[212:215], v[208:211], v[2:17]
	ds_read_b128 v[212:215], v167 offset:4704
	v_mfma_f32_32x32x16_bf16 v[50:65], v[216:219], v[208:211], v[50:65]
	ds_read_b128 v[208:211], v220 offset:23136
	s_waitcnt lgkmcnt(2)
	v_mfma_f32_32x32x16_bf16 v[34:49], v[200:203], v[204:207], v[34:49]
	s_waitcnt lgkmcnt(1)
	v_mfma_f32_32x32x16_bf16 v[18:33], v[212:215], v[204:207], v[18:33]
	s_waitcnt lgkmcnt(0)
	v_mfma_f32_32x32x16_bf16 v[2:17], v[200:203], v[208:211], v[2:17]
	v_mfma_f32_32x32x16_bf16 v[50:65], v[212:215], v[208:211], v[50:65]
	s_add_i32 s37, s37, 2
	s_and_b32 s38, s37, 2
	s_mulk_i32 s38, 0x4800
	v_add_u32_e32 v167, s38, v135
	v_lshl_add_u64 v[146:147], v[146:147], 0, s[8:9]
	v_lshl_add_u64 v[148:149], v[148:149], 0, s[8:9]
	v_lshl_add_u64 v[150:151], v[150:151], 0, s[8:9]
	v_lshl_add_u64 v[152:153], v[152:153], 0, s[8:9]
	v_lshl_add_u64 v[154:155], v[154:155], 0, s[8:9]
	v_lshl_add_u64 v[156:157], v[156:157], 0, s[8:9]
	v_lshl_add_u64 v[158:159], v[158:159], 0, s[8:9]
	v_lshl_add_u64 v[160:161], v[160:161], 0, s[8:9]
	s_waitcnt vmcnt(7)
	ds_write_b128 v167, v[168:171]
	s_waitcnt vmcnt(6)
	ds_write_b128 v167, v[172:175] offset:4608
	s_waitcnt vmcnt(5)
	ds_write_b128 v167, v[176:179] offset:9216
	s_waitcnt vmcnt(4)
	ds_write_b128 v167, v[180:183] offset:13824
	s_waitcnt vmcnt(3)
	ds_write_b128 v167, v[184:187] offset:18432
	s_waitcnt vmcnt(2)
	ds_write_b128 v167, v[188:191] offset:23040
	s_waitcnt vmcnt(1)
	ds_write_b128 v167, v[192:195] offset:27648
	s_waitcnt vmcnt(0)
	ds_write_b128 v167, v[196:199] offset:32256
	s_waitcnt lgkmcnt(0)
	s_barrier
	v_lshl_add_u64 v[180:181], v[160:161], 0, v[68:69]
	v_lshl_add_u64 v[176:177], v[158:159], 0, v[68:69]
	v_lshl_add_u64 v[172:173], v[156:157], 0, v[68:69]
	v_lshl_add_u64 v[168:169], v[154:155], 0, v[68:69]
	v_lshl_add_u64 v[158:159], v[152:153], 0, v[68:69]
	v_lshl_add_u64 v[154:155], v[150:151], 0, v[68:69]
	v_lshl_add_u64 v[150:151], v[148:149], 0, v[68:69]
	v_lshl_add_u64 v[146:147], v[146:147], 0, v[68:69]
	s_nop 0
	s_nop 0
	s_nop 0
	s_nop 0
	s_nop 0
	s_nop 0
	s_nop 0
	v_add3_u32 v68, s38, v162, v163
	v_add3_u32 v167, s38, v164, v163
	ds_read_b128 v[184:187], v68 offset:0
	ds_read_b128 v[188:191], v167 offset:18432
	ds_read_b128 v[196:199], v68 offset:4608
	ds_read_b128 v[192:195], v167 offset:23040
	s_waitcnt lgkmcnt(2)
	v_mfma_f32_32x32x16_bf16 v[34:49], v[184:187], v[188:191], v[34:49]
	ds_read_b128 v[200:203], v68 offset:32
	s_waitcnt lgkmcnt(2)
	v_mfma_f32_32x32x16_bf16 v[18:33], v[196:199], v[188:191], v[18:33]
	ds_read_b128 v[188:191], v167 offset:18464
	s_waitcnt lgkmcnt(2)
	v_mfma_f32_32x32x16_bf16 v[2:17], v[184:187], v[192:195], v[2:17]
	ds_read_b128 v[184:187], v68 offset:4640
	v_mfma_f32_32x32x16_bf16 v[50:65], v[196:199], v[192:195], v[50:65]
	ds_read_b128 v[192:195], v167 offset:23072
	s_waitcnt lgkmcnt(2)
	v_mfma_f32_32x32x16_bf16 v[34:49], v[200:203], v[188:191], v[34:49]
	ds_read_b128 v[196:199], v68 offset:64
	s_waitcnt lgkmcnt(2)
	v_mfma_f32_32x32x16_bf16 v[18:33], v[184:187], v[188:191], v[18:33]
	ds_read_b128 v[188:191], v167 offset:18496
	s_waitcnt lgkmcnt(2)
	v_mfma_f32_32x32x16_bf16 v[2:17], v[200:203], v[192:195], v[2:17]
	ds_read_b128 v[200:203], v68 offset:4672
	v_mfma_f32_32x32x16_bf16 v[50:65], v[184:187], v[192:195], v[50:65]
	ds_read_b128 v[192:195], v167 offset:23104
	s_waitcnt lgkmcnt(2)
	v_mfma_f32_32x32x16_bf16 v[34:49], v[196:199], v[188:191], v[34:49]
	ds_read_b128 v[184:187], v68 offset:96
	s_waitcnt lgkmcnt(2)
	v_mfma_f32_32x32x16_bf16 v[18:33], v[200:203], v[188:191], v[18:33]
	ds_read_b128 v[188:191], v167 offset:18528
	s_waitcnt lgkmcnt(2)
	v_mfma_f32_32x32x16_bf16 v[2:17], v[196:199], v[192:195], v[2:17]
	ds_read_b128 v[196:199], v68 offset:4704
	v_mfma_f32_32x32x16_bf16 v[50:65], v[200:203], v[192:195], v[50:65]
	ds_read_b128 v[192:195], v167 offset:23136
	s_waitcnt lgkmcnt(2)
	v_mfma_f32_32x32x16_bf16 v[34:49], v[184:187], v[188:191], v[34:49]
	s_waitcnt lgkmcnt(1)
	v_mfma_f32_32x32x16_bf16 v[18:33], v[196:199], v[188:191], v[18:33]
	s_waitcnt lgkmcnt(0)
	v_mfma_f32_32x32x16_bf16 v[2:17], v[184:187], v[192:195], v[2:17]
	v_mfma_f32_32x32x16_bf16 v[50:65], v[196:199], v[192:195], v[50:65]
	s_waitcnt lgkmcnt(0)
	s_barrier
	ds_write2_b32 v165, v34, v2 offset1:32
	ds_write2_b32 v165, v35, v3 offset0:132 offset1:164
	v_add_u32_e32 v2, 0x400, v165
	ds_write2_b32 v2, v36, v4 offset0:8 offset1:40
	ds_write2_b32 v2, v37, v5 offset0:140 offset1:172
	v_add_u32_e32 v2, 0x1000, v165
	ds_write2_b32 v2, v38, v6 offset0:32 offset1:64
	ds_write2_b32 v2, v39, v7 offset0:164 offset1:196
	v_add_u32_e32 v2, 0x1400, v165
	ds_write2_b32 v2, v40, v8 offset0:40 offset1:72
	ds_write2_b32 v2, v41, v9 offset0:172 offset1:204
	v_add_u32_e32 v2, 0x2000, v165
	ds_write2_b32 v2, v42, v10 offset0:64 offset1:96
	ds_write2_b32 v2, v43, v11 offset0:196 offset1:228
	v_add_u32_e32 v2, 0x2400, v165
	ds_write2_b32 v2, v44, v12 offset0:72 offset1:104
	ds_write2_b32 v2, v45, v13 offset0:204 offset1:236
	v_add_u32_e32 v2, 0x3000, v165
	ds_write2_b32 v2, v46, v14 offset0:96 offset1:128
	v_add_u32_e32 v2, 0x3200, v165
	ds_write2_b32 v2, v47, v15 offset0:100 offset1:132
	v_add_u32_e32 v2, 0x3400, v165
	ds_write2_b32 v2, v48, v16 offset0:104 offset1:136
	v_add_u32_e32 v2, 0x3600, v165
	ds_write2_b32 v2, v49, v17 offset0:108 offset1:140
	v_add_u32_e32 v2, 0x4000, v165
	ds_write2_b32 v2, v18, v50 offset0:128 offset1:160
	v_add_u32_e32 v2, 0x4400, v165
	ds_write2_b32 v2, v19, v51 offset0:4 offset1:36
	ds_write2_b32 v2, v20, v52 offset0:136 offset1:168
	v_add_u32_e32 v2, 0x4800, v165
	ds_write2_b32 v2, v21, v53 offset0:12 offset1:44
	v_add_u32_e32 v2, 0x5000, v165
	ds_write2_b32 v2, v22, v54 offset0:160 offset1:192
	v_add_u32_e32 v2, 0x5400, v165
	ds_write2_b32 v2, v23, v55 offset0:36 offset1:68
	ds_write2_b32 v2, v24, v56 offset0:168 offset1:200
	v_add_u32_e32 v2, 0x5800, v165
	ds_write2_b32 v2, v25, v57 offset0:44 offset1:76
	v_add_u32_e32 v2, 0x6000, v165
	ds_write2_b32 v2, v26, v58 offset0:192 offset1:224
	v_add_u32_e32 v2, 0x6400, v165
	ds_write2_b32 v2, v27, v59 offset0:68 offset1:100
	ds_write2_b32 v2, v28, v60 offset0:200 offset1:232
	v_add_u32_e32 v2, 0x6800, v165
	ds_write2_b32 v2, v29, v61 offset0:76 offset1:108
	v_add_u32_e32 v2, 0x7200, v165
	ds_write2_b32 v2, v30, v62 offset0:96 offset1:128
	v_add_u32_e32 v2, 0x7400, v165
	ds_write2_b32 v2, v31, v63 offset0:100 offset1:132
	v_add_u32_e32 v2, 0x7600, v165
	s_lshl_b32 s6, s36, 11
	ds_write2_b32 v2, v32, v64 offset0:104 offset1:136
	v_add_u32_e32 v2, 0x7800, v165
	v_lshl_add_u64 v[46:47], v[116:117], 0, s[6:7]
	ds_write2_b32 v2, v33, v65 offset0:108 offset1:140
	s_waitcnt lgkmcnt(0)
	s_barrier
; __device__ __forceinline__ void merge_tile(const Params& P, int l, int mt, int nt, char* smem) {
;     ...
;   for (int br = 0; br < 3; ++br) {
;     f32x16 acc[2][2];
;     zero_acc(acc);
;     const int K = (br == 0) ? 256 : 384;
;     const u16* A = WSP(u16, br == 0 ? OFF_FTO : (br == 1 ? OFF_ONA : OFF_ODF)) + (size_t)mt * 128 * K;
;     const u16* Bt = WSP(u16, br == 0 ? OFF_WFT : (br == 1 ? OFF_WNA : OFF_WDF)) + ((size_t)l * DM + nt * 128) * K;
;     gemm_main<false>([&](int rr) { return A + (size_t)rr * K; }, Bt, K, K, smem, acc);
;     acc_to_lds(acc, cs);
;     const u16* gp = WSP(u16, OFF_G) + grow * 3072 + br * 1024 + nt * 128 + half * 64;
; #pragma unroll
;     for (int q = 0; q < 8; ++q) {
;       uint4 gq = *(const uint4*)(gp + q * 8);
;       float4 a = *(const float4*)(cs + r * CSTR + half * 64 + q * 8);
;       float4 c = *(const float4*)(cs + r * CSTR + half * 64 + q * 8 + 4);
;       macc[q * 8 + 0] += __uint_as_float(gq.x << 16) * a.x;
;       macc[q * 8 + 1] += __uint_as_float(gq.x & 0xffff0000u) * a.y;
;       macc[q * 8 + 2] += __uint_as_float(gq.y << 16) * a.z;
;       macc[q * 8 + 3] += __uint_as_float(gq.y & 0xffff0000u) * a.w;
;       macc[q * 8 + 4] += __uint_as_float(gq.z << 16) * c.x;
;       macc[q * 8 + 5] += __uint_as_float(gq.z & 0xffff0000u) * c.y;
;       macc[q * 8 + 6] += __uint_as_float(gq.w << 16) * c.z;
;       macc[q * 8 + 7] += __uint_as_float(gq.w & 0xffff0000u) * c.w;
;     }
;     __syncthreads();
;   }
	global_load_dwordx4 v[2:5], v[46:47], off
	global_load_dwordx4 v[6:9], v[46:47], off offset:16
	global_load_dwordx4 v[10:13], v[46:47], off offset:32
	global_load_dwordx4 v[14:17], v[46:47], off offset:48
	global_load_dwordx4 v[18:21], v[46:47], off offset:64
	global_load_dwordx4 v[22:25], v[46:47], off offset:80
	ds_read_b128 v[26:29], v166
	ds_read_b128 v[30:33], v166 offset:16
	ds_read_b128 v[34:37], v166 offset:32
	ds_read_b128 v[38:41], v166 offset:48
	global_load_dwordx4 v[42:45], v[46:47], off offset:112
	s_nop 0
	global_load_dwordx4 v[46:49], v[46:47], off offset:96
	s_add_i32 s36, s36, 1
	s_cmp_lg_u32 s36, 3
	s_waitcnt vmcnt(7)
	v_lshlrev_b32_e32 v50, 16, v2
	v_and_b32_e32 v51, 0xffff0000, v2
	v_lshlrev_b32_e32 v2, 16, v3
	v_and_b32_e32 v3, 0xffff0000, v3
	s_waitcnt lgkmcnt(3)
	v_pk_fma_f32 v[142:143], v[28:29], v[2:3], v[142:143]
	v_lshlrev_b32_e32 v2, 16, v4
	v_and_b32_e32 v3, 0xffff0000, v4
	s_waitcnt lgkmcnt(2)
	v_pk_fma_f32 v[140:141], v[30:31], v[2:3], v[140:141]
	v_lshlrev_b32_e32 v2, 16, v5
	v_and_b32_e32 v3, 0xffff0000, v5
	v_pk_fma_f32 v[138:139], v[32:33], v[2:3], v[138:139]
	s_waitcnt vmcnt(6)
	v_lshlrev_b32_e32 v2, 16, v6
	v_and_b32_e32 v3, 0xffff0000, v6
	s_waitcnt lgkmcnt(1)
	v_pk_fma_f32 v[136:137], v[34:35], v[2:3], v[136:137]
	v_lshlrev_b32_e32 v2, 16, v7
	v_and_b32_e32 v3, 0xffff0000, v7
	v_pk_fma_f32 v[132:133], v[36:37], v[2:3], v[132:133]
	v_lshlrev_b32_e32 v2, 16, v8
	v_and_b32_e32 v3, 0xffff0000, v8
	s_waitcnt lgkmcnt(0)
	v_pk_fma_f32 v[130:131], v[38:39], v[2:3], v[130:131]
	ds_read_b128 v[2:5], v166 offset:64
	v_lshlrev_b32_e32 v6, 16, v9
	v_and_b32_e32 v7, 0xffff0000, v9
	v_pk_fma_f32 v[128:129], v[40:41], v[6:7], v[128:129]
	ds_read_b128 v[6:9], v166 offset:80
	v_pk_fma_f32 v[144:145], v[26:27], v[50:51], v[144:145]
	s_waitcnt vmcnt(5)
	v_lshlrev_b32_e32 v26, 16, v10
	v_and_b32_e32 v27, 0xffff0000, v10
	s_waitcnt lgkmcnt(1)
	v_pk_fma_f32 v[126:127], v[2:3], v[26:27], v[126:127]
	v_lshlrev_b32_e32 v2, 16, v11
	v_and_b32_e32 v3, 0xffff0000, v11
	v_pk_fma_f32 v[124:125], v[4:5], v[2:3], v[124:125]
	v_lshlrev_b32_e32 v2, 16, v12
	v_and_b32_e32 v3, 0xffff0000, v12
	s_waitcnt lgkmcnt(0)
	v_pk_fma_f32 v[122:123], v[6:7], v[2:3], v[122:123]
	ds_read_b128 v[2:5], v166 offset:96
	v_lshlrev_b32_e32 v6, 16, v13
	v_and_b32_e32 v7, 0xffff0000, v13
	v_pk_fma_f32 v[120:121], v[8:9], v[6:7], v[120:121]
	ds_read_b128 v[6:9], v166 offset:112
	s_waitcnt vmcnt(4)
	v_lshlrev_b32_e32 v10, 16, v14
	v_and_b32_e32 v11, 0xffff0000, v14
	s_waitcnt lgkmcnt(1)
	v_pk_fma_f32 v[118:119], v[2:3], v[10:11], v[118:119]
	v_lshlrev_b32_e32 v2, 16, v15
	v_and_b32_e32 v3, 0xffff0000, v15
	v_pk_fma_f32 v[114:115], v[4:5], v[2:3], v[114:115]
	v_lshlrev_b32_e32 v2, 16, v16
	v_and_b32_e32 v3, 0xffff0000, v16
	s_waitcnt lgkmcnt(0)
	v_pk_fma_f32 v[112:113], v[6:7], v[2:3], v[112:113]
	ds_read_b128 v[2:5], v166 offset:128
	v_lshlrev_b32_e32 v6, 16, v17
	v_and_b32_e32 v7, 0xffff0000, v17
	v_pk_fma_f32 v[110:111], v[8:9], v[6:7], v[110:111]
	ds_read_b128 v[6:9], v166 offset:144
	s_waitcnt vmcnt(3)
	v_lshlrev_b32_e32 v10, 16, v18
	v_and_b32_e32 v11, 0xffff0000, v18
	s_waitcnt lgkmcnt(1)
	v_pk_fma_f32 v[106:107], v[2:3], v[10:11], v[106:107]
	v_lshlrev_b32_e32 v2, 16, v19
	v_and_b32_e32 v3, 0xffff0000, v19
	v_pk_fma_f32 v[104:105], v[4:5], v[2:3], v[104:105]
	v_lshlrev_b32_e32 v2, 16, v20
	v_and_b32_e32 v3, 0xffff0000, v20
	s_waitcnt lgkmcnt(0)
	v_pk_fma_f32 v[102:103], v[6:7], v[2:3], v[102:103]
	ds_read_b128 v[2:5], v166 offset:160
	v_lshlrev_b32_e32 v6, 16, v21
	v_and_b32_e32 v7, 0xffff0000, v21
	v_pk_fma_f32 v[100:101], v[8:9], v[6:7], v[100:101]
	ds_read_b128 v[6:9], v166 offset:176
	s_waitcnt vmcnt(2)
	v_lshlrev_b32_e32 v10, 16, v22
	v_and_b32_e32 v11, 0xffff0000, v22
	s_waitcnt lgkmcnt(1)
	v_pk_fma_f32 v[98:99], v[2:3], v[10:11], v[98:99]
	v_lshlrev_b32_e32 v2, 16, v23
	v_and_b32_e32 v3, 0xffff0000, v23
	v_pk_fma_f32 v[96:97], v[4:5], v[2:3], v[96:97]
	v_lshlrev_b32_e32 v2, 16, v24
	v_and_b32_e32 v3, 0xffff0000, v24
	s_waitcnt lgkmcnt(0)
	v_pk_fma_f32 v[94:95], v[6:7], v[2:3], v[94:95]
	ds_read_b128 v[2:5], v166 offset:192
	v_lshlrev_b32_e32 v6, 16, v25
	v_and_b32_e32 v7, 0xffff0000, v25
	v_pk_fma_f32 v[92:93], v[8:9], v[6:7], v[92:93]
	ds_read_b128 v[6:9], v166 offset:208
	s_waitcnt vmcnt(0)
	v_lshlrev_b32_e32 v10, 16, v46
	v_and_b32_e32 v11, 0xffff0000, v46
	s_waitcnt lgkmcnt(1)
	v_pk_fma_f32 v[90:91], v[2:3], v[10:11], v[90:91]
	v_lshlrev_b32_e32 v2, 16, v47
	v_and_b32_e32 v3, 0xffff0000, v47
	v_pk_fma_f32 v[88:89], v[4:5], v[2:3], v[88:89]
	v_lshlrev_b32_e32 v2, 16, v48
	v_and_b32_e32 v3, 0xffff0000, v48
	s_waitcnt lgkmcnt(0)
	v_pk_fma_f32 v[86:87], v[6:7], v[2:3], v[86:87]
	ds_read_b128 v[2:5], v166 offset:224
	v_lshlrev_b32_e32 v6, 16, v49
	v_and_b32_e32 v7, 0xffff0000, v49
	v_pk_fma_f32 v[84:85], v[8:9], v[6:7], v[84:85]
	ds_read_b128 v[6:9], v166 offset:240
	v_lshlrev_b32_e32 v10, 16, v42
	v_and_b32_e32 v11, 0xffff0000, v42
	s_waitcnt lgkmcnt(1)
	v_pk_fma_f32 v[82:83], v[2:3], v[10:11], v[82:83]
	v_lshlrev_b32_e32 v2, 16, v43
	v_and_b32_e32 v3, 0xffff0000, v43
	v_pk_fma_f32 v[80:81], v[4:5], v[2:3], v[80:81]
	v_lshlrev_b32_e32 v2, 16, v44
	v_and_b32_e32 v3, 0xffff0000, v44
	s_waitcnt lgkmcnt(0)
	v_pk_fma_f32 v[78:79], v[6:7], v[2:3], v[78:79]
	v_lshlrev_b32_e32 v2, 16, v45
	v_and_b32_e32 v3, 0xffff0000, v45
	v_pk_fma_f32 v[76:77], v[8:9], v[2:3], v[76:77]
	s_barrier
; __device__ __forceinline__ void store_row64_bf16(const float* v, u16* dst) {
; #pragma unroll
;   for (int q = 0; q < 8; ++q) {
;     uint4 o;
;     o.x = pack2(v[q * 8 + 0], v[q * 8 + 1]);
;     o.y = pack2(v[q * 8 + 2], v[q * 8 + 3]);
;     o.z = pack2(v[q * 8 + 4], v[q * 8 + 5]);
;     o.w = pack2(v[q * 8 + 6], v[q * 8 + 7]);
;     *(uint4*)(dst + q * 8) = o;
;   }
	s_cbranch_scc1 .LBB0_631
	v_lshlrev_b64 v[2:3], 11, v[108:109]
	v_lshl_add_u64 v[2:3], s[4:5], 0, v[2:3]
	v_lshl_add_u64 v[2:3], s[12:13], 1, v[2:3]
	v_mov_b32_e32 v75, v69
	v_lshl_add_u64 v[6:7], v[2:3], 0, v[74:75]
	v_cvt_pk_bf16_f32 v2, v144, v145
	v_cvt_pk_bf16_f32 v3, v142, v143
	v_cvt_pk_bf16_f32 v4, v140, v141
	v_cvt_pk_bf16_f32 v5, v138, v139
	global_store_dwordx4 v[6:7], v[2:5], off
	v_readlane_b32 s40, v253, 37
	v_readlane_b32 s48, v253, 45
	v_cvt_pk_bf16_f32 v2, v136, v137
	v_cvt_pk_bf16_f32 v3, v132, v133
	v_cvt_pk_bf16_f32 v4, v130, v131
	v_cvt_pk_bf16_f32 v5, v128, v129
	global_store_dwordx4 v[6:7], v[2:5], off offset:16
	v_readlane_b32 s49, v253, 46
	v_readlane_b32 s50, v253, 47
	v_cvt_pk_bf16_f32 v2, v126, v127
	v_cvt_pk_bf16_f32 v3, v124, v125
	v_cvt_pk_bf16_f32 v4, v122, v123
	v_cvt_pk_bf16_f32 v5, v120, v121
	global_store_dwordx4 v[6:7], v[2:5], off offset:32
	v_readlane_b32 s51, v253, 48
	v_readlane_b32 s52, v253, 49
	v_cvt_pk_bf16_f32 v2, v118, v119
	v_cvt_pk_bf16_f32 v3, v114, v115
	v_cvt_pk_bf16_f32 v4, v112, v113
	v_cvt_pk_bf16_f32 v5, v110, v111
	global_store_dwordx4 v[6:7], v[2:5], off offset:48
	v_readlane_b32 s53, v253, 50
	v_readlane_b32 s54, v253, 51
	v_cvt_pk_bf16_f32 v2, v106, v107
	v_cvt_pk_bf16_f32 v3, v104, v105
	v_cvt_pk_bf16_f32 v4, v102, v103
	v_cvt_pk_bf16_f32 v5, v100, v101
	global_store_dwordx4 v[6:7], v[2:5], off offset:64
	v_readlane_b32 s55, v253, 52
	v_readlane_b32 s41, v253, 38
	v_cvt_pk_bf16_f32 v2, v98, v99
	v_cvt_pk_bf16_f32 v3, v96, v97
	v_cvt_pk_bf16_f32 v4, v94, v95
	v_cvt_pk_bf16_f32 v5, v92, v93
	global_store_dwordx4 v[6:7], v[2:5], off offset:80
	v_readlane_b32 s42, v253, 39
	v_readlane_b32 s43, v253, 40
	v_cvt_pk_bf16_f32 v2, v90, v91
	v_cvt_pk_bf16_f32 v3, v88, v89
	v_cvt_pk_bf16_f32 v4, v86, v87
	v_cvt_pk_bf16_f32 v5, v84, v85
	global_store_dwordx4 v[6:7], v[2:5], off offset:96
	v_readlane_b32 s44, v253, 41
	v_readlane_b32 s45, v253, 42
	v_cvt_pk_bf16_f32 v2, v82, v83
	v_cvt_pk_bf16_f32 v3, v80, v81
	v_cvt_pk_bf16_f32 v4, v78, v79
	v_cvt_pk_bf16_f32 v5, v76, v77
	global_store_dwordx4 v[6:7], v[2:5], off offset:112
	v_readlane_b32 s46, v253, 43
	v_readlane_b32 s47, v253, 44
	s_branch .LBB0_628

;     ...
;   for (int kt = 0; kt < nk; ++kt) {
;     const int kn = (kt + 1 < nk) ? kt + 1 : kt;
;     GW_LOAD2(kn * 64, kn * bkstep)
;     __builtin_amdgcn_sched_barrier(0);
;     __builtin_amdgcn_s_setprio(1);
; #pragma unroll
;     for (int st = 0; st < 4; ++st) {
;       bf16x8 a0 = *(const bf16x8*)(Ab + st * 32);
;       bf16x8 a1 = *(const bf16x8*)(Ab + 32 * LSTR + st * 32);
;       bf16x8 b0 = *(const bf16x8*)(Bb + st * 32);
;       bf16x8 b1 = *(const bf16x8*)(Bb + 32 * LSTR + st * 32);
;       bf16x8 b2 = *(const bf16x8*)(Bb + 64 * LSTR + st * 32);
;       bf16x8 b3 = *(const bf16x8*)(Bb + 96 * LSTR + st * 32);
;       acc[0][0] = mfma32(a0, b0, acc[0][0]);
;       acc[0][1] = mfma32(a0, b1, acc[0][1]);
;       acc[0][2] = mfma32(a0, b2, acc[0][2]);
;       acc[0][3] = mfma32(a0, b3, acc[0][3]);
;       acc[1][0] = mfma32(a1, b0, acc[1][0]);
;       acc[1][1] = mfma32(a1, b1, acc[1][1]);
;       acc[1][2] = mfma32(a1, b2, acc[1][2]);
;       acc[1][3] = mfma32(a1, b3, acc[1][3]);
;     }
;     __builtin_amdgcn_s_setprio(0);
;     __builtin_amdgcn_sched_barrier(0);
;     __syncthreads();
.LBB0_707:
	s_barrier
	s_setprio 1
	ds_read_b128 v[200:203], v130 offset:0
	ds_read_b128 v[212:215], v133 offset:18432
	ds_read_b128 v[216:219], v133 offset:23040
	ds_read_b128 v[224:227], v133 offset:27648
	ds_read_b128 v[228:231], v133 offset:32256
	ds_read_b128 v[208:211], v130 offset:4608
	s_waitcnt lgkmcnt(4)
	v_mfma_f32_32x32x16_bf16 v[114:129], v[200:203], v[212:215], v[114:129]
	ds_read_b128 v[204:207], v130 offset:32
	ds_read_b128 v[232:235], v133 offset:18464
	s_waitcnt lgkmcnt(5)
	v_mfma_f32_32x32x16_bf16 v[98:113], v[200:203], v[216:219], v[98:113]
	ds_read_b128 v[236:239], v133 offset:23072
	s_waitcnt lgkmcnt(5)
	v_mfma_f32_32x32x16_bf16 v[82:97], v[200:203], v[224:227], v[82:97]
	ds_read_b128 v[240:243], v133 offset:27680
	s_waitcnt lgkmcnt(5)
	v_mfma_f32_32x32x16_bf16 v[66:81], v[200:203], v[228:231], v[66:81]
	ds_read_b128 v[244:247], v133 offset:32288
	s_waitcnt lgkmcnt(5)
	v_mfma_f32_32x32x16_bf16 v[50:65], v[208:211], v[212:215], v[50:65]
	v_lshl_add_u64 v[152:153], v[146:147], 0, s[18:19]
	v_add_co_u32_e32 v152, vcc, s39, v152
	s_nop 1
	v_addc_co_u32_e32 v153, vcc, 0, v153, vcc
	global_load_dwordx4 v[152:155], v[152:153], off offset:384
	v_mfma_f32_32x32x16_bf16 v[34:49], v[208:211], v[216:219], v[34:49]
	v_lshl_add_u64 v[156:157], v[146:147], 0, s[18:19]
	v_add_co_u32_e32 v156, vcc, s40, v156
	s_nop 1
	v_addc_co_u32_e32 v157, vcc, 0, v157, vcc
	global_load_dwordx4 v[156:159], v[156:157], off offset:384
	v_mfma_f32_32x32x16_bf16 v[18:33], v[208:211], v[224:227], v[18:33]
	v_lshl_add_u64 v[160:161], v[146:147], 0, s[18:19]
	v_add_co_u32_e32 v160, vcc, s41, v160
	s_nop 1
	v_addc_co_u32_e32 v161, vcc, 0, v161, vcc
	global_load_dwordx4 v[160:163], v[160:161], off offset:384
	v_mfma_f32_32x32x16_bf16 v[2:17], v[208:211], v[228:231], v[2:17]
	v_lshl_add_u64 v[164:165], v[146:147], 0, s[18:19]
	v_add_co_u32_e32 v164, vcc, s42, v164
	s_nop 1
	v_addc_co_u32_e32 v165, vcc, 0, v165, vcc
	global_load_dwordx4 v[164:167], v[164:165], off offset:384
	ds_read_b128 v[208:211], v130 offset:4640
	s_waitcnt lgkmcnt(4)
	v_mfma_f32_32x32x16_bf16 v[114:129], v[204:207], v[232:235], v[114:129]
	ds_read_b128 v[200:203], v130 offset:64
	ds_read_b128 v[212:215], v133 offset:18496
	s_waitcnt lgkmcnt(5)
	v_mfma_f32_32x32x16_bf16 v[98:113], v[204:207], v[236:239], v[98:113]
	ds_read_b128 v[216:219], v133 offset:23104
	s_waitcnt lgkmcnt(5)
	v_mfma_f32_32x32x16_bf16 v[82:97], v[204:207], v[240:243], v[82:97]
	ds_read_b128 v[224:227], v133 offset:27712
	s_waitcnt lgkmcnt(5)
	v_mfma_f32_32x32x16_bf16 v[66:81], v[204:207], v[244:247], v[66:81]
	ds_read_b128 v[228:231], v133 offset:32320
	s_waitcnt lgkmcnt(5)
	v_mfma_f32_32x32x16_bf16 v[50:65], v[208:211], v[232:235], v[50:65]
	v_lshl_add_u64 v[168:169], v[148:149], 0, s[18:19]
	v_add_co_u32_e32 v168, vcc, s43, v168
	s_nop 1
	v_addc_co_u32_e32 v169, vcc, 0, v169, vcc
	global_load_dwordx4 v[168:171], v[168:169], off offset:128
	v_mfma_f32_32x32x16_bf16 v[34:49], v[208:211], v[236:239], v[34:49]
	v_lshl_add_u64 v[172:173], v[148:149], 0, s[18:19]
	v_add_co_u32_e32 v172, vcc, s44, v172
	s_nop 1
	v_addc_co_u32_e32 v173, vcc, 0, v173, vcc
	global_load_dwordx4 v[172:175], v[172:173], off offset:128
	v_mfma_f32_32x32x16_bf16 v[18:33], v[208:211], v[240:243], v[18:33]
	v_lshl_add_u64 v[176:177], v[148:149], 0, s[18:19]
	v_add_co_u32_e32 v176, vcc, s45, v176
	s_nop 1
	v_addc_co_u32_e32 v177, vcc, 0, v177, vcc
	global_load_dwordx4 v[176:179], v[176:177], off offset:128
	v_mfma_f32_32x32x16_bf16 v[2:17], v[208:211], v[244:247], v[2:17]
	v_lshl_add_u64 v[180:181], v[148:149], 0, s[18:19]
	v_add_co_u32_e32 v180, vcc, s46, v180
	s_nop 1
	v_addc_co_u32_e32 v181, vcc, 0, v181, vcc
	global_load_dwordx4 v[180:183], v[180:181], off offset:128
	ds_read_b128 v[208:211], v130 offset:4672
	s_waitcnt lgkmcnt(4)
	v_mfma_f32_32x32x16_bf16 v[114:129], v[200:203], v[212:215], v[114:129]
	ds_read_b128 v[204:207], v130 offset:96
	ds_read_b128 v[232:235], v133 offset:18528
	s_waitcnt lgkmcnt(5)
	v_mfma_f32_32x32x16_bf16 v[98:113], v[200:203], v[216:219], v[98:113]
	ds_read_b128 v[236:239], v133 offset:23136
	s_waitcnt lgkmcnt(5)
	v_mfma_f32_32x32x16_bf16 v[82:97], v[200:203], v[224:227], v[82:97]
	ds_read_b128 v[240:243], v133 offset:27744
	s_waitcnt lgkmcnt(5)
	v_mfma_f32_32x32x16_bf16 v[66:81], v[200:203], v[228:231], v[66:81]
	ds_read_b128 v[244:247], v133 offset:32352
	s_waitcnt lgkmcnt(5)
	v_mfma_f32_32x32x16_bf16 v[50:65], v[208:211], v[212:215], v[50:65]
	v_lshl_add_u64 v[184:185], v[148:149], 0, s[18:19]
	v_add_co_u32_e32 v184, vcc, s47, v184
	s_nop 1
	v_addc_co_u32_e32 v185, vcc, 0, v185, vcc
	global_load_dwordx4 v[184:187], v[184:185], off offset:128
	v_mfma_f32_32x32x16_bf16 v[34:49], v[208:211], v[216:219], v[34:49]
	v_lshl_add_u64 v[188:189], v[148:149], 0, s[18:19]
	v_add_co_u32_e32 v188, vcc, s48, v188
	s_nop 1
	v_addc_co_u32_e32 v189, vcc, 0, v189, vcc
	global_load_dwordx4 v[188:191], v[188:189], off offset:128
	v_mfma_f32_32x32x16_bf16 v[18:33], v[208:211], v[224:227], v[18:33]
	v_lshl_add_u64 v[192:193], v[148:149], 0, s[18:19]
	v_add_co_u32_e32 v192, vcc, s49, v192
	s_nop 1
	v_addc_co_u32_e32 v193, vcc, 0, v193, vcc
	global_load_dwordx4 v[192:195], v[192:193], off offset:128
	v_mfma_f32_32x32x16_bf16 v[2:17], v[208:211], v[228:231], v[2:17]
	v_lshl_add_u64 v[196:197], v[148:149], 0, s[18:19]
	v_add_co_u32_e32 v196, vcc, s50, v196
	s_nop 1
	v_addc_co_u32_e32 v197, vcc, 0, v197, vcc
	global_load_dwordx4 v[196:199], v[196:197], off offset:128
	ds_read_b128 v[208:211], v130 offset:4704
	s_waitcnt lgkmcnt(4)
	v_mfma_f32_32x32x16_bf16 v[114:129], v[204:207], v[232:235], v[114:129]
	s_waitcnt lgkmcnt(3)
	v_mfma_f32_32x32x16_bf16 v[98:113], v[204:207], v[236:239], v[98:113]
	s_waitcnt lgkmcnt(2)
	v_mfma_f32_32x32x16_bf16 v[82:97], v[204:207], v[240:243], v[82:97]
	s_waitcnt lgkmcnt(1)
	v_mfma_f32_32x32x16_bf16 v[66:81], v[204:207], v[244:247], v[66:81]
	s_waitcnt lgkmcnt(0)
	v_mfma_f32_32x32x16_bf16 v[50:65], v[208:211], v[232:235], v[50:65]
	v_mfma_f32_32x32x16_bf16 v[34:49], v[208:211], v[236:239], v[34:49]
	v_mfma_f32_32x32x16_bf16 v[18:33], v[208:211], v[240:243], v[18:33]
	v_mfma_f32_32x32x16_bf16 v[2:17], v[208:211], v[244:247], v[2:17]
	s_setprio 0
	s_add_u32 s18, s18, 0x80
	s_addc_u32 s19, s19, 0
	s_cmpk_lg_i32 s18, 0x700
	s_barrier
;     ...
;   for (int kt = 0; kt < nk; ++kt) {
;     const int kn = (kt + 1 < nk) ? kt + 1 : kt;
;     GW_LOAD2(kn * 64, kn * bkstep)
;     __builtin_amdgcn_sched_barrier(0);
;     __builtin_amdgcn_s_setprio(1);
; #pragma unroll
;     for (int st = 0; st < 4; ++st) {
;       bf16x8 a0 = *(const bf16x8*)(Ab + st * 32);
;       bf16x8 a1 = *(const bf16x8*)(Ab + 32 * LSTR + st * 32);
;       bf16x8 b0 = *(const bf16x8*)(Bb + st * 32);
;       bf16x8 b1 = *(const bf16x8*)(Bb + 32 * LSTR + st * 32);
;       bf16x8 b2 = *(const bf16x8*)(Bb + 64 * LSTR + st * 32);
;       bf16x8 b3 = *(const bf16x8*)(Bb + 96 * LSTR + st * 32);
;       acc[0][0] = mfma32(a0, b0, acc[0][0]);
;       acc[0][1] = mfma32(a0, b1, acc[0][1]);
;       acc[0][2] = mfma32(a0, b2, acc[0][2]);
;       acc[0][3] = mfma32(a0, b3, acc[0][3]);
;       acc[1][0] = mfma32(a1, b0, acc[1][0]);
;       acc[1][1] = mfma32(a1, b1, acc[1][1]);
;       acc[1][2] = mfma32(a1, b2, acc[1][2]);
;       acc[1][3] = mfma32(a1, b3, acc[1][3]);
;     }
;     __builtin_amdgcn_s_setprio(0);
;     __builtin_amdgcn_sched_barrier(0);
;     __syncthreads();
;     GW_STORE()
;     __syncthreads();
	s_waitcnt vmcnt(11)
	ds_write_b128 v132, v[152:155]
	s_waitcnt vmcnt(10)
	ds_write_b128 v132, v[156:159] offset:4608
	s_waitcnt vmcnt(9)
	ds_write_b128 v132, v[160:163] offset:9216
	s_waitcnt vmcnt(8)
	ds_write_b128 v132, v[164:167] offset:13824
	s_waitcnt vmcnt(7)
	ds_write_b128 v132, v[168:171] offset:18432
	s_waitcnt vmcnt(6)
	ds_write_b128 v132, v[172:175] offset:23040
	s_waitcnt vmcnt(5)
	ds_write_b128 v132, v[176:179] offset:27648
	s_waitcnt vmcnt(4)
	ds_write_b128 v132, v[180:183] offset:32256
	s_waitcnt vmcnt(3)
	ds_write_b128 v132, v[184:187] offset:36864
	s_waitcnt vmcnt(2)
	ds_write_b128 v132, v[188:191] offset:41472
	s_waitcnt vmcnt(1)
	ds_write_b128 v132, v[192:195] offset:46080
	s_waitcnt vmcnt(0)
	ds_write_b128 v132, v[196:199] offset:50688
	s_waitcnt lgkmcnt(0)
	s_cbranch_scc1 .LBB0_707
	s_barrier
	s_setprio 1
	ds_read_b128 v[200:203], v130 offset:0
	ds_read_b128 v[212:215], v133 offset:18432
	ds_read_b128 v[216:219], v133 offset:23040
	ds_read_b128 v[224:227], v133 offset:27648
	ds_read_b128 v[228:231], v133 offset:32256
	ds_read_b128 v[208:211], v130 offset:4608
	s_waitcnt lgkmcnt(4)
	v_mfma_f32_32x32x16_bf16 v[114:129], v[200:203], v[212:215], v[114:129]
	ds_read_b128 v[204:207], v130 offset:32
	ds_read_b128 v[232:235], v133 offset:18464
	s_waitcnt lgkmcnt(5)
	v_mfma_f32_32x32x16_bf16 v[98:113], v[200:203], v[216:219], v[98:113]
	ds_read_b128 v[236:239], v133 offset:23072
	s_waitcnt lgkmcnt(5)
	v_mfma_f32_32x32x16_bf16 v[82:97], v[200:203], v[224:227], v[82:97]
	ds_read_b128 v[240:243], v133 offset:27680
	s_waitcnt lgkmcnt(5)
	v_mfma_f32_32x32x16_bf16 v[66:81], v[200:203], v[228:231], v[66:81]
	ds_read_b128 v[244:247], v133 offset:32288
	s_waitcnt lgkmcnt(5)
	v_mfma_f32_32x32x16_bf16 v[50:65], v[208:211], v[212:215], v[50:65]
	v_lshl_add_u64 v[152:153], v[146:147], 0, s[18:19]
	v_add_co_u32_e32 v152, vcc, s39, v152
	s_nop 1
	v_addc_co_u32_e32 v153, vcc, 0, v153, vcc
	global_load_dwordx4 v[152:155], v[152:153], off offset:384
	v_mfma_f32_32x32x16_bf16 v[34:49], v[208:211], v[216:219], v[34:49]
	v_lshl_add_u64 v[156:157], v[146:147], 0, s[18:19]
	v_add_co_u32_e32 v156, vcc, s40, v156
	s_nop 1
	v_addc_co_u32_e32 v157, vcc, 0, v157, vcc
	global_load_dwordx4 v[156:159], v[156:157], off offset:384
	v_mfma_f32_32x32x16_bf16 v[18:33], v[208:211], v[224:227], v[18:33]
	v_lshl_add_u64 v[160:161], v[146:147], 0, s[18:19]
	v_add_co_u32_e32 v160, vcc, s41, v160
	s_nop 1
	v_addc_co_u32_e32 v161, vcc, 0, v161, vcc
	global_load_dwordx4 v[160:163], v[160:161], off offset:384
	v_mfma_f32_32x32x16_bf16 v[2:17], v[208:211], v[228:231], v[2:17]
	v_lshl_add_u64 v[164:165], v[146:147], 0, s[18:19]
	v_add_co_u32_e32 v164, vcc, s42, v164
	s_nop 1
	v_addc_co_u32_e32 v165, vcc, 0, v165, vcc
	global_load_dwordx4 v[164:167], v[164:165], off offset:384
	ds_read_b128 v[208:211], v130 offset:4640
	s_waitcnt lgkmcnt(4)
	v_mfma_f32_32x32x16_bf16 v[114:129], v[204:207], v[232:235], v[114:129]
	ds_read_b128 v[200:203], v130 offset:64
	ds_read_b128 v[212:215], v133 offset:18496
	s_waitcnt lgkmcnt(5)
	v_mfma_f32_32x32x16_bf16 v[98:113], v[204:207], v[236:239], v[98:113]
	ds_read_b128 v[216:219], v133 offset:23104
	s_waitcnt lgkmcnt(5)
	v_mfma_f32_32x32x16_bf16 v[82:97], v[204:207], v[240:243], v[82:97]
	ds_read_b128 v[224:227], v133 offset:27712
	s_waitcnt lgkmcnt(5)
	v_mfma_f32_32x32x16_bf16 v[66:81], v[204:207], v[244:247], v[66:81]
	ds_read_b128 v[228:231], v133 offset:32320
	s_waitcnt lgkmcnt(5)
	v_mfma_f32_32x32x16_bf16 v[50:65], v[208:211], v[232:235], v[50:65]
	v_lshl_add_u64 v[168:169], v[148:149], 0, s[18:19]
	v_add_co_u32_e32 v168, vcc, s43, v168
	s_nop 1
	v_addc_co_u32_e32 v169, vcc, 0, v169, vcc
	global_load_dwordx4 v[168:171], v[168:169], off offset:128
	v_mfma_f32_32x32x16_bf16 v[34:49], v[208:211], v[236:239], v[34:49]
	v_lshl_add_u64 v[172:173], v[148:149], 0, s[18:19]
	v_add_co_u32_e32 v172, vcc, s44, v172
	s_nop 1
	v_addc_co_u32_e32 v173, vcc, 0, v173, vcc
	global_load_dwordx4 v[172:175], v[172:173], off offset:128
	v_mfma_f32_32x32x16_bf16 v[18:33], v[208:211], v[240:243], v[18:33]
	v_lshl_add_u64 v[176:177], v[148:149], 0, s[18:19]
	v_add_co_u32_e32 v176, vcc, s45, v176
	s_nop 1
	v_addc_co_u32_e32 v177, vcc, 0, v177, vcc
	global_load_dwordx4 v[176:179], v[176:177], off offset:128
	v_mfma_f32_32x32x16_bf16 v[2:17], v[208:211], v[244:247], v[2:17]
	v_lshl_add_u64 v[180:181], v[148:149], 0, s[18:19]
	v_add_co_u32_e32 v180, vcc, s46, v180
	s_nop 1
	v_addc_co_u32_e32 v181, vcc, 0, v181, vcc
	global_load_dwordx4 v[180:183], v[180:181], off offset:128
	ds_read_b128 v[208:211], v130 offset:4672
	s_waitcnt lgkmcnt(4)
	v_mfma_f32_32x32x16_bf16 v[114:129], v[200:203], v[212:215], v[114:129]
	ds_read_b128 v[204:207], v130 offset:96
	ds_read_b128 v[232:235], v133 offset:18528
	s_waitcnt lgkmcnt(5)
	v_mfma_f32_32x32x16_bf16 v[98:113], v[200:203], v[216:219], v[98:113]
	ds_read_b128 v[236:239], v133 offset:23136
	s_waitcnt lgkmcnt(5)
	v_mfma_f32_32x32x16_bf16 v[82:97], v[200:203], v[224:227], v[82:97]
	ds_read_b128 v[240:243], v133 offset:27744
	s_waitcnt lgkmcnt(5)
	v_mfma_f32_32x32x16_bf16 v[66:81], v[200:203], v[228:231], v[66:81]
	ds_read_b128 v[244:247], v133 offset:32352
	s_waitcnt lgkmcnt(5)
;     ...
;     for (int st = 0; st < 4; ++st) {
;       bf16x8 a0 = *(const bf16x8*)(Ab + st * 32);
;       bf16x8 a1 = *(const bf16x8*)(Ab + 32 * LSTR + st * 32);
;       bf16x8 b0 = *(const bf16x8*)(Bb + st * 32);
;       bf16x8 b1 = *(const bf16x8*)(Bb + 32 * LSTR + st * 32);
;       bf16x8 b2 = *(const bf16x8*)(Bb + 64 * LSTR + st * 32);
;       bf16x8 b3 = *(const bf16x8*)(Bb + 96 * LSTR + st * 32);
;       acc[0][0] = mfma32(a0, b0, acc[0][0]);
;       acc[0][1] = mfma32(a0, b1, acc[0][1]);
;       acc[0][2] = mfma32(a0, b2, acc[0][2]);
;       acc[0][3] = mfma32(a0, b3, acc[0][3]);
;       acc[1][0] = mfma32(a1, b0, acc[1][0]);
;       acc[1][1] = mfma32(a1, b1, acc[1][1]);
;       acc[1][2] = mfma32(a1, b2, acc[1][2]);
;       acc[1][3] = mfma32(a1, b3, acc[1][3]);
;     }
;     __builtin_amdgcn_s_setprio(0);
;     __builtin_amdgcn_sched_barrier(0);
;     __syncthreads();
;     GW_STORE()
;     __syncthreads();
	v_mfma_f32_32x32x16_bf16 v[50:65], v[208:211], v[212:215], v[50:65]
	v_lshl_add_u64 v[184:185], v[148:149], 0, s[18:19]
	v_add_co_u32_e32 v184, vcc, s47, v184
	s_nop 1
	v_addc_co_u32_e32 v185, vcc, 0, v185, vcc
	global_load_dwordx4 v[184:187], v[184:185], off offset:128
	v_mfma_f32_32x32x16_bf16 v[34:49], v[208:211], v[216:219], v[34:49]
	v_lshl_add_u64 v[188:189], v[148:149], 0, s[18:19]
	v_add_co_u32_e32 v188, vcc, s48, v188
	s_nop 1
	v_addc_co_u32_e32 v189, vcc, 0, v189, vcc
	global_load_dwordx4 v[188:191], v[188:189], off offset:128
	v_mfma_f32_32x32x16_bf16 v[18:33], v[208:211], v[224:227], v[18:33]
	v_lshl_add_u64 v[192:193], v[148:149], 0, s[18:19]
	v_add_co_u32_e32 v192, vcc, s49, v192
	s_nop 1
	v_addc_co_u32_e32 v193, vcc, 0, v193, vcc
	global_load_dwordx4 v[192:195], v[192:193], off offset:128
	v_mfma_f32_32x32x16_bf16 v[2:17], v[208:211], v[228:231], v[2:17]
	v_lshl_add_u64 v[196:197], v[148:149], 0, s[18:19]
	v_add_co_u32_e32 v196, vcc, s50, v196
	s_nop 1
	v_addc_co_u32_e32 v197, vcc, 0, v197, vcc
	global_load_dwordx4 v[196:199], v[196:197], off offset:128
	ds_read_b128 v[208:211], v130 offset:4704
	s_waitcnt lgkmcnt(4)
	v_mfma_f32_32x32x16_bf16 v[114:129], v[204:207], v[232:235], v[114:129]
	s_waitcnt lgkmcnt(3)
	v_mfma_f32_32x32x16_bf16 v[98:113], v[204:207], v[236:239], v[98:113]
	s_waitcnt lgkmcnt(2)
	v_mfma_f32_32x32x16_bf16 v[82:97], v[204:207], v[240:243], v[82:97]
	s_waitcnt lgkmcnt(1)
	v_mfma_f32_32x32x16_bf16 v[66:81], v[204:207], v[244:247], v[66:81]
	s_waitcnt lgkmcnt(0)
	v_mfma_f32_32x32x16_bf16 v[50:65], v[208:211], v[232:235], v[50:65]
	v_mfma_f32_32x32x16_bf16 v[34:49], v[208:211], v[236:239], v[34:49]
	v_mfma_f32_32x32x16_bf16 v[18:33], v[208:211], v[240:243], v[18:33]
	v_mfma_f32_32x32x16_bf16 v[2:17], v[208:211], v[244:247], v[2:17]
	s_setprio 0
	s_add_u32 s18, s18, 0x80
	s_addc_u32 s19, s19, 0
	s_barrier
	s_waitcnt vmcnt(11)
	ds_write_b128 v132, v[152:155]
	s_waitcnt vmcnt(10)
	ds_write_b128 v132, v[156:159] offset:4608
	s_waitcnt vmcnt(9)
	ds_write_b128 v132, v[160:163] offset:9216
	s_waitcnt vmcnt(8)
	ds_write_b128 v132, v[164:167] offset:13824
	s_waitcnt vmcnt(7)
	ds_write_b128 v132, v[168:171] offset:18432
	s_waitcnt vmcnt(6)
	ds_write_b128 v132, v[172:175] offset:23040
	s_waitcnt vmcnt(5)
	ds_write_b128 v132, v[176:179] offset:27648
	s_waitcnt vmcnt(4)
	ds_write_b128 v132, v[180:183] offset:32256
	s_waitcnt vmcnt(3)
	ds_write_b128 v132, v[184:187] offset:36864
	s_waitcnt vmcnt(2)
	ds_write_b128 v132, v[188:191] offset:41472
	s_waitcnt vmcnt(1)
	ds_write_b128 v132, v[192:195] offset:46080
	s_waitcnt vmcnt(0)
	ds_write_b128 v132, v[196:199] offset:50688
	s_waitcnt lgkmcnt(0)
	s_barrier
;     ...
;   for (int kt = 0; kt < nk; ++kt) {
;     const int kn = (kt + 1 < nk) ? kt + 1 : kt;
;     GW_LOAD2(kn * 64, kn * bkstep)
;     __builtin_amdgcn_sched_barrier(0);
;     __builtin_amdgcn_s_setprio(1);
; #pragma unroll
;     for (int st = 0; st < 4; ++st) {
;       bf16x8 a0 = *(const bf16x8*)(Ab + st * 32);
;       bf16x8 a1 = *(const bf16x8*)(Ab + 32 * LSTR + st * 32);
;       bf16x8 b0 = *(const bf16x8*)(Bb + st * 32);
;       bf16x8 b1 = *(const bf16x8*)(Bb + 32 * LSTR + st * 32);
;       bf16x8 b2 = *(const bf16x8*)(Bb + 64 * LSTR + st * 32);
;       bf16x8 b3 = *(const bf16x8*)(Bb + 96 * LSTR + st * 32);
;       acc[0][0] = mfma32(a0, b0, acc[0][0]);
;       acc[0][1] = mfma32(a0, b1, acc[0][1]);
;       acc[0][2] = mfma32(a0, b2, acc[0][2]);
;       acc[0][3] = mfma32(a0, b3, acc[0][3]);
;       acc[1][0] = mfma32(a1, b0, acc[1][0]);
;       acc[1][1] = mfma32(a1, b1, acc[1][1]);
;       acc[1][2] = mfma32(a1, b2, acc[1][2]);
;       acc[1][3] = mfma32(a1, b3, acc[1][3]);
;     }
;     __builtin_amdgcn_s_setprio(0);
;     __builtin_amdgcn_sched_barrier(0);
	v_add_co_u32_e32 v160, vcc, 0x10000, v136
	s_nop 0
	s_nop 0
	s_nop 0
	v_addc_co_u32_e32 v161, vcc, 0, v137, vcc
	v_add_co_u32_e32 v164, vcc, 0x20000, v136
	s_nop 0
	v_addc_co_u32_e32 v165, vcc, 0, v137, vcc
	v_add_co_u32_e32 v168, vcc, 0x30000, v136
	s_lshl_b64 s[16:17], s[16:17], 7
	s_nop 0
	v_addc_co_u32_e32 v169, vcc, 0, v137, vcc
	v_add_co_u32_e32 v172, vcc, 0x40000, v136
	s_nop 0
	v_addc_co_u32_e32 v173, vcc, 0, v137, vcc
	v_add_co_u32_e32 v176, vcc, 0x50000, v136
	s_mov_b32 s15, 0
	s_nop 0
	v_addc_co_u32_e32 v177, vcc, 0, v137, vcc
	v_add_co_u32_e32 v180, vcc, 0x60000, v136
	s_nop 0
	v_addc_co_u32_e32 v181, vcc, 0, v137, vcc
	v_add_co_u32_e32 v136, vcc, 0x70000, v136
	s_nop 1
	v_addc_co_u32_e32 v137, vcc, 0, v137, vcc
	s_nop 0
	s_setprio 1
	ds_read_b128 v[188:191], v130 offset:0
	ds_read_b128 v[200:203], v133 offset:18432
	ds_read_b128 v[204:207], v133 offset:23040
	ds_read_b128 v[208:211], v133 offset:27648
	ds_read_b128 v[212:215], v133 offset:32256
	ds_read_b128 v[196:199], v130 offset:4608
	s_waitcnt lgkmcnt(4)
	v_mfma_f32_32x32x16_bf16 v[114:129], v[188:191], v[200:203], v[114:129]
	ds_read_b128 v[192:195], v130 offset:32
	ds_read_b128 v[216:219], v133 offset:18464
	s_waitcnt lgkmcnt(5)
	v_mfma_f32_32x32x16_bf16 v[98:113], v[188:191], v[204:207], v[98:113]
	ds_read_b128 v[224:227], v133 offset:23072
	s_waitcnt lgkmcnt(5)
	v_mfma_f32_32x32x16_bf16 v[82:97], v[188:191], v[208:211], v[82:97]
	ds_read_b128 v[228:231], v133 offset:27680
	s_waitcnt lgkmcnt(5)
	v_mfma_f32_32x32x16_bf16 v[66:81], v[188:191], v[212:215], v[66:81]
	ds_read_b128 v[232:235], v133 offset:32288
	s_waitcnt lgkmcnt(5)
	v_mfma_f32_32x32x16_bf16 v[50:65], v[196:199], v[200:203], v[50:65]
	v_mfma_f32_32x32x16_bf16 v[34:49], v[196:199], v[204:207], v[34:49]
	v_mfma_f32_32x32x16_bf16 v[18:33], v[196:199], v[208:211], v[18:33]
	v_mfma_f32_32x32x16_bf16 v[2:17], v[196:199], v[212:215], v[2:17]
	ds_read_b128 v[196:199], v130 offset:4640
	s_waitcnt lgkmcnt(4)
	v_mfma_f32_32x32x16_bf16 v[114:129], v[192:195], v[216:219], v[114:129]
	ds_read_b128 v[188:191], v130 offset:64
	ds_read_b128 v[200:203], v133 offset:18496
	s_waitcnt lgkmcnt(5)
	v_mfma_f32_32x32x16_bf16 v[98:113], v[192:195], v[224:227], v[98:113]
	ds_read_b128 v[204:207], v133 offset:23104
	s_waitcnt lgkmcnt(5)
	v_mfma_f32_32x32x16_bf16 v[82:97], v[192:195], v[228:231], v[82:97]
	ds_read_b128 v[208:211], v133 offset:27712
	s_waitcnt lgkmcnt(5)
	v_mfma_f32_32x32x16_bf16 v[66:81], v[192:195], v[232:235], v[66:81]
	ds_read_b128 v[212:215], v133 offset:32320
	s_waitcnt lgkmcnt(5)
	v_mfma_f32_32x32x16_bf16 v[50:65], v[196:199], v[216:219], v[50:65]
	v_mfma_f32_32x32x16_bf16 v[34:49], v[196:199], v[224:227], v[34:49]
	v_mfma_f32_32x32x16_bf16 v[18:33], v[196:199], v[228:231], v[18:33]
	v_mfma_f32_32x32x16_bf16 v[2:17], v[196:199], v[232:235], v[2:17]
	ds_read_b128 v[196:199], v130 offset:4672
	s_waitcnt lgkmcnt(4)
	v_mfma_f32_32x32x16_bf16 v[114:129], v[188:191], v[200:203], v[114:129]
	ds_read_b128 v[192:195], v130 offset:96
	ds_read_b128 v[216:219], v133 offset:18528
	s_waitcnt lgkmcnt(5)
	v_mfma_f32_32x32x16_bf16 v[98:113], v[188:191], v[204:207], v[98:113]
	ds_read_b128 v[224:227], v133 offset:23136
	s_waitcnt lgkmcnt(5)
	v_mfma_f32_32x32x16_bf16 v[82:97], v[188:191], v[208:211], v[82:97]
	ds_read_b128 v[228:231], v133 offset:27744
	s_waitcnt lgkmcnt(5)
	v_mfma_f32_32x32x16_bf16 v[66:81], v[188:191], v[212:215], v[66:81]
	ds_read_b128 v[232:235], v133 offset:32352
	s_waitcnt lgkmcnt(5)
	v_mfma_f32_32x32x16_bf16 v[50:65], v[196:199], v[200:203], v[50:65]
	v_mfma_f32_32x32x16_bf16 v[34:49], v[196:199], v[204:207], v[34:49]
	v_mfma_f32_32x32x16_bf16 v[18:33], v[196:199], v[208:211], v[18:33]
	v_mfma_f32_32x32x16_bf16 v[2:17], v[196:199], v[212:215], v[2:17]
	ds_read_b128 v[196:199], v130 offset:4704
	s_waitcnt lgkmcnt(4)
	v_mfma_f32_32x32x16_bf16 v[114:129], v[192:195], v[216:219], v[114:129]
	s_waitcnt lgkmcnt(3)
	v_mfma_f32_32x32x16_bf16 v[98:113], v[192:195], v[224:227], v[98:113]
	s_waitcnt lgkmcnt(2)
	v_mfma_f32_32x32x16_bf16 v[82:97], v[192:195], v[228:231], v[82:97]
	s_waitcnt lgkmcnt(1)
	v_mfma_f32_32x32x16_bf16 v[66:81], v[192:195], v[232:235], v[66:81]
	s_waitcnt lgkmcnt(0)
	v_mfma_f32_32x32x16_bf16 v[50:65], v[196:199], v[216:219], v[50:65]
	v_mfma_f32_32x32x16_bf16 v[34:49], v[196:199], v[224:227], v[34:49]
	v_mfma_f32_32x32x16_bf16 v[18:33], v[196:199], v[228:231], v[18:33]
	v_mfma_f32_32x32x16_bf16 v[2:17], v[196:199], v[232:235], v[2:17]
	s_setprio 0
	s_mov_b64 s[18:19], -1
	s_barrier
	s_waitcnt lgkmcnt(0)

; #define GM_LOAD(KOFF) GM_LOAD2(KOFF, 0)
;   const int tid = threadIdx.x, lane = tid & 63, wave = tid >> 6;
;   const int wm = wave >> 1, wn = wave & 1;
;   const int lr = tid >> 3, kc = tid & 7;
;   const u16* ap0 = arow(lr) + kc * 8;
;   const u16* ap1 = arow(lr + 32) + kc * 8;
;   const u16* ap2 = arow(lr + 64) + kc * 8;
;   const u16* ap3 = arow(lr + 96) + kc * 8;
;   const u16* bp0 = Bt + (size_t)lr * ldb + kc * 8;
;   const size_t bstep = 32 * ldb;
;   const int so = lr * LSTR + kc * 16;
;   uint4 ra0, ra1, ra2, ra3, rb0, rb1, rb2, rb3;
;     ...
;   GM_LOAD(0)
;   GM_STORE(smem)
;   __syncthreads();
;   const int nk = K >> 6;
;   const int aoff = (wm * 64 + (lane & 31)) * LSTR + (lane >> 5) * 16;
;   const int boff = (wn * 64 + (lane & 31)) * LSTR + (lane >> 5) * 16;
;   for (int kt = 0; kt < nk; ++kt) {
;     const int kn = (kt + 1 < nk) ? kt + 1 : kt;
;     GM_LOAD2(kn * 64, kn * bkstep)
; __device__ __forceinline__ void zero_acc(f32x16 (&acc)[2][2]) {
; #pragma unroll
;   for (int i = 0; i < 2; ++i)
; #pragma unroll
;     for (int j = 0; j < 2; ++j)
; #pragma unroll
;       for (int r = 0; r < 16; ++r) acc[i][j][r] = 0.f;
.LBB0_721:
	s_ashr_i32 s18, s35, 3
	s_add_i32 s14, s18, 0x100
	s_ashr_i32 s15, s14, 31
	s_lshl_b64 s[16:17], s[14:15], 18
	v_lshl_add_u64 v[2:3], v[68:69], 0, s[16:17]
	v_lshl_add_u64 v[80:81], v[2:3], 0, v[74:75]
	v_add_co_u32_e32 v2, vcc, s21, v80
	s_and_b32 s36, s34, 7
	s_nop 0
	v_addc_co_u32_e32 v3, vcc, 0, v81, vcc
	s_lshl_b32 s2, s36, 18
	v_add_co_u32_e32 v4, vcc, s22, v80
	v_lshl_add_u64 v[78:79], v[72:73], 0, s[2:3]
	s_and_b32 s2, s35, 7
	v_addc_co_u32_e32 v5, vcc, 0, v81, vcc
	s_lshl_b32 s2, s2, 18
	global_load_dwordx4 v[28:31], v[2:3], off
	global_load_dwordx4 v[32:35], v[4:5], off
	v_add_co_u32_e32 v2, vcc, s23, v80
	v_lshl_add_u64 v[76:77], v[70:71], 0, s[2:3]
	s_nop 0
	v_addc_co_u32_e32 v3, vcc, 0, v81, vcc
	v_add_co_u32_e32 v4, vcc, s22, v76
	global_load_dwordx4 v[36:39], v[80:81], off
	global_load_dwordx4 v[40:43], v[76:77], off
	v_addc_co_u32_e32 v5, vcc, 0, v77, vcc
	v_add_co_u32_e32 v6, vcc, s23, v76
	s_ashr_i32 s19, s18, 31
	s_nop 0
	v_addc_co_u32_e32 v7, vcc, 0, v77, vcc
	global_load_dwordx4 v[44:47], v[4:5], off
	global_load_dwordx4 v[48:51], v[6:7], off
	v_add_co_u32_e32 v4, vcc, s21, v76
	s_lshl_b64 s[18:19], s[18:19], 18
	s_nop 0
	v_addc_co_u32_e32 v5, vcc, 0, v77, vcc
	global_load_dwordx4 v[52:55], v[2:3], off
	global_load_dwordx4 v[56:59], v[4:5], off
	s_mov_b64 s[16:17], 0
	s_mov_b32 s2, 0
	v_mov_b32_e32 v2, 0
	v_mov_b32_e32 v3, v67
	v_mov_b32_e32 v4, v67
	v_mov_b32_e32 v5, v67
	v_mov_b32_e32 v6, v67
	v_mov_b32_e32 v7, v67
	v_mov_b32_e32 v8, v67
	v_mov_b32_e32 v9, v67
	v_mov_b32_e32 v10, v67
	v_mov_b32_e32 v11, v67
	v_mov_b32_e32 v12, v67
	v_mov_b32_e32 v13, v67
	v_mov_b32_e32 v14, v67
	v_mov_b32_e32 v15, v67
	v_mov_b32_e32 v16, v67
	v_mov_b32_e32 v17, v67
	v_mov_b32_e32 v18, 0
	v_mov_b32_e32 v19, v67
	v_mov_b32_e32 v20, v67
	v_mov_b32_e32 v21, v67
	v_mov_b32_e32 v22, v67
	v_mov_b32_e32 v23, v67
	v_mov_b32_e32 v24, v67
	v_mov_b32_e32 v25, v67
	v_mov_b32_e32 v26, v67
	v_lshl_add_u64 v[88:89], v[72:73], 0, s[18:19]
	v_lshl_add_u64 v[82:83], v[80:81], 0, s[4:5]
	v_lshl_add_u64 v[84:85], v[80:81], 0, s[6:7]
	v_lshl_add_u64 v[86:87], v[80:81], 0, s[8:9]
	v_mov_b32_e32 v27, v67
	v_mov_b32_e32 v60, v67
	v_mov_b32_e32 v61, v67
	v_mov_b32_e32 v62, v67
	v_mov_b32_e32 v63, v67
	v_mov_b32_e32 v64, v67
	v_mov_b32_e32 v65, v67
	s_waitcnt vmcnt(3)
	ds_write_b128 v1, v[44:47] offset:27648
	s_waitcnt vmcnt(2)
	ds_write_b128 v1, v[48:51] offset:32256
	ds_write_b128 v1, v[36:39]
	ds_write_b128 v1, v[40:43] offset:18432
	ds_write_b128 v1, v[28:31] offset:4608
	ds_write_b128 v1, v[32:35] offset:9216
	s_waitcnt vmcnt(1)
	ds_write_b128 v1, v[52:55] offset:13824
	s_waitcnt vmcnt(0)
	ds_write_b128 v1, v[56:59] offset:23040
	v_mov_b32_e32 v28, v67
	v_mov_b32_e32 v29, v67
	v_mov_b32_e32 v30, v67
	v_mov_b32_e32 v31, v67
	v_mov_b32_e32 v32, v67
	v_mov_b32_e32 v33, v67
	v_mov_b32_e32 v34, 0
	v_mov_b32_e32 v35, v67
	v_mov_b32_e32 v36, v67
	v_mov_b32_e32 v37, v67
	v_mov_b32_e32 v38, v67
	v_mov_b32_e32 v39, v67
	v_mov_b32_e32 v40, v67
	v_mov_b32_e32 v41, v67
	v_mov_b32_e32 v42, v67
	v_mov_b32_e32 v43, v67
	v_mov_b32_e32 v44, v67
	v_mov_b32_e32 v45, v67
	v_mov_b32_e32 v46, v67
	v_mov_b32_e32 v47, v67
	v_mov_b32_e32 v48, v67
	v_mov_b32_e32 v49, v67
	v_mov_b32_e32 v50, 0
	v_mov_b32_e32 v51, v67
	v_mov_b32_e32 v52, v67
	v_mov_b32_e32 v53, v67
	v_mov_b32_e32 v54, v67
	v_mov_b32_e32 v55, v67
	v_mov_b32_e32 v56, v67
	v_mov_b32_e32 v57, v67
	v_mov_b32_e32 v58, v67
	v_mov_b32_e32 v59, v67
	s_waitcnt lgkmcnt(0)
	v_lshl_add_u64 v[104:105], v[88:89], 0, s[16:17]
	v_add_co_u32_e32 v96, vcc, s24, v104
	v_lshl_add_u64 v[120:121], v[78:79], 0, s[16:17]
	s_nop 0
	v_addc_co_u32_e32 v97, vcc, 0, v105, vcc
	v_add_co_u32_e32 v100, vcc, s25, v104
	s_nop 1
	v_addc_co_u32_e32 v101, vcc, 0, v105, vcc
	v_add_co_u32_e32 v106, vcc, s26, v104
	global_load_dwordx4 v[96:99], v[96:97], off offset:384
	s_nop 0
	global_load_dwordx4 v[100:103], v[100:101], off offset:384
	v_addc_co_u32_e32 v107, vcc, 0, v105, vcc
	v_add_co_u32_e32 v108, vcc, s27, v104
	s_nop 1
	v_addc_co_u32_e32 v109, vcc, 0, v105, vcc
	v_add_co_u32_e32 v112, vcc, s28, v120
	global_load_dwordx4 v[104:107], v[106:107], off offset:384
	s_nop 0
	global_load_dwordx4 v[108:111], v[108:109], off offset:384
	v_addc_co_u32_e32 v113, vcc, 0, v121, vcc
	v_add_co_u32_e32 v116, vcc, s29, v120
	s_nop 1
	v_addc_co_u32_e32 v117, vcc, 0, v121, vcc
	v_add_co_u32_e32 v122, vcc, s30, v120
	global_load_dwordx4 v[112:115], v[112:113], off offset:128
	s_nop 0
	global_load_dwordx4 v[116:119], v[116:117], off offset:128
	v_addc_co_u32_e32 v123, vcc, 0, v121, vcc
	v_add_co_u32_e32 v124, vcc, s31, v120
	s_nop 1
	v_addc_co_u32_e32 v125, vcc, 0, v121, vcc
	global_load_dwordx4 v[120:123], v[122:123], off offset:128
	s_nop 0
	global_load_dwordx4 v[124:127], v[124:125], off offset:128
;     ...
;   for (int kt = 0; kt < nk; ++kt) {
;     const int kn = (kt + 1 < nk) ? kt + 1 : kt;
;     GM_LOAD2(kn * 64, kn * bkstep)
;     __builtin_amdgcn_sched_barrier(0);
;     const char* As = smem + (kt & 1) * 2 * TILE_B;
;     const char* Bs = As + TILE_B;
;     if constexpr (HOIST) {
;       bf16x8 fa0[4], fa1[4], fb0[4], fb1[4];
; #pragma unroll
;       for (int st = 0; st < 4; ++st) {
;         fa0[st] = *(const bf16x8*)(As + aoff + st * 32);
;         fb0[st] = *(const bf16x8*)(Bs + boff + st * 32);
;         fa1[st] = *(const bf16x8*)(As + aoff + 32 * LSTR + st * 32);
;         fb1[st] = *(const bf16x8*)(Bs + boff + 32 * LSTR + st * 32);
;       }
;       __builtin_amdgcn_sched_barrier(0);
; #pragma unroll
;       for (int st = 0; st < 4; ++st) {
;         acc[0][0] = mfma32(fa0[st], fb0[st], acc[0][0]);
;         acc[0][1] = mfma32(fa0[st], fb1[st], acc[0][1]);
;         acc[1][0] = mfma32(fa1[st], fb0[st], acc[1][0]);
;         acc[1][1] = mfma32(fa1[st], fb1[st], acc[1][1]);
;       }
;     } else {
; #pragma unroll
;       for (int st = 0; st < 4; ++st) {
;         bf16x8 a0 = *(const bf16x8*)(As + aoff + st * 32);
;         bf16x8 a1 = *(const bf16x8*)(As + aoff + 32 * LSTR + st * 32);
;         bf16x8 b0 = *(const bf16x8*)(Bs + boff + st * 32);
;         bf16x8 b1 = *(const bf16x8*)(Bs + boff + 32 * LSTR + st * 32);
;         acc[0][0] = mfma32(a0, b0, acc[0][0]);
;         acc[0][1] = mfma32(a0, b1, acc[0][1]);
;         acc[1][0] = mfma32(a1, b0, acc[1][0]);
;         acc[1][1] = mfma32(a1, b1, acc[1][1]);
;       }
;     }
;     __builtin_amdgcn_sched_barrier(0);
;     {
;       char* Ad = smem + ((kt + 1) & 1) * 2 * TILE_B;
;       GM_STORE(Ad)
;     }
;     __syncthreads();
.LBB0_722:
	s_barrier
	s_and_b32 s18, s2, 2
	s_mulk_i32 s18, 0x4800
	v_add3_u32 v66, s18, v90, v91
	v_add3_u32 v95, s18, v92, v91
	ds_read_b128 v[128:131], v66 offset:0
	ds_read_b128 v[136:139], v95 offset:18432
	ds_read_b128 v[144:147], v66 offset:4608
	ds_read_b128 v[140:143], v95 offset:23040
	s_waitcnt lgkmcnt(2)
	v_mfma_f32_32x32x16_bf16 v[50:65], v[128:131], v[136:139], v[50:65]
	ds_read_b128 v[148:151], v66 offset:32
	s_waitcnt lgkmcnt(2)
	v_mfma_f32_32x32x16_bf16 v[18:33], v[144:147], v[136:139], v[18:33]
	ds_read_b128 v[136:139], v95 offset:18464
	s_waitcnt lgkmcnt(2)
	v_mfma_f32_32x32x16_bf16 v[34:49], v[128:131], v[140:143], v[34:49]
	ds_read_b128 v[128:131], v66 offset:4640
	v_mfma_f32_32x32x16_bf16 v[2:17], v[144:147], v[140:143], v[2:17]
	ds_read_b128 v[140:143], v95 offset:23072
	s_waitcnt lgkmcnt(2)
	v_mfma_f32_32x32x16_bf16 v[50:65], v[148:151], v[136:139], v[50:65]
	ds_read_b128 v[144:147], v66 offset:64
	s_waitcnt lgkmcnt(2)
	v_mfma_f32_32x32x16_bf16 v[18:33], v[128:131], v[136:139], v[18:33]
	ds_read_b128 v[136:139], v95 offset:18496
	s_waitcnt lgkmcnt(2)
	v_mfma_f32_32x32x16_bf16 v[34:49], v[148:151], v[140:143], v[34:49]
	ds_read_b128 v[148:151], v66 offset:4672
	v_mfma_f32_32x32x16_bf16 v[2:17], v[128:131], v[140:143], v[2:17]
	ds_read_b128 v[140:143], v95 offset:23104
	s_waitcnt lgkmcnt(2)
	v_mfma_f32_32x32x16_bf16 v[50:65], v[144:147], v[136:139], v[50:65]
	ds_read_b128 v[128:131], v66 offset:96
	s_waitcnt lgkmcnt(2)
	v_mfma_f32_32x32x16_bf16 v[18:33], v[148:151], v[136:139], v[18:33]
	ds_read_b128 v[136:139], v95 offset:18528
	s_waitcnt lgkmcnt(2)
	v_mfma_f32_32x32x16_bf16 v[34:49], v[144:147], v[140:143], v[34:49]
	ds_read_b128 v[144:147], v66 offset:4704
	v_mfma_f32_32x32x16_bf16 v[2:17], v[148:151], v[140:143], v[2:17]
	ds_read_b128 v[140:143], v95 offset:23136
	s_waitcnt lgkmcnt(2)
	v_mfma_f32_32x32x16_bf16 v[50:65], v[128:131], v[136:139], v[50:65]
	s_waitcnt lgkmcnt(1)
	v_mfma_f32_32x32x16_bf16 v[18:33], v[144:147], v[136:139], v[18:33]
	s_waitcnt lgkmcnt(0)
	v_mfma_f32_32x32x16_bf16 v[34:49], v[128:131], v[140:143], v[34:49]
	v_mfma_f32_32x32x16_bf16 v[2:17], v[144:147], v[140:143], v[2:17]
	s_add_i32 s2, s2, 2
	s_and_b32 s18, s2, 2
	s_add_u32 s16, s16, 0x80
	s_mulk_i32 s18, 0x4800
	s_addc_u32 s17, s17, 0
	v_add_u32_e32 v66, s18, v1
	s_cmpk_lg_i32 s16, 0x700
	s_waitcnt vmcnt(7)
	ds_write_b128 v66, v[96:99]
	v_lshl_add_u64 v[96:97], v[88:89], 0, s[16:17]
	v_add_co_u32_e32 v96, vcc, s24, v96
	s_nop 1
	v_addc_co_u32_e32 v97, vcc, 0, v97, vcc
	global_load_dwordx4 v[96:99], v[96:97], off offset:384
	s_waitcnt vmcnt(7)
	ds_write_b128 v66, v[100:103] offset:4608
	v_lshl_add_u64 v[100:101], v[88:89], 0, s[16:17]
	v_add_co_u32_e32 v100, vcc, s25, v100
	s_nop 1
	v_addc_co_u32_e32 v101, vcc, 0, v101, vcc
	global_load_dwordx4 v[100:103], v[100:101], off offset:384
	s_waitcnt vmcnt(7)
	ds_write_b128 v66, v[104:107] offset:9216
	v_lshl_add_u64 v[104:105], v[88:89], 0, s[16:17]
	v_add_co_u32_e32 v104, vcc, s26, v104
	s_nop 1
	v_addc_co_u32_e32 v105, vcc, 0, v105, vcc
	global_load_dwordx4 v[104:107], v[104:105], off offset:384
	s_waitcnt vmcnt(7)
	ds_write_b128 v66, v[108:111] offset:13824
	v_lshl_add_u64 v[108:109], v[88:89], 0, s[16:17]
	v_add_co_u32_e32 v108, vcc, s27, v108
	s_nop 1
	v_addc_co_u32_e32 v109, vcc, 0, v109, vcc
	global_load_dwordx4 v[108:111], v[108:109], off offset:384
	s_waitcnt vmcnt(7)
	ds_write_b128 v66, v[112:115] offset:18432
	v_lshl_add_u64 v[112:113], v[78:79], 0, s[16:17]
	v_add_co_u32_e32 v112, vcc, s28, v112
	s_nop 1
	v_addc_co_u32_e32 v113, vcc, 0, v113, vcc
	global_load_dwordx4 v[112:115], v[112:113], off offset:128
	s_waitcnt vmcnt(7)
	ds_write_b128 v66, v[116:119] offset:23040
	v_lshl_add_u64 v[116:117], v[78:79], 0, s[16:17]
	v_add_co_u32_e32 v116, vcc, s29, v116
	s_nop 1
	v_addc_co_u32_e32 v117, vcc, 0, v117, vcc
	global_load_dwordx4 v[116:119], v[116:117], off offset:128
	s_waitcnt vmcnt(7)
	ds_write_b128 v66, v[120:123] offset:27648
	v_lshl_add_u64 v[120:121], v[78:79], 0, s[16:17]
	v_add_co_u32_e32 v120, vcc, s30, v120
	s_nop 1
	v_addc_co_u32_e32 v121, vcc, 0, v121, vcc
	global_load_dwordx4 v[120:123], v[120:121], off offset:128
	s_waitcnt vmcnt(7)
	ds_write_b128 v66, v[124:127] offset:32256
	v_lshl_add_u64 v[124:125], v[78:79], 0, s[16:17]
	v_add_co_u32_e32 v124, vcc, s31, v124
	s_nop 1
	v_addc_co_u32_e32 v125, vcc, 0, v125, vcc
	global_load_dwordx4 v[124:127], v[124:125], off offset:128
	s_waitcnt lgkmcnt(0)
	s_cbranch_scc1 .LBB0_722
	s_barrier
;     ...
;   for (int kt = 0; kt < nk; ++kt) {
;     const int kn = (kt + 1 < nk) ? kt + 1 : kt;
;     GM_LOAD2(kn * 64, kn * bkstep)
;     __builtin_amdgcn_sched_barrier(0);
;     const char* As = smem + (kt & 1) * 2 * TILE_B;
;     const char* Bs = As + TILE_B;
;     if constexpr (HOIST) {
;       bf16x8 fa0[4], fa1[4], fb0[4], fb1[4];
; #pragma unroll
;       for (int st = 0; st < 4; ++st) {
;         fa0[st] = *(const bf16x8*)(As + aoff + st * 32);
;         fb0[st] = *(const bf16x8*)(Bs + boff + st * 32);
;         fa1[st] = *(const bf16x8*)(As + aoff + 32 * LSTR + st * 32);
;         fb1[st] = *(const bf16x8*)(Bs + boff + 32 * LSTR + st * 32);
;       }
;       __builtin_amdgcn_sched_barrier(0);
; #pragma unroll
;       for (int st = 0; st < 4; ++st) {
;         acc[0][0] = mfma32(fa0[st], fb0[st], acc[0][0]);
;         acc[0][1] = mfma32(fa0[st], fb1[st], acc[0][1]);
;         acc[1][0] = mfma32(fa1[st], fb0[st], acc[1][0]);
;         acc[1][1] = mfma32(fa1[st], fb1[st], acc[1][1]);
;       }
;     } else {
; #pragma unroll
;       for (int st = 0; st < 4; ++st) {
;         bf16x8 a0 = *(const bf16x8*)(As + aoff + st * 32);
;         bf16x8 a1 = *(const bf16x8*)(As + aoff + 32 * LSTR + st * 32);
;         bf16x8 b0 = *(const bf16x8*)(Bs + boff + st * 32);
;         bf16x8 b1 = *(const bf16x8*)(Bs + boff + 32 * LSTR + st * 32);
;         acc[0][0] = mfma32(a0, b0, acc[0][0]);
;         acc[0][1] = mfma32(a0, b1, acc[0][1]);
;         acc[1][0] = mfma32(a1, b0, acc[1][0]);
;         acc[1][1] = mfma32(a1, b1, acc[1][1]);
;       }
;     }
;     __builtin_amdgcn_sched_barrier(0);
;     {
;       char* Ad = smem + ((kt + 1) & 1) * 2 * TILE_B;
;       GM_STORE(Ad)
;     }
;     __syncthreads();
	s_and_b32 s18, s2, 2
	s_mulk_i32 s18, 0x4800
	v_add3_u32 v66, s18, v90, v91
	v_add3_u32 v95, s18, v92, v91
	ds_read_b128 v[128:131], v66 offset:0
	ds_read_b128 v[136:139], v95 offset:18432
	ds_read_b128 v[144:147], v66 offset:4608
	ds_read_b128 v[140:143], v95 offset:23040
	s_waitcnt lgkmcnt(2)
	v_mfma_f32_32x32x16_bf16 v[50:65], v[128:131], v[136:139], v[50:65]
	ds_read_b128 v[148:151], v66 offset:32
	s_waitcnt lgkmcnt(2)
	v_mfma_f32_32x32x16_bf16 v[18:33], v[144:147], v[136:139], v[18:33]
	ds_read_b128 v[136:139], v95 offset:18464
	s_waitcnt lgkmcnt(2)
	v_mfma_f32_32x32x16_bf16 v[34:49], v[128:131], v[140:143], v[34:49]
	ds_read_b128 v[128:131], v66 offset:4640
	v_mfma_f32_32x32x16_bf16 v[2:17], v[144:147], v[140:143], v[2:17]
	ds_read_b128 v[140:143], v95 offset:23072
	s_waitcnt lgkmcnt(2)
	v_mfma_f32_32x32x16_bf16 v[50:65], v[148:151], v[136:139], v[50:65]
	ds_read_b128 v[144:147], v66 offset:64
	s_waitcnt lgkmcnt(2)
	v_mfma_f32_32x32x16_bf16 v[18:33], v[128:131], v[136:139], v[18:33]
	ds_read_b128 v[136:139], v95 offset:18496
	s_waitcnt lgkmcnt(2)
	v_mfma_f32_32x32x16_bf16 v[34:49], v[148:151], v[140:143], v[34:49]
	ds_read_b128 v[148:151], v66 offset:4672
	v_mfma_f32_32x32x16_bf16 v[2:17], v[128:131], v[140:143], v[2:17]
	ds_read_b128 v[140:143], v95 offset:23104
	s_waitcnt lgkmcnt(2)
	v_mfma_f32_32x32x16_bf16 v[50:65], v[144:147], v[136:139], v[50:65]
	ds_read_b128 v[128:131], v66 offset:96
	s_waitcnt lgkmcnt(2)
	v_mfma_f32_32x32x16_bf16 v[18:33], v[148:151], v[136:139], v[18:33]
	ds_read_b128 v[136:139], v95 offset:18528
	s_waitcnt lgkmcnt(2)
	v_mfma_f32_32x32x16_bf16 v[34:49], v[144:147], v[140:143], v[34:49]
	ds_read_b128 v[144:147], v66 offset:4704
	v_mfma_f32_32x32x16_bf16 v[2:17], v[148:151], v[140:143], v[2:17]
	ds_read_b128 v[140:143], v95 offset:23136
	s_waitcnt lgkmcnt(2)
	v_mfma_f32_32x32x16_bf16 v[50:65], v[128:131], v[136:139], v[50:65]
	s_waitcnt lgkmcnt(1)
	v_mfma_f32_32x32x16_bf16 v[18:33], v[144:147], v[136:139], v[18:33]
	s_waitcnt lgkmcnt(0)
	v_mfma_f32_32x32x16_bf16 v[34:49], v[128:131], v[140:143], v[34:49]
	v_mfma_f32_32x32x16_bf16 v[2:17], v[144:147], v[140:143], v[2:17]
	s_add_i32 s2, s2, 2
	s_and_b32 s18, s2, 2
	s_add_u32 s16, s16, 0x80
	s_mulk_i32 s18, 0x4800
	s_addc_u32 s17, s17, 0
	v_add_u32_e32 v66, s18, v1
	s_waitcnt vmcnt(7)
	ds_write_b128 v66, v[96:99]
	s_waitcnt vmcnt(6)
	ds_write_b128 v66, v[100:103] offset:4608
	s_waitcnt vmcnt(5)
	ds_write_b128 v66, v[104:107] offset:9216
	s_waitcnt vmcnt(4)
	ds_write_b128 v66, v[108:111] offset:13824
	s_waitcnt vmcnt(3)
	ds_write_b128 v66, v[112:115] offset:18432
	s_waitcnt vmcnt(2)
	ds_write_b128 v66, v[116:119] offset:23040
	s_waitcnt vmcnt(1)
	ds_write_b128 v66, v[120:123] offset:27648
	s_waitcnt vmcnt(0)
	ds_write_b128 v66, v[124:127] offset:32256
	s_waitcnt lgkmcnt(0)
	s_barrier
	v_add_co_u32_e32 v104, vcc, 0x10000, v76
	s_nop 0
	s_nop 0
	s_nop 0
	v_addc_co_u32_e32 v105, vcc, 0, v77, vcc
	v_add_co_u32_e32 v108, vcc, 0x20000, v76
	s_nop 0
	v_addc_co_u32_e32 v109, vcc, 0, v77, vcc
	v_add_co_u32_e32 v76, vcc, 0x30000, v76
	s_lshl_b64 s[14:15], s[14:15], 7
	s_nop 0
	v_addc_co_u32_e32 v77, vcc, 0, v77, vcc
	s_nop 0
	v_add_u32_e32 v66, v90, v91
	v_add_u32_e32 v76, v92, v91
	ds_read_b128 v[116:119], v66 offset:36864
	ds_read_b128 v[120:123], v76 offset:55296
	ds_read_b128 v[128:131], v66 offset:41472
	ds_read_b128 v[124:127], v76 offset:59904
	s_waitcnt lgkmcnt(2)
	v_mfma_f32_32x32x16_bf16 v[50:65], v[116:119], v[120:123], v[50:65]
	ds_read_b128 v[136:139], v66 offset:36896
	s_waitcnt lgkmcnt(2)
	v_mfma_f32_32x32x16_bf16 v[18:33], v[128:131], v[120:123], v[18:33]
	ds_read_b128 v[120:123], v76 offset:55328
	s_waitcnt lgkmcnt(2)
	v_mfma_f32_32x32x16_bf16 v[34:49], v[116:119], v[124:127], v[34:49]
	ds_read_b128 v[116:119], v66 offset:41504
	v_mfma_f32_32x32x16_bf16 v[2:17], v[128:131], v[124:127], v[2:17]
	ds_read_b128 v[124:127], v76 offset:59936
	s_waitcnt lgkmcnt(2)
	v_mfma_f32_32x32x16_bf16 v[50:65], v[136:139], v[120:123], v[50:65]
	ds_read_b128 v[128:131], v66 offset:36928
	s_waitcnt lgkmcnt(2)
	v_mfma_f32_32x32x16_bf16 v[18:33], v[116:119], v[120:123], v[18:33]
	ds_read_b128 v[120:123], v76 offset:55360
	s_waitcnt lgkmcnt(2)
	v_mfma_f32_32x32x16_bf16 v[34:49], v[136:139], v[124:127], v[34:49]
	ds_read_b128 v[136:139], v66 offset:41536
	v_mfma_f32_32x32x16_bf16 v[2:17], v[116:119], v[124:127], v[2:17]
	ds_read_b128 v[124:127], v76 offset:59968
	s_waitcnt lgkmcnt(2)
	v_mfma_f32_32x32x16_bf16 v[50:65], v[128:131], v[120:123], v[50:65]
	ds_read_b128 v[116:119], v66 offset:36960
	s_waitcnt lgkmcnt(2)
	v_mfma_f32_32x32x16_bf16 v[18:33], v[136:139], v[120:123], v[18:33]
	ds_read_b128 v[120:123], v76 offset:55392
	s_waitcnt lgkmcnt(2)
	v_mfma_f32_32x32x16_bf16 v[34:49], v[128:131], v[124:127], v[34:49]
	ds_read_b128 v[128:131], v66 offset:41568
	v_mfma_f32_32x32x16_bf16 v[2:17], v[136:139], v[124:127], v[2:17]
	ds_read_b128 v[124:127], v76 offset:60000
	s_waitcnt lgkmcnt(2)
	v_mfma_f32_32x32x16_bf16 v[50:65], v[116:119], v[120:123], v[50:65]
	s_waitcnt lgkmcnt(1)
	v_mfma_f32_32x32x16_bf16 v[18:33], v[128:131], v[120:123], v[18:33]
	s_waitcnt lgkmcnt(0)
	v_mfma_f32_32x32x16_bf16 v[34:49], v[116:119], v[124:127], v[34:49]
	v_mfma_f32_32x32x16_bf16 v[2:17], v[128:131], v[124:127], v[2:17]
	s_waitcnt lgkmcnt(0)
	s_barrier
; __device__ __forceinline__ void acc_to_lds(const f32x16 (&acc)[2][2], float* cs) {
;   const int tid = threadIdx.x, lane = tid & 63, wave = tid >> 6;
;   const int wm = wave >> 1, wn = wave & 1;
; #pragma unroll
;   for (int i = 0; i < 2; ++i)
; #pragma unroll
;     for (int j = 0; j < 2; ++j)
; #pragma unroll
;       for (int r = 0; r < 16; ++r) {
;         int row = wm * 64 + i * 32 + (r & 3) + 8 * (r >> 2) + 4 * (lane >> 5);
;         int col = wn * 64 + j * 32 + (lane & 31);
;         cs[row * CSTR + col] = acc[i][j][r];
;       }
;   __syncthreads();
; template <bool WIDE>
; __device__ __forceinline__ void outproj_tile(const Params& P, int l, int mt, int nt, char* smem) {
;     ...
;     int tid_ = threadIdx.x;
;     asm volatile("" : "+v"(tid_));
;     const int lane = tid_ & 63, wave = tid_ >> 6;
;     const int r = 32 * wave + (lane & 31), half = lane >> 5;
;     const size_t grow = (size_t)mt * 128 + r;
;     const bool isctx = grow >= NLAT;
;     const int modrow = isctx ? 8 : (int)(grow >> 12);
;     const int col = (nt + hsel) * 128 + half * 64;
;     const float* g1 = WSP(float, OFF_MOD) + ((size_t)l * 9 + modrow) * 6144 + 2048 + col;
;     const float* xin;
;     float* xo;
;     if (!isctx) { xin = (l == 0 ? P.x : P.out) + grow * DM + col; xo = P.out + grow * DM + col; }
;     else { xin = (l == 0 ? P.ctx : WSP(float, OFF_XC)) + (grow - NLAT) * DM + col; xo = WSP(float, OFF_XC) + (grow - NLAT) * DM + col; }
	ds_write2_b32 v93, v50, v34 offset1:32
	ds_write2_b32 v93, v51, v35 offset0:132 offset1:164
	v_add_u32_e32 v34, 0x400, v93
	ds_write2_b32 v34, v52, v36 offset0:8 offset1:40
	ds_write2_b32 v34, v53, v37 offset0:140 offset1:172
	v_add_u32_e32 v34, 0x1000, v93
	ds_write2_b32 v34, v54, v38 offset0:32 offset1:64
	ds_write2_b32 v34, v55, v39 offset0:164 offset1:196
	v_add_u32_e32 v34, 0x1400, v93
	ds_write2_b32 v34, v56, v40 offset0:40 offset1:72
	ds_write2_b32 v34, v57, v41 offset0:172 offset1:204
	v_add_u32_e32 v34, 0x2000, v93
	ds_write2_b32 v34, v58, v42 offset0:64 offset1:96
	ds_write2_b32 v34, v59, v43 offset0:196 offset1:228
	v_add_u32_e32 v34, 0x2400, v93
	ds_write2_b32 v34, v60, v44 offset0:72 offset1:104
	ds_write2_b32 v34, v61, v45 offset0:204 offset1:236
	v_add_u32_e32 v34, 0x3000, v93
	ds_write2_b32 v34, v62, v46 offset0:96 offset1:128
	v_add_u32_e32 v34, 0x3200, v93
	ds_write2_b32 v34, v63, v47 offset0:100 offset1:132
	v_add_u32_e32 v34, 0x3400, v93
	ds_write2_b32 v34, v64, v48 offset0:104 offset1:136
	v_add_u32_e32 v34, 0x3600, v93
	ds_write2_b32 v34, v65, v49 offset0:108 offset1:140
	v_add_u32_e32 v34, 0x4000, v93
	ds_write2_b32 v34, v18, v2 offset0:128 offset1:160
	v_add_u32_e32 v2, 0x4400, v93
	ds_write2_b32 v2, v19, v3 offset0:4 offset1:36
	ds_write2_b32 v2, v20, v4 offset0:136 offset1:168
	v_add_u32_e32 v2, 0x4800, v93
	ds_write2_b32 v2, v21, v5 offset0:12 offset1:44
	v_add_u32_e32 v2, 0x5000, v93
	ds_write2_b32 v2, v22, v6 offset0:160 offset1:192
	v_add_u32_e32 v2, 0x5400, v93
	ds_write2_b32 v2, v23, v7 offset0:36 offset1:68
	ds_write2_b32 v2, v24, v8 offset0:168 offset1:200
	v_add_u32_e32 v2, 0x5800, v93
	ds_write2_b32 v2, v25, v9 offset0:44 offset1:76
	v_add_u32_e32 v2, 0x6000, v93
	ds_write2_b32 v2, v26, v10 offset0:192 offset1:224
	v_add_u32_e32 v2, 0x6400, v93
	ds_write2_b32 v2, v27, v11 offset0:68 offset1:100
	ds_write2_b32 v2, v28, v12 offset0:200 offset1:232
	v_add_u32_e32 v2, 0x6800, v93
	ds_write2_b32 v2, v29, v13 offset0:76 offset1:108
	v_add_u32_e32 v2, 0x7200, v93
	ds_write2_b32 v2, v30, v14 offset0:96 offset1:128
	v_add_u32_e32 v2, 0x7400, v93
	ds_write2_b32 v2, v31, v15 offset0:100 offset1:132
	v_add_u32_e32 v2, 0x7600, v93
	ds_write2_b32 v2, v32, v16 offset0:104 offset1:136
	v_add_u32_e32 v2, 0x7800, v93
	v_mov_b32_e32 v12, v134
	ds_write2_b32 v2, v33, v17 offset0:108 offset1:140
	s_waitcnt lgkmcnt(0)
	s_barrier
	s_nop 0
	v_ashrrev_i32_e32 v2, 1, v12
	v_bfi_b32 v2, s33, v2, v12
	v_ashrrev_i32_e32 v3, 31, v2
	v_lshl_add_u64 v[4:5], s[14:15], 0, v[2:3]
	v_cmp_gt_u64_e32 vcc, s[10:11], v[4:5]
	v_lshlrev_b64 v[10:11], 10, v[4:5]
	s_and_saveexec_b64 s[14:15], vcc
	s_xor_b64 s[14:15], exec, s[14:15]
	s_cbranch_execz .LBB0_725
	v_readlane_b32 s56, v253, 21
	v_lshlrev_b64 v[8:9], 2, v[10:11]
	v_readlane_b32 s57, v253, 22
	v_readlane_b32 s58, v253, 23
	v_readlane_b32 s59, v253, 24
	v_lshl_add_u64 v[6:7], s[56:57], 0, v[8:9]
	v_lshl_add_u64 v[8:9], s[88:89], 0, v[8:9]
	v_readlane_b32 s60, v253, 25
	v_readlane_b32 s61, v253, 26
	v_readlane_b32 s62, v253, 27
	v_readlane_b32 s63, v253, 28
	v_readlane_b32 s64, v253, 29
	v_readlane_b32 s65, v253, 30
	v_readlane_b32 s66, v253, 31
	v_readlane_b32 s67, v253, 32
	v_readlane_b32 s68, v253, 33
	v_readlane_b32 s69, v253, 34
	v_readlane_b32 s70, v253, 35
	v_readlane_b32 s71, v253, 36

;     ...
;   for (int kt = 0; kt < nk; ++kt) {
;     const int kn = (kt + 1 < nk) ? kt + 1 : kt;
;     GW_LOAD2(kn * 64, kn * bkstep)
;     __builtin_amdgcn_sched_barrier(0);
;     __builtin_amdgcn_s_setprio(1);
; #pragma unroll
;     for (int st = 0; st < 4; ++st) {
;       bf16x8 a0 = *(const bf16x8*)(Ab + st * 32);
;       bf16x8 a1 = *(const bf16x8*)(Ab + 32 * LSTR + st * 32);
;       bf16x8 b0 = *(const bf16x8*)(Bb + st * 32);
;       bf16x8 b1 = *(const bf16x8*)(Bb + 32 * LSTR + st * 32);
;       bf16x8 b2 = *(const bf16x8*)(Bb + 64 * LSTR + st * 32);
;       bf16x8 b3 = *(const bf16x8*)(Bb + 96 * LSTR + st * 32);
;       acc[0][0] = mfma32(a0, b0, acc[0][0]);
;       acc[0][1] = mfma32(a0, b1, acc[0][1]);
;       acc[0][2] = mfma32(a0, b2, acc[0][2]);
;       acc[0][3] = mfma32(a0, b3, acc[0][3]);
;       acc[1][0] = mfma32(a1, b0, acc[1][0]);
;       acc[1][1] = mfma32(a1, b1, acc[1][1]);
;       acc[1][2] = mfma32(a1, b2, acc[1][2]);
;       acc[1][3] = mfma32(a1, b3, acc[1][3]);
;     }
;     __builtin_amdgcn_s_setprio(0);
;     __builtin_amdgcn_sched_barrier(0);
;     __syncthreads();
.LBB0_1035:
	s_barrier
	s_setprio 1
	ds_read_b128 v[206:209], v133 offset:0
	ds_read_b128 v[218:221], v156 offset:18432
	ds_read_b128 v[224:227], v156 offset:23040
	ds_read_b128 v[228:231], v156 offset:27648
	ds_read_b128 v[232:235], v156 offset:32256
	ds_read_b128 v[214:217], v133 offset:4608
	s_waitcnt lgkmcnt(4)
	v_mfma_f32_32x32x16_bf16 v[114:129], v[206:209], v[218:221], v[114:129]
	ds_read_b128 v[210:213], v133 offset:32
	ds_read_b128 v[236:239], v156 offset:18464
	s_waitcnt lgkmcnt(5)
	v_mfma_f32_32x32x16_bf16 v[98:113], v[206:209], v[224:227], v[98:113]
	ds_read_b128 v[240:243], v156 offset:23072
	s_waitcnt lgkmcnt(5)
	v_mfma_f32_32x32x16_bf16 v[82:97], v[206:209], v[228:231], v[82:97]
	ds_read_b128 v[244:247], v156 offset:27680
	s_waitcnt lgkmcnt(5)
	v_mfma_f32_32x32x16_bf16 v[66:81], v[206:209], v[232:235], v[66:81]
	ds_read_b128 v[248:251], v156 offset:32288
	s_waitcnt lgkmcnt(5)
	v_mfma_f32_32x32x16_bf16 v[50:65], v[214:217], v[218:221], v[50:65]
	v_lshl_add_u64 v[158:159], v[148:149], 0, v[130:131]
	global_load_dwordx4 v[158:161], v[158:159], off
	v_mfma_f32_32x32x16_bf16 v[34:49], v[214:217], v[224:227], v[34:49]
	v_lshl_add_u64 v[162:163], v[150:151], 0, v[130:131]
	global_load_dwordx4 v[162:165], v[162:163], off
	v_mfma_f32_32x32x16_bf16 v[18:33], v[214:217], v[228:231], v[18:33]
	v_lshl_add_u64 v[166:167], v[152:153], 0, v[130:131]
	global_load_dwordx4 v[166:169], v[166:167], off
	v_mfma_f32_32x32x16_bf16 v[2:17], v[214:217], v[232:235], v[2:17]
	v_lshl_add_u64 v[170:171], v[154:155], 0, v[130:131]
	global_load_dwordx4 v[170:173], v[170:171], off
	ds_read_b128 v[214:217], v133 offset:4640
	s_waitcnt lgkmcnt(4)
	v_mfma_f32_32x32x16_bf16 v[114:129], v[210:213], v[236:239], v[114:129]
	ds_read_b128 v[206:209], v133 offset:64
	ds_read_b128 v[218:221], v156 offset:18496
	s_waitcnt lgkmcnt(5)
	v_mfma_f32_32x32x16_bf16 v[98:113], v[210:213], v[240:243], v[98:113]
	ds_read_b128 v[224:227], v156 offset:23104
	s_waitcnt lgkmcnt(5)
	v_mfma_f32_32x32x16_bf16 v[82:97], v[210:213], v[244:247], v[82:97]
	ds_read_b128 v[228:231], v156 offset:27712
	s_waitcnt lgkmcnt(5)
	v_mfma_f32_32x32x16_bf16 v[66:81], v[210:213], v[248:251], v[66:81]
	ds_read_b128 v[232:235], v156 offset:32320
	s_waitcnt lgkmcnt(5)
	v_mfma_f32_32x32x16_bf16 v[50:65], v[214:217], v[236:239], v[50:65]
	v_lshl_add_u64 v[174:175], v[146:147], 0, v[130:131]
	v_add_co_u32_e32 v174, vcc, s35, v174
	s_nop 1
	v_addc_co_u32_e32 v175, vcc, 0, v175, vcc
	global_load_dwordx4 v[174:177], v[174:175], off offset:-4096
	v_mfma_f32_32x32x16_bf16 v[34:49], v[214:217], v[240:243], v[34:49]
	v_lshl_add_u64 v[178:179], v[146:147], 0, v[130:131]
	v_add_co_u32_e32 v178, vcc, s35, v178
	s_nop 1
	v_addc_co_u32_e32 v179, vcc, 0, v179, vcc
	global_load_dwordx4 v[178:181], v[178:179], off
	v_mfma_f32_32x32x16_bf16 v[18:33], v[214:217], v[244:247], v[18:33]
	v_lshl_add_u64 v[182:183], v[146:147], 0, v[130:131]
	v_add_co_u32_e32 v182, vcc, s36, v182
	s_nop 1
	v_addc_co_u32_e32 v183, vcc, 0, v183, vcc
	global_load_dwordx4 v[182:185], v[182:183], off offset:-4096
	v_mfma_f32_32x32x16_bf16 v[2:17], v[214:217], v[248:251], v[2:17]
	v_lshl_add_u64 v[186:187], v[146:147], 0, v[130:131]
	v_add_co_u32_e32 v186, vcc, s36, v186
	s_nop 1
	v_addc_co_u32_e32 v187, vcc, 0, v187, vcc
	global_load_dwordx4 v[186:189], v[186:187], off
	ds_read_b128 v[214:217], v133 offset:4672
	s_waitcnt lgkmcnt(4)
	v_mfma_f32_32x32x16_bf16 v[114:129], v[206:209], v[218:221], v[114:129]
	ds_read_b128 v[210:213], v133 offset:96
	ds_read_b128 v[236:239], v156 offset:18528
	s_waitcnt lgkmcnt(5)
	v_mfma_f32_32x32x16_bf16 v[98:113], v[206:209], v[224:227], v[98:113]
	ds_read_b128 v[240:243], v156 offset:23136
	s_waitcnt lgkmcnt(5)
	v_mfma_f32_32x32x16_bf16 v[82:97], v[206:209], v[228:231], v[82:97]
	ds_read_b128 v[244:247], v156 offset:27744
	s_waitcnt lgkmcnt(5)
	v_mfma_f32_32x32x16_bf16 v[66:81], v[206:209], v[232:235], v[66:81]
	ds_read_b128 v[248:251], v156 offset:32352
	s_waitcnt lgkmcnt(5)
	v_mfma_f32_32x32x16_bf16 v[50:65], v[214:217], v[218:221], v[50:65]
	v_lshl_add_u64 v[190:191], v[146:147], 0, v[130:131]
	v_add_co_u32_e32 v190, vcc, s37, v190
	s_nop 1
	v_addc_co_u32_e32 v191, vcc, 0, v191, vcc
	global_load_dwordx4 v[190:193], v[190:191], off offset:-4096
	v_mfma_f32_32x32x16_bf16 v[34:49], v[214:217], v[224:227], v[34:49]
	v_lshl_add_u64 v[194:195], v[146:147], 0, v[130:131]
	v_add_co_u32_e32 v194, vcc, s37, v194
	s_nop 1
	v_addc_co_u32_e32 v195, vcc, 0, v195, vcc
	global_load_dwordx4 v[194:197], v[194:195], off
	v_mfma_f32_32x32x16_bf16 v[18:33], v[214:217], v[228:231], v[18:33]
	v_lshl_add_u64 v[198:199], v[146:147], 0, v[130:131]
	v_add_co_u32_e32 v198, vcc, s38, v198
	s_nop 1
	v_addc_co_u32_e32 v199, vcc, 0, v199, vcc
	global_load_dwordx4 v[198:201], v[198:199], off offset:-4096
	v_mfma_f32_32x32x16_bf16 v[2:17], v[214:217], v[232:235], v[2:17]
	v_lshl_add_u64 v[202:203], v[146:147], 0, v[130:131]
	v_add_co_u32_e32 v202, vcc, s38, v202
	s_nop 1
	v_addc_co_u32_e32 v203, vcc, 0, v203, vcc
	global_load_dwordx4 v[202:205], v[202:203], off
	ds_read_b128 v[214:217], v133 offset:4704
	s_waitcnt lgkmcnt(4)
	v_mfma_f32_32x32x16_bf16 v[114:129], v[210:213], v[236:239], v[114:129]
	s_waitcnt lgkmcnt(3)
	v_mfma_f32_32x32x16_bf16 v[98:113], v[210:213], v[240:243], v[98:113]
	s_waitcnt lgkmcnt(2)
	v_mfma_f32_32x32x16_bf16 v[82:97], v[210:213], v[244:247], v[82:97]
	s_waitcnt lgkmcnt(1)
	v_mfma_f32_32x32x16_bf16 v[66:81], v[210:213], v[248:251], v[66:81]
	s_waitcnt lgkmcnt(0)
	v_mfma_f32_32x32x16_bf16 v[50:65], v[214:217], v[236:239], v[50:65]
	v_mfma_f32_32x32x16_bf16 v[34:49], v[214:217], v[240:243], v[34:49]
	v_mfma_f32_32x32x16_bf16 v[18:33], v[214:217], v[244:247], v[18:33]
	v_mfma_f32_32x32x16_bf16 v[2:17], v[214:217], v[248:251], v[2:17]
	s_setprio 0
	s_add_i32 s41, s41, -1
	v_lshl_add_u64 v[146:147], v[146:147], 0, s[8:9]
	v_lshl_add_u64 v[148:149], v[148:149], 0, s[10:11]
	v_lshl_add_u64 v[150:151], v[150:151], 0, s[10:11]
	v_lshl_add_u64 v[152:153], v[152:153], 0, s[10:11]
	s_cmp_lg_u32 s41, 0
	v_lshl_add_u64 v[154:155], v[154:155], 0, s[10:11]
	s_barrier
;     ...
;   for (int kt = 0; kt < nk; ++kt) {
;     const int kn = (kt + 1 < nk) ? kt + 1 : kt;
;     GW_LOAD2(kn * 64, kn * bkstep)
;     __builtin_amdgcn_sched_barrier(0);
;     __builtin_amdgcn_s_setprio(1);
; #pragma unroll
;     for (int st = 0; st < 4; ++st) {
;       bf16x8 a0 = *(const bf16x8*)(Ab + st * 32);
;       bf16x8 a1 = *(const bf16x8*)(Ab + 32 * LSTR + st * 32);
;       bf16x8 b0 = *(const bf16x8*)(Bb + st * 32);
;       bf16x8 b1 = *(const bf16x8*)(Bb + 32 * LSTR + st * 32);
;       bf16x8 b2 = *(const bf16x8*)(Bb + 64 * LSTR + st * 32);
;       bf16x8 b3 = *(const bf16x8*)(Bb + 96 * LSTR + st * 32);
;       acc[0][0] = mfma32(a0, b0, acc[0][0]);
;       acc[0][1] = mfma32(a0, b1, acc[0][1]);
;       acc[0][2] = mfma32(a0, b2, acc[0][2]);
;       acc[0][3] = mfma32(a0, b3, acc[0][3]);
;       acc[1][0] = mfma32(a1, b0, acc[1][0]);
;       acc[1][1] = mfma32(a1, b1, acc[1][1]);
;       acc[1][2] = mfma32(a1, b2, acc[1][2]);
;       acc[1][3] = mfma32(a1, b3, acc[1][3]);
;     }
;     __builtin_amdgcn_s_setprio(0);
;     __builtin_amdgcn_sched_barrier(0);
;     __syncthreads();
;     GW_STORE()
;     __syncthreads();
	s_waitcnt vmcnt(11)
	ds_write_b128 v132, v[158:161]
	s_waitcnt vmcnt(10)
	ds_write_b128 v132, v[162:165] offset:4608
	s_waitcnt vmcnt(9)
	ds_write_b128 v132, v[166:169] offset:9216
	s_waitcnt vmcnt(8)
	ds_write_b128 v132, v[170:173] offset:13824
	s_waitcnt vmcnt(7)
	ds_write_b128 v132, v[174:177] offset:18432
	s_waitcnt vmcnt(6)
	ds_write_b128 v132, v[178:181] offset:23040
	s_waitcnt vmcnt(5)
	ds_write_b128 v132, v[182:185] offset:27648
	s_waitcnt vmcnt(4)
	ds_write_b128 v132, v[186:189] offset:32256
	s_waitcnt vmcnt(3)
	ds_write_b128 v132, v[190:193] offset:36864
	s_waitcnt vmcnt(2)
	ds_write_b128 v132, v[194:197] offset:41472
	s_waitcnt vmcnt(1)
	ds_write_b128 v132, v[198:201] offset:46080
	s_waitcnt vmcnt(0)
	ds_write_b128 v132, v[202:205] offset:50688
	s_waitcnt lgkmcnt(0)
	s_cbranch_scc1 .LBB0_1035
	s_barrier
	s_setprio 1
	ds_read_b128 v[206:209], v133 offset:0
	ds_read_b128 v[218:221], v156 offset:18432
	ds_read_b128 v[224:227], v156 offset:23040
	ds_read_b128 v[228:231], v156 offset:27648
	ds_read_b128 v[232:235], v156 offset:32256
	ds_read_b128 v[214:217], v133 offset:4608
	s_waitcnt lgkmcnt(4)
	v_mfma_f32_32x32x16_bf16 v[114:129], v[206:209], v[218:221], v[114:129]
	ds_read_b128 v[210:213], v133 offset:32
	ds_read_b128 v[236:239], v156 offset:18464
	s_waitcnt lgkmcnt(5)
	v_mfma_f32_32x32x16_bf16 v[98:113], v[206:209], v[224:227], v[98:113]
	ds_read_b128 v[240:243], v156 offset:23072
	s_waitcnt lgkmcnt(5)
	v_mfma_f32_32x32x16_bf16 v[82:97], v[206:209], v[228:231], v[82:97]
	ds_read_b128 v[244:247], v156 offset:27680
	s_waitcnt lgkmcnt(5)
	v_mfma_f32_32x32x16_bf16 v[66:81], v[206:209], v[232:235], v[66:81]
	ds_read_b128 v[248:251], v156 offset:32288
	s_waitcnt lgkmcnt(5)
	v_mfma_f32_32x32x16_bf16 v[50:65], v[214:217], v[218:221], v[50:65]
	v_lshl_add_u64 v[158:159], v[148:149], 0, v[130:131]
	global_load_dwordx4 v[158:161], v[158:159], off
	v_mfma_f32_32x32x16_bf16 v[34:49], v[214:217], v[224:227], v[34:49]
	v_lshl_add_u64 v[162:163], v[150:151], 0, v[130:131]
	global_load_dwordx4 v[162:165], v[162:163], off
	v_mfma_f32_32x32x16_bf16 v[18:33], v[214:217], v[228:231], v[18:33]
	v_lshl_add_u64 v[166:167], v[152:153], 0, v[130:131]
	global_load_dwordx4 v[166:169], v[166:167], off
	v_mfma_f32_32x32x16_bf16 v[2:17], v[214:217], v[232:235], v[2:17]
	v_lshl_add_u64 v[170:171], v[154:155], 0, v[130:131]
	global_load_dwordx4 v[170:173], v[170:171], off
	ds_read_b128 v[214:217], v133 offset:4640
	s_waitcnt lgkmcnt(4)
	v_mfma_f32_32x32x16_bf16 v[114:129], v[210:213], v[236:239], v[114:129]
	ds_read_b128 v[206:209], v133 offset:64
	ds_read_b128 v[218:221], v156 offset:18496
	s_waitcnt lgkmcnt(5)
	v_mfma_f32_32x32x16_bf16 v[98:113], v[210:213], v[240:243], v[98:113]
	ds_read_b128 v[224:227], v156 offset:23104
	s_waitcnt lgkmcnt(5)
	v_mfma_f32_32x32x16_bf16 v[82:97], v[210:213], v[244:247], v[82:97]
	ds_read_b128 v[228:231], v156 offset:27712
	s_waitcnt lgkmcnt(5)
	v_mfma_f32_32x32x16_bf16 v[66:81], v[210:213], v[248:251], v[66:81]
	ds_read_b128 v[232:235], v156 offset:32320
	s_waitcnt lgkmcnt(5)
	v_mfma_f32_32x32x16_bf16 v[50:65], v[214:217], v[236:239], v[50:65]
	v_lshl_add_u64 v[174:175], v[146:147], 0, v[130:131]
	v_add_co_u32_e32 v174, vcc, s35, v174
	s_nop 1
	v_addc_co_u32_e32 v175, vcc, 0, v175, vcc
	global_load_dwordx4 v[174:177], v[174:175], off offset:-4096
	v_mfma_f32_32x32x16_bf16 v[34:49], v[214:217], v[240:243], v[34:49]
	v_lshl_add_u64 v[178:179], v[146:147], 0, v[130:131]
	v_add_co_u32_e32 v178, vcc, s35, v178
	s_nop 1
	v_addc_co_u32_e32 v179, vcc, 0, v179, vcc
	global_load_dwordx4 v[178:181], v[178:179], off
	v_mfma_f32_32x32x16_bf16 v[18:33], v[214:217], v[244:247], v[18:33]
	v_lshl_add_u64 v[182:183], v[146:147], 0, v[130:131]
	v_add_co_u32_e32 v182, vcc, s36, v182
	s_nop 1
	v_addc_co_u32_e32 v183, vcc, 0, v183, vcc
	global_load_dwordx4 v[182:185], v[182:183], off offset:-4096
	v_mfma_f32_32x32x16_bf16 v[2:17], v[214:217], v[248:251], v[2:17]
	v_lshl_add_u64 v[186:187], v[146:147], 0, v[130:131]
	v_add_co_u32_e32 v186, vcc, s36, v186
	s_nop 1
	v_addc_co_u32_e32 v187, vcc, 0, v187, vcc
	global_load_dwordx4 v[186:189], v[186:187], off
	ds_read_b128 v[214:217], v133 offset:4672
	s_waitcnt lgkmcnt(4)
	v_mfma_f32_32x32x16_bf16 v[114:129], v[206:209], v[218:221], v[114:129]
	ds_read_b128 v[210:213], v133 offset:96
	ds_read_b128 v[236:239], v156 offset:18528
	s_waitcnt lgkmcnt(5)
	v_mfma_f32_32x32x16_bf16 v[98:113], v[206:209], v[224:227], v[98:113]
	ds_read_b128 v[240:243], v156 offset:23136
	s_waitcnt lgkmcnt(5)
	v_mfma_f32_32x32x16_bf16 v[82:97], v[206:209], v[228:231], v[82:97]
	ds_read_b128 v[244:247], v156 offset:27744
	s_waitcnt lgkmcnt(5)
	v_mfma_f32_32x32x16_bf16 v[66:81], v[206:209], v[232:235], v[66:81]
	ds_read_b128 v[248:251], v156 offset:32352
	s_waitcnt lgkmcnt(5)
	v_mfma_f32_32x32x16_bf16 v[50:65], v[214:217], v[218:221], v[50:65]
	v_lshl_add_u64 v[190:191], v[146:147], 0, v[130:131]
	v_add_co_u32_e32 v190, vcc, s37, v190
	s_nop 1
	v_addc_co_u32_e32 v191, vcc, 0, v191, vcc
	global_load_dwordx4 v[190:193], v[190:191], off offset:-4096
	v_mfma_f32_32x32x16_bf16 v[34:49], v[214:217], v[224:227], v[34:49]
	v_lshl_add_u64 v[194:195], v[146:147], 0, v[130:131]
	v_add_co_u32_e32 v194, vcc, s37, v194
	s_nop 1
	v_addc_co_u32_e32 v195, vcc, 0, v195, vcc
	global_load_dwordx4 v[194:197], v[194:195], off
	v_mfma_f32_32x32x16_bf16 v[18:33], v[214:217], v[228:231], v[18:33]
	v_lshl_add_u64 v[198:199], v[146:147], 0, v[130:131]
	v_add_co_u32_e32 v198, vcc, s38, v198
	s_nop 1
	v_addc_co_u32_e32 v199, vcc, 0, v199, vcc
	global_load_dwordx4 v[198:201], v[198:199], off offset:-4096
	v_mfma_f32_32x32x16_bf16 v[2:17], v[214:217], v[232:235], v[2:17]
	v_lshl_add_u64 v[202:203], v[146:147], 0, v[130:131]
	v_add_co_u32_e32 v202, vcc, s38, v202
	s_nop 1
	v_addc_co_u32_e32 v203, vcc, 0, v203, vcc
	global_load_dwordx4 v[202:205], v[202:203], off
	ds_read_b128 v[214:217], v133 offset:4704
	s_waitcnt lgkmcnt(4)
	v_mfma_f32_32x32x16_bf16 v[114:129], v[210:213], v[236:239], v[114:129]
	s_waitcnt lgkmcnt(3)
	v_mfma_f32_32x32x16_bf16 v[98:113], v[210:213], v[240:243], v[98:113]
	s_waitcnt lgkmcnt(2)
	v_mfma_f32_32x32x16_bf16 v[82:97], v[210:213], v[244:247], v[82:97]
	s_waitcnt lgkmcnt(1)
	v_mfma_f32_32x32x16_bf16 v[66:81], v[210:213], v[248:251], v[66:81]
	s_waitcnt lgkmcnt(0)
	v_mfma_f32_32x32x16_bf16 v[50:65], v[214:217], v[236:239], v[50:65]
	v_mfma_f32_32x32x16_bf16 v[34:49], v[214:217], v[240:243], v[34:49]
	v_mfma_f32_32x32x16_bf16 v[18:33], v[214:217], v[244:247], v[18:33]
	v_mfma_f32_32x32x16_bf16 v[2:17], v[214:217], v[248:251], v[2:17]
	s_setprio 0
	v_lshl_add_u64 v[146:147], v[146:147], 0, s[8:9]
	v_lshl_add_u64 v[148:149], v[148:149], 0, s[10:11]
	v_lshl_add_u64 v[150:151], v[150:151], 0, s[10:11]
	v_lshl_add_u64 v[152:153], v[152:153], 0, s[10:11]
	v_lshl_add_u64 v[154:155], v[154:155], 0, s[10:11]
	s_barrier
;     ...
;   for (int kt = 0; kt < nk; ++kt) {
;     const int kn = (kt + 1 < nk) ? kt + 1 : kt;
;     GW_LOAD2(kn * 64, kn * bkstep)
;     __builtin_amdgcn_sched_barrier(0);
;     __builtin_amdgcn_s_setprio(1);
; #pragma unroll
;     for (int st = 0; st < 4; ++st) {
;       bf16x8 a0 = *(const bf16x8*)(Ab + st * 32);
;       bf16x8 a1 = *(const bf16x8*)(Ab + 32 * LSTR + st * 32);
;       bf16x8 b0 = *(const bf16x8*)(Bb + st * 32);
;       bf16x8 b1 = *(const bf16x8*)(Bb + 32 * LSTR + st * 32);
;       bf16x8 b2 = *(const bf16x8*)(Bb + 64 * LSTR + st * 32);
;       bf16x8 b3 = *(const bf16x8*)(Bb + 96 * LSTR + st * 32);
;       acc[0][0] = mfma32(a0, b0, acc[0][0]);
;       acc[0][1] = mfma32(a0, b1, acc[0][1]);
;       acc[0][2] = mfma32(a0, b2, acc[0][2]);
;       acc[0][3] = mfma32(a0, b3, acc[0][3]);
;       acc[1][0] = mfma32(a1, b0, acc[1][0]);
;       acc[1][1] = mfma32(a1, b1, acc[1][1]);
;       acc[1][2] = mfma32(a1, b2, acc[1][2]);
;       acc[1][3] = mfma32(a1, b3, acc[1][3]);
;     }
;     __builtin_amdgcn_s_setprio(0);
;     __builtin_amdgcn_sched_barrier(0);
; __device__ __forceinline__ void expert1_tile(const Params& P, int e, int mt, int ntw, char* smem) {
;     ...
;   int tid_ = threadIdx.x;
;   asm volatile("" : "+v"(tid_));
;   const int lane = tid_ & 63, wave = tid_ >> 6;
;   const int r = 32 * wave + (lane & 31), part = lane >> 5;
; #pragma unroll 1
;   for (int h = 0; h < 2; ++h) {
;     wide_acc_to_lds(acc, cs, h);
;     u16* dst = WSP(u16, OFF_HID) + ((size_t)e * EROWS + mt * 128 + r) * 2048 + (ntw * 2 + h) * 64 + part * 32;
	s_waitcnt vmcnt(11)
	ds_write_b128 v132, v[158:161]
	s_waitcnt vmcnt(10)
	ds_write_b128 v132, v[162:165] offset:4608
	s_waitcnt vmcnt(9)
	ds_write_b128 v132, v[166:169] offset:9216
	s_waitcnt vmcnt(8)
	ds_write_b128 v132, v[170:173] offset:13824
	s_waitcnt vmcnt(7)
	ds_write_b128 v132, v[174:177] offset:18432
	s_waitcnt vmcnt(6)
	ds_write_b128 v132, v[178:181] offset:23040
	s_waitcnt vmcnt(5)
	ds_write_b128 v132, v[182:185] offset:27648
	s_waitcnt vmcnt(4)
	ds_write_b128 v132, v[186:189] offset:32256
	s_waitcnt vmcnt(3)
	ds_write_b128 v132, v[190:193] offset:36864
	s_waitcnt vmcnt(2)
	ds_write_b128 v132, v[194:197] offset:41472
	s_waitcnt vmcnt(1)
	ds_write_b128 v132, v[198:201] offset:46080
	s_waitcnt vmcnt(0)
	ds_write_b128 v132, v[202:205] offset:50688
	s_waitcnt lgkmcnt(0)
	s_barrier
	v_add_co_u32_e32 v154, vcc, 0x780000, v136
	s_nop 0
	s_nop 0
	s_nop 0
	v_addc_co_u32_e32 v155, vcc, 0, v137, vcc
	v_add_co_u32_e32 v162, vcc, 0x781000, v136
	s_mov_b32 s18, 0
	s_nop 0
	v_addc_co_u32_e32 v163, vcc, 0, v137, vcc
	s_nop 0
	v_add_co_u32_e32 v154, vcc, 0x782000, v136
	s_nop 1
	v_addc_co_u32_e32 v155, vcc, 0, v137, vcc
	v_add_co_u32_e32 v170, vcc, 0x783000, v136
	s_nop 1
	v_addc_co_u32_e32 v171, vcc, 0, v137, vcc
	s_nop 0
	v_add_co_u32_e32 v154, vcc, 0x784000, v136
	s_nop 1
	v_addc_co_u32_e32 v155, vcc, 0, v137, vcc
	v_add_co_u32_e32 v178, vcc, 0x785000, v136
	s_nop 1
	v_addc_co_u32_e32 v179, vcc, 0, v137, vcc
	s_nop 0
	v_add_co_u32_e32 v154, vcc, 0x786000, v136
	s_nop 1
	v_addc_co_u32_e32 v155, vcc, 0, v137, vcc
	v_add_co_u32_e32 v136, vcc, 0x787000, v136
	s_nop 1
	v_addc_co_u32_e32 v137, vcc, 0, v137, vcc
	s_setprio 1
	ds_read_b128 v[190:193], v133 offset:0
	ds_read_b128 v[202:205], v156 offset:18432
	ds_read_b128 v[206:209], v156 offset:23040
	ds_read_b128 v[210:213], v156 offset:27648
	ds_read_b128 v[214:217], v156 offset:32256
	ds_read_b128 v[198:201], v133 offset:4608
	s_waitcnt lgkmcnt(4)
	v_mfma_f32_32x32x16_bf16 v[114:129], v[190:193], v[202:205], v[114:129]
	ds_read_b128 v[194:197], v133 offset:32
	ds_read_b128 v[218:221], v156 offset:18464
	s_waitcnt lgkmcnt(5)
	v_mfma_f32_32x32x16_bf16 v[98:113], v[190:193], v[206:209], v[98:113]
	ds_read_b128 v[224:227], v156 offset:23072
	s_waitcnt lgkmcnt(5)
	v_mfma_f32_32x32x16_bf16 v[82:97], v[190:193], v[210:213], v[82:97]
	ds_read_b128 v[228:231], v156 offset:27680
	s_waitcnt lgkmcnt(5)
	v_mfma_f32_32x32x16_bf16 v[66:81], v[190:193], v[214:217], v[66:81]
	ds_read_b128 v[232:235], v156 offset:32288
	s_waitcnt lgkmcnt(5)
	v_mfma_f32_32x32x16_bf16 v[50:65], v[198:201], v[202:205], v[50:65]
	v_mfma_f32_32x32x16_bf16 v[34:49], v[198:201], v[206:209], v[34:49]
	v_mfma_f32_32x32x16_bf16 v[18:33], v[198:201], v[210:213], v[18:33]
	v_mfma_f32_32x32x16_bf16 v[2:17], v[198:201], v[214:217], v[2:17]
	ds_read_b128 v[198:201], v133 offset:4640
	s_waitcnt lgkmcnt(4)
	v_mfma_f32_32x32x16_bf16 v[114:129], v[194:197], v[218:221], v[114:129]
	ds_read_b128 v[190:193], v133 offset:64
	ds_read_b128 v[202:205], v156 offset:18496
	s_waitcnt lgkmcnt(5)
	v_mfma_f32_32x32x16_bf16 v[98:113], v[194:197], v[224:227], v[98:113]
	ds_read_b128 v[206:209], v156 offset:23104
	s_waitcnt lgkmcnt(5)
	v_mfma_f32_32x32x16_bf16 v[82:97], v[194:197], v[228:231], v[82:97]
	ds_read_b128 v[210:213], v156 offset:27712
	s_waitcnt lgkmcnt(5)
	v_mfma_f32_32x32x16_bf16 v[66:81], v[194:197], v[232:235], v[66:81]
	ds_read_b128 v[214:217], v156 offset:32320
	s_waitcnt lgkmcnt(5)
	v_mfma_f32_32x32x16_bf16 v[50:65], v[198:201], v[218:221], v[50:65]
	v_mfma_f32_32x32x16_bf16 v[34:49], v[198:201], v[224:227], v[34:49]
	v_mfma_f32_32x32x16_bf16 v[18:33], v[198:201], v[228:231], v[18:33]
	v_mfma_f32_32x32x16_bf16 v[2:17], v[198:201], v[232:235], v[2:17]
	ds_read_b128 v[198:201], v133 offset:4672
	s_waitcnt lgkmcnt(4)
	v_mfma_f32_32x32x16_bf16 v[114:129], v[190:193], v[202:205], v[114:129]
	ds_read_b128 v[194:197], v133 offset:96
	ds_read_b128 v[218:221], v156 offset:18528
	s_waitcnt lgkmcnt(5)
	v_mfma_f32_32x32x16_bf16 v[98:113], v[190:193], v[206:209], v[98:113]
	ds_read_b128 v[224:227], v156 offset:23136
	s_waitcnt lgkmcnt(5)
	v_mfma_f32_32x32x16_bf16 v[82:97], v[190:193], v[210:213], v[82:97]
	ds_read_b128 v[228:231], v156 offset:27744
	s_waitcnt lgkmcnt(5)
	v_mfma_f32_32x32x16_bf16 v[66:81], v[190:193], v[214:217], v[66:81]
	ds_read_b128 v[232:235], v156 offset:32352
	s_waitcnt lgkmcnt(5)
	v_mfma_f32_32x32x16_bf16 v[50:65], v[198:201], v[202:205], v[50:65]
	v_mfma_f32_32x32x16_bf16 v[34:49], v[198:201], v[206:209], v[34:49]
	v_mfma_f32_32x32x16_bf16 v[18:33], v[198:201], v[210:213], v[18:33]
	v_mfma_f32_32x32x16_bf16 v[2:17], v[198:201], v[214:217], v[2:17]
	ds_read_b128 v[198:201], v133 offset:4704
	s_waitcnt lgkmcnt(4)
	v_mfma_f32_32x32x16_bf16 v[114:129], v[194:197], v[218:221], v[114:129]
	s_waitcnt lgkmcnt(3)
	v_mfma_f32_32x32x16_bf16 v[98:113], v[194:197], v[224:227], v[98:113]
	s_waitcnt lgkmcnt(2)
	v_mfma_f32_32x32x16_bf16 v[82:97], v[194:197], v[228:231], v[82:97]
	s_waitcnt lgkmcnt(1)
	v_mfma_f32_32x32x16_bf16 v[66:81], v[194:197], v[232:235], v[66:81]
	s_waitcnt lgkmcnt(0)
	v_mfma_f32_32x32x16_bf16 v[50:65], v[198:201], v[218:221], v[50:65]
	v_mfma_f32_32x32x16_bf16 v[34:49], v[198:201], v[224:227], v[34:49]
	v_mfma_f32_32x32x16_bf16 v[18:33], v[198:201], v[228:231], v[18:33]
	v_mfma_f32_32x32x16_bf16 v[2:17], v[198:201], v[232:235], v[2:17]
	s_setprio 0
	v_mov_b32_e32 v130, v134
	s_barrier
	s_waitcnt lgkmcnt(0)
	s_mul_hi_i32 s13, s14, 0x1100
	v_ashrrev_i32_e32 v132, 1, v130
	s_mulk_i32 s14, 0x1100
	v_bfi_b32 v132, s39, v132, v130
	s_add_u32 s14, s14, s16
	s_addc_u32 s15, s13, s17
	v_ashrrev_i32_e32 v133, 31, v132
	v_lshl_add_u64 v[136:137], s[14:15], 0, v[132:133]
	v_and_b32_e32 v130, 32, v130
	v_lshlrev_b64 v[136:137], 12, v[136:137]
	v_mul_lo_u32 v132, v132, s22
	v_lshl_add_u32 v138, v130, 2, v132
	v_lshl_add_u64 v[132:133], s[4:5], 0, v[136:137]
	v_lshlrev_b32_e32 v130, 1, v130
	s_lshl_b32 s16, s12, 7
	v_lshl_add_u64 v[132:133], v[132:133], 0, v[130:131]
	s_mov_b64 s[12:13], -1
	s_branch .LBB0_1038

;     ...
;   for (int kt = 0; kt < nk; ++kt) {
;     const int kn = (kt + 1 < nk) ? kt + 1 : kt;
;     GW_LOAD2(kn * 64, kn * bkstep)
;     __builtin_amdgcn_sched_barrier(0);
;     __builtin_amdgcn_s_setprio(1);
; #pragma unroll
;     for (int st = 0; st < 4; ++st) {
;       bf16x8 a0 = *(const bf16x8*)(Ab + st * 32);
;       bf16x8 a1 = *(const bf16x8*)(Ab + 32 * LSTR + st * 32);
;       bf16x8 b0 = *(const bf16x8*)(Bb + st * 32);
;       bf16x8 b1 = *(const bf16x8*)(Bb + 32 * LSTR + st * 32);
;       bf16x8 b2 = *(const bf16x8*)(Bb + 64 * LSTR + st * 32);
;       bf16x8 b3 = *(const bf16x8*)(Bb + 96 * LSTR + st * 32);
;       acc[0][0] = mfma32(a0, b0, acc[0][0]);
;       acc[0][1] = mfma32(a0, b1, acc[0][1]);
;       acc[0][2] = mfma32(a0, b2, acc[0][2]);
;       acc[0][3] = mfma32(a0, b3, acc[0][3]);
;       acc[1][0] = mfma32(a1, b0, acc[1][0]);
;       acc[1][1] = mfma32(a1, b1, acc[1][1]);
;       acc[1][2] = mfma32(a1, b2, acc[1][2]);
;       acc[1][3] = mfma32(a1, b3, acc[1][3]);
;     }
;     __builtin_amdgcn_s_setprio(0);
;     __builtin_amdgcn_sched_barrier(0);
;     __syncthreads();
.LBB0_1113:
	s_barrier
	s_setprio 1
	ds_read_b128 v[200:203], v133 offset:0
	ds_read_b128 v[212:215], v150 offset:18432
	ds_read_b128 v[216:219], v150 offset:23040
	ds_read_b128 v[224:227], v150 offset:27648
	ds_read_b128 v[228:231], v150 offset:32256
	ds_read_b128 v[208:211], v133 offset:4608
	s_waitcnt lgkmcnt(4)
	v_mfma_f32_32x32x16_bf16 v[114:129], v[200:203], v[212:215], v[114:129]
	ds_read_b128 v[204:207], v133 offset:32
	ds_read_b128 v[232:235], v150 offset:18464
	s_waitcnt lgkmcnt(5)
	v_mfma_f32_32x32x16_bf16 v[98:113], v[200:203], v[216:219], v[98:113]
	ds_read_b128 v[236:239], v150 offset:23072
	s_waitcnt lgkmcnt(5)
	v_mfma_f32_32x32x16_bf16 v[82:97], v[200:203], v[224:227], v[82:97]
	ds_read_b128 v[240:243], v150 offset:27680
	s_waitcnt lgkmcnt(5)
	v_mfma_f32_32x32x16_bf16 v[66:81], v[200:203], v[228:231], v[66:81]
	ds_read_b128 v[244:247], v150 offset:32288
	s_waitcnt lgkmcnt(5)
	v_mfma_f32_32x32x16_bf16 v[50:65], v[208:211], v[212:215], v[50:65]
	v_lshl_add_u64 v[152:153], v[148:149], 0, v[130:131]
	v_add_co_u32_e32 v152, vcc, s37, v152
	s_nop 1
	v_addc_co_u32_e32 v153, vcc, 0, v153, vcc
	global_load_dwordx4 v[152:155], v[152:153], off offset:384
	v_mfma_f32_32x32x16_bf16 v[34:49], v[208:211], v[216:219], v[34:49]
	v_lshl_add_u64 v[156:157], v[148:149], 0, v[130:131]
	v_add_co_u32_e32 v156, vcc, s38, v156
	s_nop 1
	v_addc_co_u32_e32 v157, vcc, 0, v157, vcc
	global_load_dwordx4 v[156:159], v[156:157], off offset:384
	v_mfma_f32_32x32x16_bf16 v[18:33], v[208:211], v[224:227], v[18:33]
	v_lshl_add_u64 v[160:161], v[148:149], 0, v[130:131]
	v_add_co_u32_e32 v160, vcc, s39, v160
	s_nop 1
	v_addc_co_u32_e32 v161, vcc, 0, v161, vcc
	global_load_dwordx4 v[160:163], v[160:161], off offset:384
	v_mfma_f32_32x32x16_bf16 v[2:17], v[208:211], v[228:231], v[2:17]
	v_lshl_add_u64 v[164:165], v[148:149], 0, v[130:131]
	v_add_co_u32_e32 v164, vcc, s40, v164
	s_nop 1
	v_addc_co_u32_e32 v165, vcc, 0, v165, vcc
	global_load_dwordx4 v[164:167], v[164:165], off offset:384
	ds_read_b128 v[208:211], v133 offset:4640
	s_waitcnt lgkmcnt(4)
	v_mfma_f32_32x32x16_bf16 v[114:129], v[204:207], v[232:235], v[114:129]
	ds_read_b128 v[200:203], v133 offset:64
	ds_read_b128 v[212:215], v150 offset:18496
	s_waitcnt lgkmcnt(5)
	v_mfma_f32_32x32x16_bf16 v[98:113], v[204:207], v[236:239], v[98:113]
	ds_read_b128 v[216:219], v150 offset:23104
	s_waitcnt lgkmcnt(5)
	v_mfma_f32_32x32x16_bf16 v[82:97], v[204:207], v[240:243], v[82:97]
	ds_read_b128 v[224:227], v150 offset:27712
	s_waitcnt lgkmcnt(5)
	v_mfma_f32_32x32x16_bf16 v[66:81], v[204:207], v[244:247], v[66:81]
	ds_read_b128 v[228:231], v150 offset:32320
	s_waitcnt lgkmcnt(5)
	v_mfma_f32_32x32x16_bf16 v[50:65], v[208:211], v[232:235], v[50:65]
	v_lshl_add_u64 v[168:169], v[146:147], 0, v[130:131]
	v_add_co_u32_e32 v168, vcc, s41, v168
	s_nop 1
	v_addc_co_u32_e32 v169, vcc, 0, v169, vcc
	global_load_dwordx4 v[168:171], v[168:169], off offset:-4096
	v_mfma_f32_32x32x16_bf16 v[34:49], v[208:211], v[236:239], v[34:49]
	v_lshl_add_u64 v[172:173], v[146:147], 0, v[130:131]
	v_add_co_u32_e32 v172, vcc, s41, v172
	s_nop 1
	v_addc_co_u32_e32 v173, vcc, 0, v173, vcc
	global_load_dwordx4 v[172:175], v[172:173], off
	v_mfma_f32_32x32x16_bf16 v[18:33], v[208:211], v[240:243], v[18:33]
	v_lshl_add_u64 v[176:177], v[146:147], 0, v[130:131]
	v_add_co_u32_e32 v176, vcc, s42, v176
	s_nop 1
	v_addc_co_u32_e32 v177, vcc, 0, v177, vcc
	global_load_dwordx4 v[176:179], v[176:177], off offset:-4096
	v_mfma_f32_32x32x16_bf16 v[2:17], v[208:211], v[244:247], v[2:17]
	v_lshl_add_u64 v[180:181], v[146:147], 0, v[130:131]
	v_add_co_u32_e32 v180, vcc, s42, v180
	s_nop 1
	v_addc_co_u32_e32 v181, vcc, 0, v181, vcc
	global_load_dwordx4 v[180:183], v[180:181], off
	ds_read_b128 v[208:211], v133 offset:4672
	s_waitcnt lgkmcnt(4)
	v_mfma_f32_32x32x16_bf16 v[114:129], v[200:203], v[212:215], v[114:129]
	ds_read_b128 v[204:207], v133 offset:96
	ds_read_b128 v[232:235], v150 offset:18528
	s_waitcnt lgkmcnt(5)
	v_mfma_f32_32x32x16_bf16 v[98:113], v[200:203], v[216:219], v[98:113]
	ds_read_b128 v[236:239], v150 offset:23136
	s_waitcnt lgkmcnt(5)
	v_mfma_f32_32x32x16_bf16 v[82:97], v[200:203], v[224:227], v[82:97]
	ds_read_b128 v[240:243], v150 offset:27744
	s_waitcnt lgkmcnt(5)
	v_mfma_f32_32x32x16_bf16 v[66:81], v[200:203], v[228:231], v[66:81]
	ds_read_b128 v[244:247], v150 offset:32352
	s_waitcnt lgkmcnt(5)
	v_mfma_f32_32x32x16_bf16 v[50:65], v[208:211], v[212:215], v[50:65]
	v_lshl_add_u64 v[184:185], v[146:147], 0, v[130:131]
	v_add_co_u32_e32 v184, vcc, s43, v184
	s_nop 1
	v_addc_co_u32_e32 v185, vcc, 0, v185, vcc
	global_load_dwordx4 v[184:187], v[184:185], off offset:-4096
	v_mfma_f32_32x32x16_bf16 v[34:49], v[208:211], v[216:219], v[34:49]
	v_lshl_add_u64 v[188:189], v[146:147], 0, v[130:131]
	v_add_co_u32_e32 v188, vcc, s43, v188
	s_nop 1
	v_addc_co_u32_e32 v189, vcc, 0, v189, vcc
	global_load_dwordx4 v[188:191], v[188:189], off
	v_mfma_f32_32x32x16_bf16 v[18:33], v[208:211], v[224:227], v[18:33]
	v_lshl_add_u64 v[192:193], v[146:147], 0, v[130:131]
	v_add_co_u32_e32 v192, vcc, s44, v192
	s_nop 1
	v_addc_co_u32_e32 v193, vcc, 0, v193, vcc
	global_load_dwordx4 v[192:195], v[192:193], off offset:-4096
	v_mfma_f32_32x32x16_bf16 v[2:17], v[208:211], v[228:231], v[2:17]
	v_lshl_add_u64 v[196:197], v[146:147], 0, v[130:131]
	v_add_co_u32_e32 v196, vcc, s44, v196
	s_nop 1
	v_addc_co_u32_e32 v197, vcc, 0, v197, vcc
	global_load_dwordx4 v[196:199], v[196:197], off
	ds_read_b128 v[208:211], v133 offset:4704
	s_waitcnt lgkmcnt(4)
	v_mfma_f32_32x32x16_bf16 v[114:129], v[204:207], v[232:235], v[114:129]
	s_waitcnt lgkmcnt(3)
	v_mfma_f32_32x32x16_bf16 v[98:113], v[204:207], v[236:239], v[98:113]
	s_waitcnt lgkmcnt(2)
	v_mfma_f32_32x32x16_bf16 v[82:97], v[204:207], v[240:243], v[82:97]
	s_waitcnt lgkmcnt(1)
	v_mfma_f32_32x32x16_bf16 v[66:81], v[204:207], v[244:247], v[66:81]
	s_waitcnt lgkmcnt(0)
	v_mfma_f32_32x32x16_bf16 v[50:65], v[208:211], v[232:235], v[50:65]
	v_mfma_f32_32x32x16_bf16 v[34:49], v[208:211], v[236:239], v[34:49]
	v_mfma_f32_32x32x16_bf16 v[18:33], v[208:211], v[240:243], v[18:33]
	v_mfma_f32_32x32x16_bf16 v[2:17], v[208:211], v[244:247], v[2:17]
	s_setprio 0
	s_add_i32 s15, s15, -1
	v_lshl_add_u64 v[146:147], v[146:147], 0, s[4:5]
	s_cmp_lg_u32 s15, 0
	v_lshl_add_u64 v[148:149], v[148:149], 0, s[10:11]
	s_barrier
;     ...
;   for (int kt = 0; kt < nk; ++kt) {
;     const int kn = (kt + 1 < nk) ? kt + 1 : kt;
;     GW_LOAD2(kn * 64, kn * bkstep)
;     __builtin_amdgcn_sched_barrier(0);
;     __builtin_amdgcn_s_setprio(1);
; #pragma unroll
;     for (int st = 0; st < 4; ++st) {
;       bf16x8 a0 = *(const bf16x8*)(Ab + st * 32);
;       bf16x8 a1 = *(const bf16x8*)(Ab + 32 * LSTR + st * 32);
;       bf16x8 b0 = *(const bf16x8*)(Bb + st * 32);
;       bf16x8 b1 = *(const bf16x8*)(Bb + 32 * LSTR + st * 32);
;       bf16x8 b2 = *(const bf16x8*)(Bb + 64 * LSTR + st * 32);
;       bf16x8 b3 = *(const bf16x8*)(Bb + 96 * LSTR + st * 32);
;       acc[0][0] = mfma32(a0, b0, acc[0][0]);
;       acc[0][1] = mfma32(a0, b1, acc[0][1]);
;       acc[0][2] = mfma32(a0, b2, acc[0][2]);
;       acc[0][3] = mfma32(a0, b3, acc[0][3]);
;       acc[1][0] = mfma32(a1, b0, acc[1][0]);
;       acc[1][1] = mfma32(a1, b1, acc[1][1]);
;       acc[1][2] = mfma32(a1, b2, acc[1][2]);
;       acc[1][3] = mfma32(a1, b3, acc[1][3]);
;     }
;     __builtin_amdgcn_s_setprio(0);
;     __builtin_amdgcn_sched_barrier(0);
;     __syncthreads();
;     GW_STORE()
;     __syncthreads();
	s_waitcnt vmcnt(11)
	ds_write_b128 v132, v[152:155]
	s_waitcnt vmcnt(10)
	ds_write_b128 v132, v[156:159] offset:4608
	s_waitcnt vmcnt(9)
	ds_write_b128 v132, v[160:163] offset:9216
	s_waitcnt vmcnt(8)
	ds_write_b128 v132, v[164:167] offset:13824
	s_waitcnt vmcnt(7)
	ds_write_b128 v132, v[168:171] offset:18432
	s_waitcnt vmcnt(6)
	ds_write_b128 v132, v[172:175] offset:23040
	s_waitcnt vmcnt(5)
	ds_write_b128 v132, v[176:179] offset:27648
	s_waitcnt vmcnt(4)
	ds_write_b128 v132, v[180:183] offset:32256
	s_waitcnt vmcnt(3)
	ds_write_b128 v132, v[184:187] offset:36864
	s_waitcnt vmcnt(2)
	ds_write_b128 v132, v[188:191] offset:41472
	s_waitcnt vmcnt(1)
	ds_write_b128 v132, v[192:195] offset:46080
	s_waitcnt vmcnt(0)
	ds_write_b128 v132, v[196:199] offset:50688
	s_waitcnt lgkmcnt(0)
	s_cbranch_scc1 .LBB0_1113
	s_barrier
	s_setprio 1
	ds_read_b128 v[200:203], v133 offset:0
	ds_read_b128 v[212:215], v150 offset:18432
	ds_read_b128 v[216:219], v150 offset:23040
	ds_read_b128 v[224:227], v150 offset:27648
	ds_read_b128 v[228:231], v150 offset:32256
	ds_read_b128 v[208:211], v133 offset:4608
	s_waitcnt lgkmcnt(4)
	v_mfma_f32_32x32x16_bf16 v[114:129], v[200:203], v[212:215], v[114:129]
	ds_read_b128 v[204:207], v133 offset:32
	ds_read_b128 v[232:235], v150 offset:18464
	s_waitcnt lgkmcnt(5)
	v_mfma_f32_32x32x16_bf16 v[98:113], v[200:203], v[216:219], v[98:113]
	ds_read_b128 v[236:239], v150 offset:23072
	s_waitcnt lgkmcnt(5)
	v_mfma_f32_32x32x16_bf16 v[82:97], v[200:203], v[224:227], v[82:97]
	ds_read_b128 v[240:243], v150 offset:27680
	s_waitcnt lgkmcnt(5)
	v_mfma_f32_32x32x16_bf16 v[66:81], v[200:203], v[228:231], v[66:81]
	ds_read_b128 v[244:247], v150 offset:32288
	s_waitcnt lgkmcnt(5)
	v_mfma_f32_32x32x16_bf16 v[50:65], v[208:211], v[212:215], v[50:65]
	v_lshl_add_u64 v[152:153], v[148:149], 0, v[130:131]
	v_add_co_u32_e32 v152, vcc, s37, v152
	s_nop 1
	v_addc_co_u32_e32 v153, vcc, 0, v153, vcc
	global_load_dwordx4 v[152:155], v[152:153], off offset:384
	v_mfma_f32_32x32x16_bf16 v[34:49], v[208:211], v[216:219], v[34:49]
	v_lshl_add_u64 v[156:157], v[148:149], 0, v[130:131]
	v_add_co_u32_e32 v156, vcc, s38, v156
	s_nop 1
	v_addc_co_u32_e32 v157, vcc, 0, v157, vcc
	global_load_dwordx4 v[156:159], v[156:157], off offset:384
	v_mfma_f32_32x32x16_bf16 v[18:33], v[208:211], v[224:227], v[18:33]
	v_lshl_add_u64 v[160:161], v[148:149], 0, v[130:131]
	v_add_co_u32_e32 v160, vcc, s39, v160
	s_nop 1
	v_addc_co_u32_e32 v161, vcc, 0, v161, vcc
	global_load_dwordx4 v[160:163], v[160:161], off offset:384
	v_mfma_f32_32x32x16_bf16 v[2:17], v[208:211], v[228:231], v[2:17]
	v_lshl_add_u64 v[164:165], v[148:149], 0, v[130:131]
	v_add_co_u32_e32 v164, vcc, s40, v164
	s_nop 1
	v_addc_co_u32_e32 v165, vcc, 0, v165, vcc
	global_load_dwordx4 v[164:167], v[164:165], off offset:384
	ds_read_b128 v[208:211], v133 offset:4640
	s_waitcnt lgkmcnt(4)
	v_mfma_f32_32x32x16_bf16 v[114:129], v[204:207], v[232:235], v[114:129]
	ds_read_b128 v[200:203], v133 offset:64
	ds_read_b128 v[212:215], v150 offset:18496
	s_waitcnt lgkmcnt(5)
	v_mfma_f32_32x32x16_bf16 v[98:113], v[204:207], v[236:239], v[98:113]
	ds_read_b128 v[216:219], v150 offset:23104
	s_waitcnt lgkmcnt(5)
	v_mfma_f32_32x32x16_bf16 v[82:97], v[204:207], v[240:243], v[82:97]
	ds_read_b128 v[224:227], v150 offset:27712
	s_waitcnt lgkmcnt(5)
	v_mfma_f32_32x32x16_bf16 v[66:81], v[204:207], v[244:247], v[66:81]
	ds_read_b128 v[228:231], v150 offset:32320
	s_waitcnt lgkmcnt(5)
	v_mfma_f32_32x32x16_bf16 v[50:65], v[208:211], v[232:235], v[50:65]
	v_lshl_add_u64 v[168:169], v[146:147], 0, v[130:131]
	v_add_co_u32_e32 v168, vcc, s41, v168
	s_nop 1
	v_addc_co_u32_e32 v169, vcc, 0, v169, vcc
	global_load_dwordx4 v[168:171], v[168:169], off offset:-4096
	v_mfma_f32_32x32x16_bf16 v[34:49], v[208:211], v[236:239], v[34:49]
	v_lshl_add_u64 v[172:173], v[146:147], 0, v[130:131]
	v_add_co_u32_e32 v172, vcc, s41, v172
	s_nop 1
	v_addc_co_u32_e32 v173, vcc, 0, v173, vcc
	global_load_dwordx4 v[172:175], v[172:173], off
	v_mfma_f32_32x32x16_bf16 v[18:33], v[208:211], v[240:243], v[18:33]
	v_lshl_add_u64 v[176:177], v[146:147], 0, v[130:131]
	v_add_co_u32_e32 v176, vcc, s42, v176
	s_nop 1
	v_addc_co_u32_e32 v177, vcc, 0, v177, vcc
	global_load_dwordx4 v[176:179], v[176:177], off offset:-4096
	v_mfma_f32_32x32x16_bf16 v[2:17], v[208:211], v[244:247], v[2:17]
	v_lshl_add_u64 v[180:181], v[146:147], 0, v[130:131]
	v_add_co_u32_e32 v180, vcc, s42, v180
	s_nop 1
	v_addc_co_u32_e32 v181, vcc, 0, v181, vcc
	global_load_dwordx4 v[180:183], v[180:181], off
	ds_read_b128 v[208:211], v133 offset:4672
	s_waitcnt lgkmcnt(4)
	v_mfma_f32_32x32x16_bf16 v[114:129], v[200:203], v[212:215], v[114:129]
	ds_read_b128 v[204:207], v133 offset:96
	ds_read_b128 v[232:235], v150 offset:18528
	s_waitcnt lgkmcnt(5)
	v_mfma_f32_32x32x16_bf16 v[98:113], v[200:203], v[216:219], v[98:113]
	ds_read_b128 v[236:239], v150 offset:23136
	s_waitcnt lgkmcnt(5)
	v_mfma_f32_32x32x16_bf16 v[82:97], v[200:203], v[224:227], v[82:97]
	ds_read_b128 v[240:243], v150 offset:27744
	s_waitcnt lgkmcnt(5)
	v_mfma_f32_32x32x16_bf16 v[66:81], v[200:203], v[228:231], v[66:81]
	ds_read_b128 v[244:247], v150 offset:32352
	s_waitcnt lgkmcnt(5)
;     ...
;     for (int st = 0; st < 4; ++st) {
;       bf16x8 a0 = *(const bf16x8*)(Ab + st * 32);
;       bf16x8 a1 = *(const bf16x8*)(Ab + 32 * LSTR + st * 32);
;       bf16x8 b0 = *(const bf16x8*)(Bb + st * 32);
;       bf16x8 b1 = *(const bf16x8*)(Bb + 32 * LSTR + st * 32);
;       bf16x8 b2 = *(const bf16x8*)(Bb + 64 * LSTR + st * 32);
;       bf16x8 b3 = *(const bf16x8*)(Bb + 96 * LSTR + st * 32);
;       acc[0][0] = mfma32(a0, b0, acc[0][0]);
;       acc[0][1] = mfma32(a0, b1, acc[0][1]);
;       acc[0][2] = mfma32(a0, b2, acc[0][2]);
;       acc[0][3] = mfma32(a0, b3, acc[0][3]);
;       acc[1][0] = mfma32(a1, b0, acc[1][0]);
;       acc[1][1] = mfma32(a1, b1, acc[1][1]);
;       acc[1][2] = mfma32(a1, b2, acc[1][2]);
;       acc[1][3] = mfma32(a1, b3, acc[1][3]);
;     }
;     __builtin_amdgcn_s_setprio(0);
;     __builtin_amdgcn_sched_barrier(0);
;     __syncthreads();
;     GW_STORE()
;     __syncthreads();
	v_mfma_f32_32x32x16_bf16 v[50:65], v[208:211], v[212:215], v[50:65]
	v_lshl_add_u64 v[184:185], v[146:147], 0, v[130:131]
	v_add_co_u32_e32 v184, vcc, s43, v184
	s_nop 1
	v_addc_co_u32_e32 v185, vcc, 0, v185, vcc
	global_load_dwordx4 v[184:187], v[184:185], off offset:-4096
	v_mfma_f32_32x32x16_bf16 v[34:49], v[208:211], v[216:219], v[34:49]
	v_lshl_add_u64 v[188:189], v[146:147], 0, v[130:131]
	v_add_co_u32_e32 v188, vcc, s43, v188
	s_nop 1
	v_addc_co_u32_e32 v189, vcc, 0, v189, vcc
	global_load_dwordx4 v[188:191], v[188:189], off
	v_mfma_f32_32x32x16_bf16 v[18:33], v[208:211], v[224:227], v[18:33]
	v_lshl_add_u64 v[192:193], v[146:147], 0, v[130:131]
	v_add_co_u32_e32 v192, vcc, s44, v192
	s_nop 1
	v_addc_co_u32_e32 v193, vcc, 0, v193, vcc
	global_load_dwordx4 v[192:195], v[192:193], off offset:-4096
	v_mfma_f32_32x32x16_bf16 v[2:17], v[208:211], v[228:231], v[2:17]
	v_lshl_add_u64 v[196:197], v[146:147], 0, v[130:131]
	v_add_co_u32_e32 v196, vcc, s44, v196
	s_nop 1
	v_addc_co_u32_e32 v197, vcc, 0, v197, vcc
	global_load_dwordx4 v[196:199], v[196:197], off
	ds_read_b128 v[208:211], v133 offset:4704
	s_waitcnt lgkmcnt(4)
	v_mfma_f32_32x32x16_bf16 v[114:129], v[204:207], v[232:235], v[114:129]
	s_waitcnt lgkmcnt(3)
	v_mfma_f32_32x32x16_bf16 v[98:113], v[204:207], v[236:239], v[98:113]
	s_waitcnt lgkmcnt(2)
	v_mfma_f32_32x32x16_bf16 v[82:97], v[204:207], v[240:243], v[82:97]
	s_waitcnt lgkmcnt(1)
	v_mfma_f32_32x32x16_bf16 v[66:81], v[204:207], v[244:247], v[66:81]
	s_waitcnt lgkmcnt(0)
	v_mfma_f32_32x32x16_bf16 v[50:65], v[208:211], v[232:235], v[50:65]
	v_mfma_f32_32x32x16_bf16 v[34:49], v[208:211], v[236:239], v[34:49]
	v_mfma_f32_32x32x16_bf16 v[18:33], v[208:211], v[240:243], v[18:33]
	v_mfma_f32_32x32x16_bf16 v[2:17], v[208:211], v[244:247], v[2:17]
	s_setprio 0
	v_lshl_add_u64 v[146:147], v[146:147], 0, s[4:5]
	v_lshl_add_u64 v[148:149], v[148:149], 0, s[10:11]
	s_barrier
	s_waitcnt vmcnt(11)
	ds_write_b128 v132, v[152:155]
	s_waitcnt vmcnt(10)
	ds_write_b128 v132, v[156:159] offset:4608
	s_waitcnt vmcnt(9)
	ds_write_b128 v132, v[160:163] offset:9216
	s_waitcnt vmcnt(8)
	ds_write_b128 v132, v[164:167] offset:13824
	s_waitcnt vmcnt(7)
	ds_write_b128 v132, v[168:171] offset:18432
	s_waitcnt vmcnt(6)
	ds_write_b128 v132, v[172:175] offset:23040
	s_waitcnt vmcnt(5)
	ds_write_b128 v132, v[176:179] offset:27648
	s_waitcnt vmcnt(4)
	ds_write_b128 v132, v[180:183] offset:32256
	s_waitcnt vmcnt(3)
	ds_write_b128 v132, v[184:187] offset:36864
	s_waitcnt vmcnt(2)
	ds_write_b128 v132, v[188:191] offset:41472
	s_waitcnt vmcnt(1)
	ds_write_b128 v132, v[192:195] offset:46080
	s_waitcnt vmcnt(0)
	ds_write_b128 v132, v[196:199] offset:50688
	s_waitcnt lgkmcnt(0)
	s_barrier
;     ...
;   for (int kt = 0; kt < nk; ++kt) {
;     const int kn = (kt + 1 < nk) ? kt + 1 : kt;
;     GW_LOAD2(kn * 64, kn * bkstep)
;     __builtin_amdgcn_sched_barrier(0);
;     __builtin_amdgcn_s_setprio(1);
; #pragma unroll
;     for (int st = 0; st < 4; ++st) {
;       bf16x8 a0 = *(const bf16x8*)(Ab + st * 32);
;       bf16x8 a1 = *(const bf16x8*)(Ab + 32 * LSTR + st * 32);
;       bf16x8 b0 = *(const bf16x8*)(Bb + st * 32);
;       bf16x8 b1 = *(const bf16x8*)(Bb + 32 * LSTR + st * 32);
;       bf16x8 b2 = *(const bf16x8*)(Bb + 64 * LSTR + st * 32);
;       bf16x8 b3 = *(const bf16x8*)(Bb + 96 * LSTR + st * 32);
;       acc[0][0] = mfma32(a0, b0, acc[0][0]);
;       acc[0][1] = mfma32(a0, b1, acc[0][1]);
;       acc[0][2] = mfma32(a0, b2, acc[0][2]);
;       acc[0][3] = mfma32(a0, b3, acc[0][3]);
;       acc[1][0] = mfma32(a1, b0, acc[1][0]);
;       acc[1][1] = mfma32(a1, b1, acc[1][1]);
;       acc[1][2] = mfma32(a1, b2, acc[1][2]);
;       acc[1][3] = mfma32(a1, b3, acc[1][3]);
;     }
;     __builtin_amdgcn_s_setprio(0);
;     __builtin_amdgcn_sched_barrier(0);
	v_add_co_u32_e32 v156, vcc, 0x3e0000, v136
	s_nop 0
	s_nop 0
	s_nop 0
	v_addc_co_u32_e32 v157, vcc, 0, v137, vcc
	v_add_co_u32_e32 v160, vcc, 0x3e1000, v136
	s_mov_b32 s18, 0
	s_nop 0
	v_addc_co_u32_e32 v161, vcc, 0, v137, vcc
	v_add_co_u32_e32 v164, vcc, 0x3e2000, v136
	s_nop 0
	v_addc_co_u32_e32 v165, vcc, 0, v137, vcc
	v_add_co_u32_e32 v168, vcc, 0x3e3000, v136
	s_nop 1
	v_addc_co_u32_e32 v169, vcc, 0, v137, vcc
	v_add_co_u32_e32 v172, vcc, 0x3e4000, v136
	s_nop 0
	v_addc_co_u32_e32 v173, vcc, 0, v137, vcc
	v_add_co_u32_e32 v176, vcc, 0x3e5000, v136
	s_nop 1
	v_addc_co_u32_e32 v177, vcc, 0, v137, vcc
	v_add_co_u32_e32 v180, vcc, 0x3e6000, v136
	s_nop 0
	v_addc_co_u32_e32 v181, vcc, 0, v137, vcc
	v_add_co_u32_e32 v136, vcc, 0x3e7000, v136
	s_nop 1
	v_addc_co_u32_e32 v137, vcc, 0, v137, vcc
	s_nop 0
	s_setprio 1
	ds_read_b128 v[188:191], v133 offset:0
	ds_read_b128 v[200:203], v150 offset:18432
	ds_read_b128 v[204:207], v150 offset:23040
	ds_read_b128 v[208:211], v150 offset:27648
	ds_read_b128 v[212:215], v150 offset:32256
	ds_read_b128 v[196:199], v133 offset:4608
	s_waitcnt lgkmcnt(4)
	v_mfma_f32_32x32x16_bf16 v[114:129], v[188:191], v[200:203], v[114:129]
	ds_read_b128 v[192:195], v133 offset:32
	ds_read_b128 v[216:219], v150 offset:18464
	s_waitcnt lgkmcnt(5)
	v_mfma_f32_32x32x16_bf16 v[98:113], v[188:191], v[204:207], v[98:113]
	ds_read_b128 v[224:227], v150 offset:23072
	s_waitcnt lgkmcnt(5)
	v_mfma_f32_32x32x16_bf16 v[82:97], v[188:191], v[208:211], v[82:97]
	ds_read_b128 v[228:231], v150 offset:27680
	s_waitcnt lgkmcnt(5)
	v_mfma_f32_32x32x16_bf16 v[66:81], v[188:191], v[212:215], v[66:81]
	ds_read_b128 v[232:235], v150 offset:32288
	s_waitcnt lgkmcnt(5)
	v_mfma_f32_32x32x16_bf16 v[50:65], v[196:199], v[200:203], v[50:65]
	v_mfma_f32_32x32x16_bf16 v[34:49], v[196:199], v[204:207], v[34:49]
	v_mfma_f32_32x32x16_bf16 v[18:33], v[196:199], v[208:211], v[18:33]
	v_mfma_f32_32x32x16_bf16 v[2:17], v[196:199], v[212:215], v[2:17]
	ds_read_b128 v[196:199], v133 offset:4640
	s_waitcnt lgkmcnt(4)
	v_mfma_f32_32x32x16_bf16 v[114:129], v[192:195], v[216:219], v[114:129]
	ds_read_b128 v[188:191], v133 offset:64
	ds_read_b128 v[200:203], v150 offset:18496
	s_waitcnt lgkmcnt(5)
	v_mfma_f32_32x32x16_bf16 v[98:113], v[192:195], v[224:227], v[98:113]
	ds_read_b128 v[204:207], v150 offset:23104
	s_waitcnt lgkmcnt(5)
	v_mfma_f32_32x32x16_bf16 v[82:97], v[192:195], v[228:231], v[82:97]
	ds_read_b128 v[208:211], v150 offset:27712
	s_waitcnt lgkmcnt(5)
	v_mfma_f32_32x32x16_bf16 v[66:81], v[192:195], v[232:235], v[66:81]
	ds_read_b128 v[212:215], v150 offset:32320
	s_waitcnt lgkmcnt(5)
	v_mfma_f32_32x32x16_bf16 v[50:65], v[196:199], v[216:219], v[50:65]
	v_mfma_f32_32x32x16_bf16 v[34:49], v[196:199], v[224:227], v[34:49]
	v_mfma_f32_32x32x16_bf16 v[18:33], v[196:199], v[228:231], v[18:33]
	v_mfma_f32_32x32x16_bf16 v[2:17], v[196:199], v[232:235], v[2:17]
	ds_read_b128 v[196:199], v133 offset:4672
	s_waitcnt lgkmcnt(4)
	v_mfma_f32_32x32x16_bf16 v[114:129], v[188:191], v[200:203], v[114:129]
	ds_read_b128 v[192:195], v133 offset:96
	ds_read_b128 v[216:219], v150 offset:18528
	s_waitcnt lgkmcnt(5)
	v_mfma_f32_32x32x16_bf16 v[98:113], v[188:191], v[204:207], v[98:113]
	ds_read_b128 v[224:227], v150 offset:23136
	s_waitcnt lgkmcnt(5)
	v_mfma_f32_32x32x16_bf16 v[82:97], v[188:191], v[208:211], v[82:97]
	ds_read_b128 v[228:231], v150 offset:27744
	s_waitcnt lgkmcnt(5)
	v_mfma_f32_32x32x16_bf16 v[66:81], v[188:191], v[212:215], v[66:81]
	ds_read_b128 v[232:235], v150 offset:32352
	s_waitcnt lgkmcnt(5)
	v_mfma_f32_32x32x16_bf16 v[50:65], v[196:199], v[200:203], v[50:65]
	v_mfma_f32_32x32x16_bf16 v[34:49], v[196:199], v[204:207], v[34:49]
	v_mfma_f32_32x32x16_bf16 v[18:33], v[196:199], v[208:211], v[18:33]
	v_mfma_f32_32x32x16_bf16 v[2:17], v[196:199], v[212:215], v[2:17]
	ds_read_b128 v[196:199], v133 offset:4704
	s_waitcnt lgkmcnt(4)
	v_mfma_f32_32x32x16_bf16 v[114:129], v[192:195], v[216:219], v[114:129]
	s_waitcnt lgkmcnt(3)
	v_mfma_f32_32x32x16_bf16 v[98:113], v[192:195], v[224:227], v[98:113]
	s_waitcnt lgkmcnt(2)
	v_mfma_f32_32x32x16_bf16 v[82:97], v[192:195], v[228:231], v[82:97]
	s_waitcnt lgkmcnt(1)
	v_mfma_f32_32x32x16_bf16 v[66:81], v[192:195], v[232:235], v[66:81]
	s_waitcnt lgkmcnt(0)
	v_mfma_f32_32x32x16_bf16 v[50:65], v[196:199], v[216:219], v[50:65]
	v_mfma_f32_32x32x16_bf16 v[34:49], v[196:199], v[224:227], v[34:49]
	v_mfma_f32_32x32x16_bf16 v[18:33], v[196:199], v[228:231], v[18:33]
	v_mfma_f32_32x32x16_bf16 v[2:17], v[196:199], v[232:235], v[2:17]
	s_setprio 0
	v_readlane_b32 s48, v253, 37
	v_readlane_b32 s49, v253, 38
	v_readlane_b32 s50, v253, 39
	v_readlane_b32 s51, v253, 40
	v_readlane_b32 s52, v253, 41
	v_readlane_b32 s53, v253, 42
	v_readlane_b32 s54, v253, 43
	v_readlane_b32 s55, v253, 44
	v_readlane_b32 s56, v253, 45
	v_readlane_b32 s57, v253, 46
	v_readlane_b32 s58, v253, 47
	v_readlane_b32 s59, v253, 48
	v_readlane_b32 s60, v253, 49
	v_readlane_b32 s61, v253, 50
	v_readlane_b32 s62, v253, 51
	v_readlane_b32 s63, v253, 52
	s_mov_b64 s[48:49], s[56:57]
	s_lshl_b32 s19, s14, 8
	s_mov_b64 s[14:15], -1
	s_mov_b64 s[50:51], s[58:59]
	s_mov_b64 s[52:53], s[60:61]
	s_mov_b64 s[54:55], s[62:63]
	s_barrier
	s_waitcnt lgkmcnt(0)
	s_branch .LBB0_1116

; #define GM_LOAD(KOFF) GM_LOAD2(KOFF, 0)
;   const int tid = threadIdx.x, lane = tid & 63, wave = tid >> 6;
;   const int wm = wave >> 1, wn = wave & 1;
;   const int lr = tid >> 3, kc = tid & 7;
;   const u16* ap0 = arow(lr) + kc * 8;
;   const u16* ap1 = arow(lr + 32) + kc * 8;
;   const u16* ap2 = arow(lr + 64) + kc * 8;
;   const u16* ap3 = arow(lr + 96) + kc * 8;
;   const u16* bp0 = Bt + (size_t)lr * ldb + kc * 8;
;   const size_t bstep = 32 * ldb;
;   const int so = lr * LSTR + kc * 16;
;   uint4 ra0, ra1, ra2, ra3, rb0, rb1, rb2, rb3;
;     ...
;   GM_LOAD(0)
;   GM_STORE(smem)
;   __syncthreads();
;   const int nk = K >> 6;
;   const int aoff = (wm * 64 + (lane & 31)) * LSTR + (lane >> 5) * 16;
;   const int boff = (wn * 64 + (lane & 31)) * LSTR + (lane >> 5) * 16;
;   for (int kt = 0; kt < nk; ++kt) {
;     const int kn = (kt + 1 < nk) ? kt + 1 : kt;
;     GM_LOAD2(kn * 64, kn * bkstep)
; __device__ __forceinline__ void zero_acc(f32x16 (&acc)[2][2]) {
; #pragma unroll
;   for (int i = 0; i < 2; ++i)
; #pragma unroll
;     for (int j = 0; j < 2; ++j)
; #pragma unroll
;       for (int r = 0; r < 16; ++r) acc[i][j][r] = 0.f;
.LBB0_1120:
	s_and_b32 s2, s34, 7
	s_lshl_b32 s36, s35, 4
	s_lshl_b32 s42, s2, 14
	s_lshl_b32 s2, s19, 12
	s_ashr_i32 s14, s35, 4
	s_and_b32 s36, s36, 0x80
	s_and_b32 s43, s2, 0x80000
	s_and_b32 s2, s35, 7
	s_ashr_i32 s15, s14, 31
	s_mul_i32 s12, s14, 0x1100
	s_bitset1_b32 s36, 12
	s_mul_hi_i32 s13, s14, 0x1100
	s_add_u32 s12, s12, s36
	s_addc_u32 s13, s13, 0
	s_lshl_b64 s[36:37], s[12:13], 12
	s_lshl_b64 s[38:39], s[14:15], 22
	s_add_u32 s15, s17, s38
	s_addc_u32 s41, s18, s39
	s_lshl_b32 s40, s2, 14
	s_add_u32 s40, s15, s40
	s_addc_u32 s41, s41, 0
	v_lshl_add_u64 v[2:3], v[72:73], 0, s[36:37]
	v_lshl_add_u64 v[82:83], v[2:3], 0, v[76:77]
	v_lshl_add_u64 v[2:3], s[40:41], 0, v[78:79]
	v_lshl_add_u64 v[80:81], v[2:3], 0, v[76:77]
	v_add_co_u32_e32 v2, vcc, s21, v82
	s_mul_hi_i32 s37, s14, 0x1100000
	s_nop 0
	v_addc_co_u32_e32 v3, vcc, 0, v83, vcc
	v_add_co_u32_e32 v4, vcc, s22, v82
	s_mul_i32 s14, s14, 0x1100000
	s_nop 0
	v_addc_co_u32_e32 v5, vcc, 0, v83, vcc
	global_load_dwordx4 v[22:25], v[2:3], off
	global_load_dwordx4 v[26:29], v[4:5], off
	v_add_co_u32_e32 v2, vcc, s23, v82
	s_or_b32 s38, s38, s42
	s_nop 0
	v_addc_co_u32_e32 v3, vcc, 0, v83, vcc
	global_load_dwordx4 v[30:33], v[2:3], off
	global_load_dwordx4 v[34:37], v[82:83], off
	global_load_dwordx4 v[38:41], v[80:81], off
	v_add_co_u32_e32 v2, vcc, s24, v80
	s_or_b32 s36, s14, s43
	s_nop 0
	v_addc_co_u32_e32 v3, vcc, 0, v81, vcc
	global_load_dwordx4 v[42:45], v[2:3], off offset:-4096
	global_load_dwordx4 v[46:49], v[2:3], off
	v_add_co_u32_e32 v2, vcc, s25, v80
	s_mov_b32 s15, 0
	s_nop 0
	v_addc_co_u32_e32 v3, vcc, 0, v81, vcc
	global_load_dwordx4 v[50:53], v[2:3], off
	v_mov_b32_e32 v2, 0
	v_mov_b32_e32 v3, v67
	v_mov_b32_e32 v4, v67
	v_mov_b32_e32 v5, v67
	v_mov_b32_e32 v6, v67
	v_mov_b32_e32 v7, v67
	v_mov_b32_e32 v8, v67
	v_mov_b32_e32 v9, v67
	v_mov_b32_e32 v10, v67
	v_mov_b32_e32 v11, v67
	v_mov_b32_e32 v12, v67
	v_mov_b32_e32 v13, v67
	v_mov_b32_e32 v14, v67
	v_mov_b32_e32 v15, v67
	v_mov_b32_e32 v16, v67
	v_mov_b32_e32 v17, v67
	v_mov_b32_e32 v18, 0
	v_mov_b32_e32 v19, v67
	v_mov_b32_e32 v20, v67
	v_mov_b32_e32 v21, v67
	v_lshl_add_u64 v[84:85], v[82:83], 0, s[4:5]
	v_lshl_add_u64 v[86:87], v[82:83], 0, s[6:7]
	v_lshl_add_u64 v[88:89], v[82:83], 0, s[8:9]
	v_lshl_add_u64 v[90:91], v[74:75], 0, s[38:39]
	v_lshl_add_u64 v[92:93], v[70:71], 0, s[36:37]
	v_mov_b32_e32 v54, v67
	v_mov_b32_e32 v55, v67
	v_mov_b32_e32 v56, v67
	v_mov_b32_e32 v57, v67
	v_mov_b32_e32 v58, v67
	v_mov_b32_e32 v59, v67
	v_mov_b32_e32 v60, v67
	v_mov_b32_e32 v61, v67
	v_mov_b32_e32 v62, v67
	v_mov_b32_e32 v63, v67
	v_mov_b32_e32 v64, v67
	v_mov_b32_e32 v65, v67
	s_waitcnt vmcnt(4)
	ds_write_b128 v1, v[34:37]
	ds_write_b128 v1, v[22:25] offset:4608
	ds_write_b128 v1, v[26:29] offset:9216
	ds_write_b128 v1, v[30:33] offset:13824
	s_waitcnt vmcnt(3)
	ds_write_b128 v1, v[38:41] offset:18432
	s_waitcnt vmcnt(2)
	ds_write_b128 v1, v[42:45] offset:23040
	s_waitcnt vmcnt(1)
	ds_write_b128 v1, v[46:49] offset:27648
	s_waitcnt vmcnt(0)
	ds_write_b128 v1, v[50:53] offset:32256
	v_mov_b32_e32 v22, v67
	v_mov_b32_e32 v23, v67
	v_mov_b32_e32 v24, v67
	v_mov_b32_e32 v25, v67
	v_mov_b32_e32 v26, v67
	v_mov_b32_e32 v27, v67
	v_mov_b32_e32 v28, v67
	v_mov_b32_e32 v29, v67
	v_mov_b32_e32 v30, v67
	v_mov_b32_e32 v31, v67
	v_mov_b32_e32 v32, v67
	v_mov_b32_e32 v33, v67
	v_mov_b32_e32 v50, 0
	v_mov_b32_e32 v51, v67
	v_mov_b32_e32 v52, v67
	v_mov_b32_e32 v53, v67
	v_mov_b32_e32 v34, 0
	v_mov_b32_e32 v35, v67
	v_mov_b32_e32 v36, v67
	v_mov_b32_e32 v37, v67
	v_mov_b32_e32 v38, v67
	v_mov_b32_e32 v39, v67
	v_mov_b32_e32 v40, v67
	v_mov_b32_e32 v41, v67
	v_mov_b32_e32 v42, v67
	v_mov_b32_e32 v43, v67
	v_mov_b32_e32 v44, v67
	v_mov_b32_e32 v45, v67
	v_mov_b32_e32 v46, v67
	v_mov_b32_e32 v47, v67
	v_mov_b32_e32 v48, v67
	v_mov_b32_e32 v49, v67
	s_waitcnt lgkmcnt(0)
	v_lshl_add_u64 v[106:107], v[92:93], 0, v[68:69]
	v_add_co_u32_e32 v98, vcc, s26, v106
	v_lshl_add_u64 v[122:123], v[90:91], 0, v[68:69]
	s_nop 0
	v_addc_co_u32_e32 v99, vcc, 0, v107, vcc
	v_add_co_u32_e32 v102, vcc, s27, v106
	s_nop 1
	v_addc_co_u32_e32 v103, vcc, 0, v107, vcc
	v_add_co_u32_e32 v108, vcc, s28, v106
	global_load_dwordx4 v[98:101], v[98:99], off offset:384
	s_nop 0
	global_load_dwordx4 v[102:105], v[102:103], off offset:384
	v_addc_co_u32_e32 v109, vcc, 0, v107, vcc
	v_add_co_u32_e32 v110, vcc, s29, v106
	s_nop 1
	v_addc_co_u32_e32 v111, vcc, 0, v107, vcc
	v_add_co_u32_e32 v118, vcc, s30, v122
	global_load_dwordx4 v[106:109], v[108:109], off offset:384
	s_nop 0
	global_load_dwordx4 v[110:113], v[110:111], off offset:384
	v_addc_co_u32_e32 v119, vcc, 0, v123, vcc
	v_add_co_u32_e32 v126, vcc, s31, v122
	global_load_dwordx4 v[114:117], v[118:119], off offset:-4096
	s_nop 0
	global_load_dwordx4 v[118:121], v[118:119], off
	v_addc_co_u32_e32 v127, vcc, 0, v123, vcc
	global_load_dwordx4 v[122:125], v[126:127], off offset:-4096
	s_nop 0
	global_load_dwordx4 v[126:129], v[126:127], off
;     ...
;   for (int kt = 0; kt < nk; ++kt) {
;     const int kn = (kt + 1 < nk) ? kt + 1 : kt;
;     GM_LOAD2(kn * 64, kn * bkstep)
;     __builtin_amdgcn_sched_barrier(0);
;     const char* As = smem + (kt & 1) * 2 * TILE_B;
;     const char* Bs = As + TILE_B;
;     if constexpr (HOIST) {
;       bf16x8 fa0[4], fa1[4], fb0[4], fb1[4];
; #pragma unroll
;       for (int st = 0; st < 4; ++st) {
;         fa0[st] = *(const bf16x8*)(As + aoff + st * 32);
;         fb0[st] = *(const bf16x8*)(Bs + boff + st * 32);
;         fa1[st] = *(const bf16x8*)(As + aoff + 32 * LSTR + st * 32);
;         fb1[st] = *(const bf16x8*)(Bs + boff + 32 * LSTR + st * 32);
;       }
;       __builtin_amdgcn_sched_barrier(0);
; #pragma unroll
;       for (int st = 0; st < 4; ++st) {
;         acc[0][0] = mfma32(fa0[st], fb0[st], acc[0][0]);
;         acc[0][1] = mfma32(fa0[st], fb1[st], acc[0][1]);
;         acc[1][0] = mfma32(fa1[st], fb0[st], acc[1][0]);
;         acc[1][1] = mfma32(fa1[st], fb1[st], acc[1][1]);
;       }
;     } else {
; #pragma unroll
;       for (int st = 0; st < 4; ++st) {
;         bf16x8 a0 = *(const bf16x8*)(As + aoff + st * 32);
;         bf16x8 a1 = *(const bf16x8*)(As + aoff + 32 * LSTR + st * 32);
;         bf16x8 b0 = *(const bf16x8*)(Bs + boff + st * 32);
;         bf16x8 b1 = *(const bf16x8*)(Bs + boff + 32 * LSTR + st * 32);
;         acc[0][0] = mfma32(a0, b0, acc[0][0]);
;         acc[0][1] = mfma32(a0, b1, acc[0][1]);
;         acc[1][0] = mfma32(a1, b0, acc[1][0]);
;         acc[1][1] = mfma32(a1, b1, acc[1][1]);
;       }
;     }
;     __builtin_amdgcn_sched_barrier(0);
;     {
;       char* Ad = smem + ((kt + 1) & 1) * 2 * TILE_B;
;       GM_STORE(Ad)
;     }
;     __syncthreads();
.LBB0_1121:
	s_barrier
	s_and_b32 s14, s15, 2
	s_mulk_i32 s14, 0x4800
	v_add3_u32 v66, s14, v94, v95
	v_add3_u32 v135, s14, v96, v95
	ds_read_b128 v[130:133], v66 offset:0
	ds_read_b128 v[136:139], v135 offset:18432
	ds_read_b128 v[144:147], v66 offset:4608
	ds_read_b128 v[140:143], v135 offset:23040
	s_waitcnt lgkmcnt(2)
	v_mfma_f32_32x32x16_bf16 v[50:65], v[130:133], v[136:139], v[50:65]
	ds_read_b128 v[148:151], v66 offset:32
	s_waitcnt lgkmcnt(2)
	v_mfma_f32_32x32x16_bf16 v[2:17], v[144:147], v[136:139], v[2:17]
	ds_read_b128 v[136:139], v135 offset:18464
	s_waitcnt lgkmcnt(2)
	v_mfma_f32_32x32x16_bf16 v[18:33], v[130:133], v[140:143], v[18:33]
	ds_read_b128 v[130:133], v66 offset:4640
	v_mfma_f32_32x32x16_bf16 v[34:49], v[144:147], v[140:143], v[34:49]
	ds_read_b128 v[140:143], v135 offset:23072
	s_waitcnt lgkmcnt(2)
	v_mfma_f32_32x32x16_bf16 v[50:65], v[148:151], v[136:139], v[50:65]
	ds_read_b128 v[144:147], v66 offset:64
	s_waitcnt lgkmcnt(2)
	v_mfma_f32_32x32x16_bf16 v[2:17], v[130:133], v[136:139], v[2:17]
	ds_read_b128 v[136:139], v135 offset:18496
	s_waitcnt lgkmcnt(2)
	v_mfma_f32_32x32x16_bf16 v[18:33], v[148:151], v[140:143], v[18:33]
	ds_read_b128 v[148:151], v66 offset:4672
	v_mfma_f32_32x32x16_bf16 v[34:49], v[130:133], v[140:143], v[34:49]
	ds_read_b128 v[140:143], v135 offset:23104
	s_waitcnt lgkmcnt(2)
	v_mfma_f32_32x32x16_bf16 v[50:65], v[144:147], v[136:139], v[50:65]
	ds_read_b128 v[130:133], v66 offset:96
	s_waitcnt lgkmcnt(2)
	v_mfma_f32_32x32x16_bf16 v[2:17], v[148:151], v[136:139], v[2:17]
	ds_read_b128 v[136:139], v135 offset:18528
	s_waitcnt lgkmcnt(2)
	v_mfma_f32_32x32x16_bf16 v[18:33], v[144:147], v[140:143], v[18:33]
	ds_read_b128 v[144:147], v66 offset:4704
	v_mfma_f32_32x32x16_bf16 v[34:49], v[148:151], v[140:143], v[34:49]
	ds_read_b128 v[140:143], v135 offset:23136
	s_waitcnt lgkmcnt(2)
	v_mfma_f32_32x32x16_bf16 v[50:65], v[130:133], v[136:139], v[50:65]
	s_waitcnt lgkmcnt(1)
	v_mfma_f32_32x32x16_bf16 v[2:17], v[144:147], v[136:139], v[2:17]
	s_waitcnt lgkmcnt(0)
	v_mfma_f32_32x32x16_bf16 v[18:33], v[130:133], v[140:143], v[18:33]
	v_mfma_f32_32x32x16_bf16 v[34:49], v[144:147], v[140:143], v[34:49]
	s_add_i32 s15, s15, 2
	s_and_b32 s14, s15, 2
	s_mulk_i32 s14, 0x4800
	v_add_u32_e32 v66, s14, v1
	v_lshl_add_u64 v[90:91], v[90:91], 0, s[4:5]
	v_lshl_add_u64 v[92:93], v[92:93], 0, s[10:11]
	s_cmp_lg_u32 s15, 60
	s_waitcnt vmcnt(7)
	ds_write_b128 v66, v[98:101]
	v_lshl_add_u64 v[98:99], v[92:93], 0, v[68:69]
	v_add_co_u32_e32 v98, vcc, s26, v98
	s_nop 1
	v_addc_co_u32_e32 v99, vcc, 0, v99, vcc
	global_load_dwordx4 v[98:101], v[98:99], off offset:384
	s_waitcnt vmcnt(7)
	ds_write_b128 v66, v[102:105] offset:4608
	v_lshl_add_u64 v[102:103], v[92:93], 0, v[68:69]
	v_add_co_u32_e32 v102, vcc, s27, v102
	s_nop 1
	v_addc_co_u32_e32 v103, vcc, 0, v103, vcc
	global_load_dwordx4 v[102:105], v[102:103], off offset:384
	s_waitcnt vmcnt(7)
	ds_write_b128 v66, v[106:109] offset:9216
	v_lshl_add_u64 v[106:107], v[92:93], 0, v[68:69]
	v_add_co_u32_e32 v106, vcc, s28, v106
	s_nop 1
	v_addc_co_u32_e32 v107, vcc, 0, v107, vcc
	global_load_dwordx4 v[106:109], v[106:107], off offset:384
	s_waitcnt vmcnt(7)
	ds_write_b128 v66, v[110:113] offset:13824
	v_lshl_add_u64 v[110:111], v[92:93], 0, v[68:69]
	v_add_co_u32_e32 v110, vcc, s29, v110
	s_nop 1
	v_addc_co_u32_e32 v111, vcc, 0, v111, vcc
	global_load_dwordx4 v[110:113], v[110:111], off offset:384
	s_waitcnt vmcnt(7)
	ds_write_b128 v66, v[114:117] offset:18432
	v_lshl_add_u64 v[114:115], v[90:91], 0, v[68:69]
	v_add_co_u32_e32 v114, vcc, s30, v114
	s_nop 1
	v_addc_co_u32_e32 v115, vcc, 0, v115, vcc
	global_load_dwordx4 v[114:117], v[114:115], off offset:-4096
	s_waitcnt vmcnt(7)
	ds_write_b128 v66, v[118:121] offset:23040
	v_lshl_add_u64 v[118:119], v[90:91], 0, v[68:69]
	v_add_co_u32_e32 v118, vcc, s30, v118
	s_nop 1
	v_addc_co_u32_e32 v119, vcc, 0, v119, vcc
	global_load_dwordx4 v[118:121], v[118:119], off
	s_waitcnt vmcnt(7)
	ds_write_b128 v66, v[122:125] offset:27648
	v_lshl_add_u64 v[122:123], v[90:91], 0, v[68:69]
	v_add_co_u32_e32 v122, vcc, s31, v122
	s_nop 1
	v_addc_co_u32_e32 v123, vcc, 0, v123, vcc
	global_load_dwordx4 v[122:125], v[122:123], off offset:-4096
	s_waitcnt vmcnt(7)
	ds_write_b128 v66, v[126:129] offset:32256
	v_lshl_add_u64 v[126:127], v[90:91], 0, v[68:69]
	v_add_co_u32_e32 v126, vcc, s31, v126
	s_nop 1
	v_addc_co_u32_e32 v127, vcc, 0, v127, vcc
	global_load_dwordx4 v[126:129], v[126:127], off
	s_waitcnt lgkmcnt(0)
	s_cbranch_scc1 .LBB0_1121
	s_barrier
;     ...
;   for (int kt = 0; kt < nk; ++kt) {
;     const int kn = (kt + 1 < nk) ? kt + 1 : kt;
;     GM_LOAD2(kn * 64, kn * bkstep)
;     __builtin_amdgcn_sched_barrier(0);
;     const char* As = smem + (kt & 1) * 2 * TILE_B;
;     const char* Bs = As + TILE_B;
;     if constexpr (HOIST) {
;       bf16x8 fa0[4], fa1[4], fb0[4], fb1[4];
; #pragma unroll
;       for (int st = 0; st < 4; ++st) {
;         fa0[st] = *(const bf16x8*)(As + aoff + st * 32);
;         fb0[st] = *(const bf16x8*)(Bs + boff + st * 32);
;         fa1[st] = *(const bf16x8*)(As + aoff + 32 * LSTR + st * 32);
;         fb1[st] = *(const bf16x8*)(Bs + boff + 32 * LSTR + st * 32);
;       }
;       __builtin_amdgcn_sched_barrier(0);
; #pragma unroll
;       for (int st = 0; st < 4; ++st) {
;         acc[0][0] = mfma32(fa0[st], fb0[st], acc[0][0]);
;         acc[0][1] = mfma32(fa0[st], fb1[st], acc[0][1]);
;         acc[1][0] = mfma32(fa1[st], fb0[st], acc[1][0]);
;         acc[1][1] = mfma32(fa1[st], fb1[st], acc[1][1]);
;       }
;     } else {
; #pragma unroll
;       for (int st = 0; st < 4; ++st) {
;         bf16x8 a0 = *(const bf16x8*)(As + aoff + st * 32);
;         bf16x8 a1 = *(const bf16x8*)(As + aoff + 32 * LSTR + st * 32);
;         bf16x8 b0 = *(const bf16x8*)(Bs + boff + st * 32);
;         bf16x8 b1 = *(const bf16x8*)(Bs + boff + 32 * LSTR + st * 32);
;         acc[0][0] = mfma32(a0, b0, acc[0][0]);
;         acc[0][1] = mfma32(a0, b1, acc[0][1]);
;         acc[1][0] = mfma32(a1, b0, acc[1][0]);
;         acc[1][1] = mfma32(a1, b1, acc[1][1]);
;       }
;     }
;     __builtin_amdgcn_sched_barrier(0);
;     {
;       char* Ad = smem + ((kt + 1) & 1) * 2 * TILE_B;
;       GM_STORE(Ad)
;     }
;     __syncthreads();
	s_and_b32 s14, s15, 2
	s_mulk_i32 s14, 0x4800
	v_add3_u32 v66, s14, v94, v95
	v_add3_u32 v135, s14, v96, v95
	ds_read_b128 v[130:133], v66 offset:0
	ds_read_b128 v[136:139], v135 offset:18432
	ds_read_b128 v[144:147], v66 offset:4608
	ds_read_b128 v[140:143], v135 offset:23040
	s_waitcnt lgkmcnt(2)
	v_mfma_f32_32x32x16_bf16 v[50:65], v[130:133], v[136:139], v[50:65]
	ds_read_b128 v[148:151], v66 offset:32
	s_waitcnt lgkmcnt(2)
	v_mfma_f32_32x32x16_bf16 v[2:17], v[144:147], v[136:139], v[2:17]
	ds_read_b128 v[136:139], v135 offset:18464
	s_waitcnt lgkmcnt(2)
	v_mfma_f32_32x32x16_bf16 v[18:33], v[130:133], v[140:143], v[18:33]
	ds_read_b128 v[130:133], v66 offset:4640
	v_mfma_f32_32x32x16_bf16 v[34:49], v[144:147], v[140:143], v[34:49]
	ds_read_b128 v[140:143], v135 offset:23072
	s_waitcnt lgkmcnt(2)
	v_mfma_f32_32x32x16_bf16 v[50:65], v[148:151], v[136:139], v[50:65]
	ds_read_b128 v[144:147], v66 offset:64
	s_waitcnt lgkmcnt(2)
	v_mfma_f32_32x32x16_bf16 v[2:17], v[130:133], v[136:139], v[2:17]
	ds_read_b128 v[136:139], v135 offset:18496
	s_waitcnt lgkmcnt(2)
	v_mfma_f32_32x32x16_bf16 v[18:33], v[148:151], v[140:143], v[18:33]
	ds_read_b128 v[148:151], v66 offset:4672
	v_mfma_f32_32x32x16_bf16 v[34:49], v[130:133], v[140:143], v[34:49]
	ds_read_b128 v[140:143], v135 offset:23104
	s_waitcnt lgkmcnt(2)
	v_mfma_f32_32x32x16_bf16 v[50:65], v[144:147], v[136:139], v[50:65]
	ds_read_b128 v[130:133], v66 offset:96
	s_waitcnt lgkmcnt(2)
	v_mfma_f32_32x32x16_bf16 v[2:17], v[148:151], v[136:139], v[2:17]
	ds_read_b128 v[136:139], v135 offset:18528
	s_waitcnt lgkmcnt(2)
	v_mfma_f32_32x32x16_bf16 v[18:33], v[144:147], v[140:143], v[18:33]
	ds_read_b128 v[144:147], v66 offset:4704
	v_mfma_f32_32x32x16_bf16 v[34:49], v[148:151], v[140:143], v[34:49]
	ds_read_b128 v[140:143], v135 offset:23136
	s_waitcnt lgkmcnt(2)
	v_mfma_f32_32x32x16_bf16 v[50:65], v[130:133], v[136:139], v[50:65]
	s_waitcnt lgkmcnt(1)
	v_mfma_f32_32x32x16_bf16 v[2:17], v[144:147], v[136:139], v[2:17]
	s_waitcnt lgkmcnt(0)
	v_mfma_f32_32x32x16_bf16 v[18:33], v[130:133], v[140:143], v[18:33]
	v_mfma_f32_32x32x16_bf16 v[34:49], v[144:147], v[140:143], v[34:49]
	s_add_i32 s15, s15, 2
	s_and_b32 s14, s15, 2
	s_mulk_i32 s14, 0x4800
	v_add_u32_e32 v66, s14, v1
	v_lshl_add_u64 v[90:91], v[90:91], 0, s[4:5]
	v_lshl_add_u64 v[92:93], v[92:93], 0, s[10:11]
	s_waitcnt vmcnt(7)
	ds_write_b128 v66, v[98:101]
	s_waitcnt vmcnt(6)
	ds_write_b128 v66, v[102:105] offset:4608
	s_waitcnt vmcnt(5)
	ds_write_b128 v66, v[106:109] offset:9216
	s_waitcnt vmcnt(4)
	ds_write_b128 v66, v[110:113] offset:13824
	s_waitcnt vmcnt(3)
	ds_write_b128 v66, v[114:117] offset:18432
	s_waitcnt vmcnt(2)
	ds_write_b128 v66, v[118:121] offset:23040
	s_waitcnt vmcnt(1)
	ds_write_b128 v66, v[122:125] offset:27648
	s_waitcnt vmcnt(0)
	ds_write_b128 v66, v[126:129] offset:32256
	s_waitcnt lgkmcnt(0)
	s_barrier
	v_add_co_u32_e32 v102, vcc, 0x3e0000, v80
	s_nop 0
	s_nop 0
	s_nop 0
	v_addc_co_u32_e32 v103, vcc, 0, v81, vcc
	v_add_co_u32_e32 v106, vcc, 0x3e1000, v80
	s_nop 1
	v_addc_co_u32_e32 v107, vcc, 0, v81, vcc
	v_add_co_u32_e32 v110, vcc, 0x3e2000, v80
	s_nop 0
	v_addc_co_u32_e32 v111, vcc, 0, v81, vcc
	v_add_co_u32_e32 v80, vcc, 0x3e3000, v80
	s_nop 1
	v_addc_co_u32_e32 v81, vcc, 0, v81, vcc
	s_nop 0
	v_add_u32_e32 v66, v94, v95
	v_add_u32_e32 v80, v96, v95
	ds_read_b128 v[118:121], v66 offset:36864
	ds_read_b128 v[122:125], v80 offset:55296
	ds_read_b128 v[130:133], v66 offset:41472
	ds_read_b128 v[126:129], v80 offset:59904
	s_waitcnt lgkmcnt(2)
	v_mfma_f32_32x32x16_bf16 v[50:65], v[118:121], v[122:125], v[50:65]
	ds_read_b128 v[136:139], v66 offset:36896
	s_waitcnt lgkmcnt(2)
	v_mfma_f32_32x32x16_bf16 v[2:17], v[130:133], v[122:125], v[2:17]
	ds_read_b128 v[122:125], v80 offset:55328
	s_waitcnt lgkmcnt(2)
	v_mfma_f32_32x32x16_bf16 v[18:33], v[118:121], v[126:129], v[18:33]
	ds_read_b128 v[118:121], v66 offset:41504
	v_mfma_f32_32x32x16_bf16 v[34:49], v[130:133], v[126:129], v[34:49]
	ds_read_b128 v[126:129], v80 offset:59936
	s_waitcnt lgkmcnt(2)
	v_mfma_f32_32x32x16_bf16 v[50:65], v[136:139], v[122:125], v[50:65]
	ds_read_b128 v[130:133], v66 offset:36928
	s_waitcnt lgkmcnt(2)
	v_mfma_f32_32x32x16_bf16 v[2:17], v[118:121], v[122:125], v[2:17]
	ds_read_b128 v[122:125], v80 offset:55360
	s_waitcnt lgkmcnt(2)
	v_mfma_f32_32x32x16_bf16 v[18:33], v[136:139], v[126:129], v[18:33]
	ds_read_b128 v[136:139], v66 offset:41536
	v_mfma_f32_32x32x16_bf16 v[34:49], v[118:121], v[126:129], v[34:49]
	ds_read_b128 v[126:129], v80 offset:59968
	s_waitcnt lgkmcnt(2)
	v_mfma_f32_32x32x16_bf16 v[50:65], v[130:133], v[122:125], v[50:65]
	ds_read_b128 v[118:121], v66 offset:36960
	s_waitcnt lgkmcnt(2)
	v_mfma_f32_32x32x16_bf16 v[2:17], v[136:139], v[122:125], v[2:17]
	ds_read_b128 v[122:125], v80 offset:55392
	s_waitcnt lgkmcnt(2)
	v_mfma_f32_32x32x16_bf16 v[18:33], v[130:133], v[126:129], v[18:33]
	ds_read_b128 v[130:133], v66 offset:41568
	v_mfma_f32_32x32x16_bf16 v[34:49], v[136:139], v[126:129], v[34:49]
	ds_read_b128 v[126:129], v80 offset:60000
	s_waitcnt lgkmcnt(2)
	v_mfma_f32_32x32x16_bf16 v[50:65], v[118:121], v[122:125], v[50:65]
	s_waitcnt lgkmcnt(1)
	v_mfma_f32_32x32x16_bf16 v[2:17], v[130:133], v[122:125], v[2:17]
	s_waitcnt lgkmcnt(0)
	v_mfma_f32_32x32x16_bf16 v[18:33], v[118:121], v[126:129], v[18:33]
	v_mfma_f32_32x32x16_bf16 v[34:49], v[130:133], v[126:129], v[34:49]
	s_waitcnt lgkmcnt(0)
	s_barrier
; __device__ __forceinline__ void acc_to_lds(const f32x16 (&acc)[2][2], float* cs) {
;   const int tid = threadIdx.x, lane = tid & 63, wave = tid >> 6;
;   const int wm = wave >> 1, wn = wave & 1;
; #pragma unroll
;   for (int i = 0; i < 2; ++i)
; #pragma unroll
;     for (int j = 0; j < 2; ++j)
; #pragma unroll
;       for (int r = 0; r < 16; ++r) {
;         int row = wm * 64 + i * 32 + (r & 3) + 8 * (r >> 2) + 4 * (lane >> 5);
;         int col = wn * 64 + j * 32 + (lane & 31);
;         cs[row * CSTR + col] = acc[i][j][r];
;       }
;   __syncthreads();
; __device__ __forceinline__ void epi_plain(const float* cs, u16* out, size_t ld, size_t row0, int col0) {
;   int tid_ = threadIdx.x;
;   asm volatile("" : "+v"(tid_));
;   const int lane = tid_ & 63, wave = tid_ >> 6;
;   const int r = 32 * wave + (lane & 31), half = lane >> 5;
;   const float* src = cs + r * CSTR + half * 64;
;   u16* dst = out + (row0 + r) * ld + col0 + half * 64;
; #pragma unroll
;   for (int q = 0; q < 8; ++q) {
;     float4 a = *(const float4*)(src + q * 8);
;     float4 b = *(const float4*)(src + q * 8 + 4);
;     uint4 o;
;     o.x = pack2(a.x, a.y); o.y = pack2(a.z, a.w); o.z = pack2(b.x, b.y); o.w = pack2(b.z, b.w);
;     *(uint4*)(dst + q * 8) = o;
;   }
	ds_write2_b32 v97, v50, v18 offset1:32
	ds_write2_b32 v97, v51, v19 offset0:132 offset1:164
	v_add_u32_e32 v18, 0x400, v97
	ds_write2_b32 v18, v52, v20 offset0:8 offset1:40
	ds_write2_b32 v18, v53, v21 offset0:140 offset1:172
	v_add_u32_e32 v18, 0x1000, v97
	ds_write2_b32 v18, v54, v22 offset0:32 offset1:64
	ds_write2_b32 v18, v55, v23 offset0:164 offset1:196
	v_add_u32_e32 v18, 0x1400, v97
	ds_write2_b32 v18, v56, v24 offset0:40 offset1:72
	ds_write2_b32 v18, v57, v25 offset0:172 offset1:204
	v_add_u32_e32 v18, 0x2000, v97
	ds_write2_b32 v18, v58, v26 offset0:64 offset1:96
	ds_write2_b32 v18, v59, v27 offset0:196 offset1:228
	v_add_u32_e32 v18, 0x2400, v97
	ds_write2_b32 v18, v60, v28 offset0:72 offset1:104
	ds_write2_b32 v18, v61, v29 offset0:204 offset1:236
	v_add_u32_e32 v18, 0x3000, v97
	ds_write2_b32 v18, v62, v30 offset0:96 offset1:128
	v_add_u32_e32 v18, 0x3200, v97
	ds_write2_b32 v18, v63, v31 offset0:100 offset1:132
	v_add_u32_e32 v18, 0x3400, v97
	ds_write2_b32 v18, v64, v32 offset0:104 offset1:136
	v_add_u32_e32 v18, 0x3600, v97
	ds_write2_b32 v18, v65, v33 offset0:108 offset1:140
	v_add_u32_e32 v18, 0x4000, v97
	ds_write2_b32 v18, v2, v34 offset0:128 offset1:160
	v_add_u32_e32 v2, 0x4400, v97
	ds_write2_b32 v2, v3, v35 offset0:4 offset1:36
	ds_write2_b32 v2, v4, v36 offset0:136 offset1:168
	v_add_u32_e32 v2, 0x4800, v97
	ds_write2_b32 v2, v5, v37 offset0:12 offset1:44
	v_add_u32_e32 v2, 0x5000, v97
	ds_write2_b32 v2, v6, v38 offset0:160 offset1:192
	v_add_u32_e32 v2, 0x5400, v97
	ds_write2_b32 v2, v7, v39 offset0:36 offset1:68
	ds_write2_b32 v2, v8, v40 offset0:168 offset1:200
	v_add_u32_e32 v2, 0x5800, v97
	ds_write2_b32 v2, v9, v41 offset0:44 offset1:76
	v_add_u32_e32 v2, 0x6000, v97
	ds_write2_b32 v2, v10, v42 offset0:192 offset1:224
	v_add_u32_e32 v2, 0x6400, v97
	ds_write2_b32 v2, v11, v43 offset0:68 offset1:100
	ds_write2_b32 v2, v12, v44 offset0:200 offset1:232
	v_add_u32_e32 v2, 0x6800, v97
	ds_write2_b32 v2, v13, v45 offset0:76 offset1:108
	v_add_u32_e32 v2, 0x7200, v97
	ds_write2_b32 v2, v14, v46 offset0:96 offset1:128
	v_add_u32_e32 v2, 0x7400, v97
	ds_write2_b32 v2, v15, v47 offset0:100 offset1:132
	v_add_u32_e32 v2, 0x7600, v97
	ds_write2_b32 v2, v16, v48 offset0:104 offset1:136
	v_add_u32_e32 v2, 0x7800, v97
	v_mov_b32_e32 v3, v134
	ds_write2_b32 v2, v17, v49 offset0:108 offset1:140
	s_waitcnt lgkmcnt(0)
	s_barrier
	s_lshl_b32 s2, s2, 8
	v_ashrrev_i32_e32 v2, 1, v3
	v_bfi_b32 v2, s33, v2, v3
	v_lshlrev_b32_e32 v3, 1, v3
	v_and_b32_e32 v5, 64, v3
	v_ashrrev_i32_e32 v3, 31, v2
	v_mul_lo_u32 v4, v2, s16
	v_lshl_add_u64 v[2:3], s[12:13], 0, v[2:3]
	v_lshlrev_b64 v[2:3], 11, v[2:3]
	v_lshl_add_u64 v[2:3], s[0:1], 0, v[2:3]
	v_lshl_add_u32 v20, v5, 2, v4
	v_lshl_add_u64 v[6:7], v[2:3], 0, s[2:3]
	v_lshlrev_b32_e32 v66, 1, v5
	ds_read_b128 v[2:5], v20
	v_lshl_add_u64 v[18:19], v[6:7], 0, v[66:67]
	ds_read_b128 v[6:9], v20 offset:16
	ds_read_b128 v[10:13], v20 offset:32
	ds_read_b128 v[14:17], v20 offset:48
	s_waitcnt lgkmcnt(3)
	v_cvt_pk_bf16_f32 v2, v2, v3
	v_cvt_pk_bf16_f32 v3, v4, v5
	s_waitcnt lgkmcnt(2)
	v_cvt_pk_bf16_f32 v4, v6, v7
	v_cvt_pk_bf16_f32 v5, v8, v9
	global_store_dwordx4 v[18:19], v[2:5], off
	ds_read_b128 v[6:9], v20 offset:64
	s_add_i32 s35, s35, s94
	s_waitcnt lgkmcnt(2)
	v_cvt_pk_bf16_f32 v2, v10, v11
	v_cvt_pk_bf16_f32 v3, v12, v13
	s_waitcnt lgkmcnt(1)
	v_cvt_pk_bf16_f32 v4, v14, v15
	v_cvt_pk_bf16_f32 v5, v16, v17
	ds_read_b128 v[10:13], v20 offset:80
	global_store_dwordx4 v[18:19], v[2:5], off offset:16
	s_add_i32 s34, s34, s94
	s_add_i32 s19, s19, s20
	s_waitcnt lgkmcnt(1)
	v_cvt_pk_bf16_f32 v2, v6, v7
	v_cvt_pk_bf16_f32 v3, v8, v9
	s_waitcnt lgkmcnt(0)
	v_cvt_pk_bf16_f32 v4, v10, v11
	v_cvt_pk_bf16_f32 v5, v12, v13
	ds_read_b128 v[6:9], v20 offset:96
	ds_read_b128 v[10:13], v20 offset:112
	global_store_dwordx4 v[18:19], v[2:5], off offset:32
	s_cmpk_lt_i32 s35, 0x100
	ds_read_b128 v[14:17], v20 offset:240
	s_waitcnt lgkmcnt(2)
	v_cvt_pk_bf16_f32 v2, v6, v7
	v_cvt_pk_bf16_f32 v3, v8, v9
	s_waitcnt lgkmcnt(1)
	v_cvt_pk_bf16_f32 v4, v10, v11
	v_cvt_pk_bf16_f32 v5, v12, v13
	ds_read_b128 v[6:9], v20 offset:128
	ds_read_b128 v[10:13], v20 offset:144
	global_store_dwordx4 v[18:19], v[2:5], off offset:48
	s_waitcnt lgkmcnt(1)
	s_nop 0
	v_cvt_pk_bf16_f32 v2, v6, v7
	v_cvt_pk_bf16_f32 v3, v8, v9
	s_waitcnt lgkmcnt(0)
	v_cvt_pk_bf16_f32 v4, v10, v11
	v_cvt_pk_bf16_f32 v5, v12, v13
	ds_read_b128 v[6:9], v20 offset:160
	ds_read_b128 v[10:13], v20 offset:176
	global_store_dwordx4 v[18:19], v[2:5], off offset:64
	s_waitcnt lgkmcnt(1)
	s_nop 0
	v_cvt_pk_bf16_f32 v2, v6, v7
	v_cvt_pk_bf16_f32 v3, v8, v9
	s_waitcnt lgkmcnt(0)
	v_cvt_pk_bf16_f32 v4, v10, v11
	v_cvt_pk_bf16_f32 v5, v12, v13
	ds_read_b128 v[6:9], v20 offset:192
	ds_read_b128 v[10:13], v20 offset:208
	global_store_dwordx4 v[18:19], v[2:5], off offset:80
	s_waitcnt lgkmcnt(1)
	s_nop 0
	v_cvt_pk_bf16_f32 v2, v6, v7
	v_cvt_pk_bf16_f32 v3, v8, v9
	s_waitcnt lgkmcnt(0)
	v_cvt_pk_bf16_f32 v4, v10, v11
	v_cvt_pk_bf16_f32 v5, v12, v13
	ds_read_b128 v[6:9], v20 offset:224
	global_store_dwordx4 v[18:19], v[2:5], off offset:96
	s_waitcnt lgkmcnt(0)
	s_nop 0
	v_cvt_pk_bf16_f32 v2, v6, v7
	v_cvt_pk_bf16_f32 v3, v8, v9
	v_cvt_pk_bf16_f32 v4, v14, v15
	v_cvt_pk_bf16_f32 v5, v16, v17
	global_store_dwordx4 v[18:19], v[2:5], off offset:112
	s_barrier
	s_cbranch_scc1 .LBB0_1120

;     ...
;   for (int kt = 0; kt < nk; ++kt) {
;     const int kn = (kt + 1 < nk) ? kt + 1 : kt;
;     GW_LOAD2(kn * 64, kn * bkstep)
;     __builtin_amdgcn_sched_barrier(0);
;     __builtin_amdgcn_s_setprio(1);
; #pragma unroll
;     for (int st = 0; st < 4; ++st) {
;       bf16x8 a0 = *(const bf16x8*)(Ab + st * 32);
;       bf16x8 a1 = *(const bf16x8*)(Ab + 32 * LSTR + st * 32);
;       bf16x8 b0 = *(const bf16x8*)(Bb + st * 32);
;       bf16x8 b1 = *(const bf16x8*)(Bb + 32 * LSTR + st * 32);
;       bf16x8 b2 = *(const bf16x8*)(Bb + 64 * LSTR + st * 32);
;       bf16x8 b3 = *(const bf16x8*)(Bb + 96 * LSTR + st * 32);
;       acc[0][0] = mfma32(a0, b0, acc[0][0]);
;       acc[0][1] = mfma32(a0, b1, acc[0][1]);
;       acc[0][2] = mfma32(a0, b2, acc[0][2]);
;       acc[0][3] = mfma32(a0, b3, acc[0][3]);
;       acc[1][0] = mfma32(a1, b0, acc[1][0]);
;       acc[1][1] = mfma32(a1, b1, acc[1][1]);
;       acc[1][2] = mfma32(a1, b2, acc[1][2]);
;       acc[1][3] = mfma32(a1, b3, acc[1][3]);
;     }
;     __builtin_amdgcn_s_setprio(0);
;     __builtin_amdgcn_sched_barrier(0);
;     __syncthreads();
.LBB0_1284:
	s_barrier
	s_setprio 1
	ds_read_b128 v[204:207], v131 offset:0
	ds_read_b128 v[216:219], v138 offset:18432
	ds_read_b128 v[224:227], v138 offset:23040
	ds_read_b128 v[228:231], v138 offset:27648
	ds_read_b128 v[232:235], v138 offset:32256
	ds_read_b128 v[212:215], v131 offset:4608
	s_waitcnt lgkmcnt(4)
	v_mfma_f32_32x32x16_bf16 v[114:129], v[204:207], v[216:219], v[114:129]
	ds_read_b128 v[208:211], v131 offset:32
	ds_read_b128 v[236:239], v138 offset:18464
	s_waitcnt lgkmcnt(5)
	v_mfma_f32_32x32x16_bf16 v[98:113], v[204:207], v[224:227], v[98:113]
	ds_read_b128 v[240:243], v138 offset:23072
	s_waitcnt lgkmcnt(5)
	v_mfma_f32_32x32x16_bf16 v[82:97], v[204:207], v[228:231], v[82:97]
	ds_read_b128 v[244:247], v138 offset:27680
	s_waitcnt lgkmcnt(5)
	v_mfma_f32_32x32x16_bf16 v[66:81], v[204:207], v[232:235], v[66:81]
	ds_read_b128 v[248:251], v138 offset:32288
	s_waitcnt lgkmcnt(5)
	v_mfma_f32_32x32x16_bf16 v[50:65], v[212:215], v[216:219], v[50:65]
	v_lshl_add_u64 v[154:155], v[150:151], 0, s[8:9]
	v_add_co_u32_e32 v154, vcc, s43, v154
	s_nop 1
	v_addc_co_u32_e32 v155, vcc, 0, v155, vcc
	global_load_dwordx4 v[154:157], v[154:155], off offset:384
	v_mfma_f32_32x32x16_bf16 v[34:49], v[212:215], v[224:227], v[34:49]
	v_lshl_add_u64 v[158:159], v[150:151], 0, s[8:9]
	v_add_co_u32_e32 v158, vcc, s44, v158
	s_nop 1
	v_addc_co_u32_e32 v159, vcc, 0, v159, vcc
	global_load_dwordx4 v[158:161], v[158:159], off offset:384
	v_mfma_f32_32x32x16_bf16 v[18:33], v[212:215], v[228:231], v[18:33]
	v_lshl_add_u64 v[162:163], v[150:151], 0, s[8:9]
	v_add_co_u32_e32 v162, vcc, s45, v162
	s_nop 1
	v_addc_co_u32_e32 v163, vcc, 0, v163, vcc
	global_load_dwordx4 v[162:165], v[162:163], off offset:384
	v_mfma_f32_32x32x16_bf16 v[2:17], v[212:215], v[232:235], v[2:17]
	v_lshl_add_u64 v[166:167], v[150:151], 0, s[8:9]
	v_add_co_u32_e32 v166, vcc, s46, v166
	s_nop 1
	v_addc_co_u32_e32 v167, vcc, 0, v167, vcc
	global_load_dwordx4 v[166:169], v[166:167], off offset:384
	ds_read_b128 v[212:215], v131 offset:4640
	s_waitcnt lgkmcnt(4)
	v_mfma_f32_32x32x16_bf16 v[114:129], v[208:211], v[236:239], v[114:129]
	ds_read_b128 v[204:207], v131 offset:64
	ds_read_b128 v[216:219], v138 offset:18496
	s_waitcnt lgkmcnt(5)
	v_mfma_f32_32x32x16_bf16 v[98:113], v[208:211], v[240:243], v[98:113]
	ds_read_b128 v[224:227], v138 offset:23104
	s_waitcnt lgkmcnt(5)
	v_mfma_f32_32x32x16_bf16 v[82:97], v[208:211], v[244:247], v[82:97]
	ds_read_b128 v[228:231], v138 offset:27712
	s_waitcnt lgkmcnt(5)
	v_mfma_f32_32x32x16_bf16 v[66:81], v[208:211], v[248:251], v[66:81]
	ds_read_b128 v[232:235], v138 offset:32320
	s_waitcnt lgkmcnt(5)
	v_mfma_f32_32x32x16_bf16 v[50:65], v[212:215], v[236:239], v[50:65]
	v_lshl_add_u64 v[170:171], v[152:153], 0, s[8:9]
	v_add_co_u32_e32 v170, vcc, s35, v170
	s_nop 1
	v_addc_co_u32_e32 v171, vcc, 0, v171, vcc
	global_load_dwordx4 v[170:173], v[170:171], off offset:128
	v_mfma_f32_32x32x16_bf16 v[34:49], v[212:215], v[240:243], v[34:49]
	v_lshl_add_u64 v[174:175], v[152:153], 0, s[8:9]
	v_add_co_u32_e32 v174, vcc, s36, v174
	s_nop 1
	v_addc_co_u32_e32 v175, vcc, 0, v175, vcc
	global_load_dwordx4 v[174:177], v[174:175], off offset:128
	v_mfma_f32_32x32x16_bf16 v[18:33], v[212:215], v[244:247], v[18:33]
	v_lshl_add_u64 v[178:179], v[152:153], 0, s[8:9]
	v_add_co_u32_e32 v178, vcc, s37, v178
	s_nop 1
	v_addc_co_u32_e32 v179, vcc, 0, v179, vcc
	global_load_dwordx4 v[178:181], v[178:179], off offset:128
	v_mfma_f32_32x32x16_bf16 v[2:17], v[212:215], v[248:251], v[2:17]
	v_lshl_add_u64 v[184:185], v[152:153], 0, s[8:9]
	v_add_co_u32_e32 v184, vcc, s38, v184
	s_nop 1
	v_addc_co_u32_e32 v185, vcc, 0, v185, vcc
	global_load_dwordx4 v[184:187], v[184:185], off offset:128
	ds_read_b128 v[212:215], v131 offset:4672
	s_waitcnt lgkmcnt(4)
	v_mfma_f32_32x32x16_bf16 v[114:129], v[204:207], v[216:219], v[114:129]
	ds_read_b128 v[208:211], v131 offset:96
	ds_read_b128 v[236:239], v138 offset:18528
	s_waitcnt lgkmcnt(5)
	v_mfma_f32_32x32x16_bf16 v[98:113], v[204:207], v[224:227], v[98:113]
	ds_read_b128 v[240:243], v138 offset:23136
	s_waitcnt lgkmcnt(5)
	v_mfma_f32_32x32x16_bf16 v[82:97], v[204:207], v[228:231], v[82:97]
	ds_read_b128 v[244:247], v138 offset:27744
	s_waitcnt lgkmcnt(5)
	v_mfma_f32_32x32x16_bf16 v[66:81], v[204:207], v[232:235], v[66:81]
	ds_read_b128 v[248:251], v138 offset:32352
	s_waitcnt lgkmcnt(5)
	v_mfma_f32_32x32x16_bf16 v[50:65], v[212:215], v[216:219], v[50:65]
	v_lshl_add_u64 v[188:189], v[152:153], 0, s[8:9]
	v_add_co_u32_e32 v188, vcc, s39, v188
	s_nop 1
	v_addc_co_u32_e32 v189, vcc, 0, v189, vcc
	global_load_dwordx4 v[188:191], v[188:189], off offset:128
	v_mfma_f32_32x32x16_bf16 v[34:49], v[212:215], v[224:227], v[34:49]
	v_lshl_add_u64 v[192:193], v[152:153], 0, s[8:9]
	v_add_co_u32_e32 v192, vcc, s40, v192
	s_nop 1
	v_addc_co_u32_e32 v193, vcc, 0, v193, vcc
	global_load_dwordx4 v[192:195], v[192:193], off offset:128
	v_mfma_f32_32x32x16_bf16 v[18:33], v[212:215], v[228:231], v[18:33]
	v_lshl_add_u64 v[196:197], v[152:153], 0, s[8:9]
	v_add_co_u32_e32 v196, vcc, s41, v196
	s_nop 1
	v_addc_co_u32_e32 v197, vcc, 0, v197, vcc
	global_load_dwordx4 v[196:199], v[196:197], off offset:128
	v_mfma_f32_32x32x16_bf16 v[2:17], v[212:215], v[232:235], v[2:17]
	v_lshl_add_u64 v[200:201], v[152:153], 0, s[8:9]
	v_add_co_u32_e32 v200, vcc, s42, v200
	s_nop 1
	v_addc_co_u32_e32 v201, vcc, 0, v201, vcc
	global_load_dwordx4 v[200:203], v[200:201], off offset:128
	ds_read_b128 v[212:215], v131 offset:4704
	s_waitcnt lgkmcnt(4)
	v_mfma_f32_32x32x16_bf16 v[114:129], v[208:211], v[236:239], v[114:129]
	s_waitcnt lgkmcnt(3)
	v_mfma_f32_32x32x16_bf16 v[98:113], v[208:211], v[240:243], v[98:113]
	s_waitcnt lgkmcnt(2)
	v_mfma_f32_32x32x16_bf16 v[82:97], v[208:211], v[244:247], v[82:97]
	s_waitcnt lgkmcnt(1)
	v_mfma_f32_32x32x16_bf16 v[66:81], v[208:211], v[248:251], v[66:81]
	s_waitcnt lgkmcnt(0)
	v_mfma_f32_32x32x16_bf16 v[50:65], v[212:215], v[236:239], v[50:65]
	v_mfma_f32_32x32x16_bf16 v[34:49], v[212:215], v[240:243], v[34:49]
	v_mfma_f32_32x32x16_bf16 v[18:33], v[212:215], v[244:247], v[18:33]
	v_mfma_f32_32x32x16_bf16 v[2:17], v[212:215], v[248:251], v[2:17]
	s_setprio 0
	s_add_u32 s8, s8, 0x80
	s_addc_u32 s9, s9, 0
	s_cmpk_lg_i32 s8, 0x700
	s_barrier
;     ...
;   for (int kt = 0; kt < nk; ++kt) {
;     const int kn = (kt + 1 < nk) ? kt + 1 : kt;
;     GW_LOAD2(kn * 64, kn * bkstep)
;     __builtin_amdgcn_sched_barrier(0);
;     __builtin_amdgcn_s_setprio(1);
; #pragma unroll
;     for (int st = 0; st < 4; ++st) {
;       bf16x8 a0 = *(const bf16x8*)(Ab + st * 32);
;       bf16x8 a1 = *(const bf16x8*)(Ab + 32 * LSTR + st * 32);
;       bf16x8 b0 = *(const bf16x8*)(Bb + st * 32);
;       bf16x8 b1 = *(const bf16x8*)(Bb + 32 * LSTR + st * 32);
;       bf16x8 b2 = *(const bf16x8*)(Bb + 64 * LSTR + st * 32);
;       bf16x8 b3 = *(const bf16x8*)(Bb + 96 * LSTR + st * 32);
;       acc[0][0] = mfma32(a0, b0, acc[0][0]);
;       acc[0][1] = mfma32(a0, b1, acc[0][1]);
;       acc[0][2] = mfma32(a0, b2, acc[0][2]);
;       acc[0][3] = mfma32(a0, b3, acc[0][3]);
;       acc[1][0] = mfma32(a1, b0, acc[1][0]);
;       acc[1][1] = mfma32(a1, b1, acc[1][1]);
;       acc[1][2] = mfma32(a1, b2, acc[1][2]);
;       acc[1][3] = mfma32(a1, b3, acc[1][3]);
;     }
;     __builtin_amdgcn_s_setprio(0);
;     __builtin_amdgcn_sched_barrier(0);
;     __syncthreads();
	s_waitcnt vmcnt(11)
	ds_write_b128 v130, v[154:157]
	s_waitcnt vmcnt(10)
	ds_write_b128 v130, v[158:161] offset:4608
	s_waitcnt vmcnt(9)
	ds_write_b128 v130, v[162:165] offset:9216
	s_waitcnt vmcnt(8)
	ds_write_b128 v130, v[166:169] offset:13824
	s_waitcnt vmcnt(7)
	ds_write_b128 v130, v[170:173] offset:18432
	s_waitcnt vmcnt(6)
	ds_write_b128 v130, v[174:177] offset:23040
	s_waitcnt vmcnt(5)
	ds_write_b128 v130, v[178:181] offset:27648
	s_waitcnt vmcnt(4)
	ds_write_b128 v130, v[184:187] offset:32256
	s_waitcnt vmcnt(3)
	ds_write_b128 v130, v[188:191] offset:36864
	s_waitcnt vmcnt(2)
	ds_write_b128 v130, v[192:195] offset:41472
	s_waitcnt vmcnt(1)
	ds_write_b128 v130, v[196:199] offset:46080
	s_waitcnt vmcnt(0)
	ds_write_b128 v130, v[200:203] offset:50688
	s_waitcnt lgkmcnt(0)
	s_cbranch_scc1 .LBB0_1284
	s_barrier
	s_setprio 1
	ds_read_b128 v[204:207], v131 offset:0
	ds_read_b128 v[216:219], v138 offset:18432
	ds_read_b128 v[224:227], v138 offset:23040
	ds_read_b128 v[228:231], v138 offset:27648
	ds_read_b128 v[232:235], v138 offset:32256
	ds_read_b128 v[212:215], v131 offset:4608
	s_waitcnt lgkmcnt(4)
	v_mfma_f32_32x32x16_bf16 v[114:129], v[204:207], v[216:219], v[114:129]
	ds_read_b128 v[208:211], v131 offset:32
	ds_read_b128 v[236:239], v138 offset:18464
	s_waitcnt lgkmcnt(5)
	v_mfma_f32_32x32x16_bf16 v[98:113], v[204:207], v[224:227], v[98:113]
	ds_read_b128 v[240:243], v138 offset:23072
	s_waitcnt lgkmcnt(5)
	v_mfma_f32_32x32x16_bf16 v[82:97], v[204:207], v[228:231], v[82:97]
	ds_read_b128 v[244:247], v138 offset:27680
	s_waitcnt lgkmcnt(5)
	v_mfma_f32_32x32x16_bf16 v[66:81], v[204:207], v[232:235], v[66:81]
	ds_read_b128 v[248:251], v138 offset:32288
	s_waitcnt lgkmcnt(5)
	v_mfma_f32_32x32x16_bf16 v[50:65], v[212:215], v[216:219], v[50:65]
	v_lshl_add_u64 v[154:155], v[150:151], 0, s[8:9]
	v_add_co_u32_e32 v154, vcc, s43, v154
	s_nop 1
	v_addc_co_u32_e32 v155, vcc, 0, v155, vcc
	global_load_dwordx4 v[154:157], v[154:155], off offset:384
	v_mfma_f32_32x32x16_bf16 v[34:49], v[212:215], v[224:227], v[34:49]
	v_lshl_add_u64 v[158:159], v[150:151], 0, s[8:9]
	v_add_co_u32_e32 v158, vcc, s44, v158
	s_nop 1
	v_addc_co_u32_e32 v159, vcc, 0, v159, vcc
	global_load_dwordx4 v[158:161], v[158:159], off offset:384
	v_mfma_f32_32x32x16_bf16 v[18:33], v[212:215], v[228:231], v[18:33]
	v_lshl_add_u64 v[162:163], v[150:151], 0, s[8:9]
	v_add_co_u32_e32 v162, vcc, s45, v162
	s_nop 1
	v_addc_co_u32_e32 v163, vcc, 0, v163, vcc
	global_load_dwordx4 v[162:165], v[162:163], off offset:384
	v_mfma_f32_32x32x16_bf16 v[2:17], v[212:215], v[232:235], v[2:17]
	v_lshl_add_u64 v[166:167], v[150:151], 0, s[8:9]
	v_add_co_u32_e32 v166, vcc, s46, v166
	s_nop 1
	v_addc_co_u32_e32 v167, vcc, 0, v167, vcc
	global_load_dwordx4 v[166:169], v[166:167], off offset:384
	ds_read_b128 v[212:215], v131 offset:4640
	s_waitcnt lgkmcnt(4)
	v_mfma_f32_32x32x16_bf16 v[114:129], v[208:211], v[236:239], v[114:129]
	ds_read_b128 v[204:207], v131 offset:64
	ds_read_b128 v[216:219], v138 offset:18496
	s_waitcnt lgkmcnt(5)
	v_mfma_f32_32x32x16_bf16 v[98:113], v[208:211], v[240:243], v[98:113]
	ds_read_b128 v[224:227], v138 offset:23104
	s_waitcnt lgkmcnt(5)
	v_mfma_f32_32x32x16_bf16 v[82:97], v[208:211], v[244:247], v[82:97]
	ds_read_b128 v[228:231], v138 offset:27712
	s_waitcnt lgkmcnt(5)
	v_mfma_f32_32x32x16_bf16 v[66:81], v[208:211], v[248:251], v[66:81]
	ds_read_b128 v[232:235], v138 offset:32320
	s_waitcnt lgkmcnt(5)
	v_mfma_f32_32x32x16_bf16 v[50:65], v[212:215], v[236:239], v[50:65]
	v_lshl_add_u64 v[170:171], v[152:153], 0, s[8:9]
	v_add_co_u32_e32 v170, vcc, s35, v170
	s_nop 1
	v_addc_co_u32_e32 v171, vcc, 0, v171, vcc
	global_load_dwordx4 v[170:173], v[170:171], off offset:128
	v_mfma_f32_32x32x16_bf16 v[34:49], v[212:215], v[240:243], v[34:49]
	v_lshl_add_u64 v[174:175], v[152:153], 0, s[8:9]
	v_add_co_u32_e32 v174, vcc, s36, v174
	s_nop 1
	v_addc_co_u32_e32 v175, vcc, 0, v175, vcc
	global_load_dwordx4 v[174:177], v[174:175], off offset:128
	v_mfma_f32_32x32x16_bf16 v[18:33], v[212:215], v[244:247], v[18:33]
	v_lshl_add_u64 v[178:179], v[152:153], 0, s[8:9]
	v_add_co_u32_e32 v178, vcc, s37, v178
	s_nop 1
	v_addc_co_u32_e32 v179, vcc, 0, v179, vcc
	global_load_dwordx4 v[178:181], v[178:179], off offset:128
	v_mfma_f32_32x32x16_bf16 v[2:17], v[212:215], v[248:251], v[2:17]
	v_lshl_add_u64 v[184:185], v[152:153], 0, s[8:9]
	v_add_co_u32_e32 v184, vcc, s38, v184
	s_nop 1
	v_addc_co_u32_e32 v185, vcc, 0, v185, vcc
	global_load_dwordx4 v[184:187], v[184:185], off offset:128
	ds_read_b128 v[212:215], v131 offset:4672
	s_waitcnt lgkmcnt(4)
	v_mfma_f32_32x32x16_bf16 v[114:129], v[204:207], v[216:219], v[114:129]
	ds_read_b128 v[208:211], v131 offset:96
	ds_read_b128 v[236:239], v138 offset:18528
	s_waitcnt lgkmcnt(5)
	v_mfma_f32_32x32x16_bf16 v[98:113], v[204:207], v[224:227], v[98:113]
	ds_read_b128 v[240:243], v138 offset:23136
	s_waitcnt lgkmcnt(5)
	v_mfma_f32_32x32x16_bf16 v[82:97], v[204:207], v[228:231], v[82:97]
	ds_read_b128 v[244:247], v138 offset:27744
	s_waitcnt lgkmcnt(5)
	v_mfma_f32_32x32x16_bf16 v[66:81], v[204:207], v[232:235], v[66:81]
	ds_read_b128 v[248:251], v138 offset:32352
	s_waitcnt lgkmcnt(5)
	v_mfma_f32_32x32x16_bf16 v[50:65], v[212:215], v[216:219], v[50:65]
	v_lshl_add_u64 v[188:189], v[152:153], 0, s[8:9]
	v_add_co_u32_e32 v188, vcc, s39, v188
	s_nop 1
	v_addc_co_u32_e32 v189, vcc, 0, v189, vcc
	global_load_dwordx4 v[188:191], v[188:189], off offset:128
	v_mfma_f32_32x32x16_bf16 v[34:49], v[212:215], v[224:227], v[34:49]
	v_lshl_add_u64 v[192:193], v[152:153], 0, s[8:9]
	v_add_co_u32_e32 v192, vcc, s40, v192
	s_nop 1
	v_addc_co_u32_e32 v193, vcc, 0, v193, vcc
	global_load_dwordx4 v[192:195], v[192:193], off offset:128
	v_mfma_f32_32x32x16_bf16 v[18:33], v[212:215], v[228:231], v[18:33]
	v_lshl_add_u64 v[196:197], v[152:153], 0, s[8:9]
	v_add_co_u32_e32 v196, vcc, s41, v196
	s_nop 1
	v_addc_co_u32_e32 v197, vcc, 0, v197, vcc
	global_load_dwordx4 v[196:199], v[196:197], off offset:128
	v_mfma_f32_32x32x16_bf16 v[2:17], v[212:215], v[232:235], v[2:17]
	v_lshl_add_u64 v[200:201], v[152:153], 0, s[8:9]
	v_add_co_u32_e32 v200, vcc, s42, v200
	s_nop 1
	v_addc_co_u32_e32 v201, vcc, 0, v201, vcc
	global_load_dwordx4 v[200:203], v[200:201], off offset:128
	ds_read_b128 v[212:215], v131 offset:4704
	s_waitcnt lgkmcnt(4)
	v_mfma_f32_32x32x16_bf16 v[114:129], v[208:211], v[236:239], v[114:129]
	s_waitcnt lgkmcnt(3)
	v_mfma_f32_32x32x16_bf16 v[98:113], v[208:211], v[240:243], v[98:113]
	s_waitcnt lgkmcnt(2)
	v_mfma_f32_32x32x16_bf16 v[82:97], v[208:211], v[244:247], v[82:97]
	s_waitcnt lgkmcnt(1)
	v_mfma_f32_32x32x16_bf16 v[66:81], v[208:211], v[248:251], v[66:81]
	s_waitcnt lgkmcnt(0)
	v_mfma_f32_32x32x16_bf16 v[50:65], v[212:215], v[236:239], v[50:65]
	v_mfma_f32_32x32x16_bf16 v[34:49], v[212:215], v[240:243], v[34:49]
	v_mfma_f32_32x32x16_bf16 v[18:33], v[212:215], v[244:247], v[18:33]
	v_mfma_f32_32x32x16_bf16 v[2:17], v[212:215], v[248:251], v[2:17]
	s_setprio 0
	s_add_u32 s8, s8, 0x80
	s_addc_u32 s9, s9, 0
	s_barrier
;     ...
;   for (int kt = 0; kt < nk; ++kt) {
;     const int kn = (kt + 1 < nk) ? kt + 1 : kt;
;     GW_LOAD2(kn * 64, kn * bkstep)
;     __builtin_amdgcn_sched_barrier(0);
;     __builtin_amdgcn_s_setprio(1);
; #pragma unroll
;     for (int st = 0; st < 4; ++st) {
;       bf16x8 a0 = *(const bf16x8*)(Ab + st * 32);
;       bf16x8 a1 = *(const bf16x8*)(Ab + 32 * LSTR + st * 32);
;       bf16x8 b0 = *(const bf16x8*)(Bb + st * 32);
;       bf16x8 b1 = *(const bf16x8*)(Bb + 32 * LSTR + st * 32);
;       bf16x8 b2 = *(const bf16x8*)(Bb + 64 * LSTR + st * 32);
;       bf16x8 b3 = *(const bf16x8*)(Bb + 96 * LSTR + st * 32);
;       acc[0][0] = mfma32(a0, b0, acc[0][0]);
;       acc[0][1] = mfma32(a0, b1, acc[0][1]);
;       acc[0][2] = mfma32(a0, b2, acc[0][2]);
;       acc[0][3] = mfma32(a0, b3, acc[0][3]);
;       acc[1][0] = mfma32(a1, b0, acc[1][0]);
;       acc[1][1] = mfma32(a1, b1, acc[1][1]);
;       acc[1][2] = mfma32(a1, b2, acc[1][2]);
;       acc[1][3] = mfma32(a1, b3, acc[1][3]);
;     }
;     __builtin_amdgcn_s_setprio(0);
;     __builtin_amdgcn_sched_barrier(0);
;     __syncthreads();
;     GW_STORE()
;     __syncthreads();
;   }
	s_waitcnt vmcnt(11)
	ds_write_b128 v130, v[154:157]
	s_waitcnt vmcnt(10)
	ds_write_b128 v130, v[158:161] offset:4608
	s_waitcnt vmcnt(9)
	ds_write_b128 v130, v[162:165] offset:9216
	s_waitcnt vmcnt(8)
	ds_write_b128 v130, v[166:169] offset:13824
	s_waitcnt vmcnt(7)
	ds_write_b128 v130, v[170:173] offset:18432
	s_waitcnt vmcnt(6)
	ds_write_b128 v130, v[174:177] offset:23040
	s_waitcnt vmcnt(5)
	ds_write_b128 v130, v[178:181] offset:27648
	s_waitcnt vmcnt(4)
	ds_write_b128 v130, v[184:187] offset:32256
	s_waitcnt vmcnt(3)
	ds_write_b128 v130, v[188:191] offset:36864
	s_waitcnt vmcnt(2)
	ds_write_b128 v130, v[192:195] offset:41472
	s_waitcnt vmcnt(1)
	ds_write_b128 v130, v[196:199] offset:46080
	s_waitcnt vmcnt(0)
	ds_write_b128 v130, v[200:203] offset:50688
	s_waitcnt lgkmcnt(0)
	s_barrier
	s_nop 0
	s_nop 0
	v_add_co_u32_e32 v132, vcc, 0x10000, v142
	s_mov_b32 s58, 0
	s_nop 0
	v_addc_co_u32_e32 v133, vcc, 0, v143, vcc
	v_add_co_u32_e32 v132, vcc, 0x20000, v142
	s_nop 1
	v_addc_co_u32_e32 v133, vcc, 0, v143, vcc
	v_add_co_u32_e32 v148, vcc, 0x30000, v142
	s_nop 1
	v_addc_co_u32_e32 v149, vcc, 0, v143, vcc
	v_add_co_u32_e32 v132, vcc, 0x40000, v142
	s_nop 1
	v_addc_co_u32_e32 v133, vcc, 0, v143, vcc
	v_add_co_u32_e32 v148, vcc, 0x50000, v142
	s_nop 1
	v_addc_co_u32_e32 v149, vcc, 0, v143, vcc
	v_add_co_u32_e32 v132, vcc, 0x60000, v142
	s_nop 1
	v_addc_co_u32_e32 v133, vcc, 0, v143, vcc
	v_add_co_u32_e32 v142, vcc, 0x70000, v142
	s_nop 1
	v_addc_co_u32_e32 v143, vcc, 0, v143, vcc
	s_setprio 1
	ds_read_b128 v[196:199], v131 offset:0
	ds_read_b128 v[208:211], v138 offset:18432
	ds_read_b128 v[212:215], v138 offset:23040
	ds_read_b128 v[216:219], v138 offset:27648
	ds_read_b128 v[224:227], v138 offset:32256
	ds_read_b128 v[204:207], v131 offset:4608
	s_waitcnt lgkmcnt(4)
	v_mfma_f32_32x32x16_bf16 v[114:129], v[196:199], v[208:211], v[114:129]
	ds_read_b128 v[200:203], v131 offset:32
	ds_read_b128 v[228:231], v138 offset:18464
	s_waitcnt lgkmcnt(5)
	v_mfma_f32_32x32x16_bf16 v[98:113], v[196:199], v[212:215], v[98:113]
	ds_read_b128 v[232:235], v138 offset:23072
	s_waitcnt lgkmcnt(5)
	v_mfma_f32_32x32x16_bf16 v[82:97], v[196:199], v[216:219], v[82:97]
	ds_read_b128 v[236:239], v138 offset:27680
	s_waitcnt lgkmcnt(5)
	v_mfma_f32_32x32x16_bf16 v[66:81], v[196:199], v[224:227], v[66:81]
	ds_read_b128 v[240:243], v138 offset:32288
	s_waitcnt lgkmcnt(5)
	v_mfma_f32_32x32x16_bf16 v[50:65], v[204:207], v[208:211], v[50:65]
	v_mfma_f32_32x32x16_bf16 v[34:49], v[204:207], v[212:215], v[34:49]
	v_mfma_f32_32x32x16_bf16 v[18:33], v[204:207], v[216:219], v[18:33]
	v_mfma_f32_32x32x16_bf16 v[2:17], v[204:207], v[224:227], v[2:17]
	ds_read_b128 v[204:207], v131 offset:4640
	s_waitcnt lgkmcnt(4)
	v_mfma_f32_32x32x16_bf16 v[114:129], v[200:203], v[228:231], v[114:129]
	ds_read_b128 v[196:199], v131 offset:64
	ds_read_b128 v[208:211], v138 offset:18496
	s_waitcnt lgkmcnt(5)
	v_mfma_f32_32x32x16_bf16 v[98:113], v[200:203], v[232:235], v[98:113]
	ds_read_b128 v[212:215], v138 offset:23104
	s_waitcnt lgkmcnt(5)
	v_mfma_f32_32x32x16_bf16 v[82:97], v[200:203], v[236:239], v[82:97]
	ds_read_b128 v[216:219], v138 offset:27712
	s_waitcnt lgkmcnt(5)
	v_mfma_f32_32x32x16_bf16 v[66:81], v[200:203], v[240:243], v[66:81]
	ds_read_b128 v[224:227], v138 offset:32320
	s_waitcnt lgkmcnt(5)
	v_mfma_f32_32x32x16_bf16 v[50:65], v[204:207], v[228:231], v[50:65]
	v_mfma_f32_32x32x16_bf16 v[34:49], v[204:207], v[232:235], v[34:49]
	v_mfma_f32_32x32x16_bf16 v[18:33], v[204:207], v[236:239], v[18:33]
	v_mfma_f32_32x32x16_bf16 v[2:17], v[204:207], v[240:243], v[2:17]
	ds_read_b128 v[204:207], v131 offset:4672
	s_waitcnt lgkmcnt(4)
	v_mfma_f32_32x32x16_bf16 v[114:129], v[196:199], v[208:211], v[114:129]
	ds_read_b128 v[200:203], v131 offset:96
	ds_read_b128 v[228:231], v138 offset:18528
	s_waitcnt lgkmcnt(5)
	v_mfma_f32_32x32x16_bf16 v[98:113], v[196:199], v[212:215], v[98:113]
	ds_read_b128 v[232:235], v138 offset:23136
	s_waitcnt lgkmcnt(5)
	v_mfma_f32_32x32x16_bf16 v[82:97], v[196:199], v[216:219], v[82:97]
	ds_read_b128 v[236:239], v138 offset:27744
	s_waitcnt lgkmcnt(5)
	v_mfma_f32_32x32x16_bf16 v[66:81], v[196:199], v[224:227], v[66:81]
	ds_read_b128 v[240:243], v138 offset:32352
	s_waitcnt lgkmcnt(5)
	v_mfma_f32_32x32x16_bf16 v[50:65], v[204:207], v[208:211], v[50:65]
	v_mfma_f32_32x32x16_bf16 v[34:49], v[204:207], v[212:215], v[34:49]
	v_mfma_f32_32x32x16_bf16 v[18:33], v[204:207], v[216:219], v[18:33]
	v_mfma_f32_32x32x16_bf16 v[2:17], v[204:207], v[224:227], v[2:17]
	ds_read_b128 v[204:207], v131 offset:4704
	s_waitcnt lgkmcnt(4)
	v_mfma_f32_32x32x16_bf16 v[114:129], v[200:203], v[228:231], v[114:129]
	s_waitcnt lgkmcnt(3)
	v_mfma_f32_32x32x16_bf16 v[98:113], v[200:203], v[232:235], v[98:113]
	s_waitcnt lgkmcnt(2)
	v_mfma_f32_32x32x16_bf16 v[82:97], v[200:203], v[236:239], v[82:97]
	s_waitcnt lgkmcnt(1)
	v_mfma_f32_32x32x16_bf16 v[66:81], v[200:203], v[240:243], v[66:81]
	s_waitcnt lgkmcnt(0)
	v_mfma_f32_32x32x16_bf16 v[50:65], v[204:207], v[228:231], v[50:65]
	v_mfma_f32_32x32x16_bf16 v[34:49], v[204:207], v[232:235], v[34:49]
	v_mfma_f32_32x32x16_bf16 v[18:33], v[204:207], v[236:239], v[18:33]
	v_mfma_f32_32x32x16_bf16 v[2:17], v[204:207], v[240:243], v[2:17]
	s_setprio 0
	s_lshl_b32 s18, s10, 7
	s_cmpk_lt_i32 s10, 0x100
	s_cselect_b64 s[8:9], -1, 0
	s_add_i32 s6, s18, 0xffff8000
	s_and_b32 s57, s18, 0x80
	s_barrier
; __device__ __forceinline__ void inproj_tile(const Params& P, int l, int mt, int ntw, char* smem) {
;     ...
;   float* cs = (float*)smem;
;   const int row0 = mt * 128;
;   const bool isctx = row0 >= NLAT;
;   const int b = isctx ? ((row0 - NLAT) >> 8) : (row0 >> 12);
;   const int pos0 = isctx ? ((row0 - NLAT) & 255) : (row0 & 4095);
;   const int tk0 = isctx ? (SEQ + pos0) : pos0;
;   int tid_ = threadIdx.x;
;   asm volatile("" : "+v"(tid_));
;   const int lane = tid_ & 63, wave = tid_ >> 6;
;   const int r = 32 * wave + (lane & 31), half = lane >> 5;
;   const size_t grow = (size_t)row0 + r;
;   const float* crow = cs + r * CSTR + half * 64;
; #pragma unroll 1
;   for (int hsel = 0; hsel < 2; ++hsel) {
;     const int nt = ntw * 2 + hsel;
;     wide_acc_to_lds(acc, cs, hsel);
;     if (nt < 4) {
;       const int part = nt >> 1, cb = (nt & 1) * 128;
;       if (!isctx) {
;         u16* base = WSP(u16, OFF_FTT) + (size_t)b * 256 * 8192 + part * 4096 + pos0;
;         epi_transposed(cs, [&](int ch) { return base + (size_t)(cb + ch) * 8192; });
;       } else {
;         u16* base = WSP(u16, OFF_FTTC) + (size_t)b * 256 * 512 + part * 256 + pos0;
;         epi_transposed(cs, [&](int ch) { return base + (size_t)(cb + ch) * 512; });
;       }
;     } else if (nt < 7 || (nt >= 10 && nt < 13)) {
;       const bool isq = nt < 7;
;       const int head = (isq ? (nt - 4) : (nt - 10)) * 2 + half;
;       const float* g = (isq ? P.na_qn_g : P.na_kn_g) + l * 64;
;       float ss = 0.f;
; #pragma unroll
;       for (int q = 0; q < 16; ++q) {
;         float4 a = *(const float4*)(crow + q * 4);
;         ss += a.x * a.x + a.y * a.y + a.z * a.z + a.w * a.w;
;       }
;       const float rinv = rsqrtf(ss * (1.f / 64.f) + EPS) * (isq ? (0.125f * LOG2E) : 1.f);
;       u16* dst = WSP(u16, isq ? OFF_QN : OFF_KN) + grow * 384 + head * 64;
	s_lshr_b32 s6, s6, 8
	s_ashr_i32 s12, s10, 5
	s_and_b32 s59, s18, 0xf80
	s_or_b32 s11, s57, 0x1000
	v_mov_b32_e32 v154, v134
	s_waitcnt lgkmcnt(0)
	s_cmpk_gt_i32 s10, 0xff
	s_cselect_b32 s60, s11, s59
	v_ashrrev_i32_e32 v155, 1, v154
	v_bfi_b32 v130, s47, v155, v154
	s_movk_i32 s11, 0x210
	v_lshlrev_b32_e32 v133, 1, v154
	s_cselect_b32 s13, s57, s59
	v_mul_lo_u32 v132, v130, s11
	v_and_b32_e32 v184, 64, v133
	s_cselect_b32 s10, s6, s12
	v_lshl_add_u32 v185, v184, 2, v132
	s_lshl_b32 s33, s16, 1
	v_add_u32_e32 v132, s13, v155
	s_ashr_i32 s13, s12, 31
	s_lshl_b32 s16, s16, 12
	s_ashr_i32 s19, s18, 31
	s_lshl_b64 s[20:21], s[12:13], 22
	s_ashr_i32 s17, s16, 31
	s_lshl_b64 s[22:23], s[6:7], 18
	s_mul_i32 s11, s10, 6
	s_cmp_gt_u32 s33, 9
	s_mul_i32 s61, s10, 0x330000
	s_mul_hi_i32 s62, s11, 0x88000
	s_cselect_b64 s[10:11], -1, 0
	s_cmp_gt_u32 s33, 21
	s_cselect_b64 s[12:13], -1, 0
	s_cmp_lt_u32 s33, 16
	v_ashrrev_i32_e32 v132, 2, v132
	s_cselect_b64 s[24:25], -1, 0
	v_ashrrev_i32_e32 v131, 31, v130
	v_and_b32_e32 v142, -16, v132
	v_lshlrev_b32_e32 v132, 4, v130
	s_and_b64 s[24:25], s[24:25], exec
	v_and_b32_e32 v138, 0x3f0, v132
	s_cselect_b32 s6, s49, 0x343b1100
	v_lshl_add_u64 v[130:131], s[18:19], 0, v[130:131]
	v_mov_b64_e32 v[132:133], s[90:91]
	s_cselect_b32 s56, s48, 0x1ffffed
	v_mad_u64_u32 v[146:147], s[18:19], v130, s50, v[132:133]
	s_add_u32 s6, s90, s6
	s_addc_u32 s18, s91, 0
	s_add_u32 s6, s6, s61
	s_addc_u32 s19, s18, s62
	s_lshl_b32 s18, s60, 1
	s_add_u32 s18, s6, s18
	s_addc_u32 s19, s19, 0
	v_mov_b32_e32 v141, v139
	s_add_u32 s6, s28, s20
	v_lshl_add_u64 v[148:149], s[18:19], 0, v[140:141]
	s_addc_u32 s18, s29, s21
	s_lshl_b64 s[16:17], s[16:17], 1
	s_add_u32 s6, s6, s16
	s_addc_u32 s17, s18, s17
	s_lshl_b32 s16, s59, 1
	s_add_u32 s16, s6, s16
	s_addc_u32 s17, s17, 0
	s_add_u32 s6, s30, s22
	v_lshl_add_u64 v[150:151], s[16:17], 0, v[140:141]
	s_addc_u32 s18, s31, s23
	s_lshl_b64 s[16:17], s[14:15], 1
	s_add_u32 s6, s6, s16
	s_addc_u32 s15, s18, s17
	s_lshl_b32 s16, s57, 1
	s_add_u32 s16, s6, s16
	v_and_b32_e32 v156, 31, v154
	v_mov_b64_e32 v[144:145], v[138:139]
	s_addc_u32 s17, s15, 0
	v_lshrrev_b32_e32 v132, 5, v155
	v_bfe_u32 v138, v154, 5, 1
	v_lshl_add_u64 v[152:153], s[16:17], 0, v[140:141]
	v_mul_lo_u32 v132, v132, s51
	v_mul_u32_u24_e32 v133, 0x210, v156
	v_lshlrev_b32_e32 v141, 8, v138
	v_add3_u32 v141, v132, v133, v141
	v_mad_u64_u32 v[132:133], s[16:17], v130, s52, 0
	v_mad_i32_i24 v147, v131, s50, v147
	v_mad_i32_i24 v131, v131, s52, v133
	v_lshl_or_b32 v130, v138, 7, v132
	v_ashrrev_i32_e32 v143, 31, v142
	v_lshl_add_u64 v[154:155], s[4:5], 0, v[130:131]
	s_add_i32 s57, s14, 0xfffff500
	s_mov_b64 s[14:15], -1
	s_branch .LBB0_1287

; #define GM_LOAD(KOFF) GM_LOAD2(KOFF, 0)
;     ...
;   const u16* bp0 = Bt + (size_t)lr * ldb + kc * 8;
;   const size_t bstep = 32 * ldb;
;   const int so = lr * LSTR + kc * 16;
;   uint4 ra0, ra1, ra2, ra3, rb0, rb1, rb2, rb3;
;     ...
;   GM_LOAD(0)
;   GM_STORE(smem)
;   __syncthreads();
;   const int nk = K >> 6;
;   const int aoff = (wm * 64 + (lane & 31)) * LSTR + (lane >> 5) * 16;
;   const int boff = (wn * 64 + (lane & 31)) * LSTR + (lane >> 5) * 16;
;   for (int kt = 0; kt < nk; ++kt) {
;     const int kn = (kt + 1 < nk) ? kt + 1 : kt;
;     GM_LOAD2(kn * 64, kn * bkstep)
; __device__ __forceinline__ void zero_acc(f32x16 (&acc)[2][2]) {
; #pragma unroll
;   for (int i = 0; i < 2; ++i)
; #pragma unroll
;     for (int j = 0; j < 2; ++j)
; #pragma unroll
;       for (int r = 0; r < 16; ++r) acc[i][j][r] = 0.f;
.LBB0_1400:
	s_lshl_b64 s[26:27], s[10:11], 1
	v_lshl_add_u64 v[2:3], v[152:153], 0, s[26:27]
	v_lshl_add_u64 v[2:3], v[2:3], 0, v[142:143]
	v_add_co_u32_e32 v6, vcc, s15, v2
	v_lshl_add_u64 v[4:5], v[146:147], 0, s[26:27]
	s_nop 0
	v_addc_co_u32_e32 v7, vcc, 0, v3, vcc
	v_add_co_u32_e32 v8, vcc, s16, v2
	s_xor_b64 s[8:9], s[8:9], -1
	s_nop 0
	v_addc_co_u32_e32 v9, vcc, 0, v3, vcc
	global_load_dwordx4 v[34:37], v[6:7], off
	global_load_dwordx4 v[38:41], v[8:9], off
	v_add_co_u32_e32 v6, vcc, s17, v2
	global_load_dwordx4 v[42:45], v[2:3], off
	global_load_dwordx4 v[46:49], v[4:5], off
	v_addc_co_u32_e32 v7, vcc, 0, v3, vcc
	v_add_co_u32_e32 v2, vcc, s16, v4
	s_mov_b32 s6, 0
	s_nop 0
	v_addc_co_u32_e32 v3, vcc, 0, v5, vcc
	v_add_co_u32_e32 v8, vcc, s17, v4
	s_mov_b64 s[10:11], 0
	s_nop 0
	v_addc_co_u32_e32 v9, vcc, 0, v5, vcc
	global_load_dwordx4 v[52:55], v[2:3], off
	global_load_dwordx4 v[56:59], v[8:9], off
	v_add_co_u32_e32 v2, vcc, s15, v4
	v_lshl_add_u64 v[158:159], v[154:155], 0, s[26:27]
	s_nop 0
	v_addc_co_u32_e32 v3, vcc, 0, v5, vcc
	global_load_dwordx4 v[60:63], v[6:7], off
	global_load_dwordx4 v[170:173], v[2:3], off
	v_mov_b32_e32 v2, 0
	v_lshl_add_u64 v[160:161], v[156:157], 0, s[26:27]
	v_mov_b32_e32 v3, v2
	v_mov_b32_e32 v4, v2
	v_mov_b32_e32 v5, v2
	v_mov_b32_e32 v6, v2
	v_mov_b32_e32 v7, v2
	v_mov_b32_e32 v8, v2
	v_mov_b32_e32 v9, v2
	v_mov_b32_e32 v10, v2
	v_mov_b32_e32 v11, v2
	v_mov_b32_e32 v12, v2
	v_mov_b32_e32 v13, v2
	v_mov_b32_e32 v14, v2
	v_mov_b32_e32 v15, v2
	v_mov_b32_e32 v16, v2
	v_mov_b32_e32 v17, v2
	v_mov_b32_e32 v18, v2
	v_mov_b32_e32 v19, v2
	v_mov_b32_e32 v20, v2
	v_mov_b32_e32 v21, v2
	v_mov_b32_e32 v22, v2
	v_mov_b32_e32 v23, v2
	v_mov_b32_e32 v24, v2
	v_mov_b32_e32 v25, v2
	v_mov_b32_e32 v26, v2
	v_mov_b32_e32 v27, v2
	v_mov_b32_e32 v28, v2
	v_mov_b32_e32 v29, v2
	v_mov_b32_e32 v30, v2
	v_mov_b32_e32 v31, v2
	v_mov_b32_e32 v32, v2
	v_mov_b32_e32 v33, v2
	v_mov_b32_e32 v50, v2
	v_mov_b32_e32 v51, v2
	v_mov_b32_e32 v64, v2
	v_mov_b32_e32 v65, v2
	s_waitcnt vmcnt(5)
	ds_write_b128 v137, v[42:45]
	s_waitcnt vmcnt(4)
	ds_write_b128 v137, v[46:49] offset:18432
	s_waitcnt vmcnt(3)
	ds_write_b128 v137, v[52:55] offset:27648
	s_waitcnt vmcnt(2)
	ds_write_b128 v137, v[56:59] offset:32256
	ds_write_b128 v137, v[34:37] offset:4608
	ds_write_b128 v137, v[38:41] offset:9216
	s_waitcnt vmcnt(1)
	ds_write_b128 v137, v[60:63] offset:13824
	s_waitcnt vmcnt(0)
	ds_write_b128 v137, v[170:173] offset:23040
	v_mov_b32_e32 v52, v2
	v_mov_b32_e32 v53, v2
	v_mov_b32_e32 v54, v2
	v_mov_b32_e32 v55, v2
	v_mov_b32_e32 v56, v2
	v_mov_b32_e32 v57, v2
	v_mov_b32_e32 v58, v2
	v_mov_b32_e32 v59, v2
	v_mov_b32_e32 v60, v2
	v_mov_b32_e32 v61, v2
	v_mov_b32_e32 v62, v2
	v_mov_b32_e32 v63, v2
	v_mov_b32_e32 v34, v2
	v_mov_b32_e32 v35, v2
	v_mov_b32_e32 v36, v2
	v_mov_b32_e32 v37, v2
	v_mov_b32_e32 v38, v2
	v_mov_b32_e32 v39, v2
	v_mov_b32_e32 v40, v2
	v_mov_b32_e32 v41, v2
	v_mov_b32_e32 v42, v2
	v_mov_b32_e32 v43, v2
	v_mov_b32_e32 v44, v2
	v_mov_b32_e32 v45, v2
	v_mov_b32_e32 v46, v2
	v_mov_b32_e32 v47, v2
	v_mov_b32_e32 v48, v2
	v_mov_b32_e32 v49, v2
	s_waitcnt lgkmcnt(0)
	v_lshl_add_u64 v[178:179], v[158:159], 0, s[10:11]
	v_add_co_u32_e32 v170, vcc, s18, v178
	v_lshl_add_u64 v[194:195], v[160:161], 0, s[10:11]
	s_nop 0
	v_addc_co_u32_e32 v171, vcc, 0, v179, vcc
	v_add_co_u32_e32 v174, vcc, s19, v178
	s_nop 1
	v_addc_co_u32_e32 v175, vcc, 0, v179, vcc
	v_add_co_u32_e32 v180, vcc, s20, v178
	global_load_dwordx4 v[170:173], v[170:171], off offset:128
	s_nop 0
	global_load_dwordx4 v[174:177], v[174:175], off offset:128
	v_addc_co_u32_e32 v181, vcc, 0, v179, vcc
	v_add_co_u32_e32 v182, vcc, s21, v178
	s_nop 1
	v_addc_co_u32_e32 v183, vcc, 0, v179, vcc
	v_add_co_u32_e32 v186, vcc, s22, v194
	global_load_dwordx4 v[178:181], v[180:181], off offset:128
	s_nop 0
	global_load_dwordx4 v[182:185], v[182:183], off offset:128
	v_addc_co_u32_e32 v187, vcc, 0, v195, vcc
	v_add_co_u32_e32 v190, vcc, s23, v194
	s_nop 1
	v_addc_co_u32_e32 v191, vcc, 0, v195, vcc
	v_add_co_u32_e32 v196, vcc, s24, v194
	global_load_dwordx4 v[186:189], v[186:187], off offset:384
	s_nop 0
	global_load_dwordx4 v[190:193], v[190:191], off offset:384
	v_addc_co_u32_e32 v197, vcc, 0, v195, vcc
	v_add_co_u32_e32 v198, vcc, s25, v194
	s_nop 1
	v_addc_co_u32_e32 v199, vcc, 0, v195, vcc
	global_load_dwordx4 v[194:197], v[196:197], off offset:384
	s_nop 0
	global_load_dwordx4 v[198:201], v[198:199], off offset:384
;     ...
;   for (int kt = 0; kt < nk; ++kt) {
;     const int kn = (kt + 1 < nk) ? kt + 1 : kt;
;     GM_LOAD2(kn * 64, kn * bkstep)
;     __builtin_amdgcn_sched_barrier(0);
;     const char* As = smem + (kt & 1) * 2 * TILE_B;
;     const char* Bs = As + TILE_B;
;     if constexpr (HOIST) {
;       bf16x8 fa0[4], fa1[4], fb0[4], fb1[4];
; #pragma unroll
;       for (int st = 0; st < 4; ++st) {
;         fa0[st] = *(const bf16x8*)(As + aoff + st * 32);
;         fb0[st] = *(const bf16x8*)(Bs + boff + st * 32);
;         fa1[st] = *(const bf16x8*)(As + aoff + 32 * LSTR + st * 32);
;         fb1[st] = *(const bf16x8*)(Bs + boff + 32 * LSTR + st * 32);
;       }
;       __builtin_amdgcn_sched_barrier(0);
; #pragma unroll
;       for (int st = 0; st < 4; ++st) {
;         acc[0][0] = mfma32(fa0[st], fb0[st], acc[0][0]);
;         acc[0][1] = mfma32(fa0[st], fb1[st], acc[0][1]);
;         acc[1][0] = mfma32(fa1[st], fb0[st], acc[1][0]);
;         acc[1][1] = mfma32(fa1[st], fb1[st], acc[1][1]);
;       }
;     } else {
; #pragma unroll
;       for (int st = 0; st < 4; ++st) {
;         bf16x8 a0 = *(const bf16x8*)(As + aoff + st * 32);
;         bf16x8 a1 = *(const bf16x8*)(As + aoff + 32 * LSTR + st * 32);
;         bf16x8 b0 = *(const bf16x8*)(Bs + boff + st * 32);
;         bf16x8 b1 = *(const bf16x8*)(Bs + boff + 32 * LSTR + st * 32);
;         acc[0][0] = mfma32(a0, b0, acc[0][0]);
;         acc[0][1] = mfma32(a0, b1, acc[0][1]);
;         acc[1][0] = mfma32(a1, b0, acc[1][0]);
;         acc[1][1] = mfma32(a1, b1, acc[1][1]);
;       }
;     }
;     __builtin_amdgcn_sched_barrier(0);
;     {
;       char* Ad = smem + ((kt + 1) & 1) * 2 * TILE_B;
;       GM_STORE(Ad)
;     }
;     __syncthreads();
;   }
.LBB0_1401:
	s_barrier
	s_and_b32 s26, s6, 2
	s_mulk_i32 s26, 0x4800
	v_add3_u32 v130, s26, v163, v164
	v_add3_u32 v169, s26, v165, v164
	ds_read_b128 v[202:205], v130 offset:0
	ds_read_b128 v[206:209], v169 offset:18432
	ds_read_b128 v[214:217], v130 offset:4608
	ds_read_b128 v[210:213], v169 offset:23040
	s_waitcnt lgkmcnt(2)
	v_mfma_f32_32x32x16_bf16 v[50:65], v[202:205], v[206:209], v[50:65]
	ds_read_b128 v[218:221], v130 offset:32
	s_waitcnt lgkmcnt(2)
	v_mfma_f32_32x32x16_bf16 v[2:17], v[214:217], v[206:209], v[2:17]
	ds_read_b128 v[206:209], v169 offset:18464
	s_waitcnt lgkmcnt(2)
	v_mfma_f32_32x32x16_bf16 v[18:33], v[202:205], v[210:213], v[18:33]
	ds_read_b128 v[202:205], v130 offset:4640
	v_mfma_f32_32x32x16_bf16 v[34:49], v[214:217], v[210:213], v[34:49]
	ds_read_b128 v[210:213], v169 offset:23072
	s_waitcnt lgkmcnt(2)
	v_mfma_f32_32x32x16_bf16 v[50:65], v[218:221], v[206:209], v[50:65]
	ds_read_b128 v[214:217], v130 offset:64
	s_waitcnt lgkmcnt(2)
	v_mfma_f32_32x32x16_bf16 v[2:17], v[202:205], v[206:209], v[2:17]
	ds_read_b128 v[206:209], v169 offset:18496
	s_waitcnt lgkmcnt(2)
	v_mfma_f32_32x32x16_bf16 v[18:33], v[218:221], v[210:213], v[18:33]
	ds_read_b128 v[218:221], v130 offset:4672
	v_mfma_f32_32x32x16_bf16 v[34:49], v[202:205], v[210:213], v[34:49]
	ds_read_b128 v[210:213], v169 offset:23104
	s_waitcnt lgkmcnt(2)
	v_mfma_f32_32x32x16_bf16 v[50:65], v[214:217], v[206:209], v[50:65]
	ds_read_b128 v[202:205], v130 offset:96
	s_waitcnt lgkmcnt(2)
	v_mfma_f32_32x32x16_bf16 v[2:17], v[218:221], v[206:209], v[2:17]
	ds_read_b128 v[206:209], v169 offset:18528
	s_waitcnt lgkmcnt(2)
	v_mfma_f32_32x32x16_bf16 v[18:33], v[214:217], v[210:213], v[18:33]
	ds_read_b128 v[214:217], v130 offset:4704
	v_mfma_f32_32x32x16_bf16 v[34:49], v[218:221], v[210:213], v[34:49]
	ds_read_b128 v[210:213], v169 offset:23136
	s_waitcnt lgkmcnt(2)
	v_mfma_f32_32x32x16_bf16 v[50:65], v[202:205], v[206:209], v[50:65]
	s_waitcnt lgkmcnt(1)
	v_mfma_f32_32x32x16_bf16 v[2:17], v[214:217], v[206:209], v[2:17]
	s_waitcnt lgkmcnt(0)
	v_mfma_f32_32x32x16_bf16 v[18:33], v[202:205], v[210:213], v[18:33]
	v_mfma_f32_32x32x16_bf16 v[34:49], v[214:217], v[210:213], v[34:49]
	s_add_i32 s6, s6, 2
	s_and_b32 s26, s6, 2
	s_add_u32 s10, s10, 0x80
	s_mulk_i32 s26, 0x4800
	s_addc_u32 s11, s11, 0
	v_add_u32_e32 v130, s26, v137
	s_cmpk_lg_i32 s10, 0x1f00
	s_waitcnt vmcnt(7)
	ds_write_b128 v130, v[170:173]
	v_lshl_add_u64 v[170:171], v[158:159], 0, s[10:11]
	v_add_co_u32_e32 v170, vcc, s18, v170
	s_nop 1
	v_addc_co_u32_e32 v171, vcc, 0, v171, vcc
	global_load_dwordx4 v[170:173], v[170:171], off offset:128
	s_waitcnt vmcnt(7)
	ds_write_b128 v130, v[174:177] offset:4608
	v_lshl_add_u64 v[174:175], v[158:159], 0, s[10:11]
	v_add_co_u32_e32 v174, vcc, s19, v174
	s_nop 1
	v_addc_co_u32_e32 v175, vcc, 0, v175, vcc
	global_load_dwordx4 v[174:177], v[174:175], off offset:128
	s_waitcnt vmcnt(7)
	ds_write_b128 v130, v[178:181] offset:9216
	v_lshl_add_u64 v[178:179], v[158:159], 0, s[10:11]
	v_add_co_u32_e32 v178, vcc, s20, v178
	s_nop 1
	v_addc_co_u32_e32 v179, vcc, 0, v179, vcc
	global_load_dwordx4 v[178:181], v[178:179], off offset:128
	s_waitcnt vmcnt(7)
	ds_write_b128 v130, v[182:185] offset:13824
	v_lshl_add_u64 v[182:183], v[158:159], 0, s[10:11]
	v_add_co_u32_e32 v182, vcc, s21, v182
	s_nop 1
	v_addc_co_u32_e32 v183, vcc, 0, v183, vcc
	global_load_dwordx4 v[182:185], v[182:183], off offset:128
	s_waitcnt vmcnt(7)
	ds_write_b128 v130, v[186:189] offset:18432
	v_lshl_add_u64 v[186:187], v[160:161], 0, s[10:11]
	v_add_co_u32_e32 v186, vcc, s22, v186
	s_nop 1
	v_addc_co_u32_e32 v187, vcc, 0, v187, vcc
	global_load_dwordx4 v[186:189], v[186:187], off offset:384
	s_waitcnt vmcnt(7)
	ds_write_b128 v130, v[190:193] offset:23040
	v_lshl_add_u64 v[190:191], v[160:161], 0, s[10:11]
	v_add_co_u32_e32 v190, vcc, s23, v190
	s_nop 1
	v_addc_co_u32_e32 v191, vcc, 0, v191, vcc
	global_load_dwordx4 v[190:193], v[190:191], off offset:384
	s_waitcnt vmcnt(7)
	ds_write_b128 v130, v[194:197] offset:27648
	v_lshl_add_u64 v[194:195], v[160:161], 0, s[10:11]
	v_add_co_u32_e32 v194, vcc, s24, v194
	s_nop 1
	v_addc_co_u32_e32 v195, vcc, 0, v195, vcc
	global_load_dwordx4 v[194:197], v[194:195], off offset:384
	s_waitcnt vmcnt(7)
	ds_write_b128 v130, v[198:201] offset:32256
	v_lshl_add_u64 v[198:199], v[160:161], 0, s[10:11]
	v_add_co_u32_e32 v198, vcc, s25, v198
	s_nop 1
	v_addc_co_u32_e32 v199, vcc, 0, v199, vcc
	global_load_dwordx4 v[198:201], v[198:199], off offset:384
	s_waitcnt lgkmcnt(0)
	s_cbranch_scc1 .LBB0_1401
	s_barrier
;     ...
;   for (int kt = 0; kt < nk; ++kt) {
;     const int kn = (kt + 1 < nk) ? kt + 1 : kt;
;     GM_LOAD2(kn * 64, kn * bkstep)
;     __builtin_amdgcn_sched_barrier(0);
;     const char* As = smem + (kt & 1) * 2 * TILE_B;
;     const char* Bs = As + TILE_B;
;     if constexpr (HOIST) {
;       bf16x8 fa0[4], fa1[4], fb0[4], fb1[4];
; #pragma unroll
;       for (int st = 0; st < 4; ++st) {
;         fa0[st] = *(const bf16x8*)(As + aoff + st * 32);
;         fb0[st] = *(const bf16x8*)(Bs + boff + st * 32);
;         fa1[st] = *(const bf16x8*)(As + aoff + 32 * LSTR + st * 32);
;         fb1[st] = *(const bf16x8*)(Bs + boff + 32 * LSTR + st * 32);
;       }
;       __builtin_amdgcn_sched_barrier(0);
; #pragma unroll
;       for (int st = 0; st < 4; ++st) {
;         acc[0][0] = mfma32(fa0[st], fb0[st], acc[0][0]);
;         acc[0][1] = mfma32(fa0[st], fb1[st], acc[0][1]);
;         acc[1][0] = mfma32(fa1[st], fb0[st], acc[1][0]);
;         acc[1][1] = mfma32(fa1[st], fb1[st], acc[1][1]);
;       }
;     } else {
; #pragma unroll
;       for (int st = 0; st < 4; ++st) {
;         bf16x8 a0 = *(const bf16x8*)(As + aoff + st * 32);
;         bf16x8 a1 = *(const bf16x8*)(As + aoff + 32 * LSTR + st * 32);
;         bf16x8 b0 = *(const bf16x8*)(Bs + boff + st * 32);
;         bf16x8 b1 = *(const bf16x8*)(Bs + boff + 32 * LSTR + st * 32);
;         acc[0][0] = mfma32(a0, b0, acc[0][0]);
;         acc[0][1] = mfma32(a0, b1, acc[0][1]);
;         acc[1][0] = mfma32(a1, b0, acc[1][0]);
;         acc[1][1] = mfma32(a1, b1, acc[1][1]);
;       }
;     }
;     __builtin_amdgcn_sched_barrier(0);
;     {
;       char* Ad = smem + ((kt + 1) & 1) * 2 * TILE_B;
;       GM_STORE(Ad)
;     }
;     __syncthreads();
;   }
	s_and_b32 s26, s6, 2
	s_mulk_i32 s26, 0x4800
	v_add3_u32 v130, s26, v163, v164
	v_add3_u32 v169, s26, v165, v164
	ds_read_b128 v[202:205], v130 offset:0
	ds_read_b128 v[206:209], v169 offset:18432
	ds_read_b128 v[214:217], v130 offset:4608
	ds_read_b128 v[210:213], v169 offset:23040
	s_waitcnt lgkmcnt(2)
	v_mfma_f32_32x32x16_bf16 v[50:65], v[202:205], v[206:209], v[50:65]
	ds_read_b128 v[218:221], v130 offset:32
	s_waitcnt lgkmcnt(2)
	v_mfma_f32_32x32x16_bf16 v[2:17], v[214:217], v[206:209], v[2:17]
	ds_read_b128 v[206:209], v169 offset:18464
	s_waitcnt lgkmcnt(2)
	v_mfma_f32_32x32x16_bf16 v[18:33], v[202:205], v[210:213], v[18:33]
	ds_read_b128 v[202:205], v130 offset:4640
	v_mfma_f32_32x32x16_bf16 v[34:49], v[214:217], v[210:213], v[34:49]
	ds_read_b128 v[210:213], v169 offset:23072
	s_waitcnt lgkmcnt(2)
	v_mfma_f32_32x32x16_bf16 v[50:65], v[218:221], v[206:209], v[50:65]
	ds_read_b128 v[214:217], v130 offset:64
	s_waitcnt lgkmcnt(2)
	v_mfma_f32_32x32x16_bf16 v[2:17], v[202:205], v[206:209], v[2:17]
	ds_read_b128 v[206:209], v169 offset:18496
	s_waitcnt lgkmcnt(2)
	v_mfma_f32_32x32x16_bf16 v[18:33], v[218:221], v[210:213], v[18:33]
	ds_read_b128 v[218:221], v130 offset:4672
	v_mfma_f32_32x32x16_bf16 v[34:49], v[202:205], v[210:213], v[34:49]
	ds_read_b128 v[210:213], v169 offset:23104
	s_waitcnt lgkmcnt(2)
	v_mfma_f32_32x32x16_bf16 v[50:65], v[214:217], v[206:209], v[50:65]
	ds_read_b128 v[202:205], v130 offset:96
	s_waitcnt lgkmcnt(2)
	v_mfma_f32_32x32x16_bf16 v[2:17], v[218:221], v[206:209], v[2:17]
	ds_read_b128 v[206:209], v169 offset:18528
	s_waitcnt lgkmcnt(2)
	v_mfma_f32_32x32x16_bf16 v[18:33], v[214:217], v[210:213], v[18:33]
	ds_read_b128 v[214:217], v130 offset:4704
	v_mfma_f32_32x32x16_bf16 v[34:49], v[218:221], v[210:213], v[34:49]
	ds_read_b128 v[210:213], v169 offset:23136
	s_waitcnt lgkmcnt(2)
	v_mfma_f32_32x32x16_bf16 v[50:65], v[202:205], v[206:209], v[50:65]
	s_waitcnt lgkmcnt(1)
	v_mfma_f32_32x32x16_bf16 v[2:17], v[214:217], v[206:209], v[2:17]
	s_waitcnt lgkmcnt(0)
	v_mfma_f32_32x32x16_bf16 v[18:33], v[202:205], v[210:213], v[18:33]
	v_mfma_f32_32x32x16_bf16 v[34:49], v[214:217], v[210:213], v[34:49]
	s_add_i32 s6, s6, 2
	s_and_b32 s26, s6, 2
	s_add_u32 s10, s10, 0x80
	s_mulk_i32 s26, 0x4800
	s_addc_u32 s11, s11, 0
	v_add_u32_e32 v130, s26, v137
	s_waitcnt vmcnt(7)
	ds_write_b128 v130, v[170:173]
	s_waitcnt vmcnt(6)
	ds_write_b128 v130, v[174:177] offset:4608
	s_waitcnt vmcnt(5)
	ds_write_b128 v130, v[178:181] offset:9216
	s_waitcnt vmcnt(4)
	ds_write_b128 v130, v[182:185] offset:13824
	s_waitcnt vmcnt(3)
	ds_write_b128 v130, v[186:189] offset:18432
	s_waitcnt vmcnt(2)
	ds_write_b128 v130, v[190:193] offset:23040
	s_waitcnt vmcnt(1)
	ds_write_b128 v130, v[194:197] offset:27648
	s_waitcnt vmcnt(0)
	ds_write_b128 v130, v[198:201] offset:32256
	s_waitcnt lgkmcnt(0)
	s_barrier
	v_lshl_add_u64 v[174:175], v[158:159], 0, s[10:11]
	v_add_co_u32_e32 v158, vcc, 0xdf00000, v174
	v_lshl_add_u64 v[190:191], v[160:161], 0, s[10:11]
	s_nop 0
	v_addc_co_u32_e32 v159, vcc, 0, v175, vcc
	v_add_co_u32_e32 v170, vcc, 0xdf80000, v174
	s_nop 1
	v_addc_co_u32_e32 v171, vcc, 0, v175, vcc
	v_add_co_u32_e32 v176, vcc, 0xe000000, v174
	s_nop 0
	v_addc_co_u32_e32 v177, vcc, 0, v175, vcc
	v_add_co_u32_e32 v178, vcc, 0xe080000, v174
	s_nop 1
	v_addc_co_u32_e32 v179, vcc, 0, v175, vcc
	v_add_co_u32_e32 v182, vcc, 0x35d31000, v190
	s_nop 0
	v_addc_co_u32_e32 v183, vcc, 0, v191, vcc
	v_add_co_u32_e32 v186, vcc, 0x35db1000, v190
	s_nop 1
	v_addc_co_u32_e32 v187, vcc, 0, v191, vcc
	v_add_co_u32_e32 v192, vcc, 0x35e31000, v190
	s_nop 0
	v_addc_co_u32_e32 v193, vcc, 0, v191, vcc
	v_add_co_u32_e32 v194, vcc, 0x35eb1000, v190
	s_nop 1
	v_addc_co_u32_e32 v195, vcc, 0, v191, vcc
	s_nop 0
	v_add3_u32 v130, s26, v163, v164
	v_add3_u32 v169, s26, v165, v164
	ds_read_b128 v[198:201], v130 offset:0
	ds_read_b128 v[202:205], v169 offset:18432
	ds_read_b128 v[210:213], v130 offset:4608
	ds_read_b128 v[206:209], v169 offset:23040
	s_waitcnt lgkmcnt(2)
	v_mfma_f32_32x32x16_bf16 v[50:65], v[198:201], v[202:205], v[50:65]
	ds_read_b128 v[214:217], v130 offset:32
	s_waitcnt lgkmcnt(2)
	v_mfma_f32_32x32x16_bf16 v[2:17], v[210:213], v[202:205], v[2:17]
	ds_read_b128 v[202:205], v169 offset:18464
	s_waitcnt lgkmcnt(2)
	v_mfma_f32_32x32x16_bf16 v[18:33], v[198:201], v[206:209], v[18:33]
	ds_read_b128 v[198:201], v130 offset:4640
	v_mfma_f32_32x32x16_bf16 v[34:49], v[210:213], v[206:209], v[34:49]
	ds_read_b128 v[206:209], v169 offset:23072
	s_waitcnt lgkmcnt(2)
	v_mfma_f32_32x32x16_bf16 v[50:65], v[214:217], v[202:205], v[50:65]
	ds_read_b128 v[210:213], v130 offset:64
	s_waitcnt lgkmcnt(2)
	v_mfma_f32_32x32x16_bf16 v[2:17], v[198:201], v[202:205], v[2:17]
	ds_read_b128 v[202:205], v169 offset:18496
	s_waitcnt lgkmcnt(2)
	v_mfma_f32_32x32x16_bf16 v[18:33], v[214:217], v[206:209], v[18:33]
	ds_read_b128 v[214:217], v130 offset:4672
	v_mfma_f32_32x32x16_bf16 v[34:49], v[198:201], v[206:209], v[34:49]
	ds_read_b128 v[206:209], v169 offset:23104
	s_waitcnt lgkmcnt(2)
	v_mfma_f32_32x32x16_bf16 v[50:65], v[210:213], v[202:205], v[50:65]
	ds_read_b128 v[198:201], v130 offset:96
	s_waitcnt lgkmcnt(2)
	v_mfma_f32_32x32x16_bf16 v[2:17], v[214:217], v[202:205], v[2:17]
	ds_read_b128 v[202:205], v169 offset:18528
	s_waitcnt lgkmcnt(2)
	v_mfma_f32_32x32x16_bf16 v[18:33], v[210:213], v[206:209], v[18:33]
	ds_read_b128 v[210:213], v130 offset:4704
	v_mfma_f32_32x32x16_bf16 v[34:49], v[214:217], v[206:209], v[34:49]
	ds_read_b128 v[206:209], v169 offset:23136
	s_waitcnt lgkmcnt(2)
	v_mfma_f32_32x32x16_bf16 v[50:65], v[198:201], v[202:205], v[50:65]
	s_waitcnt lgkmcnt(1)
	v_mfma_f32_32x32x16_bf16 v[2:17], v[210:213], v[202:205], v[2:17]
	s_waitcnt lgkmcnt(0)
	v_mfma_f32_32x32x16_bf16 v[18:33], v[198:201], v[206:209], v[18:33]
	v_mfma_f32_32x32x16_bf16 v[34:49], v[210:213], v[206:209], v[34:49]
	s_waitcnt lgkmcnt(0)
	s_barrier
; __device__ __forceinline__ void acc_to_lds(const f32x16 (&acc)[2][2], float* cs) {
;   const int tid = threadIdx.x, lane = tid & 63, wave = tid >> 6;
;   const int wm = wave >> 1, wn = wave & 1;
; #pragma unroll
;   for (int i = 0; i < 2; ++i)
; #pragma unroll
;     for (int j = 0; j < 2; ++j)
; #pragma unroll
;       for (int r = 0; r < 16; ++r) {
;         int row = wm * 64 + i * 32 + (r & 3) + 8 * (r >> 2) + 4 * (lane >> 5);
;         int col = wn * 64 + j * 32 + (lane & 31);
;         cs[row * CSTR + col] = acc[i][j][r];
;       }
;   __syncthreads();
; __device__ __forceinline__ void fourier_half_tile(const Params& P, bool isctx, int b, int mt, int nt, char* smem) {
;     ...
;     } else {
;       u16* d1 = WSP(u16, OFF_FTO) + (rowbase + k) * 256 + nt * 128 + half * 64;
;       u16* d2 = WSP(u16, OFF_FTO) + (rowbase + (k > 0 ? N - k : 0)) * 256 + nt * 128 + half * 64;
; #pragma unroll
;       for (int q = 0; q < 8; ++q) {
;         float4 a = *(const float4*)(cs + r * CSTR + half * 64 + q * 8);
;         float4 c = *(const float4*)(cs + r * CSTR + half * 64 + q * 8 + 4);
;         uint4 o1, o2;
;         o1.x = pack2(pacc[q * 8 + 0] + a.x, pacc[q * 8 + 1] + a.y); o1.y = pack2(pacc[q * 8 + 2] + a.z, pacc[q * 8 + 3] + a.w);
;         o1.z = pack2(pacc[q * 8 + 4] + c.x, pacc[q * 8 + 5] + c.y); o1.w = pack2(pacc[q * 8 + 6] + c.z, pacc[q * 8 + 7] + c.w);
;         o2.x = pack2(pacc[q * 8 + 0] - a.x, pacc[q * 8 + 1] - a.y); o2.y = pack2(pacc[q * 8 + 2] - a.z, pacc[q * 8 + 3] - a.w);
;         o2.z = pack2(pacc[q * 8 + 4] - c.x, pacc[q * 8 + 5] - c.y); o2.w = pack2(pacc[q * 8 + 6] - c.z, pacc[q * 8 + 7] - c.w);
;         *(uint4*)(d1 + q * 8) = o1;
;         if (k > 0) *(uint4*)(d2 + q * 8) = o2;
;       }
	ds_write2_b32 v166, v50, v18 offset1:32
	ds_write2_b32 v166, v51, v19 offset0:132 offset1:164
	v_add_u32_e32 v18, 0x400, v166
	ds_write2_b32 v18, v52, v20 offset0:8 offset1:40
	ds_write2_b32 v18, v53, v21 offset0:140 offset1:172
	v_add_u32_e32 v18, 0x1000, v166
	ds_write2_b32 v18, v54, v22 offset0:32 offset1:64
	ds_write2_b32 v18, v55, v23 offset0:164 offset1:196
	v_add_u32_e32 v18, 0x1400, v166
	ds_write2_b32 v18, v56, v24 offset0:40 offset1:72
	ds_write2_b32 v18, v57, v25 offset0:172 offset1:204
	v_add_u32_e32 v18, 0x2000, v166
	ds_write2_b32 v18, v58, v26 offset0:64 offset1:96
	ds_write2_b32 v18, v59, v27 offset0:196 offset1:228
	v_add_u32_e32 v18, 0x2400, v166
	ds_write2_b32 v18, v60, v28 offset0:72 offset1:104
	ds_write2_b32 v18, v61, v29 offset0:204 offset1:236
	v_add_u32_e32 v18, 0x3000, v166
	ds_write2_b32 v18, v62, v30 offset0:96 offset1:128
	v_add_u32_e32 v18, 0x3200, v166
	ds_write2_b32 v18, v63, v31 offset0:100 offset1:132
	v_add_u32_e32 v18, 0x3400, v166
	ds_write2_b32 v18, v64, v32 offset0:104 offset1:136
	v_add_u32_e32 v18, 0x3600, v166
	ds_write2_b32 v18, v65, v33 offset0:108 offset1:140
	v_add_u32_e32 v18, 0x4000, v166
	ds_write2_b32 v18, v2, v34 offset0:128 offset1:160
	v_add_u32_e32 v2, 0x4400, v166
	ds_write2_b32 v2, v3, v35 offset0:4 offset1:36
	ds_write2_b32 v2, v4, v36 offset0:136 offset1:168
	v_add_u32_e32 v2, 0x4800, v166
	ds_write2_b32 v2, v5, v37 offset0:12 offset1:44
	v_add_u32_e32 v2, 0x5000, v166
	ds_write2_b32 v2, v6, v38 offset0:160 offset1:192
	v_add_u32_e32 v2, 0x5400, v166
	ds_write2_b32 v2, v7, v39 offset0:36 offset1:68
	ds_write2_b32 v2, v8, v40 offset0:168 offset1:200
	v_add_u32_e32 v2, 0x5800, v166
	ds_write2_b32 v2, v9, v41 offset0:44 offset1:76
	v_add_u32_e32 v2, 0x6000, v166
	ds_write2_b32 v2, v10, v42 offset0:192 offset1:224
	v_add_u32_e32 v2, 0x6400, v166
	ds_write2_b32 v2, v11, v43 offset0:68 offset1:100
	ds_write2_b32 v2, v12, v44 offset0:200 offset1:232
	v_add_u32_e32 v2, 0x6800, v166
	ds_write2_b32 v2, v13, v45 offset0:76 offset1:108
	v_add_u32_e32 v2, 0x7200, v166
	ds_write2_b32 v2, v14, v46 offset0:96 offset1:128
	v_add_u32_e32 v2, 0x7400, v166
	ds_write2_b32 v2, v15, v47 offset0:100 offset1:132
	v_add_u32_e32 v2, 0x7600, v166
	ds_write2_b32 v2, v16, v48 offset0:104 offset1:136
	v_add_u32_e32 v2, 0x7800, v166
	s_mov_b64 s[10:11], -1
	s_and_b64 vcc, exec, s[8:9]
	ds_write2_b32 v2, v17, v49 offset0:108 offset1:140
	s_waitcnt lgkmcnt(0)
	s_barrier
	s_cbranch_vccz .LBB0_1420
	ds_read_b128 v[2:5], v167
	ds_read_b128 v[6:9], v167 offset:16
	s_waitcnt lgkmcnt(1)
	v_add_f32_e32 v10, v78, v2
	v_add_f32_e32 v11, v79, v3
	v_sub_f32_e32 v2, v78, v2
	v_sub_f32_e32 v3, v79, v3
	v_add_f32_e32 v12, v80, v4
	v_add_f32_e32 v13, v81, v5
	v_cvt_pk_bf16_f32 v2, v2, v3
	v_sub_f32_e32 v3, v80, v4
	v_sub_f32_e32 v4, v81, v5
	v_cvt_pk_bf16_f32 v10, v10, v11
	v_cvt_pk_bf16_f32 v11, v12, v13
	s_waitcnt lgkmcnt(0)
	v_add_f32_e32 v12, v74, v6
	v_add_f32_e32 v13, v75, v7
	v_cvt_pk_bf16_f32 v3, v3, v4
	v_sub_f32_e32 v4, v74, v6
	v_sub_f32_e32 v5, v75, v7
	v_cvt_pk_bf16_f32 v12, v12, v13
	v_add_f32_e32 v13, v76, v8
	v_cvt_pk_bf16_f32 v4, v4, v5
	v_sub_f32_e32 v5, v76, v8
	v_add_f32_e32 v14, v77, v9
	v_cvt_pk_bf16_f32 v13, v13, v14
	v_sub_f32_e32 v6, v77, v9
	v_cvt_pk_bf16_f32 v5, v5, v6
	global_store_dwordx4 v[148:149], v[10:13], off
	s_and_saveexec_b64 s[10:11], s[2:3]
	s_cbranch_execz .LBB0_1405
	global_store_dwordx4 v[150:151], v[2:5], off

; #define GM_LOAD(KOFF) GM_LOAD2(KOFF, 0)
;     ...
;   const u16* bp0 = Bt + (size_t)lr * ldb + kc * 8;
;   const size_t bstep = 32 * ldb;
;   const int so = lr * LSTR + kc * 16;
;   uint4 ra0, ra1, ra2, ra3, rb0, rb1, rb2, rb3;
;     ...
;   GM_LOAD(0)
;   GM_STORE(smem)
;   __syncthreads();
;   const int nk = K >> 6;
;   const int aoff = (wm * 64 + (lane & 31)) * LSTR + (lane >> 5) * 16;
;   const int boff = (wn * 64 + (lane & 31)) * LSTR + (lane >> 5) * 16;
;   for (int kt = 0; kt < nk; ++kt) {
;     const int kn = (kt + 1 < nk) ? kt + 1 : kt;
;     GM_LOAD2(kn * 64, kn * bkstep)
; __device__ __forceinline__ void merge_tile(const Params& P, int l, int mt, int nt, char* smem) {
;     ...
;   for (int br = 0; br < 3; ++br) {
;     f32x16 acc[2][2];
;     zero_acc(acc);
;     const int K = (br == 0) ? 256 : 384;
;     const u16* A = WSP(u16, br == 0 ? OFF_FTO : (br == 1 ? OFF_ONA : OFF_ODF)) + (size_t)mt * 128 * K;
;     const u16* Bt = WSP(u16, br == 0 ? OFF_WFT : (br == 1 ? OFF_WNA : OFF_WDF)) + ((size_t)l * DM + nt * 128) * K;
;     gemm_main<false>([&](int rr) { return A + (size_t)rr * K; }, Bt, K, K, smem, acc);
.LBB0_1639:
	s_cmp_eq_u32 s38, 1
	s_cselect_b32 s6, s21, 0x1cdb1100
	s_cselect_b32 s39, s22, 0x1980000
	s_cmp_eq_u32 s38, 0
	s_cselect_b32 s44, s23, 0x180
	s_cselect_b32 s45, 0x1e731100, s6
	s_mul_hi_u32 s6, s10, s44
	s_mul_i32 s40, s11, s44
	s_cselect_b32 s39, 0x1700000, s39
	s_add_u32 s42, s90, s45
	s_addc_u32 s43, s91, 0
	s_add_i32 s41, s6, s40
	s_mul_i32 s40, s10, s44
	s_lshl_b64 s[40:41], s[40:41], 1
	s_add_u32 s40, s42, s40
	s_addc_u32 s41, s43, s41
	s_add_u32 s6, s90, s39
	s_mul_i32 s42, s15, s44
	s_mul_hi_u32 s43, s14, s44
	s_addc_u32 s46, s91, 0
	s_add_i32 s43, s43, s42
	s_mul_i32 s42, s14, s44
	s_lshl_b64 s[42:43], s[42:43], 1
	v_mul_u32_u24_e32 v2, s44, v1
	s_add_u32 s42, s6, s42
	v_lshlrev_b32_e32 v68, 1, v2
	s_addc_u32 s43, s46, s43
	v_lshl_add_u64 v[2:3], s[40:41], 0, v[68:69]
	s_lshl_b32 s6, s44, 6
	v_lshl_add_u64 v[4:5], v[2:3], 0, v[72:73]
	v_lshl_add_u64 v[2:3], v[2:3], 0, s[6:7]
	v_lshl_add_u64 v[6:7], v[2:3], 0, v[72:73]
	v_lshl_add_u64 v[2:3], v[2:3], 0, s[6:7]
	v_lshl_add_u64 v[10:11], v[2:3], 0, v[72:73]
	v_lshl_add_u64 v[2:3], v[2:3], 0, s[6:7]
	v_lshl_add_u64 v[14:15], v[2:3], 0, v[72:73]
	v_lshl_add_u64 v[2:3], s[42:43], 0, v[68:69]
	v_lshl_add_u64 v[18:19], v[2:3], 0, v[72:73]
	v_lshl_add_u64 v[26:27], v[18:19], 0, s[6:7]
	global_load_dwordx4 v[2:5], v[4:5], off
	s_nop 0
	global_load_dwordx4 v[6:9], v[6:7], off
	s_nop 0
	global_load_dwordx4 v[10:13], v[10:11], off
	s_nop 0
	global_load_dwordx4 v[14:17], v[14:15], off
	s_nop 0
	global_load_dwordx4 v[18:21], v[18:19], off
	s_nop 0
	global_load_dwordx4 v[22:25], v[26:27], off
	v_lshl_add_u64 v[26:27], v[26:27], 0, s[6:7]
	v_lshl_add_u64 v[30:31], v[26:27], 0, s[6:7]
	global_load_dwordx4 v[26:29], v[26:27], off
	s_nop 0
	global_load_dwordx4 v[30:33], v[30:31], off
	s_mul_i32 s6, s17, s44
	s_mul_hi_u32 s40, s16, s44
	s_lshr_b32 s58, s44, 6
	s_mul_i32 s41, s16, s44
	s_add_i32 s59, s40, s6
	s_add_i32 s6, s58, -2
	s_mul_i32 s42, s26, s44
	s_mul_hi_u32 s43, s25, s44
	s_add_u32 s40, s45, s41
	s_mul_i32 s46, s25, s44
	s_addc_u32 s41, 0, s59
	s_add_i32 s43, s43, s42
	s_mul_i32 s47, s28, s44
	s_mul_hi_u32 s48, s27, s44
	v_lshl_add_u64 v[148:149], v[70:71], 0, s[40:41]
	s_add_u32 s40, s45, s46
	s_mul_i32 s49, s27, s44
	s_addc_u32 s41, 0, s43
	s_add_i32 s48, s48, s47
	s_mul_i32 s50, s30, s44
	s_mul_hi_u32 s51, s29, s44
	v_lshl_add_u64 v[150:151], v[70:71], 0, s[40:41]
	s_add_u32 s40, s45, s49
	s_mul_i32 s52, s29, s44
	s_addc_u32 s41, 0, s48
	s_add_i32 s51, s51, s50
	s_mul_i32 s53, s19, s44
	s_mul_hi_u32 s54, s18, s44
	v_lshl_add_u64 v[152:153], v[70:71], 0, s[40:41]
	s_add_u32 s40, s45, s52
	s_mul_i32 s55, s18, s44
	s_addc_u32 s41, 0, s51
	s_add_i32 s54, s54, s53
	v_lshl_add_u64 v[154:155], v[70:71], 0, s[40:41]
	s_add_u32 s40, s39, s55
	s_mul_i32 s56, s33, s44
	s_mul_hi_u32 s57, s31, s44
	s_addc_u32 s41, 0, s54
	v_lshl_add_u64 v[156:157], v[70:71], 0, s[40:41]
	s_add_i32 s57, s57, s56
	s_mul_i32 s40, s31, s44
	s_add_u32 s40, s39, s40
	s_addc_u32 s41, 0, s57
	v_lshl_add_u64 v[158:159], v[70:71], 0, s[40:41]
	s_mul_i32 s40, s35, s44
	s_mul_hi_u32 s41, s34, s44
	s_add_i32 s41, s41, s40
	s_mul_i32 s40, s34, s44
	s_add_u32 s40, s39, s40
	s_addc_u32 s41, 0, s41
	v_lshl_add_u64 v[160:161], v[70:71], 0, s[40:41]
	s_mul_i32 s40, s37, s44
	s_mul_hi_u32 s41, s36, s44
	s_add_i32 s41, s41, s40
	s_mul_i32 s40, s36, s44
	s_add_u32 s40, s39, s40
	s_addc_u32 s41, 0, s41
	s_waitcnt vmcnt(7)
	ds_write_b128 v135, v[2:5]
	s_waitcnt vmcnt(6)
	ds_write_b128 v135, v[6:9] offset:4608
	s_waitcnt vmcnt(3)
	ds_write_b128 v135, v[18:21] offset:18432
	ds_write_b128 v135, v[10:13] offset:9216
	s_waitcnt vmcnt(2)
	ds_write_b128 v135, v[22:25] offset:23040
	ds_write_b128 v135, v[14:17] offset:13824
	s_waitcnt vmcnt(1)
	ds_write_b128 v135, v[26:29] offset:27648
	s_waitcnt vmcnt(0)
	ds_write_b128 v135, v[30:33] offset:32256
	v_lshl_add_u64 v[162:163], v[70:71], 0, s[40:41]
	s_mov_b32 s39, 0
	v_mov_b32_e32 v2, 0
	v_mov_b32_e32 v3, v75
	v_mov_b32_e32 v4, v75
	v_mov_b32_e32 v5, v75
	v_mov_b32_e32 v6, v75
	v_mov_b32_e32 v7, v75
	v_mov_b32_e32 v8, v75
	v_mov_b32_e32 v9, v75
	v_mov_b32_e32 v10, v75
	v_mov_b32_e32 v11, v75
	v_mov_b32_e32 v12, v75
	v_mov_b32_e32 v13, v75
	v_mov_b32_e32 v14, v75
	v_mov_b32_e32 v15, v75
	v_mov_b32_e32 v16, v75
	v_mov_b32_e32 v17, v75
	v_mov_b32_e32 v34, 0
	v_mov_b32_e32 v35, v75
	v_mov_b32_e32 v36, v75
	v_mov_b32_e32 v37, v75
	v_mov_b32_e32 v38, v75
	v_mov_b32_e32 v39, v75
	v_mov_b32_e32 v40, v75
	v_mov_b32_e32 v41, v75
	v_mov_b32_e32 v42, v75
	v_mov_b32_e32 v43, v75
	v_mov_b32_e32 v44, v75
	v_mov_b32_e32 v45, v75
	v_mov_b32_e32 v46, v75
	v_mov_b32_e32 v47, v75
	v_mov_b32_e32 v48, v75
	v_mov_b32_e32 v49, v75
	v_mov_b32_e32 v18, 0
	v_mov_b32_e32 v19, v75
	v_mov_b32_e32 v20, v75
	v_mov_b32_e32 v21, v75
	v_mov_b32_e32 v22, v75
	v_mov_b32_e32 v23, v75
	v_mov_b32_e32 v24, v75
	v_mov_b32_e32 v25, v75
	v_mov_b32_e32 v26, v75
	v_mov_b32_e32 v27, v75
	v_mov_b32_e32 v28, v75
	v_mov_b32_e32 v29, v75
	v_mov_b32_e32 v30, v75
	v_mov_b32_e32 v31, v75
	v_mov_b32_e32 v32, v75
	v_mov_b32_e32 v33, v75
	v_mov_b32_e32 v50, 0
	v_mov_b32_e32 v51, v75
	v_mov_b32_e32 v52, v75
	v_mov_b32_e32 v53, v75
	v_mov_b32_e32 v54, v75
	v_mov_b32_e32 v55, v75
	v_mov_b32_e32 v56, v75
	v_mov_b32_e32 v57, v75
	v_mov_b32_e32 v58, v75
	v_mov_b32_e32 v59, v75
	v_mov_b32_e32 v60, v75
	v_mov_b32_e32 v61, v75
	v_mov_b32_e32 v62, v75
	v_mov_b32_e32 v63, v75
	v_mov_b32_e32 v64, v75
	v_mov_b32_e32 v65, v75
	s_waitcnt lgkmcnt(0)
	v_lshl_add_u64 v[168:169], v[148:149], 0, v[68:69]
	v_lshl_add_u64 v[172:173], v[150:151], 0, v[68:69]
	v_lshl_add_u64 v[176:177], v[152:153], 0, v[68:69]
	v_lshl_add_u64 v[180:181], v[154:155], 0, v[68:69]
	v_lshl_add_u64 v[184:185], v[156:157], 0, v[68:69]
	v_lshl_add_u64 v[188:189], v[158:159], 0, v[68:69]
	v_lshl_add_u64 v[192:193], v[160:161], 0, v[68:69]
	v_lshl_add_u64 v[196:197], v[162:163], 0, v[68:69]
	global_load_dwordx4 v[168:171], v[168:169], off offset:128
	s_nop 0
	global_load_dwordx4 v[172:175], v[172:173], off offset:128
	s_nop 0
	global_load_dwordx4 v[176:179], v[176:177], off offset:128
	s_nop 0
	global_load_dwordx4 v[180:183], v[180:181], off offset:128
	s_nop 0
	global_load_dwordx4 v[184:187], v[184:185], off offset:128
	s_nop 0
	global_load_dwordx4 v[188:191], v[188:189], off offset:128
	s_nop 0
	global_load_dwordx4 v[192:195], v[192:193], off offset:128
	s_nop 0
	global_load_dwordx4 v[196:199], v[196:197], off offset:128
;     ...
;   for (int kt = 0; kt < nk; ++kt) {
;     const int kn = (kt + 1 < nk) ? kt + 1 : kt;
;     GM_LOAD2(kn * 64, kn * bkstep)
;     __builtin_amdgcn_sched_barrier(0);
;     const char* As = smem + (kt & 1) * 2 * TILE_B;
;     const char* Bs = As + TILE_B;
;     if constexpr (HOIST) {
;       bf16x8 fa0[4], fa1[4], fb0[4], fb1[4];
; #pragma unroll
;       for (int st = 0; st < 4; ++st) {
;         fa0[st] = *(const bf16x8*)(As + aoff + st * 32);
;         fb0[st] = *(const bf16x8*)(Bs + boff + st * 32);
;         fa1[st] = *(const bf16x8*)(As + aoff + 32 * LSTR + st * 32);
;         fb1[st] = *(const bf16x8*)(Bs + boff + 32 * LSTR + st * 32);
;       }
;       __builtin_amdgcn_sched_barrier(0);
; #pragma unroll
;       for (int st = 0; st < 4; ++st) {
;         acc[0][0] = mfma32(fa0[st], fb0[st], acc[0][0]);
;         acc[0][1] = mfma32(fa0[st], fb1[st], acc[0][1]);
;         acc[1][0] = mfma32(fa1[st], fb0[st], acc[1][0]);
;         acc[1][1] = mfma32(fa1[st], fb1[st], acc[1][1]);
;       }
;     } else {
; #pragma unroll
;       for (int st = 0; st < 4; ++st) {
;         bf16x8 a0 = *(const bf16x8*)(As + aoff + st * 32);
;         bf16x8 a1 = *(const bf16x8*)(As + aoff + 32 * LSTR + st * 32);
;         bf16x8 b0 = *(const bf16x8*)(Bs + boff + st * 32);
;         bf16x8 b1 = *(const bf16x8*)(Bs + boff + 32 * LSTR + st * 32);
;         acc[0][0] = mfma32(a0, b0, acc[0][0]);
;         acc[0][1] = mfma32(a0, b1, acc[0][1]);
;         acc[1][0] = mfma32(a1, b0, acc[1][0]);
;         acc[1][1] = mfma32(a1, b1, acc[1][1]);
;       }
;     }
;     __builtin_amdgcn_sched_barrier(0);
;     {
;       char* Ad = smem + ((kt + 1) & 1) * 2 * TILE_B;
;       GM_STORE(Ad)
;     }
;     __syncthreads();
;   }
.LBB0_1640:
	s_barrier
	s_and_b32 s40, s39, 2
	s_mulk_i32 s40, 0x4800
	v_add3_u32 v220, s40, v137, v164
	v_add3_u32 v221, s40, v165, v164
	ds_read_b128 v[200:203], v220 offset:0
	ds_read_b128 v[204:207], v221 offset:18432
	ds_read_b128 v[212:215], v220 offset:4608
	ds_read_b128 v[208:211], v221 offset:23040
	s_waitcnt lgkmcnt(2)
	v_mfma_f32_32x32x16_bf16 v[34:49], v[200:203], v[204:207], v[34:49]
	ds_read_b128 v[216:219], v220 offset:32
	s_waitcnt lgkmcnt(2)
	v_mfma_f32_32x32x16_bf16 v[18:33], v[212:215], v[204:207], v[18:33]
	ds_read_b128 v[204:207], v221 offset:18464
	s_waitcnt lgkmcnt(2)
	v_mfma_f32_32x32x16_bf16 v[2:17], v[200:203], v[208:211], v[2:17]
	ds_read_b128 v[200:203], v220 offset:4640
	v_mfma_f32_32x32x16_bf16 v[50:65], v[212:215], v[208:211], v[50:65]
	ds_read_b128 v[208:211], v221 offset:23072
	s_waitcnt lgkmcnt(2)
	v_mfma_f32_32x32x16_bf16 v[34:49], v[216:219], v[204:207], v[34:49]
	ds_read_b128 v[212:215], v220 offset:64
	s_waitcnt lgkmcnt(2)
	v_mfma_f32_32x32x16_bf16 v[18:33], v[200:203], v[204:207], v[18:33]
	ds_read_b128 v[204:207], v221 offset:18496
	s_waitcnt lgkmcnt(2)
	v_mfma_f32_32x32x16_bf16 v[2:17], v[216:219], v[208:211], v[2:17]
	ds_read_b128 v[216:219], v220 offset:4672
	v_mfma_f32_32x32x16_bf16 v[50:65], v[200:203], v[208:211], v[50:65]
	ds_read_b128 v[208:211], v221 offset:23104
	s_waitcnt lgkmcnt(2)
	v_mfma_f32_32x32x16_bf16 v[34:49], v[212:215], v[204:207], v[34:49]
	ds_read_b128 v[200:203], v220 offset:96
	s_waitcnt lgkmcnt(2)
	v_mfma_f32_32x32x16_bf16 v[18:33], v[216:219], v[204:207], v[18:33]
	ds_read_b128 v[204:207], v221 offset:18528
	s_waitcnt lgkmcnt(2)
	v_mfma_f32_32x32x16_bf16 v[2:17], v[212:215], v[208:211], v[2:17]
	ds_read_b128 v[212:215], v220 offset:4704
	v_mfma_f32_32x32x16_bf16 v[50:65], v[216:219], v[208:211], v[50:65]
	ds_read_b128 v[208:211], v221 offset:23136
	s_waitcnt lgkmcnt(2)
	v_mfma_f32_32x32x16_bf16 v[34:49], v[200:203], v[204:207], v[34:49]
	s_waitcnt lgkmcnt(1)
	v_mfma_f32_32x32x16_bf16 v[18:33], v[212:215], v[204:207], v[18:33]
	s_waitcnt lgkmcnt(0)
	v_mfma_f32_32x32x16_bf16 v[2:17], v[200:203], v[208:211], v[2:17]
	v_mfma_f32_32x32x16_bf16 v[50:65], v[212:215], v[208:211], v[50:65]
	s_add_i32 s39, s39, 2
	s_and_b32 s40, s39, 2
	s_mulk_i32 s40, 0x4800
	s_add_i32 s6, s6, -1
	v_add_u32_e32 v200, s40, v135
	v_lshl_add_u64 v[148:149], v[148:149], 0, s[8:9]
	v_lshl_add_u64 v[150:151], v[150:151], 0, s[8:9]
	v_lshl_add_u64 v[152:153], v[152:153], 0, s[8:9]
	v_lshl_add_u64 v[154:155], v[154:155], 0, s[8:9]
	v_lshl_add_u64 v[156:157], v[156:157], 0, s[8:9]
	v_lshl_add_u64 v[158:159], v[158:159], 0, s[8:9]
	v_lshl_add_u64 v[160:161], v[160:161], 0, s[8:9]
	v_lshl_add_u64 v[162:163], v[162:163], 0, s[8:9]
	s_cmp_lg_u32 s6, 0
	s_waitcnt vmcnt(7)
	ds_write_b128 v200, v[168:171]
	v_lshl_add_u64 v[168:169], v[148:149], 0, v[68:69]
	global_load_dwordx4 v[168:171], v[168:169], off offset:128
	s_waitcnt vmcnt(7)
	ds_write_b128 v200, v[172:175] offset:4608
	v_lshl_add_u64 v[172:173], v[150:151], 0, v[68:69]
	global_load_dwordx4 v[172:175], v[172:173], off offset:128
	s_waitcnt vmcnt(7)
	ds_write_b128 v200, v[176:179] offset:9216
	v_lshl_add_u64 v[176:177], v[152:153], 0, v[68:69]
	global_load_dwordx4 v[176:179], v[176:177], off offset:128
	s_waitcnt vmcnt(7)
	ds_write_b128 v200, v[180:183] offset:13824
	v_lshl_add_u64 v[180:181], v[154:155], 0, v[68:69]
	global_load_dwordx4 v[180:183], v[180:181], off offset:128
	s_waitcnt vmcnt(7)
	ds_write_b128 v200, v[184:187] offset:18432
	v_lshl_add_u64 v[184:185], v[156:157], 0, v[68:69]
	global_load_dwordx4 v[184:187], v[184:185], off offset:128
	s_waitcnt vmcnt(7)
	ds_write_b128 v200, v[188:191] offset:23040
	v_lshl_add_u64 v[188:189], v[158:159], 0, v[68:69]
	global_load_dwordx4 v[188:191], v[188:189], off offset:128
	s_waitcnt vmcnt(7)
	ds_write_b128 v200, v[192:195] offset:27648
	v_lshl_add_u64 v[192:193], v[160:161], 0, v[68:69]
	global_load_dwordx4 v[192:195], v[192:193], off offset:128
	s_waitcnt vmcnt(7)
	ds_write_b128 v200, v[196:199] offset:32256
	v_lshl_add_u64 v[196:197], v[162:163], 0, v[68:69]
	global_load_dwordx4 v[196:199], v[196:197], off offset:128
	s_waitcnt lgkmcnt(0)
	s_cbranch_scc1 .LBB0_1640
	s_barrier
	s_and_b32 s40, s39, 2
	s_mulk_i32 s40, 0x4800
	v_add3_u32 v220, s40, v137, v164
	v_add3_u32 v221, s40, v165, v164
	ds_read_b128 v[200:203], v220 offset:0
	ds_read_b128 v[204:207], v221 offset:18432
	ds_read_b128 v[212:215], v220 offset:4608
	ds_read_b128 v[208:211], v221 offset:23040
	s_waitcnt lgkmcnt(2)
	v_mfma_f32_32x32x16_bf16 v[34:49], v[200:203], v[204:207], v[34:49]
	ds_read_b128 v[216:219], v220 offset:32
	s_waitcnt lgkmcnt(2)
	v_mfma_f32_32x32x16_bf16 v[18:33], v[212:215], v[204:207], v[18:33]
	ds_read_b128 v[204:207], v221 offset:18464
	s_waitcnt lgkmcnt(2)
	v_mfma_f32_32x32x16_bf16 v[2:17], v[200:203], v[208:211], v[2:17]
	ds_read_b128 v[200:203], v220 offset:4640
	v_mfma_f32_32x32x16_bf16 v[50:65], v[212:215], v[208:211], v[50:65]
	ds_read_b128 v[208:211], v221 offset:23072
	s_waitcnt lgkmcnt(2)
	v_mfma_f32_32x32x16_bf16 v[34:49], v[216:219], v[204:207], v[34:49]
	ds_read_b128 v[212:215], v220 offset:64
	s_waitcnt lgkmcnt(2)
	v_mfma_f32_32x32x16_bf16 v[18:33], v[200:203], v[204:207], v[18:33]
	ds_read_b128 v[204:207], v221 offset:18496
	s_waitcnt lgkmcnt(2)
	v_mfma_f32_32x32x16_bf16 v[2:17], v[216:219], v[208:211], v[2:17]
	ds_read_b128 v[216:219], v220 offset:4672
	v_mfma_f32_32x32x16_bf16 v[50:65], v[200:203], v[208:211], v[50:65]
	ds_read_b128 v[208:211], v221 offset:23104
	s_waitcnt lgkmcnt(2)
	v_mfma_f32_32x32x16_bf16 v[34:49], v[212:215], v[204:207], v[34:49]
	ds_read_b128 v[200:203], v220 offset:96
	s_waitcnt lgkmcnt(2)
;     ...
;   for (int kt = 0; kt < nk; ++kt) {
;     const int kn = (kt + 1 < nk) ? kt + 1 : kt;
;     GM_LOAD2(kn * 64, kn * bkstep)
;     __builtin_amdgcn_sched_barrier(0);
;     const char* As = smem + (kt & 1) * 2 * TILE_B;
;     const char* Bs = As + TILE_B;
;     if constexpr (HOIST) {
;       bf16x8 fa0[4], fa1[4], fb0[4], fb1[4];
; #pragma unroll
;       for (int st = 0; st < 4; ++st) {
;         fa0[st] = *(const bf16x8*)(As + aoff + st * 32);
;         fb0[st] = *(const bf16x8*)(Bs + boff + st * 32);
;         fa1[st] = *(const bf16x8*)(As + aoff + 32 * LSTR + st * 32);
;         fb1[st] = *(const bf16x8*)(Bs + boff + 32 * LSTR + st * 32);
;       }
;       __builtin_amdgcn_sched_barrier(0);
; #pragma unroll
;       for (int st = 0; st < 4; ++st) {
;         acc[0][0] = mfma32(fa0[st], fb0[st], acc[0][0]);
;         acc[0][1] = mfma32(fa0[st], fb1[st], acc[0][1]);
;         acc[1][0] = mfma32(fa1[st], fb0[st], acc[1][0]);
;         acc[1][1] = mfma32(fa1[st], fb1[st], acc[1][1]);
;       }
;     } else {
; #pragma unroll
;       for (int st = 0; st < 4; ++st) {
;         bf16x8 a0 = *(const bf16x8*)(As + aoff + st * 32);
;         bf16x8 a1 = *(const bf16x8*)(As + aoff + 32 * LSTR + st * 32);
;         bf16x8 b0 = *(const bf16x8*)(Bs + boff + st * 32);
;         bf16x8 b1 = *(const bf16x8*)(Bs + boff + 32 * LSTR + st * 32);
;         acc[0][0] = mfma32(a0, b0, acc[0][0]);
;         acc[0][1] = mfma32(a0, b1, acc[0][1]);
;         acc[1][0] = mfma32(a1, b0, acc[1][0]);
;         acc[1][1] = mfma32(a1, b1, acc[1][1]);
;       }
;     }
;     __builtin_amdgcn_sched_barrier(0);
;     {
;       char* Ad = smem + ((kt + 1) & 1) * 2 * TILE_B;
;       GM_STORE(Ad)
;     }
;     __syncthreads();
;   }
; __device__ __forceinline__ void acc_to_lds(const f32x16 (&acc)[2][2], float* cs) {
;   const int tid = threadIdx.x, lane = tid & 63, wave = tid >> 6;
;   const int wm = wave >> 1, wn = wave & 1;
; #pragma unroll
;   for (int i = 0; i < 2; ++i)
; #pragma unroll
;     for (int j = 0; j < 2; ++j)
; #pragma unroll
;       for (int r = 0; r < 16; ++r) {
;         int row = wm * 64 + i * 32 + (r & 3) + 8 * (r >> 2) + 4 * (lane >> 5);
;         int col = wn * 64 + j * 32 + (lane & 31);
;         cs[row * CSTR + col] = acc[i][j][r];
;       }
;   __syncthreads();
	v_mfma_f32_32x32x16_bf16 v[18:33], v[216:219], v[204:207], v[18:33]
	ds_read_b128 v[204:207], v221 offset:18528
	s_waitcnt lgkmcnt(2)
	v_mfma_f32_32x32x16_bf16 v[2:17], v[212:215], v[208:211], v[2:17]
	ds_read_b128 v[212:215], v220 offset:4704
	v_mfma_f32_32x32x16_bf16 v[50:65], v[216:219], v[208:211], v[50:65]
	ds_read_b128 v[208:211], v221 offset:23136
	s_waitcnt lgkmcnt(2)
	v_mfma_f32_32x32x16_bf16 v[34:49], v[200:203], v[204:207], v[34:49]
	s_waitcnt lgkmcnt(1)
	v_mfma_f32_32x32x16_bf16 v[18:33], v[212:215], v[204:207], v[18:33]
	s_waitcnt lgkmcnt(0)
	v_mfma_f32_32x32x16_bf16 v[2:17], v[200:203], v[208:211], v[2:17]
	v_mfma_f32_32x32x16_bf16 v[50:65], v[212:215], v[208:211], v[50:65]
	s_add_i32 s39, s39, 2
	s_and_b32 s40, s39, 2
	s_mulk_i32 s40, 0x4800
	v_add_u32_e32 v200, s40, v135
	v_lshl_add_u64 v[148:149], v[148:149], 0, s[8:9]
	v_lshl_add_u64 v[150:151], v[150:151], 0, s[8:9]
	v_lshl_add_u64 v[152:153], v[152:153], 0, s[8:9]
	v_lshl_add_u64 v[154:155], v[154:155], 0, s[8:9]
	v_lshl_add_u64 v[156:157], v[156:157], 0, s[8:9]
	v_lshl_add_u64 v[158:159], v[158:159], 0, s[8:9]
	v_lshl_add_u64 v[160:161], v[160:161], 0, s[8:9]
	v_lshl_add_u64 v[162:163], v[162:163], 0, s[8:9]
	s_waitcnt vmcnt(7)
	ds_write_b128 v200, v[168:171]
	s_waitcnt vmcnt(6)
	ds_write_b128 v200, v[172:175] offset:4608
	s_waitcnt vmcnt(5)
	ds_write_b128 v200, v[176:179] offset:9216
	s_waitcnt vmcnt(4)
	ds_write_b128 v200, v[180:183] offset:13824
	s_waitcnt vmcnt(3)
	ds_write_b128 v200, v[184:187] offset:18432
	s_waitcnt vmcnt(2)
	ds_write_b128 v200, v[188:191] offset:23040
	s_waitcnt vmcnt(1)
	ds_write_b128 v200, v[192:195] offset:27648
	s_waitcnt vmcnt(0)
	ds_write_b128 v200, v[196:199] offset:32256
	s_waitcnt lgkmcnt(0)
	s_barrier
	v_lshl_add_u64 v[180:181], v[162:163], 0, v[68:69]
	v_lshl_add_u64 v[176:177], v[160:161], 0, v[68:69]
	v_lshl_add_u64 v[172:173], v[158:159], 0, v[68:69]
	v_lshl_add_u64 v[168:169], v[156:157], 0, v[68:69]
	v_lshl_add_u64 v[160:161], v[154:155], 0, v[68:69]
	v_lshl_add_u64 v[156:157], v[152:153], 0, v[68:69]
	v_lshl_add_u64 v[152:153], v[150:151], 0, v[68:69]
	v_lshl_add_u64 v[148:149], v[148:149], 0, v[68:69]
	s_nop 0
	s_nop 0
	s_nop 0
	s_nop 0
	s_nop 0
	s_nop 0
	s_nop 0
	v_add3_u32 v68, s40, v137, v164
	v_add3_u32 v212, s40, v165, v164
	ds_read_b128 v[184:187], v68 offset:0
	ds_read_b128 v[188:191], v212 offset:18432
	ds_read_b128 v[196:199], v68 offset:4608
	ds_read_b128 v[192:195], v212 offset:23040
	s_waitcnt lgkmcnt(2)
	v_mfma_f32_32x32x16_bf16 v[34:49], v[184:187], v[188:191], v[34:49]
	ds_read_b128 v[200:203], v68 offset:32
	s_waitcnt lgkmcnt(2)
	v_mfma_f32_32x32x16_bf16 v[18:33], v[196:199], v[188:191], v[18:33]
	ds_read_b128 v[188:191], v212 offset:18464
	s_waitcnt lgkmcnt(2)
	v_mfma_f32_32x32x16_bf16 v[2:17], v[184:187], v[192:195], v[2:17]
	ds_read_b128 v[184:187], v68 offset:4640
	v_mfma_f32_32x32x16_bf16 v[50:65], v[196:199], v[192:195], v[50:65]
	ds_read_b128 v[192:195], v212 offset:23072
	s_waitcnt lgkmcnt(2)
	v_mfma_f32_32x32x16_bf16 v[34:49], v[200:203], v[188:191], v[34:49]
	ds_read_b128 v[196:199], v68 offset:64
	s_waitcnt lgkmcnt(2)
	v_mfma_f32_32x32x16_bf16 v[18:33], v[184:187], v[188:191], v[18:33]
	ds_read_b128 v[188:191], v212 offset:18496
	s_waitcnt lgkmcnt(2)
	v_mfma_f32_32x32x16_bf16 v[2:17], v[200:203], v[192:195], v[2:17]
	ds_read_b128 v[200:203], v68 offset:4672
	v_mfma_f32_32x32x16_bf16 v[50:65], v[184:187], v[192:195], v[50:65]
	ds_read_b128 v[192:195], v212 offset:23104
	s_waitcnt lgkmcnt(2)
	v_mfma_f32_32x32x16_bf16 v[34:49], v[196:199], v[188:191], v[34:49]
	ds_read_b128 v[184:187], v68 offset:96
	s_waitcnt lgkmcnt(2)
	v_mfma_f32_32x32x16_bf16 v[18:33], v[200:203], v[188:191], v[18:33]
	ds_read_b128 v[188:191], v212 offset:18528
	s_waitcnt lgkmcnt(2)
	v_mfma_f32_32x32x16_bf16 v[2:17], v[196:199], v[192:195], v[2:17]
	ds_read_b128 v[196:199], v68 offset:4704
	v_mfma_f32_32x32x16_bf16 v[50:65], v[200:203], v[192:195], v[50:65]
	ds_read_b128 v[192:195], v212 offset:23136
	s_waitcnt lgkmcnt(2)
	v_mfma_f32_32x32x16_bf16 v[34:49], v[184:187], v[188:191], v[34:49]
	s_waitcnt lgkmcnt(1)
	v_mfma_f32_32x32x16_bf16 v[18:33], v[196:199], v[188:191], v[18:33]
	s_waitcnt lgkmcnt(0)
	v_mfma_f32_32x32x16_bf16 v[2:17], v[184:187], v[192:195], v[2:17]
	v_mfma_f32_32x32x16_bf16 v[50:65], v[196:199], v[192:195], v[50:65]
	s_waitcnt lgkmcnt(0)
	s_barrier
	ds_write2_b32 v166, v34, v2 offset1:32
	ds_write2_b32 v166, v35, v3 offset0:132 offset1:164
	v_add_u32_e32 v2, 0x400, v166
	ds_write2_b32 v2, v36, v4 offset0:8 offset1:40
	ds_write2_b32 v2, v37, v5 offset0:140 offset1:172
	v_add_u32_e32 v2, 0x1000, v166
	ds_write2_b32 v2, v38, v6 offset0:32 offset1:64
	ds_write2_b32 v2, v39, v7 offset0:164 offset1:196
	v_add_u32_e32 v2, 0x1400, v166
	ds_write2_b32 v2, v40, v8 offset0:40 offset1:72
	ds_write2_b32 v2, v41, v9 offset0:172 offset1:204
	v_add_u32_e32 v2, 0x2000, v166
	ds_write2_b32 v2, v42, v10 offset0:64 offset1:96
	ds_write2_b32 v2, v43, v11 offset0:196 offset1:228
	v_add_u32_e32 v2, 0x2400, v166
	ds_write2_b32 v2, v44, v12 offset0:72 offset1:104
	ds_write2_b32 v2, v45, v13 offset0:204 offset1:236
	v_add_u32_e32 v2, 0x3000, v166
	ds_write2_b32 v2, v46, v14 offset0:96 offset1:128
	v_add_u32_e32 v2, 0x3200, v166
	ds_write2_b32 v2, v47, v15 offset0:100 offset1:132
	v_add_u32_e32 v2, 0x3400, v166
	ds_write2_b32 v2, v48, v16 offset0:104 offset1:136
	v_add_u32_e32 v2, 0x3600, v166
	ds_write2_b32 v2, v49, v17 offset0:108 offset1:140
	v_add_u32_e32 v2, 0x4000, v166
	ds_write2_b32 v2, v18, v50 offset0:128 offset1:160
	v_add_u32_e32 v2, 0x4400, v166
	ds_write2_b32 v2, v19, v51 offset0:4 offset1:36
	ds_write2_b32 v2, v20, v52 offset0:136 offset1:168
	v_add_u32_e32 v2, 0x4800, v166
	ds_write2_b32 v2, v21, v53 offset0:12 offset1:44
	v_add_u32_e32 v2, 0x5000, v166
	ds_write2_b32 v2, v22, v54 offset0:160 offset1:192
	v_add_u32_e32 v2, 0x5400, v166
	ds_write2_b32 v2, v23, v55 offset0:36 offset1:68
	ds_write2_b32 v2, v24, v56 offset0:168 offset1:200
	v_add_u32_e32 v2, 0x5800, v166
	ds_write2_b32 v2, v25, v57 offset0:44 offset1:76
	v_add_u32_e32 v2, 0x6000, v166
	ds_write2_b32 v2, v26, v58 offset0:192 offset1:224
	v_add_u32_e32 v2, 0x6400, v166
	ds_write2_b32 v2, v27, v59 offset0:68 offset1:100
	ds_write2_b32 v2, v28, v60 offset0:200 offset1:232
	v_add_u32_e32 v2, 0x6800, v166
	ds_write2_b32 v2, v29, v61 offset0:76 offset1:108
	v_add_u32_e32 v2, 0x7200, v166
	ds_write2_b32 v2, v30, v62 offset0:96 offset1:128
	v_add_u32_e32 v2, 0x7400, v166
	ds_write2_b32 v2, v31, v63 offset0:100 offset1:132
	v_add_u32_e32 v2, 0x7600, v166
	s_lshl_b32 s6, s38, 11
	ds_write2_b32 v2, v32, v64 offset0:104 offset1:136
	v_add_u32_e32 v2, 0x7800, v166
	v_lshl_add_u64 v[46:47], v[118:119], 0, s[6:7]
	ds_write2_b32 v2, v33, v65 offset0:108 offset1:140
	s_waitcnt lgkmcnt(0)
	s_barrier
; __device__ __forceinline__ void merge_tile(const Params& P, int l, int mt, int nt, char* smem) {
;     ...
;     const u16* gp = WSP(u16, OFF_G) + grow * 3072 + br * 1024 + nt * 128 + half * 64;
; #pragma unroll
;     for (int q = 0; q < 8; ++q) {
;       uint4 gq = *(const uint4*)(gp + q * 8);
;       float4 a = *(const float4*)(cs + r * CSTR + half * 64 + q * 8);
;       float4 c = *(const float4*)(cs + r * CSTR + half * 64 + q * 8 + 4);
;       macc[q * 8 + 0] += __uint_as_float(gq.x << 16) * a.x;
;       macc[q * 8 + 1] += __uint_as_float(gq.x & 0xffff0000u) * a.y;
;       macc[q * 8 + 2] += __uint_as_float(gq.y << 16) * a.z;
;       macc[q * 8 + 3] += __uint_as_float(gq.y & 0xffff0000u) * a.w;
;       macc[q * 8 + 4] += __uint_as_float(gq.z << 16) * c.x;
;       macc[q * 8 + 5] += __uint_as_float(gq.z & 0xffff0000u) * c.y;
;       macc[q * 8 + 6] += __uint_as_float(gq.w << 16) * c.z;
;       macc[q * 8 + 7] += __uint_as_float(gq.w & 0xffff0000u) * c.w;
;     }
;     __syncthreads();
;   }
	global_load_dwordx4 v[2:5], v[46:47], off
	global_load_dwordx4 v[6:9], v[46:47], off offset:16
	global_load_dwordx4 v[10:13], v[46:47], off offset:32
	global_load_dwordx4 v[14:17], v[46:47], off offset:48
	global_load_dwordx4 v[18:21], v[46:47], off offset:64
	global_load_dwordx4 v[22:25], v[46:47], off offset:80
	ds_read_b128 v[26:29], v167
	ds_read_b128 v[30:33], v167 offset:16
	ds_read_b128 v[34:37], v167 offset:32
	ds_read_b128 v[38:41], v167 offset:48
	global_load_dwordx4 v[42:45], v[46:47], off offset:112
	s_nop 0
	global_load_dwordx4 v[46:49], v[46:47], off offset:96
	s_add_i32 s38, s38, 1
	s_cmp_lg_u32 s38, 3
	s_waitcnt vmcnt(7)
	v_lshlrev_b32_e32 v50, 16, v2
	v_and_b32_e32 v51, 0xffff0000, v2
	v_lshlrev_b32_e32 v2, 16, v3
	v_and_b32_e32 v3, 0xffff0000, v3
	s_waitcnt lgkmcnt(3)
	v_pk_fma_f32 v[144:145], v[28:29], v[2:3], v[144:145]
	v_lshlrev_b32_e32 v2, 16, v4
	v_and_b32_e32 v3, 0xffff0000, v4
	s_waitcnt lgkmcnt(2)
	v_pk_fma_f32 v[142:143], v[30:31], v[2:3], v[142:143]
	v_lshlrev_b32_e32 v2, 16, v5
	v_and_b32_e32 v3, 0xffff0000, v5
	v_pk_fma_f32 v[140:141], v[32:33], v[2:3], v[140:141]
	s_waitcnt vmcnt(6)
	v_lshlrev_b32_e32 v2, 16, v6
	v_and_b32_e32 v3, 0xffff0000, v6
	s_waitcnt lgkmcnt(1)
	v_pk_fma_f32 v[138:139], v[34:35], v[2:3], v[138:139]
	v_lshlrev_b32_e32 v2, 16, v7
	v_and_b32_e32 v3, 0xffff0000, v7
	v_pk_fma_f32 v[132:133], v[36:37], v[2:3], v[132:133]
	v_lshlrev_b32_e32 v2, 16, v8
	v_and_b32_e32 v3, 0xffff0000, v8
	s_waitcnt lgkmcnt(0)
	v_pk_fma_f32 v[130:131], v[38:39], v[2:3], v[130:131]
	ds_read_b128 v[2:5], v167 offset:64
	v_lshlrev_b32_e32 v6, 16, v9
	v_and_b32_e32 v7, 0xffff0000, v9
	v_pk_fma_f32 v[128:129], v[40:41], v[6:7], v[128:129]
	ds_read_b128 v[6:9], v167 offset:80
	v_pk_fma_f32 v[146:147], v[26:27], v[50:51], v[146:147]
	s_waitcnt vmcnt(5)
	v_lshlrev_b32_e32 v26, 16, v10
	v_and_b32_e32 v27, 0xffff0000, v10
	s_waitcnt lgkmcnt(1)
	v_pk_fma_f32 v[126:127], v[2:3], v[26:27], v[126:127]
	v_lshlrev_b32_e32 v2, 16, v11
	v_and_b32_e32 v3, 0xffff0000, v11
	v_pk_fma_f32 v[124:125], v[4:5], v[2:3], v[124:125]
	v_lshlrev_b32_e32 v2, 16, v12
	v_and_b32_e32 v3, 0xffff0000, v12
	s_waitcnt lgkmcnt(0)
	v_pk_fma_f32 v[122:123], v[6:7], v[2:3], v[122:123]
	ds_read_b128 v[2:5], v167 offset:96
	v_lshlrev_b32_e32 v6, 16, v13
	v_and_b32_e32 v7, 0xffff0000, v13
	v_pk_fma_f32 v[120:121], v[8:9], v[6:7], v[120:121]
	ds_read_b128 v[6:9], v167 offset:112
	s_waitcnt vmcnt(4)
	v_lshlrev_b32_e32 v10, 16, v14
	v_and_b32_e32 v11, 0xffff0000, v14
	s_waitcnt lgkmcnt(1)
	v_pk_fma_f32 v[116:117], v[2:3], v[10:11], v[116:117]
	v_lshlrev_b32_e32 v2, 16, v15
	v_and_b32_e32 v3, 0xffff0000, v15
	v_pk_fma_f32 v[114:115], v[4:5], v[2:3], v[114:115]
	v_lshlrev_b32_e32 v2, 16, v16
	v_and_b32_e32 v3, 0xffff0000, v16
	s_waitcnt lgkmcnt(0)
	v_pk_fma_f32 v[112:113], v[6:7], v[2:3], v[112:113]
	ds_read_b128 v[2:5], v167 offset:128
	v_lshlrev_b32_e32 v6, 16, v17
	v_and_b32_e32 v7, 0xffff0000, v17
	v_pk_fma_f32 v[110:111], v[8:9], v[6:7], v[110:111]
	ds_read_b128 v[6:9], v167 offset:144
	s_waitcnt vmcnt(3)
	v_lshlrev_b32_e32 v10, 16, v18
	v_and_b32_e32 v11, 0xffff0000, v18
	s_waitcnt lgkmcnt(1)
	v_pk_fma_f32 v[106:107], v[2:3], v[10:11], v[106:107]
	v_lshlrev_b32_e32 v2, 16, v19
	v_and_b32_e32 v3, 0xffff0000, v19
	v_pk_fma_f32 v[104:105], v[4:5], v[2:3], v[104:105]
	v_lshlrev_b32_e32 v2, 16, v20
	v_and_b32_e32 v3, 0xffff0000, v20
	s_waitcnt lgkmcnt(0)
	v_pk_fma_f32 v[102:103], v[6:7], v[2:3], v[102:103]
	ds_read_b128 v[2:5], v167 offset:160
	v_lshlrev_b32_e32 v6, 16, v21
	v_and_b32_e32 v7, 0xffff0000, v21
	v_pk_fma_f32 v[100:101], v[8:9], v[6:7], v[100:101]
	ds_read_b128 v[6:9], v167 offset:176
	s_waitcnt vmcnt(2)
	v_lshlrev_b32_e32 v10, 16, v22
	v_and_b32_e32 v11, 0xffff0000, v22
	s_waitcnt lgkmcnt(1)
	v_pk_fma_f32 v[98:99], v[2:3], v[10:11], v[98:99]
	v_lshlrev_b32_e32 v2, 16, v23
	v_and_b32_e32 v3, 0xffff0000, v23
	v_pk_fma_f32 v[96:97], v[4:5], v[2:3], v[96:97]
	v_lshlrev_b32_e32 v2, 16, v24
	v_and_b32_e32 v3, 0xffff0000, v24
	s_waitcnt lgkmcnt(0)
	v_pk_fma_f32 v[94:95], v[6:7], v[2:3], v[94:95]
	ds_read_b128 v[2:5], v167 offset:192
	v_lshlrev_b32_e32 v6, 16, v25
	v_and_b32_e32 v7, 0xffff0000, v25
	v_pk_fma_f32 v[92:93], v[8:9], v[6:7], v[92:93]
	ds_read_b128 v[6:9], v167 offset:208
	s_waitcnt vmcnt(0)
	v_lshlrev_b32_e32 v10, 16, v46
	v_and_b32_e32 v11, 0xffff0000, v46
	s_waitcnt lgkmcnt(1)
	v_pk_fma_f32 v[90:91], v[2:3], v[10:11], v[90:91]
	v_lshlrev_b32_e32 v2, 16, v47
	v_and_b32_e32 v3, 0xffff0000, v47
	v_pk_fma_f32 v[88:89], v[4:5], v[2:3], v[88:89]
	v_lshlrev_b32_e32 v2, 16, v48
	v_and_b32_e32 v3, 0xffff0000, v48
	s_waitcnt lgkmcnt(0)
	v_pk_fma_f32 v[86:87], v[6:7], v[2:3], v[86:87]
	ds_read_b128 v[2:5], v167 offset:224
	v_lshlrev_b32_e32 v6, 16, v49
	v_and_b32_e32 v7, 0xffff0000, v49
	v_pk_fma_f32 v[84:85], v[8:9], v[6:7], v[84:85]
	ds_read_b128 v[6:9], v167 offset:240
	v_lshlrev_b32_e32 v10, 16, v42
	v_and_b32_e32 v11, 0xffff0000, v42
	s_waitcnt lgkmcnt(1)
	v_pk_fma_f32 v[82:83], v[2:3], v[10:11], v[82:83]
	v_lshlrev_b32_e32 v2, 16, v43
	v_and_b32_e32 v3, 0xffff0000, v43
	v_pk_fma_f32 v[80:81], v[4:5], v[2:3], v[80:81]
	v_lshlrev_b32_e32 v2, 16, v44
	v_and_b32_e32 v3, 0xffff0000, v44
	s_waitcnt lgkmcnt(0)
	v_pk_fma_f32 v[78:79], v[6:7], v[2:3], v[78:79]
	v_lshlrev_b32_e32 v2, 16, v45
	v_and_b32_e32 v3, 0xffff0000, v45
	v_pk_fma_f32 v[76:77], v[8:9], v[2:3], v[76:77]
	s_barrier
; __device__ __forceinline__ void store_row64_bf16(const float* v, u16* dst) {
; #pragma unroll
;   for (int q = 0; q < 8; ++q) {
;     uint4 o;
;     o.x = pack2(v[q * 8 + 0], v[q * 8 + 1]);
;     o.y = pack2(v[q * 8 + 2], v[q * 8 + 3]);
;     o.z = pack2(v[q * 8 + 4], v[q * 8 + 5]);
;     o.w = pack2(v[q * 8 + 6], v[q * 8 + 7]);
;     *(uint4*)(dst + q * 8) = o;
;   }
; }
; __device__ __forceinline__ void merge_tile(const Params& P, int l, int mt, int nt, char* smem) {
;     ...
;   }
;   store_row64_bf16(macc, WSP(u16, OFF_M) + grow * DM + nt * 128 + half * 64);
	s_cbranch_scc1 .LBB0_1639
	v_lshlrev_b64 v[2:3], 11, v[108:109]
	v_lshl_add_u64 v[2:3], s[4:5], 0, v[2:3]
	v_lshl_add_u64 v[2:3], s[12:13], 1, v[2:3]
	v_mov_b32_e32 v75, v69
	v_lshl_add_u64 v[6:7], v[2:3], 0, v[74:75]
	v_cvt_pk_bf16_f32 v2, v146, v147
	v_cvt_pk_bf16_f32 v3, v144, v145
	v_cvt_pk_bf16_f32 v4, v142, v143
	v_cvt_pk_bf16_f32 v5, v140, v141
	global_store_dwordx4 v[6:7], v[2:5], off
	v_readlane_b32 s40, v253, 37
	v_readlane_b32 s48, v253, 45
	v_cvt_pk_bf16_f32 v2, v138, v139
	v_cvt_pk_bf16_f32 v3, v132, v133
	v_cvt_pk_bf16_f32 v4, v130, v131
	v_cvt_pk_bf16_f32 v5, v128, v129
	global_store_dwordx4 v[6:7], v[2:5], off offset:16
	v_readlane_b32 s49, v253, 46
	v_readlane_b32 s41, v253, 38
	v_cvt_pk_bf16_f32 v2, v126, v127
	v_cvt_pk_bf16_f32 v3, v124, v125
	v_cvt_pk_bf16_f32 v4, v122, v123
	v_cvt_pk_bf16_f32 v5, v120, v121
	global_store_dwordx4 v[6:7], v[2:5], off offset:32
	v_readlane_b32 s42, v253, 39
	v_readlane_b32 s43, v253, 40
	v_cvt_pk_bf16_f32 v2, v116, v117
	v_cvt_pk_bf16_f32 v3, v114, v115
	v_cvt_pk_bf16_f32 v4, v112, v113
	v_cvt_pk_bf16_f32 v5, v110, v111
	global_store_dwordx4 v[6:7], v[2:5], off offset:48
	v_readlane_b32 s44, v253, 41
	v_readlane_b32 s45, v253, 42
	v_cvt_pk_bf16_f32 v2, v106, v107
	v_cvt_pk_bf16_f32 v3, v104, v105
	v_cvt_pk_bf16_f32 v4, v102, v103
	v_cvt_pk_bf16_f32 v5, v100, v101
	global_store_dwordx4 v[6:7], v[2:5], off offset:64
	v_readlane_b32 s46, v253, 43
	v_readlane_b32 s47, v253, 44
	v_cvt_pk_bf16_f32 v2, v98, v99
	v_cvt_pk_bf16_f32 v3, v96, v97
	v_cvt_pk_bf16_f32 v4, v94, v95
	v_cvt_pk_bf16_f32 v5, v92, v93
	global_store_dwordx4 v[6:7], v[2:5], off offset:80
	v_readlane_b32 s50, v253, 47
	v_readlane_b32 s51, v253, 48
	v_cvt_pk_bf16_f32 v2, v90, v91
	v_cvt_pk_bf16_f32 v3, v88, v89
	v_cvt_pk_bf16_f32 v4, v86, v87
	v_cvt_pk_bf16_f32 v5, v84, v85
	global_store_dwordx4 v[6:7], v[2:5], off offset:96
	v_readlane_b32 s52, v253, 49
	v_readlane_b32 s53, v253, 50
	v_cvt_pk_bf16_f32 v2, v82, v83
	v_cvt_pk_bf16_f32 v3, v80, v81
	v_cvt_pk_bf16_f32 v4, v78, v79
	v_cvt_pk_bf16_f32 v5, v76, v77
	global_store_dwordx4 v[6:7], v[2:5], off offset:112
	v_readlane_b32 s54, v253, 51
	v_readlane_b32 s55, v253, 52
	s_branch .LBB0_1636

;     ...
;   for (int kt = 0; kt < nk; ++kt) {
;     const int kn = (kt + 1 < nk) ? kt + 1 : kt;
;     GW_LOAD2(kn * 64, kn * bkstep)
;     __builtin_amdgcn_sched_barrier(0);
;     __builtin_amdgcn_s_setprio(1);
; #pragma unroll
;     for (int st = 0; st < 4; ++st) {
;       bf16x8 a0 = *(const bf16x8*)(Ab + st * 32);
;       bf16x8 a1 = *(const bf16x8*)(Ab + 32 * LSTR + st * 32);
;       bf16x8 b0 = *(const bf16x8*)(Bb + st * 32);
;       bf16x8 b1 = *(const bf16x8*)(Bb + 32 * LSTR + st * 32);
;       bf16x8 b2 = *(const bf16x8*)(Bb + 64 * LSTR + st * 32);
;       bf16x8 b3 = *(const bf16x8*)(Bb + 96 * LSTR + st * 32);
;       acc[0][0] = mfma32(a0, b0, acc[0][0]);
;       acc[0][1] = mfma32(a0, b1, acc[0][1]);
;       acc[0][2] = mfma32(a0, b2, acc[0][2]);
;       acc[0][3] = mfma32(a0, b3, acc[0][3]);
;       acc[1][0] = mfma32(a1, b0, acc[1][0]);
;       acc[1][1] = mfma32(a1, b1, acc[1][1]);
;       acc[1][2] = mfma32(a1, b2, acc[1][2]);
;       acc[1][3] = mfma32(a1, b3, acc[1][3]);
;     }
;     __builtin_amdgcn_s_setprio(0);
;     __builtin_amdgcn_sched_barrier(0);
;     __syncthreads();
;     GW_STORE()
;     __syncthreads();
;   }
.LBB0_1715:
	s_barrier
	s_setprio 1
	ds_read_b128 v[200:203], v130 offset:0
	ds_read_b128 v[212:215], v133 offset:18432
	ds_read_b128 v[216:219], v133 offset:23040
	ds_read_b128 v[224:227], v133 offset:27648
	ds_read_b128 v[228:231], v133 offset:32256
	ds_read_b128 v[208:211], v130 offset:4608
	s_waitcnt lgkmcnt(4)
	v_mfma_f32_32x32x16_bf16 v[114:129], v[200:203], v[212:215], v[114:129]
	ds_read_b128 v[204:207], v130 offset:32
	ds_read_b128 v[232:235], v133 offset:18464
	s_waitcnt lgkmcnt(5)
	v_mfma_f32_32x32x16_bf16 v[98:113], v[200:203], v[216:219], v[98:113]
	ds_read_b128 v[236:239], v133 offset:23072
	s_waitcnt lgkmcnt(5)
	v_mfma_f32_32x32x16_bf16 v[82:97], v[200:203], v[224:227], v[82:97]
	ds_read_b128 v[240:243], v133 offset:27680
	s_waitcnt lgkmcnt(5)
	v_mfma_f32_32x32x16_bf16 v[66:81], v[200:203], v[228:231], v[66:81]
	ds_read_b128 v[244:247], v133 offset:32288
	s_waitcnt lgkmcnt(5)
	v_mfma_f32_32x32x16_bf16 v[50:65], v[208:211], v[212:215], v[50:65]
	v_lshl_add_u64 v[152:153], v[148:149], 0, s[14:15]
	v_add_co_u32_e32 v152, vcc, s37, v152
	s_nop 1
	v_addc_co_u32_e32 v153, vcc, 0, v153, vcc
	global_load_dwordx4 v[152:155], v[152:153], off offset:384
	v_mfma_f32_32x32x16_bf16 v[34:49], v[208:211], v[216:219], v[34:49]
	v_lshl_add_u64 v[156:157], v[148:149], 0, s[14:15]
	v_add_co_u32_e32 v156, vcc, s38, v156
	s_nop 1
	v_addc_co_u32_e32 v157, vcc, 0, v157, vcc
	global_load_dwordx4 v[156:159], v[156:157], off offset:384
	v_mfma_f32_32x32x16_bf16 v[18:33], v[208:211], v[224:227], v[18:33]
	v_lshl_add_u64 v[160:161], v[148:149], 0, s[14:15]
	v_add_co_u32_e32 v160, vcc, s39, v160
	s_nop 1
	v_addc_co_u32_e32 v161, vcc, 0, v161, vcc
	global_load_dwordx4 v[160:163], v[160:161], off offset:384
	v_mfma_f32_32x32x16_bf16 v[2:17], v[208:211], v[228:231], v[2:17]
	v_lshl_add_u64 v[164:165], v[148:149], 0, s[14:15]
	v_add_co_u32_e32 v164, vcc, s40, v164
	s_nop 1
	v_addc_co_u32_e32 v165, vcc, 0, v165, vcc
	global_load_dwordx4 v[164:167], v[164:165], off offset:384
	ds_read_b128 v[208:211], v130 offset:4640
	s_waitcnt lgkmcnt(4)
	v_mfma_f32_32x32x16_bf16 v[114:129], v[204:207], v[232:235], v[114:129]
	ds_read_b128 v[200:203], v130 offset:64
	ds_read_b128 v[212:215], v133 offset:18496
	s_waitcnt lgkmcnt(5)
	v_mfma_f32_32x32x16_bf16 v[98:113], v[204:207], v[236:239], v[98:113]
	ds_read_b128 v[216:219], v133 offset:23104
	s_waitcnt lgkmcnt(5)
	v_mfma_f32_32x32x16_bf16 v[82:97], v[204:207], v[240:243], v[82:97]
	ds_read_b128 v[224:227], v133 offset:27712
	s_waitcnt lgkmcnt(5)
	v_mfma_f32_32x32x16_bf16 v[66:81], v[204:207], v[244:247], v[66:81]
	ds_read_b128 v[228:231], v133 offset:32320
	s_waitcnt lgkmcnt(5)
	v_mfma_f32_32x32x16_bf16 v[50:65], v[208:211], v[232:235], v[50:65]
	v_lshl_add_u64 v[168:169], v[150:151], 0, s[14:15]
	v_add_co_u32_e32 v168, vcc, s41, v168
	s_nop 1
	v_addc_co_u32_e32 v169, vcc, 0, v169, vcc
	global_load_dwordx4 v[168:171], v[168:169], off offset:128
	v_mfma_f32_32x32x16_bf16 v[34:49], v[208:211], v[236:239], v[34:49]
	v_lshl_add_u64 v[172:173], v[150:151], 0, s[14:15]
	v_add_co_u32_e32 v172, vcc, s42, v172
	s_nop 1
	v_addc_co_u32_e32 v173, vcc, 0, v173, vcc
	global_load_dwordx4 v[172:175], v[172:173], off offset:128
	v_mfma_f32_32x32x16_bf16 v[18:33], v[208:211], v[240:243], v[18:33]
	v_lshl_add_u64 v[176:177], v[150:151], 0, s[14:15]
	v_add_co_u32_e32 v176, vcc, s43, v176
	s_nop 1
	v_addc_co_u32_e32 v177, vcc, 0, v177, vcc
	global_load_dwordx4 v[176:179], v[176:177], off offset:128
	v_mfma_f32_32x32x16_bf16 v[2:17], v[208:211], v[244:247], v[2:17]
	v_lshl_add_u64 v[180:181], v[150:151], 0, s[14:15]
	v_add_co_u32_e32 v180, vcc, s44, v180
	s_nop 1
	v_addc_co_u32_e32 v181, vcc, 0, v181, vcc
	global_load_dwordx4 v[180:183], v[180:181], off offset:128
	ds_read_b128 v[208:211], v130 offset:4672
	s_waitcnt lgkmcnt(4)
	v_mfma_f32_32x32x16_bf16 v[114:129], v[200:203], v[212:215], v[114:129]
	ds_read_b128 v[204:207], v130 offset:96
	ds_read_b128 v[232:235], v133 offset:18528
	s_waitcnt lgkmcnt(5)
	v_mfma_f32_32x32x16_bf16 v[98:113], v[200:203], v[216:219], v[98:113]
	ds_read_b128 v[236:239], v133 offset:23136
	s_waitcnt lgkmcnt(5)
	v_mfma_f32_32x32x16_bf16 v[82:97], v[200:203], v[224:227], v[82:97]
	ds_read_b128 v[240:243], v133 offset:27744
	s_waitcnt lgkmcnt(5)
	v_mfma_f32_32x32x16_bf16 v[66:81], v[200:203], v[228:231], v[66:81]
	ds_read_b128 v[244:247], v133 offset:32352
	s_waitcnt lgkmcnt(5)
	v_mfma_f32_32x32x16_bf16 v[50:65], v[208:211], v[212:215], v[50:65]
	v_lshl_add_u64 v[184:185], v[150:151], 0, s[14:15]
	v_add_co_u32_e32 v184, vcc, s45, v184
	s_nop 1
	v_addc_co_u32_e32 v185, vcc, 0, v185, vcc
	global_load_dwordx4 v[184:187], v[184:185], off offset:128
	v_mfma_f32_32x32x16_bf16 v[34:49], v[208:211], v[216:219], v[34:49]
	v_lshl_add_u64 v[188:189], v[150:151], 0, s[14:15]
	v_add_co_u32_e32 v188, vcc, s46, v188
	s_nop 1
	v_addc_co_u32_e32 v189, vcc, 0, v189, vcc
	global_load_dwordx4 v[188:191], v[188:189], off offset:128
	v_mfma_f32_32x32x16_bf16 v[18:33], v[208:211], v[224:227], v[18:33]
	v_lshl_add_u64 v[192:193], v[150:151], 0, s[14:15]
	v_add_co_u32_e32 v192, vcc, s47, v192
	s_nop 1
	v_addc_co_u32_e32 v193, vcc, 0, v193, vcc
	global_load_dwordx4 v[192:195], v[192:193], off offset:128
	v_mfma_f32_32x32x16_bf16 v[2:17], v[208:211], v[228:231], v[2:17]
	v_lshl_add_u64 v[196:197], v[150:151], 0, s[14:15]
	v_add_co_u32_e32 v196, vcc, s48, v196
	s_nop 1
	v_addc_co_u32_e32 v197, vcc, 0, v197, vcc
	global_load_dwordx4 v[196:199], v[196:197], off offset:128
	ds_read_b128 v[208:211], v130 offset:4704
	s_waitcnt lgkmcnt(4)
	v_mfma_f32_32x32x16_bf16 v[114:129], v[204:207], v[232:235], v[114:129]
	s_waitcnt lgkmcnt(3)
	v_mfma_f32_32x32x16_bf16 v[98:113], v[204:207], v[236:239], v[98:113]
	s_waitcnt lgkmcnt(2)
	v_mfma_f32_32x32x16_bf16 v[82:97], v[204:207], v[240:243], v[82:97]
	s_waitcnt lgkmcnt(1)
	v_mfma_f32_32x32x16_bf16 v[66:81], v[204:207], v[244:247], v[66:81]
	s_waitcnt lgkmcnt(0)
	v_mfma_f32_32x32x16_bf16 v[50:65], v[208:211], v[232:235], v[50:65]
	v_mfma_f32_32x32x16_bf16 v[34:49], v[208:211], v[236:239], v[34:49]
	v_mfma_f32_32x32x16_bf16 v[18:33], v[208:211], v[240:243], v[18:33]
	v_mfma_f32_32x32x16_bf16 v[2:17], v[208:211], v[244:247], v[2:17]
	s_setprio 0
	s_add_u32 s14, s14, 0x80
	s_addc_u32 s15, s15, 0
	s_cmpk_lg_i32 s14, 0x700
	s_barrier
;     ...
;   for (int kt = 0; kt < nk; ++kt) {
;     const int kn = (kt + 1 < nk) ? kt + 1 : kt;
;     GW_LOAD2(kn * 64, kn * bkstep)
;     __builtin_amdgcn_sched_barrier(0);
;     __builtin_amdgcn_s_setprio(1);
; #pragma unroll
;     for (int st = 0; st < 4; ++st) {
;       bf16x8 a0 = *(const bf16x8*)(Ab + st * 32);
;       bf16x8 a1 = *(const bf16x8*)(Ab + 32 * LSTR + st * 32);
;       bf16x8 b0 = *(const bf16x8*)(Bb + st * 32);
;       bf16x8 b1 = *(const bf16x8*)(Bb + 32 * LSTR + st * 32);
;       bf16x8 b2 = *(const bf16x8*)(Bb + 64 * LSTR + st * 32);
;       bf16x8 b3 = *(const bf16x8*)(Bb + 96 * LSTR + st * 32);
;       acc[0][0] = mfma32(a0, b0, acc[0][0]);
;       acc[0][1] = mfma32(a0, b1, acc[0][1]);
;       acc[0][2] = mfma32(a0, b2, acc[0][2]);
;       acc[0][3] = mfma32(a0, b3, acc[0][3]);
;       acc[1][0] = mfma32(a1, b0, acc[1][0]);
;       acc[1][1] = mfma32(a1, b1, acc[1][1]);
;       acc[1][2] = mfma32(a1, b2, acc[1][2]);
;       acc[1][3] = mfma32(a1, b3, acc[1][3]);
;     }
;     __builtin_amdgcn_s_setprio(0);
;     __builtin_amdgcn_sched_barrier(0);
;     __syncthreads();
;     GW_STORE()
;     __syncthreads();
;   }
	s_waitcnt vmcnt(11)
	ds_write_b128 v132, v[152:155]
	s_waitcnt vmcnt(10)
	ds_write_b128 v132, v[156:159] offset:4608
	s_waitcnt vmcnt(9)
	ds_write_b128 v132, v[160:163] offset:9216
	s_waitcnt vmcnt(8)
	ds_write_b128 v132, v[164:167] offset:13824
	s_waitcnt vmcnt(7)
	ds_write_b128 v132, v[168:171] offset:18432
	s_waitcnt vmcnt(6)
	ds_write_b128 v132, v[172:175] offset:23040
	s_waitcnt vmcnt(5)
	ds_write_b128 v132, v[176:179] offset:27648
	s_waitcnt vmcnt(4)
	ds_write_b128 v132, v[180:183] offset:32256
	s_waitcnt vmcnt(3)
	ds_write_b128 v132, v[184:187] offset:36864
	s_waitcnt vmcnt(2)
	ds_write_b128 v132, v[188:191] offset:41472
	s_waitcnt vmcnt(1)
	ds_write_b128 v132, v[192:195] offset:46080
	s_waitcnt vmcnt(0)
	ds_write_b128 v132, v[196:199] offset:50688
	s_waitcnt lgkmcnt(0)
	s_cbranch_scc1 .LBB0_1715
	s_barrier
	s_setprio 1
	ds_read_b128 v[200:203], v130 offset:0
	ds_read_b128 v[212:215], v133 offset:18432
	ds_read_b128 v[216:219], v133 offset:23040
	ds_read_b128 v[224:227], v133 offset:27648
	ds_read_b128 v[228:231], v133 offset:32256
	ds_read_b128 v[208:211], v130 offset:4608
	s_waitcnt lgkmcnt(4)
	v_mfma_f32_32x32x16_bf16 v[114:129], v[200:203], v[212:215], v[114:129]
	ds_read_b128 v[204:207], v130 offset:32
	ds_read_b128 v[232:235], v133 offset:18464
	s_waitcnt lgkmcnt(5)
	v_mfma_f32_32x32x16_bf16 v[98:113], v[200:203], v[216:219], v[98:113]
	ds_read_b128 v[236:239], v133 offset:23072
	s_waitcnt lgkmcnt(5)
	v_mfma_f32_32x32x16_bf16 v[82:97], v[200:203], v[224:227], v[82:97]
	ds_read_b128 v[240:243], v133 offset:27680
	s_waitcnt lgkmcnt(5)
	v_mfma_f32_32x32x16_bf16 v[66:81], v[200:203], v[228:231], v[66:81]
	ds_read_b128 v[244:247], v133 offset:32288
	s_waitcnt lgkmcnt(5)
	v_mfma_f32_32x32x16_bf16 v[50:65], v[208:211], v[212:215], v[50:65]
	v_lshl_add_u64 v[152:153], v[148:149], 0, s[14:15]
	v_add_co_u32_e32 v152, vcc, s37, v152
	s_nop 1
	v_addc_co_u32_e32 v153, vcc, 0, v153, vcc
	global_load_dwordx4 v[152:155], v[152:153], off offset:384
	v_mfma_f32_32x32x16_bf16 v[34:49], v[208:211], v[216:219], v[34:49]
	v_lshl_add_u64 v[156:157], v[148:149], 0, s[14:15]
	v_add_co_u32_e32 v156, vcc, s38, v156
	s_nop 1
	v_addc_co_u32_e32 v157, vcc, 0, v157, vcc
	global_load_dwordx4 v[156:159], v[156:157], off offset:384
	v_mfma_f32_32x32x16_bf16 v[18:33], v[208:211], v[224:227], v[18:33]
	v_lshl_add_u64 v[160:161], v[148:149], 0, s[14:15]
	v_add_co_u32_e32 v160, vcc, s39, v160
	s_nop 1
	v_addc_co_u32_e32 v161, vcc, 0, v161, vcc
	global_load_dwordx4 v[160:163], v[160:161], off offset:384
	v_mfma_f32_32x32x16_bf16 v[2:17], v[208:211], v[228:231], v[2:17]
	v_lshl_add_u64 v[164:165], v[148:149], 0, s[14:15]
	v_add_co_u32_e32 v164, vcc, s40, v164
	s_nop 1
	v_addc_co_u32_e32 v165, vcc, 0, v165, vcc
	global_load_dwordx4 v[164:167], v[164:165], off offset:384
	ds_read_b128 v[208:211], v130 offset:4640
	s_waitcnt lgkmcnt(4)
	v_mfma_f32_32x32x16_bf16 v[114:129], v[204:207], v[232:235], v[114:129]
	ds_read_b128 v[200:203], v130 offset:64
	ds_read_b128 v[212:215], v133 offset:18496
	s_waitcnt lgkmcnt(5)
	v_mfma_f32_32x32x16_bf16 v[98:113], v[204:207], v[236:239], v[98:113]
	ds_read_b128 v[216:219], v133 offset:23104
	s_waitcnt lgkmcnt(5)
	v_mfma_f32_32x32x16_bf16 v[82:97], v[204:207], v[240:243], v[82:97]
	ds_read_b128 v[224:227], v133 offset:27712
	s_waitcnt lgkmcnt(5)
	v_mfma_f32_32x32x16_bf16 v[66:81], v[204:207], v[244:247], v[66:81]
	ds_read_b128 v[228:231], v133 offset:32320
	s_waitcnt lgkmcnt(5)
	v_mfma_f32_32x32x16_bf16 v[50:65], v[208:211], v[232:235], v[50:65]
	v_lshl_add_u64 v[168:169], v[150:151], 0, s[14:15]
	v_add_co_u32_e32 v168, vcc, s41, v168
	s_nop 1
	v_addc_co_u32_e32 v169, vcc, 0, v169, vcc
	global_load_dwordx4 v[168:171], v[168:169], off offset:128
	v_mfma_f32_32x32x16_bf16 v[34:49], v[208:211], v[236:239], v[34:49]
	v_lshl_add_u64 v[172:173], v[150:151], 0, s[14:15]
	v_add_co_u32_e32 v172, vcc, s42, v172
	s_nop 1
	v_addc_co_u32_e32 v173, vcc, 0, v173, vcc
	global_load_dwordx4 v[172:175], v[172:173], off offset:128
	v_mfma_f32_32x32x16_bf16 v[18:33], v[208:211], v[240:243], v[18:33]
	v_lshl_add_u64 v[176:177], v[150:151], 0, s[14:15]
	v_add_co_u32_e32 v176, vcc, s43, v176
	s_nop 1
	v_addc_co_u32_e32 v177, vcc, 0, v177, vcc
	global_load_dwordx4 v[176:179], v[176:177], off offset:128
	v_mfma_f32_32x32x16_bf16 v[2:17], v[208:211], v[244:247], v[2:17]
	v_lshl_add_u64 v[180:181], v[150:151], 0, s[14:15]
	v_add_co_u32_e32 v180, vcc, s44, v180
	s_nop 1
	v_addc_co_u32_e32 v181, vcc, 0, v181, vcc
	global_load_dwordx4 v[180:183], v[180:181], off offset:128
	ds_read_b128 v[208:211], v130 offset:4672
	s_waitcnt lgkmcnt(4)
	v_mfma_f32_32x32x16_bf16 v[114:129], v[200:203], v[212:215], v[114:129]
	ds_read_b128 v[204:207], v130 offset:96
	ds_read_b128 v[232:235], v133 offset:18528
	s_waitcnt lgkmcnt(5)
	v_mfma_f32_32x32x16_bf16 v[98:113], v[200:203], v[216:219], v[98:113]
	ds_read_b128 v[236:239], v133 offset:23136
	s_waitcnt lgkmcnt(5)
	v_mfma_f32_32x32x16_bf16 v[82:97], v[200:203], v[224:227], v[82:97]
	ds_read_b128 v[240:243], v133 offset:27744
	s_waitcnt lgkmcnt(5)
	v_mfma_f32_32x32x16_bf16 v[66:81], v[200:203], v[228:231], v[66:81]
	ds_read_b128 v[244:247], v133 offset:32352
	s_waitcnt lgkmcnt(5)
;     ...
;   for (int kt = 0; kt < nk; ++kt) {
;     const int kn = (kt + 1 < nk) ? kt + 1 : kt;
;     GW_LOAD2(kn * 64, kn * bkstep)
;     __builtin_amdgcn_sched_barrier(0);
;     __builtin_amdgcn_s_setprio(1);
; #pragma unroll
;     for (int st = 0; st < 4; ++st) {
;       bf16x8 a0 = *(const bf16x8*)(Ab + st * 32);
;       bf16x8 a1 = *(const bf16x8*)(Ab + 32 * LSTR + st * 32);
;       bf16x8 b0 = *(const bf16x8*)(Bb + st * 32);
;       bf16x8 b1 = *(const bf16x8*)(Bb + 32 * LSTR + st * 32);
;       bf16x8 b2 = *(const bf16x8*)(Bb + 64 * LSTR + st * 32);
;       bf16x8 b3 = *(const bf16x8*)(Bb + 96 * LSTR + st * 32);
;       acc[0][0] = mfma32(a0, b0, acc[0][0]);
;       acc[0][1] = mfma32(a0, b1, acc[0][1]);
;       acc[0][2] = mfma32(a0, b2, acc[0][2]);
;       acc[0][3] = mfma32(a0, b3, acc[0][3]);
;       acc[1][0] = mfma32(a1, b0, acc[1][0]);
;       acc[1][1] = mfma32(a1, b1, acc[1][1]);
;       acc[1][2] = mfma32(a1, b2, acc[1][2]);
;       acc[1][3] = mfma32(a1, b3, acc[1][3]);
;     }
;     __builtin_amdgcn_s_setprio(0);
;     __builtin_amdgcn_sched_barrier(0);
;     __syncthreads();
;     GW_STORE()
;     __syncthreads();
;   }
	v_mfma_f32_32x32x16_bf16 v[50:65], v[208:211], v[212:215], v[50:65]
	v_lshl_add_u64 v[184:185], v[150:151], 0, s[14:15]
	v_add_co_u32_e32 v184, vcc, s45, v184
	s_nop 1
	v_addc_co_u32_e32 v185, vcc, 0, v185, vcc
	global_load_dwordx4 v[184:187], v[184:185], off offset:128
	v_mfma_f32_32x32x16_bf16 v[34:49], v[208:211], v[216:219], v[34:49]
	v_lshl_add_u64 v[188:189], v[150:151], 0, s[14:15]
	v_add_co_u32_e32 v188, vcc, s46, v188
	s_nop 1
	v_addc_co_u32_e32 v189, vcc, 0, v189, vcc
	global_load_dwordx4 v[188:191], v[188:189], off offset:128
	v_mfma_f32_32x32x16_bf16 v[18:33], v[208:211], v[224:227], v[18:33]
	v_lshl_add_u64 v[192:193], v[150:151], 0, s[14:15]
	v_add_co_u32_e32 v192, vcc, s47, v192
	s_nop 1
	v_addc_co_u32_e32 v193, vcc, 0, v193, vcc
	global_load_dwordx4 v[192:195], v[192:193], off offset:128
	v_mfma_f32_32x32x16_bf16 v[2:17], v[208:211], v[228:231], v[2:17]
	v_lshl_add_u64 v[196:197], v[150:151], 0, s[14:15]
	v_add_co_u32_e32 v196, vcc, s48, v196
	s_nop 1
	v_addc_co_u32_e32 v197, vcc, 0, v197, vcc
	global_load_dwordx4 v[196:199], v[196:197], off offset:128
	ds_read_b128 v[208:211], v130 offset:4704
	s_waitcnt lgkmcnt(4)
	v_mfma_f32_32x32x16_bf16 v[114:129], v[204:207], v[232:235], v[114:129]
	s_waitcnt lgkmcnt(3)
	v_mfma_f32_32x32x16_bf16 v[98:113], v[204:207], v[236:239], v[98:113]
	s_waitcnt lgkmcnt(2)
	v_mfma_f32_32x32x16_bf16 v[82:97], v[204:207], v[240:243], v[82:97]
	s_waitcnt lgkmcnt(1)
	v_mfma_f32_32x32x16_bf16 v[66:81], v[204:207], v[244:247], v[66:81]
	s_waitcnt lgkmcnt(0)
	v_mfma_f32_32x32x16_bf16 v[50:65], v[208:211], v[232:235], v[50:65]
	v_mfma_f32_32x32x16_bf16 v[34:49], v[208:211], v[236:239], v[34:49]
	v_mfma_f32_32x32x16_bf16 v[18:33], v[208:211], v[240:243], v[18:33]
	v_mfma_f32_32x32x16_bf16 v[2:17], v[208:211], v[244:247], v[2:17]
	s_setprio 0
	s_add_u32 s14, s14, 0x80
	s_addc_u32 s15, s15, 0
	s_barrier
	s_waitcnt vmcnt(11)
	ds_write_b128 v132, v[152:155]
	s_waitcnt vmcnt(10)
	ds_write_b128 v132, v[156:159] offset:4608
	s_waitcnt vmcnt(9)
	ds_write_b128 v132, v[160:163] offset:9216
	s_waitcnt vmcnt(8)
	ds_write_b128 v132, v[164:167] offset:13824
	s_waitcnt vmcnt(7)
	ds_write_b128 v132, v[168:171] offset:18432
	s_waitcnt vmcnt(6)
	ds_write_b128 v132, v[172:175] offset:23040
	s_waitcnt vmcnt(5)
	ds_write_b128 v132, v[176:179] offset:27648
	s_waitcnt vmcnt(4)
	ds_write_b128 v132, v[180:183] offset:32256
	s_waitcnt vmcnt(3)
	ds_write_b128 v132, v[184:187] offset:36864
	s_waitcnt vmcnt(2)
	ds_write_b128 v132, v[188:191] offset:41472
	s_waitcnt vmcnt(1)
	ds_write_b128 v132, v[192:195] offset:46080
	s_waitcnt vmcnt(0)
	ds_write_b128 v132, v[196:199] offset:50688
	s_waitcnt lgkmcnt(0)
	s_barrier
;     ...
;   for (int kt = 0; kt < nk; ++kt) {
;     const int kn = (kt + 1 < nk) ? kt + 1 : kt;
;     GW_LOAD2(kn * 64, kn * bkstep)
;     __builtin_amdgcn_sched_barrier(0);
;     __builtin_amdgcn_s_setprio(1);
; #pragma unroll
;     for (int st = 0; st < 4; ++st) {
;       bf16x8 a0 = *(const bf16x8*)(Ab + st * 32);
;       bf16x8 a1 = *(const bf16x8*)(Ab + 32 * LSTR + st * 32);
;       bf16x8 b0 = *(const bf16x8*)(Bb + st * 32);
;       bf16x8 b1 = *(const bf16x8*)(Bb + 32 * LSTR + st * 32);
;       bf16x8 b2 = *(const bf16x8*)(Bb + 64 * LSTR + st * 32);
;       bf16x8 b3 = *(const bf16x8*)(Bb + 96 * LSTR + st * 32);
;       acc[0][0] = mfma32(a0, b0, acc[0][0]);
;       acc[0][1] = mfma32(a0, b1, acc[0][1]);
;       acc[0][2] = mfma32(a0, b2, acc[0][2]);
;       acc[0][3] = mfma32(a0, b3, acc[0][3]);
;       acc[1][0] = mfma32(a1, b0, acc[1][0]);
;       acc[1][1] = mfma32(a1, b1, acc[1][1]);
;       acc[1][2] = mfma32(a1, b2, acc[1][2]);
;       acc[1][3] = mfma32(a1, b3, acc[1][3]);
;     }
;     __builtin_amdgcn_s_setprio(0);
;     __builtin_amdgcn_sched_barrier(0);
;     __syncthreads();
;     GW_STORE()
;     __syncthreads();
;   }
; template <bool WIDE>
; __device__ __forceinline__ void outproj_tile(const Params& P, int l, int mt, int nt, char* smem) {
;     ...
;     gemm_wide([&](int rr) { return A + (size_t)rr * DM; }, Bt, DM, DM, smem, accw);
;   } else {
;     zero_acc(accn);
;     gemm_main([&](int rr) { return A + (size_t)rr * DM; }, Bt, DM, DM, smem, accn);
;   }
; #pragma unroll 1
;   for (int hsel = 0; hsel < (WIDE ? 2 : 1); ++hsel) {
;     if constexpr (WIDE) wide_acc_to_lds(accw, cs, hsel); else acc_to_lds(accn, cs);
	v_add_co_u32_e32 v160, vcc, 0x10000, v138
	s_nop 0
	s_nop 0
	s_nop 0
	v_addc_co_u32_e32 v161, vcc, 0, v139, vcc
	v_add_co_u32_e32 v164, vcc, 0x20000, v138
	s_nop 0
	v_addc_co_u32_e32 v165, vcc, 0, v139, vcc
	v_add_co_u32_e32 v168, vcc, 0x30000, v138
	s_lshl_b64 s[12:13], s[12:13], 7
	s_nop 0
	v_addc_co_u32_e32 v169, vcc, 0, v139, vcc
	v_add_co_u32_e32 v172, vcc, 0x40000, v138
	s_nop 0
	v_addc_co_u32_e32 v173, vcc, 0, v139, vcc
	v_add_co_u32_e32 v176, vcc, 0x50000, v138
	s_mov_b32 s53, 0
	s_nop 0
	v_addc_co_u32_e32 v177, vcc, 0, v139, vcc
	v_add_co_u32_e32 v180, vcc, 0x60000, v138
	s_nop 0
	v_addc_co_u32_e32 v181, vcc, 0, v139, vcc
	v_add_co_u32_e32 v138, vcc, 0x70000, v138
	s_nop 1
	v_addc_co_u32_e32 v139, vcc, 0, v139, vcc
	s_nop 0
	s_setprio 1
	ds_read_b128 v[188:191], v130 offset:0
	ds_read_b128 v[200:203], v133 offset:18432
	ds_read_b128 v[204:207], v133 offset:23040
	ds_read_b128 v[208:211], v133 offset:27648
	ds_read_b128 v[212:215], v133 offset:32256
	ds_read_b128 v[196:199], v130 offset:4608
	s_waitcnt lgkmcnt(4)
	v_mfma_f32_32x32x16_bf16 v[114:129], v[188:191], v[200:203], v[114:129]
	ds_read_b128 v[192:195], v130 offset:32
	ds_read_b128 v[216:219], v133 offset:18464
	s_waitcnt lgkmcnt(5)
	v_mfma_f32_32x32x16_bf16 v[98:113], v[188:191], v[204:207], v[98:113]
	ds_read_b128 v[224:227], v133 offset:23072
	s_waitcnt lgkmcnt(5)
	v_mfma_f32_32x32x16_bf16 v[82:97], v[188:191], v[208:211], v[82:97]
	ds_read_b128 v[228:231], v133 offset:27680
	s_waitcnt lgkmcnt(5)
	v_mfma_f32_32x32x16_bf16 v[66:81], v[188:191], v[212:215], v[66:81]
	ds_read_b128 v[232:235], v133 offset:32288
	s_waitcnt lgkmcnt(5)
	v_mfma_f32_32x32x16_bf16 v[50:65], v[196:199], v[200:203], v[50:65]
	v_mfma_f32_32x32x16_bf16 v[34:49], v[196:199], v[204:207], v[34:49]
	v_mfma_f32_32x32x16_bf16 v[18:33], v[196:199], v[208:211], v[18:33]
	v_mfma_f32_32x32x16_bf16 v[2:17], v[196:199], v[212:215], v[2:17]
	ds_read_b128 v[196:199], v130 offset:4640
	s_waitcnt lgkmcnt(4)
	v_mfma_f32_32x32x16_bf16 v[114:129], v[192:195], v[216:219], v[114:129]
	ds_read_b128 v[188:191], v130 offset:64
	ds_read_b128 v[200:203], v133 offset:18496
	s_waitcnt lgkmcnt(5)
	v_mfma_f32_32x32x16_bf16 v[98:113], v[192:195], v[224:227], v[98:113]
	ds_read_b128 v[204:207], v133 offset:23104
	s_waitcnt lgkmcnt(5)
	v_mfma_f32_32x32x16_bf16 v[82:97], v[192:195], v[228:231], v[82:97]
	ds_read_b128 v[208:211], v133 offset:27712
	s_waitcnt lgkmcnt(5)
	v_mfma_f32_32x32x16_bf16 v[66:81], v[192:195], v[232:235], v[66:81]
	ds_read_b128 v[212:215], v133 offset:32320
	s_waitcnt lgkmcnt(5)
	v_mfma_f32_32x32x16_bf16 v[50:65], v[196:199], v[216:219], v[50:65]
	v_mfma_f32_32x32x16_bf16 v[34:49], v[196:199], v[224:227], v[34:49]
	v_mfma_f32_32x32x16_bf16 v[18:33], v[196:199], v[228:231], v[18:33]
	v_mfma_f32_32x32x16_bf16 v[2:17], v[196:199], v[232:235], v[2:17]
	ds_read_b128 v[196:199], v130 offset:4672
	s_waitcnt lgkmcnt(4)
	v_mfma_f32_32x32x16_bf16 v[114:129], v[188:191], v[200:203], v[114:129]
	ds_read_b128 v[192:195], v130 offset:96
	ds_read_b128 v[216:219], v133 offset:18528
	s_waitcnt lgkmcnt(5)
	v_mfma_f32_32x32x16_bf16 v[98:113], v[188:191], v[204:207], v[98:113]
	ds_read_b128 v[224:227], v133 offset:23136
	s_waitcnt lgkmcnt(5)
	v_mfma_f32_32x32x16_bf16 v[82:97], v[188:191], v[208:211], v[82:97]
	ds_read_b128 v[228:231], v133 offset:27744
	s_waitcnt lgkmcnt(5)
	v_mfma_f32_32x32x16_bf16 v[66:81], v[188:191], v[212:215], v[66:81]
	ds_read_b128 v[232:235], v133 offset:32352
	s_waitcnt lgkmcnt(5)
	v_mfma_f32_32x32x16_bf16 v[50:65], v[196:199], v[200:203], v[50:65]
	v_mfma_f32_32x32x16_bf16 v[34:49], v[196:199], v[204:207], v[34:49]
	v_mfma_f32_32x32x16_bf16 v[18:33], v[196:199], v[208:211], v[18:33]
	v_mfma_f32_32x32x16_bf16 v[2:17], v[196:199], v[212:215], v[2:17]
	ds_read_b128 v[196:199], v130 offset:4704
	s_waitcnt lgkmcnt(4)
	v_mfma_f32_32x32x16_bf16 v[114:129], v[192:195], v[216:219], v[114:129]
	s_waitcnt lgkmcnt(3)
	v_mfma_f32_32x32x16_bf16 v[98:113], v[192:195], v[224:227], v[98:113]
	s_waitcnt lgkmcnt(2)
	v_mfma_f32_32x32x16_bf16 v[82:97], v[192:195], v[228:231], v[82:97]
	s_waitcnt lgkmcnt(1)
	v_mfma_f32_32x32x16_bf16 v[66:81], v[192:195], v[232:235], v[66:81]
	s_waitcnt lgkmcnt(0)
	v_mfma_f32_32x32x16_bf16 v[50:65], v[196:199], v[216:219], v[50:65]
	v_mfma_f32_32x32x16_bf16 v[34:49], v[196:199], v[224:227], v[34:49]
	v_mfma_f32_32x32x16_bf16 v[18:33], v[196:199], v[228:231], v[18:33]
	v_mfma_f32_32x32x16_bf16 v[2:17], v[196:199], v[232:235], v[2:17]
	s_setprio 0
	s_mov_b64 s[16:17], -1
	s_barrier
	s_waitcnt lgkmcnt(0)

;     ...
;   for (int kt = 0; kt < nk; ++kt) {
;     const int kn = (kt + 1 < nk) ? kt + 1 : kt;
;     GW_LOAD2(kn * 64, kn * bkstep)
;     __builtin_amdgcn_sched_barrier(0);
;     __builtin_amdgcn_s_setprio(1);
; #pragma unroll
;     for (int st = 0; st < 4; ++st) {
;       bf16x8 a0 = *(const bf16x8*)(Ab + st * 32);
;       bf16x8 a1 = *(const bf16x8*)(Ab + 32 * LSTR + st * 32);
;       bf16x8 b0 = *(const bf16x8*)(Bb + st * 32);
;       bf16x8 b1 = *(const bf16x8*)(Bb + 32 * LSTR + st * 32);
;       bf16x8 b2 = *(const bf16x8*)(Bb + 64 * LSTR + st * 32);
;       bf16x8 b3 = *(const bf16x8*)(Bb + 96 * LSTR + st * 32);
;       acc[0][0] = mfma32(a0, b0, acc[0][0]);
;       acc[0][1] = mfma32(a0, b1, acc[0][1]);
;       acc[0][2] = mfma32(a0, b2, acc[0][2]);
;       acc[0][3] = mfma32(a0, b3, acc[0][3]);
;       acc[1][0] = mfma32(a1, b0, acc[1][0]);
;       acc[1][1] = mfma32(a1, b1, acc[1][1]);
;       acc[1][2] = mfma32(a1, b2, acc[1][2]);
;       acc[1][3] = mfma32(a1, b3, acc[1][3]);
;     }
;     __builtin_amdgcn_s_setprio(0);
;     __builtin_amdgcn_sched_barrier(0);
;     __syncthreads();
;     GW_STORE()
;     __syncthreads();
;   }
.LBB0_2065:
	s_barrier
	s_setprio 1
	ds_read_b128 v[206:209], v133 offset:0
	ds_read_b128 v[218:221], v137 offset:18432
	ds_read_b128 v[224:227], v137 offset:23040
	ds_read_b128 v[228:231], v137 offset:27648
	ds_read_b128 v[232:235], v137 offset:32256
	ds_read_b128 v[214:217], v133 offset:4608
	s_waitcnt lgkmcnt(4)
	v_mfma_f32_32x32x16_bf16 v[114:129], v[206:209], v[218:221], v[114:129]
	ds_read_b128 v[210:213], v133 offset:32
	ds_read_b128 v[236:239], v137 offset:18464
	s_waitcnt lgkmcnt(5)
	v_mfma_f32_32x32x16_bf16 v[98:113], v[206:209], v[224:227], v[98:113]
	ds_read_b128 v[240:243], v137 offset:23072
	s_waitcnt lgkmcnt(5)
	v_mfma_f32_32x32x16_bf16 v[82:97], v[206:209], v[228:231], v[82:97]
	ds_read_b128 v[244:247], v137 offset:27680
	s_waitcnt lgkmcnt(5)
	v_mfma_f32_32x32x16_bf16 v[66:81], v[206:209], v[232:235], v[66:81]
	ds_read_b128 v[248:251], v137 offset:32288
	s_waitcnt lgkmcnt(5)
	v_mfma_f32_32x32x16_bf16 v[50:65], v[214:217], v[218:221], v[50:65]
	v_lshl_add_u64 v[158:159], v[150:151], 0, v[130:131]
	global_load_dwordx4 v[158:161], v[158:159], off
	v_mfma_f32_32x32x16_bf16 v[34:49], v[214:217], v[224:227], v[34:49]
	v_lshl_add_u64 v[162:163], v[152:153], 0, v[130:131]
	global_load_dwordx4 v[162:165], v[162:163], off
	v_mfma_f32_32x32x16_bf16 v[18:33], v[214:217], v[228:231], v[18:33]
	v_lshl_add_u64 v[166:167], v[154:155], 0, v[130:131]
	global_load_dwordx4 v[166:169], v[166:167], off
	v_mfma_f32_32x32x16_bf16 v[2:17], v[214:217], v[232:235], v[2:17]
	v_lshl_add_u64 v[170:171], v[156:157], 0, v[130:131]
	global_load_dwordx4 v[170:173], v[170:171], off
	ds_read_b128 v[214:217], v133 offset:4640
	s_waitcnt lgkmcnt(4)
	v_mfma_f32_32x32x16_bf16 v[114:129], v[210:213], v[236:239], v[114:129]
	ds_read_b128 v[206:209], v133 offset:64
	ds_read_b128 v[218:221], v137 offset:18496
	s_waitcnt lgkmcnt(5)
	v_mfma_f32_32x32x16_bf16 v[98:113], v[210:213], v[240:243], v[98:113]
	ds_read_b128 v[224:227], v137 offset:23104
	s_waitcnt lgkmcnt(5)
	v_mfma_f32_32x32x16_bf16 v[82:97], v[210:213], v[244:247], v[82:97]
	ds_read_b128 v[228:231], v137 offset:27712
	s_waitcnt lgkmcnt(5)
	v_mfma_f32_32x32x16_bf16 v[66:81], v[210:213], v[248:251], v[66:81]
	ds_read_b128 v[232:235], v137 offset:32320
	s_waitcnt lgkmcnt(5)
	v_mfma_f32_32x32x16_bf16 v[50:65], v[214:217], v[236:239], v[50:65]
	v_lshl_add_u64 v[174:175], v[148:149], 0, v[130:131]
	v_add_co_u32_e32 v174, vcc, s35, v174
	s_nop 1
	v_addc_co_u32_e32 v175, vcc, 0, v175, vcc
	global_load_dwordx4 v[174:177], v[174:175], off offset:-4096
	v_mfma_f32_32x32x16_bf16 v[34:49], v[214:217], v[240:243], v[34:49]
	v_lshl_add_u64 v[178:179], v[148:149], 0, v[130:131]
	v_add_co_u32_e32 v178, vcc, s35, v178
	s_nop 1
	v_addc_co_u32_e32 v179, vcc, 0, v179, vcc
	global_load_dwordx4 v[178:181], v[178:179], off
	v_mfma_f32_32x32x16_bf16 v[18:33], v[214:217], v[244:247], v[18:33]
	v_lshl_add_u64 v[182:183], v[148:149], 0, v[130:131]
	v_add_co_u32_e32 v182, vcc, s36, v182
	s_nop 1
	v_addc_co_u32_e32 v183, vcc, 0, v183, vcc
	global_load_dwordx4 v[182:185], v[182:183], off offset:-4096
	v_mfma_f32_32x32x16_bf16 v[2:17], v[214:217], v[248:251], v[2:17]
	v_lshl_add_u64 v[186:187], v[148:149], 0, v[130:131]
	v_add_co_u32_e32 v186, vcc, s36, v186
	s_nop 1
	v_addc_co_u32_e32 v187, vcc, 0, v187, vcc
	global_load_dwordx4 v[186:189], v[186:187], off
	ds_read_b128 v[214:217], v133 offset:4672
	s_waitcnt lgkmcnt(4)
	v_mfma_f32_32x32x16_bf16 v[114:129], v[206:209], v[218:221], v[114:129]
	ds_read_b128 v[210:213], v133 offset:96
	ds_read_b128 v[236:239], v137 offset:18528
	s_waitcnt lgkmcnt(5)
	v_mfma_f32_32x32x16_bf16 v[98:113], v[206:209], v[224:227], v[98:113]
	ds_read_b128 v[240:243], v137 offset:23136
	s_waitcnt lgkmcnt(5)
	v_mfma_f32_32x32x16_bf16 v[82:97], v[206:209], v[228:231], v[82:97]
	ds_read_b128 v[244:247], v137 offset:27744
	s_waitcnt lgkmcnt(5)
	v_mfma_f32_32x32x16_bf16 v[66:81], v[206:209], v[232:235], v[66:81]
	ds_read_b128 v[248:251], v137 offset:32352
	s_waitcnt lgkmcnt(5)
	v_mfma_f32_32x32x16_bf16 v[50:65], v[214:217], v[218:221], v[50:65]
	v_lshl_add_u64 v[190:191], v[148:149], 0, v[130:131]
	v_add_co_u32_e32 v190, vcc, s37, v190
	s_nop 1
	v_addc_co_u32_e32 v191, vcc, 0, v191, vcc
	global_load_dwordx4 v[190:193], v[190:191], off offset:-4096
	v_mfma_f32_32x32x16_bf16 v[34:49], v[214:217], v[224:227], v[34:49]
	v_lshl_add_u64 v[194:195], v[148:149], 0, v[130:131]
	v_add_co_u32_e32 v194, vcc, s37, v194
	s_nop 1
	v_addc_co_u32_e32 v195, vcc, 0, v195, vcc
	global_load_dwordx4 v[194:197], v[194:195], off
	v_mfma_f32_32x32x16_bf16 v[18:33], v[214:217], v[228:231], v[18:33]
	v_lshl_add_u64 v[198:199], v[148:149], 0, v[130:131]
	v_add_co_u32_e32 v198, vcc, s38, v198
	s_nop 1
	v_addc_co_u32_e32 v199, vcc, 0, v199, vcc
	global_load_dwordx4 v[198:201], v[198:199], off offset:-4096
	v_mfma_f32_32x32x16_bf16 v[2:17], v[214:217], v[232:235], v[2:17]
	v_lshl_add_u64 v[202:203], v[148:149], 0, v[130:131]
	v_add_co_u32_e32 v202, vcc, s38, v202
	s_nop 1
	v_addc_co_u32_e32 v203, vcc, 0, v203, vcc
	global_load_dwordx4 v[202:205], v[202:203], off
	ds_read_b128 v[214:217], v133 offset:4704
	s_waitcnt lgkmcnt(4)
	v_mfma_f32_32x32x16_bf16 v[114:129], v[210:213], v[236:239], v[114:129]
	s_waitcnt lgkmcnt(3)
	v_mfma_f32_32x32x16_bf16 v[98:113], v[210:213], v[240:243], v[98:113]
	s_waitcnt lgkmcnt(2)
	v_mfma_f32_32x32x16_bf16 v[82:97], v[210:213], v[244:247], v[82:97]
	s_waitcnt lgkmcnt(1)
	v_mfma_f32_32x32x16_bf16 v[66:81], v[210:213], v[248:251], v[66:81]
	s_waitcnt lgkmcnt(0)
	v_mfma_f32_32x32x16_bf16 v[50:65], v[214:217], v[236:239], v[50:65]
	v_mfma_f32_32x32x16_bf16 v[34:49], v[214:217], v[240:243], v[34:49]
	v_mfma_f32_32x32x16_bf16 v[18:33], v[214:217], v[244:247], v[18:33]
	v_mfma_f32_32x32x16_bf16 v[2:17], v[214:217], v[248:251], v[2:17]
	s_setprio 0
	s_add_i32 s41, s41, -1
	v_lshl_add_u64 v[148:149], v[148:149], 0, s[8:9]
	v_lshl_add_u64 v[150:151], v[150:151], 0, s[10:11]
	v_lshl_add_u64 v[152:153], v[152:153], 0, s[10:11]
	v_lshl_add_u64 v[154:155], v[154:155], 0, s[10:11]
	s_cmp_lg_u32 s41, 0
	v_lshl_add_u64 v[156:157], v[156:157], 0, s[10:11]
	s_barrier
;     ...
;   for (int kt = 0; kt < nk; ++kt) {
;     const int kn = (kt + 1 < nk) ? kt + 1 : kt;
;     GW_LOAD2(kn * 64, kn * bkstep)
;     __builtin_amdgcn_sched_barrier(0);
;     __builtin_amdgcn_s_setprio(1);
; #pragma unroll
;     for (int st = 0; st < 4; ++st) {
;       bf16x8 a0 = *(const bf16x8*)(Ab + st * 32);
;       bf16x8 a1 = *(const bf16x8*)(Ab + 32 * LSTR + st * 32);
;       bf16x8 b0 = *(const bf16x8*)(Bb + st * 32);
;       bf16x8 b1 = *(const bf16x8*)(Bb + 32 * LSTR + st * 32);
;       bf16x8 b2 = *(const bf16x8*)(Bb + 64 * LSTR + st * 32);
;       bf16x8 b3 = *(const bf16x8*)(Bb + 96 * LSTR + st * 32);
;       acc[0][0] = mfma32(a0, b0, acc[0][0]);
;       acc[0][1] = mfma32(a0, b1, acc[0][1]);
;       acc[0][2] = mfma32(a0, b2, acc[0][2]);
;       acc[0][3] = mfma32(a0, b3, acc[0][3]);
;       acc[1][0] = mfma32(a1, b0, acc[1][0]);
;       acc[1][1] = mfma32(a1, b1, acc[1][1]);
;       acc[1][2] = mfma32(a1, b2, acc[1][2]);
;       acc[1][3] = mfma32(a1, b3, acc[1][3]);
;     }
;     __builtin_amdgcn_s_setprio(0);
;     __builtin_amdgcn_sched_barrier(0);
;     __syncthreads();
;     GW_STORE()
;     __syncthreads();
;   }
	s_waitcnt vmcnt(11)
	ds_write_b128 v132, v[158:161]
	s_waitcnt vmcnt(10)
	ds_write_b128 v132, v[162:165] offset:4608
	s_waitcnt vmcnt(9)
	ds_write_b128 v132, v[166:169] offset:9216
	s_waitcnt vmcnt(8)
	ds_write_b128 v132, v[170:173] offset:13824
	s_waitcnt vmcnt(7)
	ds_write_b128 v132, v[174:177] offset:18432
	s_waitcnt vmcnt(6)
	ds_write_b128 v132, v[178:181] offset:23040
	s_waitcnt vmcnt(5)
	ds_write_b128 v132, v[182:185] offset:27648
	s_waitcnt vmcnt(4)
	ds_write_b128 v132, v[186:189] offset:32256
	s_waitcnt vmcnt(3)
	ds_write_b128 v132, v[190:193] offset:36864
	s_waitcnt vmcnt(2)
	ds_write_b128 v132, v[194:197] offset:41472
	s_waitcnt vmcnt(1)
	ds_write_b128 v132, v[198:201] offset:46080
	s_waitcnt vmcnt(0)
	ds_write_b128 v132, v[202:205] offset:50688
	s_waitcnt lgkmcnt(0)
	s_cbranch_scc1 .LBB0_2065
	s_barrier
	s_setprio 1
	ds_read_b128 v[206:209], v133 offset:0
	ds_read_b128 v[218:221], v137 offset:18432
	ds_read_b128 v[224:227], v137 offset:23040
	ds_read_b128 v[228:231], v137 offset:27648
	ds_read_b128 v[232:235], v137 offset:32256
	ds_read_b128 v[214:217], v133 offset:4608
	s_waitcnt lgkmcnt(4)
	v_mfma_f32_32x32x16_bf16 v[114:129], v[206:209], v[218:221], v[114:129]
	ds_read_b128 v[210:213], v133 offset:32
	ds_read_b128 v[236:239], v137 offset:18464
	s_waitcnt lgkmcnt(5)
	v_mfma_f32_32x32x16_bf16 v[98:113], v[206:209], v[224:227], v[98:113]
	ds_read_b128 v[240:243], v137 offset:23072
	s_waitcnt lgkmcnt(5)
	v_mfma_f32_32x32x16_bf16 v[82:97], v[206:209], v[228:231], v[82:97]
	ds_read_b128 v[244:247], v137 offset:27680
	s_waitcnt lgkmcnt(5)
	v_mfma_f32_32x32x16_bf16 v[66:81], v[206:209], v[232:235], v[66:81]
	ds_read_b128 v[248:251], v137 offset:32288
	s_waitcnt lgkmcnt(5)
	v_mfma_f32_32x32x16_bf16 v[50:65], v[214:217], v[218:221], v[50:65]
	v_lshl_add_u64 v[158:159], v[150:151], 0, v[130:131]
	global_load_dwordx4 v[158:161], v[158:159], off
	v_mfma_f32_32x32x16_bf16 v[34:49], v[214:217], v[224:227], v[34:49]
	v_lshl_add_u64 v[162:163], v[152:153], 0, v[130:131]
	global_load_dwordx4 v[162:165], v[162:163], off
	v_mfma_f32_32x32x16_bf16 v[18:33], v[214:217], v[228:231], v[18:33]
	v_lshl_add_u64 v[166:167], v[154:155], 0, v[130:131]
	global_load_dwordx4 v[166:169], v[166:167], off
	v_mfma_f32_32x32x16_bf16 v[2:17], v[214:217], v[232:235], v[2:17]
	v_lshl_add_u64 v[170:171], v[156:157], 0, v[130:131]
	global_load_dwordx4 v[170:173], v[170:171], off
	ds_read_b128 v[214:217], v133 offset:4640
	s_waitcnt lgkmcnt(4)
	v_mfma_f32_32x32x16_bf16 v[114:129], v[210:213], v[236:239], v[114:129]
	ds_read_b128 v[206:209], v133 offset:64
	ds_read_b128 v[218:221], v137 offset:18496
	s_waitcnt lgkmcnt(5)
	v_mfma_f32_32x32x16_bf16 v[98:113], v[210:213], v[240:243], v[98:113]
	ds_read_b128 v[224:227], v137 offset:23104
	s_waitcnt lgkmcnt(5)
	v_mfma_f32_32x32x16_bf16 v[82:97], v[210:213], v[244:247], v[82:97]
	ds_read_b128 v[228:231], v137 offset:27712
	s_waitcnt lgkmcnt(5)
	v_mfma_f32_32x32x16_bf16 v[66:81], v[210:213], v[248:251], v[66:81]
	ds_read_b128 v[232:235], v137 offset:32320
	s_waitcnt lgkmcnt(5)
	v_mfma_f32_32x32x16_bf16 v[50:65], v[214:217], v[236:239], v[50:65]
	v_lshl_add_u64 v[174:175], v[148:149], 0, v[130:131]
	v_add_co_u32_e32 v174, vcc, s35, v174
	s_nop 1
	v_addc_co_u32_e32 v175, vcc, 0, v175, vcc
	global_load_dwordx4 v[174:177], v[174:175], off offset:-4096
	v_mfma_f32_32x32x16_bf16 v[34:49], v[214:217], v[240:243], v[34:49]
	v_lshl_add_u64 v[178:179], v[148:149], 0, v[130:131]
	v_add_co_u32_e32 v178, vcc, s35, v178
	s_nop 1
	v_addc_co_u32_e32 v179, vcc, 0, v179, vcc
	global_load_dwordx4 v[178:181], v[178:179], off
	v_mfma_f32_32x32x16_bf16 v[18:33], v[214:217], v[244:247], v[18:33]
	v_lshl_add_u64 v[182:183], v[148:149], 0, v[130:131]
	v_add_co_u32_e32 v182, vcc, s36, v182
	s_nop 1
	v_addc_co_u32_e32 v183, vcc, 0, v183, vcc
	global_load_dwordx4 v[182:185], v[182:183], off offset:-4096
	v_mfma_f32_32x32x16_bf16 v[2:17], v[214:217], v[248:251], v[2:17]
	v_lshl_add_u64 v[186:187], v[148:149], 0, v[130:131]
	v_add_co_u32_e32 v186, vcc, s36, v186
	s_nop 1
	v_addc_co_u32_e32 v187, vcc, 0, v187, vcc
	global_load_dwordx4 v[186:189], v[186:187], off
	ds_read_b128 v[214:217], v133 offset:4672
	s_waitcnt lgkmcnt(4)
	v_mfma_f32_32x32x16_bf16 v[114:129], v[206:209], v[218:221], v[114:129]
	ds_read_b128 v[210:213], v133 offset:96
	ds_read_b128 v[236:239], v137 offset:18528
	s_waitcnt lgkmcnt(5)
	v_mfma_f32_32x32x16_bf16 v[98:113], v[206:209], v[224:227], v[98:113]
	ds_read_b128 v[240:243], v137 offset:23136
	s_waitcnt lgkmcnt(5)
	v_mfma_f32_32x32x16_bf16 v[82:97], v[206:209], v[228:231], v[82:97]
	ds_read_b128 v[244:247], v137 offset:27744
	s_waitcnt lgkmcnt(5)
	v_mfma_f32_32x32x16_bf16 v[66:81], v[206:209], v[232:235], v[66:81]
	ds_read_b128 v[248:251], v137 offset:32352
	s_waitcnt lgkmcnt(5)
	v_mfma_f32_32x32x16_bf16 v[50:65], v[214:217], v[218:221], v[50:65]
	v_lshl_add_u64 v[190:191], v[148:149], 0, v[130:131]
	v_add_co_u32_e32 v190, vcc, s37, v190
	s_nop 1
	v_addc_co_u32_e32 v191, vcc, 0, v191, vcc
	global_load_dwordx4 v[190:193], v[190:191], off offset:-4096
	v_mfma_f32_32x32x16_bf16 v[34:49], v[214:217], v[224:227], v[34:49]
	v_lshl_add_u64 v[194:195], v[148:149], 0, v[130:131]
	v_add_co_u32_e32 v194, vcc, s37, v194
	s_nop 1
	v_addc_co_u32_e32 v195, vcc, 0, v195, vcc
	global_load_dwordx4 v[194:197], v[194:195], off
	v_mfma_f32_32x32x16_bf16 v[18:33], v[214:217], v[228:231], v[18:33]
	v_lshl_add_u64 v[198:199], v[148:149], 0, v[130:131]
	v_add_co_u32_e32 v198, vcc, s38, v198
	s_nop 1
	v_addc_co_u32_e32 v199, vcc, 0, v199, vcc
	global_load_dwordx4 v[198:201], v[198:199], off offset:-4096
	v_mfma_f32_32x32x16_bf16 v[2:17], v[214:217], v[232:235], v[2:17]
	v_lshl_add_u64 v[202:203], v[148:149], 0, v[130:131]
	v_add_co_u32_e32 v202, vcc, s38, v202
	s_nop 1
	v_addc_co_u32_e32 v203, vcc, 0, v203, vcc
	global_load_dwordx4 v[202:205], v[202:203], off
	ds_read_b128 v[214:217], v133 offset:4704
	s_waitcnt lgkmcnt(4)
	v_mfma_f32_32x32x16_bf16 v[114:129], v[210:213], v[236:239], v[114:129]
	s_waitcnt lgkmcnt(3)
	v_mfma_f32_32x32x16_bf16 v[98:113], v[210:213], v[240:243], v[98:113]
	s_waitcnt lgkmcnt(2)
	v_mfma_f32_32x32x16_bf16 v[82:97], v[210:213], v[244:247], v[82:97]
	s_waitcnt lgkmcnt(1)
	v_mfma_f32_32x32x16_bf16 v[66:81], v[210:213], v[248:251], v[66:81]
	s_waitcnt lgkmcnt(0)
	v_mfma_f32_32x32x16_bf16 v[50:65], v[214:217], v[236:239], v[50:65]
	v_mfma_f32_32x32x16_bf16 v[34:49], v[214:217], v[240:243], v[34:49]
	v_mfma_f32_32x32x16_bf16 v[18:33], v[214:217], v[244:247], v[18:33]
	v_mfma_f32_32x32x16_bf16 v[2:17], v[214:217], v[248:251], v[2:17]
	s_setprio 0
	v_lshl_add_u64 v[148:149], v[148:149], 0, s[8:9]
	v_lshl_add_u64 v[150:151], v[150:151], 0, s[10:11]
	v_lshl_add_u64 v[152:153], v[152:153], 0, s[10:11]
	v_lshl_add_u64 v[154:155], v[154:155], 0, s[10:11]
	v_lshl_add_u64 v[156:157], v[156:157], 0, s[10:11]
	s_barrier
;     ...
;   for (int kt = 0; kt < nk; ++kt) {
;     const int kn = (kt + 1 < nk) ? kt + 1 : kt;
;     GW_LOAD2(kn * 64, kn * bkstep)
;     __builtin_amdgcn_sched_barrier(0);
;     __builtin_amdgcn_s_setprio(1);
; #pragma unroll
;     for (int st = 0; st < 4; ++st) {
;       bf16x8 a0 = *(const bf16x8*)(Ab + st * 32);
;       bf16x8 a1 = *(const bf16x8*)(Ab + 32 * LSTR + st * 32);
;       bf16x8 b0 = *(const bf16x8*)(Bb + st * 32);
;       bf16x8 b1 = *(const bf16x8*)(Bb + 32 * LSTR + st * 32);
;       bf16x8 b2 = *(const bf16x8*)(Bb + 64 * LSTR + st * 32);
;       bf16x8 b3 = *(const bf16x8*)(Bb + 96 * LSTR + st * 32);
;       acc[0][0] = mfma32(a0, b0, acc[0][0]);
;       acc[0][1] = mfma32(a0, b1, acc[0][1]);
;       acc[0][2] = mfma32(a0, b2, acc[0][2]);
;       acc[0][3] = mfma32(a0, b3, acc[0][3]);
;       acc[1][0] = mfma32(a1, b0, acc[1][0]);
;       acc[1][1] = mfma32(a1, b1, acc[1][1]);
;       acc[1][2] = mfma32(a1, b2, acc[1][2]);
;       acc[1][3] = mfma32(a1, b3, acc[1][3]);
;     }
;     __builtin_amdgcn_s_setprio(0);
;     __builtin_amdgcn_sched_barrier(0);
;     __syncthreads();
;     GW_STORE()
;     __syncthreads();
;   }
; __device__ __forceinline__ void expert1_tile(const Params& P, int e, int mt, int ntw, char* smem) {
;     ...
;   float* cs = (float*)smem;
;   int tid_ = threadIdx.x;
;   asm volatile("" : "+v"(tid_));
;   const int lane = tid_ & 63, wave = tid_ >> 6;
;   const int r = 32 * wave + (lane & 31), part = lane >> 5;
; #pragma unroll 1
;   for (int h = 0; h < 2; ++h) {
;     wide_acc_to_lds(acc, cs, h);
;     u16* dst = WSP(u16, OFF_HID) + ((size_t)e * EROWS + mt * 128 + r) * 2048 + (ntw * 2 + h) * 64 + part * 32;
	s_waitcnt vmcnt(11)
	ds_write_b128 v132, v[158:161]
	s_waitcnt vmcnt(10)
	ds_write_b128 v132, v[162:165] offset:4608
	s_waitcnt vmcnt(9)
	ds_write_b128 v132, v[166:169] offset:9216
	s_waitcnt vmcnt(8)
	ds_write_b128 v132, v[170:173] offset:13824
	s_waitcnt vmcnt(7)
	ds_write_b128 v132, v[174:177] offset:18432
	s_waitcnt vmcnt(6)
	ds_write_b128 v132, v[178:181] offset:23040
	s_waitcnt vmcnt(5)
	ds_write_b128 v132, v[182:185] offset:27648
	s_waitcnt vmcnt(4)
	ds_write_b128 v132, v[186:189] offset:32256
	s_waitcnt vmcnt(3)
	ds_write_b128 v132, v[190:193] offset:36864
	s_waitcnt vmcnt(2)
	ds_write_b128 v132, v[194:197] offset:41472
	s_waitcnt vmcnt(1)
	ds_write_b128 v132, v[198:201] offset:46080
	s_waitcnt vmcnt(0)
	ds_write_b128 v132, v[202:205] offset:50688
	s_waitcnt lgkmcnt(0)
	s_barrier
	v_add_co_u32_e32 v156, vcc, 0x780000, v138
	s_nop 0
	s_nop 0
	s_nop 0
	v_addc_co_u32_e32 v157, vcc, 0, v139, vcc
	v_add_co_u32_e32 v160, vcc, 0x781000, v138
	s_mov_b32 s18, 0
	s_nop 0
	v_addc_co_u32_e32 v161, vcc, 0, v139, vcc
	v_add_co_u32_e32 v164, vcc, 0x782000, v138
	s_nop 0
	v_addc_co_u32_e32 v165, vcc, 0, v139, vcc
	v_add_co_u32_e32 v168, vcc, 0x783000, v138
	s_nop 1
	v_addc_co_u32_e32 v169, vcc, 0, v139, vcc
	v_add_co_u32_e32 v172, vcc, 0x784000, v138
	s_nop 0
	v_addc_co_u32_e32 v173, vcc, 0, v139, vcc
	v_add_co_u32_e32 v176, vcc, 0x785000, v138
	s_nop 1
	v_addc_co_u32_e32 v177, vcc, 0, v139, vcc
	v_add_co_u32_e32 v180, vcc, 0x786000, v138
	s_nop 0
	v_addc_co_u32_e32 v181, vcc, 0, v139, vcc
	v_add_co_u32_e32 v138, vcc, 0x787000, v138
	s_nop 1
	v_addc_co_u32_e32 v139, vcc, 0, v139, vcc
	s_nop 0
	s_setprio 1
	ds_read_b128 v[188:191], v133 offset:0
	ds_read_b128 v[200:203], v137 offset:18432
	ds_read_b128 v[204:207], v137 offset:23040
	ds_read_b128 v[208:211], v137 offset:27648
	ds_read_b128 v[212:215], v137 offset:32256
	ds_read_b128 v[196:199], v133 offset:4608
	s_waitcnt lgkmcnt(4)
	v_mfma_f32_32x32x16_bf16 v[114:129], v[188:191], v[200:203], v[114:129]
	ds_read_b128 v[192:195], v133 offset:32
	ds_read_b128 v[216:219], v137 offset:18464
	s_waitcnt lgkmcnt(5)
	v_mfma_f32_32x32x16_bf16 v[98:113], v[188:191], v[204:207], v[98:113]
	ds_read_b128 v[224:227], v137 offset:23072
	s_waitcnt lgkmcnt(5)
	v_mfma_f32_32x32x16_bf16 v[82:97], v[188:191], v[208:211], v[82:97]
	ds_read_b128 v[228:231], v137 offset:27680
	s_waitcnt lgkmcnt(5)
	v_mfma_f32_32x32x16_bf16 v[66:81], v[188:191], v[212:215], v[66:81]
	ds_read_b128 v[232:235], v137 offset:32288
	s_waitcnt lgkmcnt(5)
	v_mfma_f32_32x32x16_bf16 v[50:65], v[196:199], v[200:203], v[50:65]
	v_mfma_f32_32x32x16_bf16 v[34:49], v[196:199], v[204:207], v[34:49]
	v_mfma_f32_32x32x16_bf16 v[18:33], v[196:199], v[208:211], v[18:33]
	v_mfma_f32_32x32x16_bf16 v[2:17], v[196:199], v[212:215], v[2:17]
	ds_read_b128 v[196:199], v133 offset:4640
	s_waitcnt lgkmcnt(4)
	v_mfma_f32_32x32x16_bf16 v[114:129], v[192:195], v[216:219], v[114:129]
	ds_read_b128 v[188:191], v133 offset:64
	ds_read_b128 v[200:203], v137 offset:18496
	s_waitcnt lgkmcnt(5)
	v_mfma_f32_32x32x16_bf16 v[98:113], v[192:195], v[224:227], v[98:113]
	ds_read_b128 v[204:207], v137 offset:23104
	s_waitcnt lgkmcnt(5)
	v_mfma_f32_32x32x16_bf16 v[82:97], v[192:195], v[228:231], v[82:97]
	ds_read_b128 v[208:211], v137 offset:27712
	s_waitcnt lgkmcnt(5)
	v_mfma_f32_32x32x16_bf16 v[66:81], v[192:195], v[232:235], v[66:81]
	ds_read_b128 v[212:215], v137 offset:32320
	s_waitcnt lgkmcnt(5)
	v_mfma_f32_32x32x16_bf16 v[50:65], v[196:199], v[216:219], v[50:65]
	v_mfma_f32_32x32x16_bf16 v[34:49], v[196:199], v[224:227], v[34:49]
	v_mfma_f32_32x32x16_bf16 v[18:33], v[196:199], v[228:231], v[18:33]
	v_mfma_f32_32x32x16_bf16 v[2:17], v[196:199], v[232:235], v[2:17]
	ds_read_b128 v[196:199], v133 offset:4672
	s_waitcnt lgkmcnt(4)
	v_mfma_f32_32x32x16_bf16 v[114:129], v[188:191], v[200:203], v[114:129]
	ds_read_b128 v[192:195], v133 offset:96
	ds_read_b128 v[216:219], v137 offset:18528
	s_waitcnt lgkmcnt(5)
	v_mfma_f32_32x32x16_bf16 v[98:113], v[188:191], v[204:207], v[98:113]
	ds_read_b128 v[224:227], v137 offset:23136
	s_waitcnt lgkmcnt(5)
	v_mfma_f32_32x32x16_bf16 v[82:97], v[188:191], v[208:211], v[82:97]
	ds_read_b128 v[228:231], v137 offset:27744
	s_waitcnt lgkmcnt(5)
	v_mfma_f32_32x32x16_bf16 v[66:81], v[188:191], v[212:215], v[66:81]
	ds_read_b128 v[232:235], v137 offset:32352
	s_waitcnt lgkmcnt(5)
	v_mfma_f32_32x32x16_bf16 v[50:65], v[196:199], v[200:203], v[50:65]
	v_mfma_f32_32x32x16_bf16 v[34:49], v[196:199], v[204:207], v[34:49]
	v_mfma_f32_32x32x16_bf16 v[18:33], v[196:199], v[208:211], v[18:33]
	v_mfma_f32_32x32x16_bf16 v[2:17], v[196:199], v[212:215], v[2:17]
	ds_read_b128 v[196:199], v133 offset:4704
	s_waitcnt lgkmcnt(4)
	v_mfma_f32_32x32x16_bf16 v[114:129], v[192:195], v[216:219], v[114:129]
	s_waitcnt lgkmcnt(3)
	v_mfma_f32_32x32x16_bf16 v[98:113], v[192:195], v[224:227], v[98:113]
	s_waitcnt lgkmcnt(2)
	v_mfma_f32_32x32x16_bf16 v[82:97], v[192:195], v[228:231], v[82:97]
	s_waitcnt lgkmcnt(1)
	v_mfma_f32_32x32x16_bf16 v[66:81], v[192:195], v[232:235], v[66:81]
	s_waitcnt lgkmcnt(0)
	v_mfma_f32_32x32x16_bf16 v[50:65], v[196:199], v[216:219], v[50:65]
	v_mfma_f32_32x32x16_bf16 v[34:49], v[196:199], v[224:227], v[34:49]
	v_mfma_f32_32x32x16_bf16 v[18:33], v[196:199], v[228:231], v[18:33]
	v_mfma_f32_32x32x16_bf16 v[2:17], v[196:199], v[232:235], v[2:17]
	s_setprio 0
	v_mov_b32_e32 v130, v134
	s_barrier
	s_waitcnt lgkmcnt(0)
	s_mul_hi_i32 s13, s14, 0x1100
	v_ashrrev_i32_e32 v132, 1, v130
	s_mulk_i32 s14, 0x1100
	v_bfi_b32 v132, s39, v132, v130
	s_add_u32 s14, s14, s16
	s_addc_u32 s15, s13, s17
	v_ashrrev_i32_e32 v133, 31, v132
	v_lshl_add_u64 v[138:139], s[14:15], 0, v[132:133]
	v_and_b32_e32 v130, 32, v130
	v_lshlrev_b64 v[138:139], 12, v[138:139]
	v_mul_lo_u32 v132, v132, s22
	v_lshl_add_u32 v137, v130, 2, v132
	v_lshl_add_u64 v[132:133], s[4:5], 0, v[138:139]
	v_lshlrev_b32_e32 v130, 1, v130
	s_lshl_b32 s16, s12, 7
	v_lshl_add_u64 v[132:133], v[132:133], 0, v[130:131]
	s_mov_b64 s[12:13], -1
	s_branch .LBB0_2068

;     ...
;   for (int kt = 0; kt < nk; ++kt) {
;     const int kn = (kt + 1 < nk) ? kt + 1 : kt;
;     GW_LOAD2(kn * 64, kn * bkstep)
;     __builtin_amdgcn_sched_barrier(0);
;     __builtin_amdgcn_s_setprio(1);
; #pragma unroll
;     for (int st = 0; st < 4; ++st) {
;       bf16x8 a0 = *(const bf16x8*)(Ab + st * 32);
;       bf16x8 a1 = *(const bf16x8*)(Ab + 32 * LSTR + st * 32);
;       bf16x8 b0 = *(const bf16x8*)(Bb + st * 32);
;       bf16x8 b1 = *(const bf16x8*)(Bb + 32 * LSTR + st * 32);
;       bf16x8 b2 = *(const bf16x8*)(Bb + 64 * LSTR + st * 32);
;       bf16x8 b3 = *(const bf16x8*)(Bb + 96 * LSTR + st * 32);
;       acc[0][0] = mfma32(a0, b0, acc[0][0]);
;       acc[0][1] = mfma32(a0, b1, acc[0][1]);
;       acc[0][2] = mfma32(a0, b2, acc[0][2]);
;       acc[0][3] = mfma32(a0, b3, acc[0][3]);
;       acc[1][0] = mfma32(a1, b0, acc[1][0]);
;       acc[1][1] = mfma32(a1, b1, acc[1][1]);
;       acc[1][2] = mfma32(a1, b2, acc[1][2]);
;       acc[1][3] = mfma32(a1, b3, acc[1][3]);
;     }
;     __builtin_amdgcn_s_setprio(0);
;     __builtin_amdgcn_sched_barrier(0);
;     __syncthreads();
;     GW_STORE()
;     __syncthreads();
;   }
.LBB0_2143:
	s_barrier
	s_setprio 1
	ds_read_b128 v[200:203], v133 offset:0
	ds_read_b128 v[212:215], v137 offset:18432
	ds_read_b128 v[216:219], v137 offset:23040
	ds_read_b128 v[224:227], v137 offset:27648
	ds_read_b128 v[228:231], v137 offset:32256
	ds_read_b128 v[208:211], v133 offset:4608
	s_waitcnt lgkmcnt(4)
	v_mfma_f32_32x32x16_bf16 v[114:129], v[200:203], v[212:215], v[114:129]
	ds_read_b128 v[204:207], v133 offset:32
	ds_read_b128 v[232:235], v137 offset:18464
	s_waitcnt lgkmcnt(5)
	v_mfma_f32_32x32x16_bf16 v[98:113], v[200:203], v[216:219], v[98:113]
	ds_read_b128 v[236:239], v137 offset:23072
	s_waitcnt lgkmcnt(5)
	v_mfma_f32_32x32x16_bf16 v[82:97], v[200:203], v[224:227], v[82:97]
	ds_read_b128 v[240:243], v137 offset:27680
	s_waitcnt lgkmcnt(5)
	v_mfma_f32_32x32x16_bf16 v[66:81], v[200:203], v[228:231], v[66:81]
	ds_read_b128 v[244:247], v137 offset:32288
	s_waitcnt lgkmcnt(5)
	v_mfma_f32_32x32x16_bf16 v[50:65], v[208:211], v[212:215], v[50:65]
	v_lshl_add_u64 v[152:153], v[150:151], 0, v[130:131]
	v_add_co_u32_e32 v152, vcc, s37, v152
	s_nop 1
	v_addc_co_u32_e32 v153, vcc, 0, v153, vcc
	global_load_dwordx4 v[152:155], v[152:153], off offset:384
	v_mfma_f32_32x32x16_bf16 v[34:49], v[208:211], v[216:219], v[34:49]
	v_lshl_add_u64 v[156:157], v[150:151], 0, v[130:131]
	v_add_co_u32_e32 v156, vcc, s38, v156
	s_nop 1
	v_addc_co_u32_e32 v157, vcc, 0, v157, vcc
	global_load_dwordx4 v[156:159], v[156:157], off offset:384
	v_mfma_f32_32x32x16_bf16 v[18:33], v[208:211], v[224:227], v[18:33]
	v_lshl_add_u64 v[160:161], v[150:151], 0, v[130:131]
	v_add_co_u32_e32 v160, vcc, s39, v160
	s_nop 1
	v_addc_co_u32_e32 v161, vcc, 0, v161, vcc
	global_load_dwordx4 v[160:163], v[160:161], off offset:384
	v_mfma_f32_32x32x16_bf16 v[2:17], v[208:211], v[228:231], v[2:17]
	v_lshl_add_u64 v[164:165], v[150:151], 0, v[130:131]
	v_add_co_u32_e32 v164, vcc, s40, v164
	s_nop 1
	v_addc_co_u32_e32 v165, vcc, 0, v165, vcc
	global_load_dwordx4 v[164:167], v[164:165], off offset:384
	ds_read_b128 v[208:211], v133 offset:4640
	s_waitcnt lgkmcnt(4)
	v_mfma_f32_32x32x16_bf16 v[114:129], v[204:207], v[232:235], v[114:129]
	ds_read_b128 v[200:203], v133 offset:64
	ds_read_b128 v[212:215], v137 offset:18496
	s_waitcnt lgkmcnt(5)
	v_mfma_f32_32x32x16_bf16 v[98:113], v[204:207], v[236:239], v[98:113]
	ds_read_b128 v[216:219], v137 offset:23104
	s_waitcnt lgkmcnt(5)
	v_mfma_f32_32x32x16_bf16 v[82:97], v[204:207], v[240:243], v[82:97]
	ds_read_b128 v[224:227], v137 offset:27712
	s_waitcnt lgkmcnt(5)
	v_mfma_f32_32x32x16_bf16 v[66:81], v[204:207], v[244:247], v[66:81]
	ds_read_b128 v[228:231], v137 offset:32320
	s_waitcnt lgkmcnt(5)
	v_mfma_f32_32x32x16_bf16 v[50:65], v[208:211], v[232:235], v[50:65]
	v_lshl_add_u64 v[168:169], v[148:149], 0, v[130:131]
	v_add_co_u32_e32 v168, vcc, s41, v168
	s_nop 1
	v_addc_co_u32_e32 v169, vcc, 0, v169, vcc
	global_load_dwordx4 v[168:171], v[168:169], off offset:-4096
	v_mfma_f32_32x32x16_bf16 v[34:49], v[208:211], v[236:239], v[34:49]
	v_lshl_add_u64 v[172:173], v[148:149], 0, v[130:131]
	v_add_co_u32_e32 v172, vcc, s41, v172
	s_nop 1
	v_addc_co_u32_e32 v173, vcc, 0, v173, vcc
	global_load_dwordx4 v[172:175], v[172:173], off
	v_mfma_f32_32x32x16_bf16 v[18:33], v[208:211], v[240:243], v[18:33]
	v_lshl_add_u64 v[176:177], v[148:149], 0, v[130:131]
	v_add_co_u32_e32 v176, vcc, s42, v176
	s_nop 1
	v_addc_co_u32_e32 v177, vcc, 0, v177, vcc
	global_load_dwordx4 v[176:179], v[176:177], off offset:-4096
	v_mfma_f32_32x32x16_bf16 v[2:17], v[208:211], v[244:247], v[2:17]
	v_lshl_add_u64 v[180:181], v[148:149], 0, v[130:131]
	v_add_co_u32_e32 v180, vcc, s42, v180
	s_nop 1
	v_addc_co_u32_e32 v181, vcc, 0, v181, vcc
	global_load_dwordx4 v[180:183], v[180:181], off
	ds_read_b128 v[208:211], v133 offset:4672
	s_waitcnt lgkmcnt(4)
	v_mfma_f32_32x32x16_bf16 v[114:129], v[200:203], v[212:215], v[114:129]
	ds_read_b128 v[204:207], v133 offset:96
	ds_read_b128 v[232:235], v137 offset:18528
	s_waitcnt lgkmcnt(5)
	v_mfma_f32_32x32x16_bf16 v[98:113], v[200:203], v[216:219], v[98:113]
	ds_read_b128 v[236:239], v137 offset:23136
	s_waitcnt lgkmcnt(5)
	v_mfma_f32_32x32x16_bf16 v[82:97], v[200:203], v[224:227], v[82:97]
	ds_read_b128 v[240:243], v137 offset:27744
	s_waitcnt lgkmcnt(5)
	v_mfma_f32_32x32x16_bf16 v[66:81], v[200:203], v[228:231], v[66:81]
	ds_read_b128 v[244:247], v137 offset:32352
	s_waitcnt lgkmcnt(5)
	v_mfma_f32_32x32x16_bf16 v[50:65], v[208:211], v[212:215], v[50:65]
	v_lshl_add_u64 v[184:185], v[148:149], 0, v[130:131]
	v_add_co_u32_e32 v184, vcc, s43, v184
	s_nop 1
	v_addc_co_u32_e32 v185, vcc, 0, v185, vcc
	global_load_dwordx4 v[184:187], v[184:185], off offset:-4096
	v_mfma_f32_32x32x16_bf16 v[34:49], v[208:211], v[216:219], v[34:49]
	v_lshl_add_u64 v[188:189], v[148:149], 0, v[130:131]
	v_add_co_u32_e32 v188, vcc, s43, v188
	s_nop 1
	v_addc_co_u32_e32 v189, vcc, 0, v189, vcc
	global_load_dwordx4 v[188:191], v[188:189], off
	v_mfma_f32_32x32x16_bf16 v[18:33], v[208:211], v[224:227], v[18:33]
	v_lshl_add_u64 v[192:193], v[148:149], 0, v[130:131]
	v_add_co_u32_e32 v192, vcc, s44, v192
	s_nop 1
	v_addc_co_u32_e32 v193, vcc, 0, v193, vcc
	global_load_dwordx4 v[192:195], v[192:193], off offset:-4096
	v_mfma_f32_32x32x16_bf16 v[2:17], v[208:211], v[228:231], v[2:17]
	v_lshl_add_u64 v[196:197], v[148:149], 0, v[130:131]
	v_add_co_u32_e32 v196, vcc, s44, v196
	s_nop 1
	v_addc_co_u32_e32 v197, vcc, 0, v197, vcc
	global_load_dwordx4 v[196:199], v[196:197], off
	ds_read_b128 v[208:211], v133 offset:4704
	s_waitcnt lgkmcnt(4)
	v_mfma_f32_32x32x16_bf16 v[114:129], v[204:207], v[232:235], v[114:129]
	s_waitcnt lgkmcnt(3)
	v_mfma_f32_32x32x16_bf16 v[98:113], v[204:207], v[236:239], v[98:113]
	s_waitcnt lgkmcnt(2)
	v_mfma_f32_32x32x16_bf16 v[82:97], v[204:207], v[240:243], v[82:97]
	s_waitcnt lgkmcnt(1)
	v_mfma_f32_32x32x16_bf16 v[66:81], v[204:207], v[244:247], v[66:81]
	s_waitcnt lgkmcnt(0)
	v_mfma_f32_32x32x16_bf16 v[50:65], v[208:211], v[232:235], v[50:65]
	v_mfma_f32_32x32x16_bf16 v[34:49], v[208:211], v[236:239], v[34:49]
	v_mfma_f32_32x32x16_bf16 v[18:33], v[208:211], v[240:243], v[18:33]
	v_mfma_f32_32x32x16_bf16 v[2:17], v[208:211], v[244:247], v[2:17]
	s_setprio 0
	s_add_i32 s15, s15, -1
	v_lshl_add_u64 v[148:149], v[148:149], 0, s[4:5]
	s_cmp_lg_u32 s15, 0
	v_lshl_add_u64 v[150:151], v[150:151], 0, s[10:11]
	s_barrier
;     ...
;   for (int kt = 0; kt < nk; ++kt) {
;     const int kn = (kt + 1 < nk) ? kt + 1 : kt;
;     GW_LOAD2(kn * 64, kn * bkstep)
;     __builtin_amdgcn_sched_barrier(0);
;     __builtin_amdgcn_s_setprio(1);
; #pragma unroll
;     for (int st = 0; st < 4; ++st) {
;       bf16x8 a0 = *(const bf16x8*)(Ab + st * 32);
;       bf16x8 a1 = *(const bf16x8*)(Ab + 32 * LSTR + st * 32);
;       bf16x8 b0 = *(const bf16x8*)(Bb + st * 32);
;       bf16x8 b1 = *(const bf16x8*)(Bb + 32 * LSTR + st * 32);
;       bf16x8 b2 = *(const bf16x8*)(Bb + 64 * LSTR + st * 32);
;       bf16x8 b3 = *(const bf16x8*)(Bb + 96 * LSTR + st * 32);
;       acc[0][0] = mfma32(a0, b0, acc[0][0]);
;       acc[0][1] = mfma32(a0, b1, acc[0][1]);
;       acc[0][2] = mfma32(a0, b2, acc[0][2]);
;       acc[0][3] = mfma32(a0, b3, acc[0][3]);
;       acc[1][0] = mfma32(a1, b0, acc[1][0]);
;       acc[1][1] = mfma32(a1, b1, acc[1][1]);
;       acc[1][2] = mfma32(a1, b2, acc[1][2]);
;       acc[1][3] = mfma32(a1, b3, acc[1][3]);
;     }
;     __builtin_amdgcn_s_setprio(0);
;     __builtin_amdgcn_sched_barrier(0);
;     __syncthreads();
;     GW_STORE()
;     __syncthreads();
;   }
	s_waitcnt vmcnt(11)
	ds_write_b128 v132, v[152:155]
	s_waitcnt vmcnt(10)
	ds_write_b128 v132, v[156:159] offset:4608
	s_waitcnt vmcnt(9)
	ds_write_b128 v132, v[160:163] offset:9216
	s_waitcnt vmcnt(8)
	ds_write_b128 v132, v[164:167] offset:13824
	s_waitcnt vmcnt(7)
	ds_write_b128 v132, v[168:171] offset:18432
	s_waitcnt vmcnt(6)
	ds_write_b128 v132, v[172:175] offset:23040
	s_waitcnt vmcnt(5)
	ds_write_b128 v132, v[176:179] offset:27648
	s_waitcnt vmcnt(4)
	ds_write_b128 v132, v[180:183] offset:32256
	s_waitcnt vmcnt(3)
	ds_write_b128 v132, v[184:187] offset:36864
	s_waitcnt vmcnt(2)
	ds_write_b128 v132, v[188:191] offset:41472
	s_waitcnt vmcnt(1)
	ds_write_b128 v132, v[192:195] offset:46080
	s_waitcnt vmcnt(0)
	ds_write_b128 v132, v[196:199] offset:50688
	s_waitcnt lgkmcnt(0)
	s_cbranch_scc1 .LBB0_2143
	s_barrier
	s_setprio 1
	ds_read_b128 v[200:203], v133 offset:0
	ds_read_b128 v[212:215], v137 offset:18432
	ds_read_b128 v[216:219], v137 offset:23040
	ds_read_b128 v[224:227], v137 offset:27648
	ds_read_b128 v[228:231], v137 offset:32256
	ds_read_b128 v[208:211], v133 offset:4608
	s_waitcnt lgkmcnt(4)
	v_mfma_f32_32x32x16_bf16 v[114:129], v[200:203], v[212:215], v[114:129]
	ds_read_b128 v[204:207], v133 offset:32
	ds_read_b128 v[232:235], v137 offset:18464
	s_waitcnt lgkmcnt(5)
	v_mfma_f32_32x32x16_bf16 v[98:113], v[200:203], v[216:219], v[98:113]
	ds_read_b128 v[236:239], v137 offset:23072
	s_waitcnt lgkmcnt(5)
	v_mfma_f32_32x32x16_bf16 v[82:97], v[200:203], v[224:227], v[82:97]
	ds_read_b128 v[240:243], v137 offset:27680
	s_waitcnt lgkmcnt(5)
	v_mfma_f32_32x32x16_bf16 v[66:81], v[200:203], v[228:231], v[66:81]
	ds_read_b128 v[244:247], v137 offset:32288
	s_waitcnt lgkmcnt(5)
	v_mfma_f32_32x32x16_bf16 v[50:65], v[208:211], v[212:215], v[50:65]
	v_lshl_add_u64 v[152:153], v[150:151], 0, v[130:131]
	v_add_co_u32_e32 v152, vcc, s37, v152
	s_nop 1
	v_addc_co_u32_e32 v153, vcc, 0, v153, vcc
	global_load_dwordx4 v[152:155], v[152:153], off offset:384
	v_mfma_f32_32x32x16_bf16 v[34:49], v[208:211], v[216:219], v[34:49]
	v_lshl_add_u64 v[156:157], v[150:151], 0, v[130:131]
	v_add_co_u32_e32 v156, vcc, s38, v156
	s_nop 1
	v_addc_co_u32_e32 v157, vcc, 0, v157, vcc
	global_load_dwordx4 v[156:159], v[156:157], off offset:384
	v_mfma_f32_32x32x16_bf16 v[18:33], v[208:211], v[224:227], v[18:33]
	v_lshl_add_u64 v[160:161], v[150:151], 0, v[130:131]
	v_add_co_u32_e32 v160, vcc, s39, v160
	s_nop 1
	v_addc_co_u32_e32 v161, vcc, 0, v161, vcc
	global_load_dwordx4 v[160:163], v[160:161], off offset:384
	v_mfma_f32_32x32x16_bf16 v[2:17], v[208:211], v[228:231], v[2:17]
	v_lshl_add_u64 v[164:165], v[150:151], 0, v[130:131]
	v_add_co_u32_e32 v164, vcc, s40, v164
	s_nop 1
	v_addc_co_u32_e32 v165, vcc, 0, v165, vcc
	global_load_dwordx4 v[164:167], v[164:165], off offset:384
	ds_read_b128 v[208:211], v133 offset:4640
	s_waitcnt lgkmcnt(4)
	v_mfma_f32_32x32x16_bf16 v[114:129], v[204:207], v[232:235], v[114:129]
	ds_read_b128 v[200:203], v133 offset:64
	ds_read_b128 v[212:215], v137 offset:18496
	s_waitcnt lgkmcnt(5)
	v_mfma_f32_32x32x16_bf16 v[98:113], v[204:207], v[236:239], v[98:113]
	ds_read_b128 v[216:219], v137 offset:23104
	s_waitcnt lgkmcnt(5)
	v_mfma_f32_32x32x16_bf16 v[82:97], v[204:207], v[240:243], v[82:97]
	ds_read_b128 v[224:227], v137 offset:27712
	s_waitcnt lgkmcnt(5)
	v_mfma_f32_32x32x16_bf16 v[66:81], v[204:207], v[244:247], v[66:81]
	ds_read_b128 v[228:231], v137 offset:32320
	s_waitcnt lgkmcnt(5)
	v_mfma_f32_32x32x16_bf16 v[50:65], v[208:211], v[232:235], v[50:65]
	v_lshl_add_u64 v[168:169], v[148:149], 0, v[130:131]
	v_add_co_u32_e32 v168, vcc, s41, v168
	s_nop 1
	v_addc_co_u32_e32 v169, vcc, 0, v169, vcc
	global_load_dwordx4 v[168:171], v[168:169], off offset:-4096
	v_mfma_f32_32x32x16_bf16 v[34:49], v[208:211], v[236:239], v[34:49]
	v_lshl_add_u64 v[172:173], v[148:149], 0, v[130:131]
	v_add_co_u32_e32 v172, vcc, s41, v172
	s_nop 1
	v_addc_co_u32_e32 v173, vcc, 0, v173, vcc
	global_load_dwordx4 v[172:175], v[172:173], off
	v_mfma_f32_32x32x16_bf16 v[18:33], v[208:211], v[240:243], v[18:33]
	v_lshl_add_u64 v[176:177], v[148:149], 0, v[130:131]
	v_add_co_u32_e32 v176, vcc, s42, v176
	s_nop 1
	v_addc_co_u32_e32 v177, vcc, 0, v177, vcc
	global_load_dwordx4 v[176:179], v[176:177], off offset:-4096
	v_mfma_f32_32x32x16_bf16 v[2:17], v[208:211], v[244:247], v[2:17]
	v_lshl_add_u64 v[180:181], v[148:149], 0, v[130:131]
	v_add_co_u32_e32 v180, vcc, s42, v180
	s_nop 1
	v_addc_co_u32_e32 v181, vcc, 0, v181, vcc
	global_load_dwordx4 v[180:183], v[180:181], off
	ds_read_b128 v[208:211], v133 offset:4672
	s_waitcnt lgkmcnt(4)
	v_mfma_f32_32x32x16_bf16 v[114:129], v[200:203], v[212:215], v[114:129]
	ds_read_b128 v[204:207], v133 offset:96
	ds_read_b128 v[232:235], v137 offset:18528
	s_waitcnt lgkmcnt(5)
	v_mfma_f32_32x32x16_bf16 v[98:113], v[200:203], v[216:219], v[98:113]
	ds_read_b128 v[236:239], v137 offset:23136
	s_waitcnt lgkmcnt(5)
	v_mfma_f32_32x32x16_bf16 v[82:97], v[200:203], v[224:227], v[82:97]
	ds_read_b128 v[240:243], v137 offset:27744
	s_waitcnt lgkmcnt(5)
	v_mfma_f32_32x32x16_bf16 v[66:81], v[200:203], v[228:231], v[66:81]
	ds_read_b128 v[244:247], v137 offset:32352
	s_waitcnt lgkmcnt(5)
;     ...
;   for (int kt = 0; kt < nk; ++kt) {
;     const int kn = (kt + 1 < nk) ? kt + 1 : kt;
;     GW_LOAD2(kn * 64, kn * bkstep)
;     __builtin_amdgcn_sched_barrier(0);
;     __builtin_amdgcn_s_setprio(1);
; #pragma unroll
;     for (int st = 0; st < 4; ++st) {
;       bf16x8 a0 = *(const bf16x8*)(Ab + st * 32);
;       bf16x8 a1 = *(const bf16x8*)(Ab + 32 * LSTR + st * 32);
;       bf16x8 b0 = *(const bf16x8*)(Bb + st * 32);
;       bf16x8 b1 = *(const bf16x8*)(Bb + 32 * LSTR + st * 32);
;       bf16x8 b2 = *(const bf16x8*)(Bb + 64 * LSTR + st * 32);
;       bf16x8 b3 = *(const bf16x8*)(Bb + 96 * LSTR + st * 32);
;       acc[0][0] = mfma32(a0, b0, acc[0][0]);
;       acc[0][1] = mfma32(a0, b1, acc[0][1]);
;       acc[0][2] = mfma32(a0, b2, acc[0][2]);
;       acc[0][3] = mfma32(a0, b3, acc[0][3]);
;       acc[1][0] = mfma32(a1, b0, acc[1][0]);
;       acc[1][1] = mfma32(a1, b1, acc[1][1]);
;       acc[1][2] = mfma32(a1, b2, acc[1][2]);
;       acc[1][3] = mfma32(a1, b3, acc[1][3]);
;     }
;     __builtin_amdgcn_s_setprio(0);
;     __builtin_amdgcn_sched_barrier(0);
;     __syncthreads();
;     GW_STORE()
;     __syncthreads();
;   }
	v_mfma_f32_32x32x16_bf16 v[50:65], v[208:211], v[212:215], v[50:65]
	v_lshl_add_u64 v[184:185], v[148:149], 0, v[130:131]
	v_add_co_u32_e32 v184, vcc, s43, v184
	s_nop 1
	v_addc_co_u32_e32 v185, vcc, 0, v185, vcc
	global_load_dwordx4 v[184:187], v[184:185], off offset:-4096
	v_mfma_f32_32x32x16_bf16 v[34:49], v[208:211], v[216:219], v[34:49]
	v_lshl_add_u64 v[188:189], v[148:149], 0, v[130:131]
	v_add_co_u32_e32 v188, vcc, s43, v188
	s_nop 1
	v_addc_co_u32_e32 v189, vcc, 0, v189, vcc
	global_load_dwordx4 v[188:191], v[188:189], off
	v_mfma_f32_32x32x16_bf16 v[18:33], v[208:211], v[224:227], v[18:33]
	v_lshl_add_u64 v[192:193], v[148:149], 0, v[130:131]
	v_add_co_u32_e32 v192, vcc, s44, v192
	s_nop 1
	v_addc_co_u32_e32 v193, vcc, 0, v193, vcc
	global_load_dwordx4 v[192:195], v[192:193], off offset:-4096
	v_mfma_f32_32x32x16_bf16 v[2:17], v[208:211], v[228:231], v[2:17]
	v_lshl_add_u64 v[196:197], v[148:149], 0, v[130:131]
	v_add_co_u32_e32 v196, vcc, s44, v196
	s_nop 1
	v_addc_co_u32_e32 v197, vcc, 0, v197, vcc
	global_load_dwordx4 v[196:199], v[196:197], off
	ds_read_b128 v[208:211], v133 offset:4704
	s_waitcnt lgkmcnt(4)
	v_mfma_f32_32x32x16_bf16 v[114:129], v[204:207], v[232:235], v[114:129]
	s_waitcnt lgkmcnt(3)
	v_mfma_f32_32x32x16_bf16 v[98:113], v[204:207], v[236:239], v[98:113]
	s_waitcnt lgkmcnt(2)
	v_mfma_f32_32x32x16_bf16 v[82:97], v[204:207], v[240:243], v[82:97]
	s_waitcnt lgkmcnt(1)
	v_mfma_f32_32x32x16_bf16 v[66:81], v[204:207], v[244:247], v[66:81]
	s_waitcnt lgkmcnt(0)
	v_mfma_f32_32x32x16_bf16 v[50:65], v[208:211], v[232:235], v[50:65]
	v_mfma_f32_32x32x16_bf16 v[34:49], v[208:211], v[236:239], v[34:49]
	v_mfma_f32_32x32x16_bf16 v[18:33], v[208:211], v[240:243], v[18:33]
	v_mfma_f32_32x32x16_bf16 v[2:17], v[208:211], v[244:247], v[2:17]
	s_setprio 0
	v_lshl_add_u64 v[148:149], v[148:149], 0, s[4:5]
	v_lshl_add_u64 v[150:151], v[150:151], 0, s[10:11]
	s_barrier
	s_waitcnt vmcnt(11)
	ds_write_b128 v132, v[152:155]
	s_waitcnt vmcnt(10)
	ds_write_b128 v132, v[156:159] offset:4608
	s_waitcnt vmcnt(9)
	ds_write_b128 v132, v[160:163] offset:9216
	s_waitcnt vmcnt(8)
	ds_write_b128 v132, v[164:167] offset:13824
	s_waitcnt vmcnt(7)
	ds_write_b128 v132, v[168:171] offset:18432
	s_waitcnt vmcnt(6)
	ds_write_b128 v132, v[172:175] offset:23040
	s_waitcnt vmcnt(5)
	ds_write_b128 v132, v[176:179] offset:27648
	s_waitcnt vmcnt(4)
	ds_write_b128 v132, v[180:183] offset:32256
	s_waitcnt vmcnt(3)
	ds_write_b128 v132, v[184:187] offset:36864
	s_waitcnt vmcnt(2)
	ds_write_b128 v132, v[188:191] offset:41472
	s_waitcnt vmcnt(1)
	ds_write_b128 v132, v[192:195] offset:46080
	s_waitcnt vmcnt(0)
	ds_write_b128 v132, v[196:199] offset:50688
	s_waitcnt lgkmcnt(0)
	s_barrier
;     ...
;   for (int kt = 0; kt < nk; ++kt) {
;     const int kn = (kt + 1 < nk) ? kt + 1 : kt;
;     GW_LOAD2(kn * 64, kn * bkstep)
;     __builtin_amdgcn_sched_barrier(0);
;     __builtin_amdgcn_s_setprio(1);
; #pragma unroll
;     for (int st = 0; st < 4; ++st) {
;       bf16x8 a0 = *(const bf16x8*)(Ab + st * 32);
;       bf16x8 a1 = *(const bf16x8*)(Ab + 32 * LSTR + st * 32);
;       bf16x8 b0 = *(const bf16x8*)(Bb + st * 32);
;       bf16x8 b1 = *(const bf16x8*)(Bb + 32 * LSTR + st * 32);
;       bf16x8 b2 = *(const bf16x8*)(Bb + 64 * LSTR + st * 32);
;       bf16x8 b3 = *(const bf16x8*)(Bb + 96 * LSTR + st * 32);
;       acc[0][0] = mfma32(a0, b0, acc[0][0]);
;       acc[0][1] = mfma32(a0, b1, acc[0][1]);
;       acc[0][2] = mfma32(a0, b2, acc[0][2]);
;       acc[0][3] = mfma32(a0, b3, acc[0][3]);
;       acc[1][0] = mfma32(a1, b0, acc[1][0]);
;       acc[1][1] = mfma32(a1, b1, acc[1][1]);
;       acc[1][2] = mfma32(a1, b2, acc[1][2]);
;       acc[1][3] = mfma32(a1, b3, acc[1][3]);
;     }
;     __builtin_amdgcn_s_setprio(0);
;     __builtin_amdgcn_sched_barrier(0);
;     __syncthreads();
;     GW_STORE()
;     __syncthreads();
;   }
	v_add_co_u32_e32 v156, vcc, 0x3e0000, v138
	s_nop 0
	s_nop 0
	s_nop 0
	v_addc_co_u32_e32 v157, vcc, 0, v139, vcc
	v_add_co_u32_e32 v160, vcc, 0x3e1000, v138
	s_mov_b32 s18, 0
	s_nop 0
	v_addc_co_u32_e32 v161, vcc, 0, v139, vcc
	v_add_co_u32_e32 v164, vcc, 0x3e2000, v138
	s_nop 0
	v_addc_co_u32_e32 v165, vcc, 0, v139, vcc
	v_add_co_u32_e32 v168, vcc, 0x3e3000, v138
	s_nop 1
	v_addc_co_u32_e32 v169, vcc, 0, v139, vcc
	v_add_co_u32_e32 v172, vcc, 0x3e4000, v138
	s_nop 0
	v_addc_co_u32_e32 v173, vcc, 0, v139, vcc
	v_add_co_u32_e32 v176, vcc, 0x3e5000, v138
	s_nop 1
	v_addc_co_u32_e32 v177, vcc, 0, v139, vcc
	v_add_co_u32_e32 v180, vcc, 0x3e6000, v138
	s_nop 0
	v_addc_co_u32_e32 v181, vcc, 0, v139, vcc
	v_add_co_u32_e32 v138, vcc, 0x3e7000, v138
	s_nop 1
	v_addc_co_u32_e32 v139, vcc, 0, v139, vcc
	s_nop 0
	s_setprio 1
	ds_read_b128 v[188:191], v133 offset:0
	ds_read_b128 v[200:203], v137 offset:18432
	ds_read_b128 v[204:207], v137 offset:23040
	ds_read_b128 v[208:211], v137 offset:27648
	ds_read_b128 v[212:215], v137 offset:32256
	ds_read_b128 v[196:199], v133 offset:4608
	s_waitcnt lgkmcnt(4)
	v_mfma_f32_32x32x16_bf16 v[114:129], v[188:191], v[200:203], v[114:129]
	ds_read_b128 v[192:195], v133 offset:32
	ds_read_b128 v[216:219], v137 offset:18464
	s_waitcnt lgkmcnt(5)
	v_mfma_f32_32x32x16_bf16 v[98:113], v[188:191], v[204:207], v[98:113]
	ds_read_b128 v[224:227], v137 offset:23072
	s_waitcnt lgkmcnt(5)
	v_mfma_f32_32x32x16_bf16 v[82:97], v[188:191], v[208:211], v[82:97]
	ds_read_b128 v[228:231], v137 offset:27680
	s_waitcnt lgkmcnt(5)
	v_mfma_f32_32x32x16_bf16 v[66:81], v[188:191], v[212:215], v[66:81]
	ds_read_b128 v[232:235], v137 offset:32288
	s_waitcnt lgkmcnt(5)
	v_mfma_f32_32x32x16_bf16 v[50:65], v[196:199], v[200:203], v[50:65]
	v_mfma_f32_32x32x16_bf16 v[34:49], v[196:199], v[204:207], v[34:49]
	v_mfma_f32_32x32x16_bf16 v[18:33], v[196:199], v[208:211], v[18:33]
	v_mfma_f32_32x32x16_bf16 v[2:17], v[196:199], v[212:215], v[2:17]
	ds_read_b128 v[196:199], v133 offset:4640
	s_waitcnt lgkmcnt(4)
	v_mfma_f32_32x32x16_bf16 v[114:129], v[192:195], v[216:219], v[114:129]
	ds_read_b128 v[188:191], v133 offset:64
	ds_read_b128 v[200:203], v137 offset:18496
	s_waitcnt lgkmcnt(5)
	v_mfma_f32_32x32x16_bf16 v[98:113], v[192:195], v[224:227], v[98:113]
	ds_read_b128 v[204:207], v137 offset:23104
	s_waitcnt lgkmcnt(5)
	v_mfma_f32_32x32x16_bf16 v[82:97], v[192:195], v[228:231], v[82:97]
	ds_read_b128 v[208:211], v137 offset:27712
	s_waitcnt lgkmcnt(5)
	v_mfma_f32_32x32x16_bf16 v[66:81], v[192:195], v[232:235], v[66:81]
	ds_read_b128 v[212:215], v137 offset:32320
	s_waitcnt lgkmcnt(5)
	v_mfma_f32_32x32x16_bf16 v[50:65], v[196:199], v[216:219], v[50:65]
	v_mfma_f32_32x32x16_bf16 v[34:49], v[196:199], v[224:227], v[34:49]
	v_mfma_f32_32x32x16_bf16 v[18:33], v[196:199], v[228:231], v[18:33]
	v_mfma_f32_32x32x16_bf16 v[2:17], v[196:199], v[232:235], v[2:17]
	ds_read_b128 v[196:199], v133 offset:4672
	s_waitcnt lgkmcnt(4)
	v_mfma_f32_32x32x16_bf16 v[114:129], v[188:191], v[200:203], v[114:129]
	ds_read_b128 v[192:195], v133 offset:96
	ds_read_b128 v[216:219], v137 offset:18528
	s_waitcnt lgkmcnt(5)
	v_mfma_f32_32x32x16_bf16 v[98:113], v[188:191], v[204:207], v[98:113]
	ds_read_b128 v[224:227], v137 offset:23136
	s_waitcnt lgkmcnt(5)
	v_mfma_f32_32x32x16_bf16 v[82:97], v[188:191], v[208:211], v[82:97]
	ds_read_b128 v[228:231], v137 offset:27744
	s_waitcnt lgkmcnt(5)
	v_mfma_f32_32x32x16_bf16 v[66:81], v[188:191], v[212:215], v[66:81]
	ds_read_b128 v[232:235], v137 offset:32352
	s_waitcnt lgkmcnt(5)
	v_mfma_f32_32x32x16_bf16 v[50:65], v[196:199], v[200:203], v[50:65]
	v_mfma_f32_32x32x16_bf16 v[34:49], v[196:199], v[204:207], v[34:49]
	v_mfma_f32_32x32x16_bf16 v[18:33], v[196:199], v[208:211], v[18:33]
	v_mfma_f32_32x32x16_bf16 v[2:17], v[196:199], v[212:215], v[2:17]
	ds_read_b128 v[196:199], v133 offset:4704
	s_waitcnt lgkmcnt(4)
	v_mfma_f32_32x32x16_bf16 v[114:129], v[192:195], v[216:219], v[114:129]
	s_waitcnt lgkmcnt(3)
	v_mfma_f32_32x32x16_bf16 v[98:113], v[192:195], v[224:227], v[98:113]
	s_waitcnt lgkmcnt(2)
	v_mfma_f32_32x32x16_bf16 v[82:97], v[192:195], v[228:231], v[82:97]
	s_waitcnt lgkmcnt(1)
	v_mfma_f32_32x32x16_bf16 v[66:81], v[192:195], v[232:235], v[66:81]
	s_waitcnt lgkmcnt(0)
	v_mfma_f32_32x32x16_bf16 v[50:65], v[196:199], v[216:219], v[50:65]
	v_mfma_f32_32x32x16_bf16 v[34:49], v[196:199], v[224:227], v[34:49]
	v_mfma_f32_32x32x16_bf16 v[18:33], v[196:199], v[228:231], v[18:33]
	v_mfma_f32_32x32x16_bf16 v[2:17], v[196:199], v[232:235], v[2:17]
	s_setprio 0
	s_lshl_b32 s19, s14, 8
	s_mov_b64 s[14:15], -1
	s_barrier
	s_waitcnt lgkmcnt(0)
	s_branch .LBB0_2146
